# v17 + nt hint on GEMM epilogue stores + s_setprio 1 around attention MFMA blocks
# speedup vs baseline: 1.0206x; 1.0133x over previous
;     __device__ __forceinline__ void operator()(const f32x4 (&acc)[2][2][4][2], const Unit& u, int wr, int wc, int fr, int fq) const {
;     ...
;                 if (MODE == 1) {
;                     if (special) {
;                         const f32x4 b0 = *(const GAS1 f32x4*)(bias + col) * -1.4426950408889634f, b1 = *(const GAS1 f32x4*)(bias + col + 4) * -1.4426950408889634f;
; #pragma unroll
;                         for (int j = 0; j < 4; ++j) { v0[j] = __builtin_amdgcn_rcpf(1.0f + __builtin_amdgcn_exp2f(__builtin_fmaf(v0[j], -1.4426950408889634f, b0[j])));
;                                                       v1[j] = __builtin_amdgcn_rcpf(1.0f + __builtin_amdgcn_exp2f(__builtin_fmaf(v1[j], -1.4426950408889634f, b1[j]))); }
;                     }
;                 }
;                 if (MODE == 2) {
;                     if (special) {
;                         const int fi = ((col & 63) >> 3) * 4;
;                         const f32x4 c = *(const GAS1 f32x4*)(cosT + (size_t)row * 32 + fi), s_ = *(const GAS1 f32x4*)(sinT + (size_t)row * 32 + fi);
;                         const f32x4 o1 = v0 * c - v1 * s_, o2 = v1 * c + v0 * s_; v0 = o1; v1 = o2;
;                     }
;                 }
;                 if (MODE == 3 || MODE == 4) {
;                     const u32x4 gw = *(const GAS1 u32x4*)(G + (size_t)row * ldg + col);
;                     const f32x4 g0 = {bf_lo(gw.x), bf_hi(gw.x), bf_lo(gw.y), bf_hi(gw.y)}, g1 = {bf_lo(gw.z), bf_hi(gw.z), bf_lo(gw.w), bf_hi(gw.w)};
;                     v0 = v0 * g0; v1 = v1 * g1;
;                     if (MODE == 4) {
;                         const u32x4 ow = *(const GAS1 u32x4*)((const bf16_t*)O + (size_t)row * ldc + col);
;                         const f32x4 o0 = {bf_lo(ow.x), bf_hi(ow.x), bf_lo(ow.y), bf_hi(ow.y)}, o1 = {bf_lo(ow.z), bf_hi(ow.z), bf_lo(ow.w), bf_hi(ow.w)};
;                         v0 += o0; v1 += o1;
;                     }
;                 }
;                 u32x4 w; w.x = cvt_pk_bf16(v0[0], v0[1]); w.y = cvt_pk_bf16(v0[2], v0[3]); w.z = cvt_pk_bf16(v1[0], v1[1]); w.w = cvt_pk_bf16(v1[2], v1[3]);
;                 if (bj == 0) asm volatile("ds_write_b128 %0, %1" :: "v"(wa), "v"(w)); else asm volatile("ds_write_b128 %0, %1 offset:64" :: "v"(wa), "v"(w));
;             }
;             asm volatile("ds_read_b128 %0, %1" : "=&v"(rb[g & 1][0]) : "v"(ra));
.LBB0_775:
	v_lshl_add_u32 v106, s36, 8, v151
	v_mov_b64_e32 v[104:105], s[16:17]
	v_mad_i64_i32 v[104:105], s[40:41], v106, s71, v[104:105]
	s_ashr_i32 s39, s38, 31
	v_lshl_add_u64 v[104:105], s[38:39], 1, v[104:105]
	v_lshl_add_u64 v[104:105], v[104:105], 0, s[12:13]
	v_lshl_add_u64 v[104:105], v[104:105], 0, v[136:137]
	v_add_co_u32_e32 v106, vcc, 0x1c000, v104
	v_cvt_pk_bf16_f32 v100, v100, v101
	v_cvt_pk_bf16_f32 v101, v102, v103
	v_cvt_pk_bf16_f32 v102, v96, v97
	v_cvt_pk_bf16_f32 v103, v98, v99
	s_nop 1
	v_addc_co_u32_e32 v107, vcc, 0, v105, vcc
	s_and_b64 vcc, exec, s[6:7]
	ds_write_b128 v153, v[100:103] offset:64
	ds_read_b128 v[100:103], v154
	ds_read_b128 v[96:99], v154 offset:1152
	s_waitcnt lgkmcnt(4)
	global_store_dwordx4 v[104:105], v[116:119], off nt
	global_store_dwordx4 v[106:107], v[112:115], off nt
	s_cbranch_vccnz .LBB0_777
	v_mov_b32_e32 v106, v176
	v_mov_b32_e32 v110, v180
	v_mov_b32_e32 v107, v177
	v_mov_b32_e32 v111, v181
	v_mov_b32_e32 v108, v178
	v_mov_b32_e32 v112, v182
	v_mov_b32_e32 v109, v179
	v_mov_b32_e32 v113, v183
	v_fmac_f32_e32 v106, 0xbfb8aa3b, v92
	v_fmac_f32_e32 v110, 0xbfb8aa3b, v88
	v_fmac_f32_e32 v107, 0xbfb8aa3b, v93
	v_fmac_f32_e32 v111, 0xbfb8aa3b, v89
	v_fmac_f32_e32 v108, 0xbfb8aa3b, v94
	v_fmac_f32_e32 v112, 0xbfb8aa3b, v90
	v_fmac_f32_e32 v109, 0xbfb8aa3b, v95
	v_fmac_f32_e32 v113, 0xbfb8aa3b, v91
	v_exp_f32_e32 v88, v106
	v_exp_f32_e32 v89, v110
	v_exp_f32_e32 v90, v107
	v_exp_f32_e32 v91, v111
	v_exp_f32_e32 v92, v108
	v_exp_f32_e32 v93, v112
	v_exp_f32_e32 v94, v109
	v_exp_f32_e32 v95, v113
	v_add_f32_e32 v88, 1.0, v88
	v_add_f32_e32 v89, 1.0, v89
	v_add_f32_e32 v90, 1.0, v90
	v_add_f32_e32 v91, 1.0, v91
	v_add_f32_e32 v106, 1.0, v92
	v_add_f32_e32 v107, 1.0, v93
	v_add_f32_e32 v108, 1.0, v94
	v_add_f32_e32 v109, 1.0, v95
	v_rcp_f32_e32 v92, v88
	v_rcp_f32_e32 v88, v89
	v_rcp_f32_e32 v93, v90
	v_rcp_f32_e32 v89, v91
	v_rcp_f32_e32 v94, v106
	v_rcp_f32_e32 v90, v107
	v_rcp_f32_e32 v95, v108
	v_rcp_f32_e32 v91, v109

;     __device__ __forceinline__ void operator()(const f32x4 (&acc)[2][2][4][2], const Unit& u, int wr, int wc, int fr, int fq) const {
;     ...
;                 if (MODE == 1) {
;                     if (special) {
;                         const f32x4 b0 = *(const GAS1 f32x4*)(bias + col) * -1.4426950408889634f, b1 = *(const GAS1 f32x4*)(bias + col + 4) * -1.4426950408889634f;
; #pragma unroll
;                         for (int j = 0; j < 4; ++j) { v0[j] = __builtin_amdgcn_rcpf(1.0f + __builtin_amdgcn_exp2f(__builtin_fmaf(v0[j], -1.4426950408889634f, b0[j])));
;                                                       v1[j] = __builtin_amdgcn_rcpf(1.0f + __builtin_amdgcn_exp2f(__builtin_fmaf(v1[j], -1.4426950408889634f, b1[j]))); }
;                     }
;                 }
;                 if (MODE == 2) {
;                     if (special) {
;                         const int fi = ((col & 63) >> 3) * 4;
;                         const f32x4 c = *(const GAS1 f32x4*)(cosT + (size_t)row * 32 + fi), s_ = *(const GAS1 f32x4*)(sinT + (size_t)row * 32 + fi);
;                         const f32x4 o1 = v0 * c - v1 * s_, o2 = v1 * c + v0 * s_; v0 = o1; v1 = o2;
;                     }
;                 }
;                 if (MODE == 3 || MODE == 4) {
;                     const u32x4 gw = *(const GAS1 u32x4*)(G + (size_t)row * ldg + col);
;                     const f32x4 g0 = {bf_lo(gw.x), bf_hi(gw.x), bf_lo(gw.y), bf_hi(gw.y)}, g1 = {bf_lo(gw.z), bf_hi(gw.z), bf_lo(gw.w), bf_hi(gw.w)};
;                     v0 = v0 * g0; v1 = v1 * g1;
;                     if (MODE == 4) {
;                         const u32x4 ow = *(const GAS1 u32x4*)((const bf16_t*)O + (size_t)row * ldc + col);
;                         const f32x4 o0 = {bf_lo(ow.x), bf_hi(ow.x), bf_lo(ow.y), bf_hi(ow.y)}, o1 = {bf_lo(ow.z), bf_hi(ow.z), bf_lo(ow.w), bf_hi(ow.w)};
;                         v0 += o0; v1 += o1;
;                     }
;                 }
;                 u32x4 w; w.x = cvt_pk_bf16(v0[0], v0[1]); w.y = cvt_pk_bf16(v0[2], v0[3]); w.z = cvt_pk_bf16(v1[0], v1[1]); w.w = cvt_pk_bf16(v1[2], v1[3]);
;                 if (bj == 0) asm volatile("ds_write_b128 %0, %1" :: "v"(wa), "v"(w)); else asm volatile("ds_write_b128 %0, %1 offset:64" :: "v"(wa), "v"(w));
;             }
;             asm volatile("ds_read_b128 %0, %1" : "=&v"(rb[g & 1][0]) : "v"(ra));
.LBB0_779:
	v_add_co_u32_e32 v88, vcc, 0x38000, v104
	v_cvt_pk_bf16_f32 v84, v84, v85
	v_cvt_pk_bf16_f32 v85, v86, v87
	v_cvt_pk_bf16_f32 v86, v80, v81
	v_cvt_pk_bf16_f32 v87, v82, v83
	s_nop 1
	v_addc_co_u32_e32 v89, vcc, 0, v105, vcc
	ds_write_b128 v153, v[84:87] offset:64
	ds_read_b128 v[84:87], v154
	ds_read_b128 v[80:83], v154 offset:1152
	s_waitcnt lgkmcnt(4)
	global_store_dwordx4 v[88:89], v[100:103], off nt
	v_add_co_u32_e32 v88, vcc, 0x54000, v104
	s_nop 1
	v_addc_co_u32_e32 v89, vcc, 0, v105, vcc
	s_and_b64 vcc, exec, s[6:7]
	global_store_dwordx4 v[88:89], v[96:99], off nt
	s_cbranch_vccnz .LBB0_781
	v_mov_b32_e32 v88, v176
	v_mov_b32_e32 v92, v180
	v_mov_b32_e32 v89, v177
	v_mov_b32_e32 v93, v181
	v_mov_b32_e32 v90, v178
	v_mov_b32_e32 v94, v182
	v_mov_b32_e32 v91, v179
	v_mov_b32_e32 v95, v183
	v_fmac_f32_e32 v88, 0xbfb8aa3b, v76
	v_fmac_f32_e32 v92, 0xbfb8aa3b, v72
	v_fmac_f32_e32 v89, 0xbfb8aa3b, v77
	v_fmac_f32_e32 v93, 0xbfb8aa3b, v73
	v_fmac_f32_e32 v90, 0xbfb8aa3b, v78
	v_fmac_f32_e32 v94, 0xbfb8aa3b, v74
	v_fmac_f32_e32 v91, 0xbfb8aa3b, v79
	v_fmac_f32_e32 v95, 0xbfb8aa3b, v75
	v_exp_f32_e32 v72, v88
	v_exp_f32_e32 v73, v92
	v_exp_f32_e32 v74, v89
	v_exp_f32_e32 v75, v93
	v_exp_f32_e32 v76, v90
	v_exp_f32_e32 v77, v94
	v_exp_f32_e32 v78, v91
	v_exp_f32_e32 v79, v95
	v_add_f32_e32 v72, 1.0, v72
	v_add_f32_e32 v73, 1.0, v73
	v_add_f32_e32 v74, 1.0, v74
	v_add_f32_e32 v75, 1.0, v75
	v_add_f32_e32 v88, 1.0, v76
	v_add_f32_e32 v89, 1.0, v77
	v_add_f32_e32 v90, 1.0, v78
	v_add_f32_e32 v91, 1.0, v79
	v_rcp_f32_e32 v76, v72
	v_rcp_f32_e32 v72, v73
	v_rcp_f32_e32 v77, v74
	v_rcp_f32_e32 v73, v75
	v_rcp_f32_e32 v78, v88
	v_rcp_f32_e32 v74, v89
	v_rcp_f32_e32 v79, v90
	v_rcp_f32_e32 v75, v91

;     __device__ __forceinline__ void operator()(const f32x4 (&acc)[2][2][4][2], const Unit& u, int wr, int wc, int fr, int fq) const {
;     ...
;                 if (MODE == 1) {
;                     if (special) {
;                         const f32x4 b0 = *(const GAS1 f32x4*)(bias + col) * -1.4426950408889634f, b1 = *(const GAS1 f32x4*)(bias + col + 4) * -1.4426950408889634f;
; #pragma unroll
;                         for (int j = 0; j < 4; ++j) { v0[j] = __builtin_amdgcn_rcpf(1.0f + __builtin_amdgcn_exp2f(__builtin_fmaf(v0[j], -1.4426950408889634f, b0[j])));
;                                                       v1[j] = __builtin_amdgcn_rcpf(1.0f + __builtin_amdgcn_exp2f(__builtin_fmaf(v1[j], -1.4426950408889634f, b1[j]))); }
;                     }
;                 }
;                 if (MODE == 2) {
;                     if (special) {
;                         const int fi = ((col & 63) >> 3) * 4;
;                         const f32x4 c = *(const GAS1 f32x4*)(cosT + (size_t)row * 32 + fi), s_ = *(const GAS1 f32x4*)(sinT + (size_t)row * 32 + fi);
;                         const f32x4 o1 = v0 * c - v1 * s_, o2 = v1 * c + v0 * s_; v0 = o1; v1 = o2;
;                     }
;                 }
;                 if (MODE == 3 || MODE == 4) {
;                     const u32x4 gw = *(const GAS1 u32x4*)(G + (size_t)row * ldg + col);
;                     const f32x4 g0 = {bf_lo(gw.x), bf_hi(gw.x), bf_lo(gw.y), bf_hi(gw.y)}, g1 = {bf_lo(gw.z), bf_hi(gw.z), bf_lo(gw.w), bf_hi(gw.w)};
;                     v0 = v0 * g0; v1 = v1 * g1;
;                     if (MODE == 4) {
;                         const u32x4 ow = *(const GAS1 u32x4*)((const bf16_t*)O + (size_t)row * ldc + col);
;                         const f32x4 o0 = {bf_lo(ow.x), bf_hi(ow.x), bf_lo(ow.y), bf_hi(ow.y)}, o1 = {bf_lo(ow.z), bf_hi(ow.z), bf_lo(ow.w), bf_hi(ow.w)};
;                         v0 += o0; v1 += o1;
;                     }
;                 }
;                 u32x4 w; w.x = cvt_pk_bf16(v0[0], v0[1]); w.y = cvt_pk_bf16(v0[2], v0[3]); w.z = cvt_pk_bf16(v1[0], v1[1]); w.w = cvt_pk_bf16(v1[2], v1[3]);
;                 if (bj == 0) asm volatile("ds_write_b128 %0, %1" :: "v"(wa), "v"(w)); else asm volatile("ds_write_b128 %0, %1 offset:64" :: "v"(wa), "v"(w));
;             }
;             asm volatile("ds_read_b128 %0, %1" : "=&v"(rb[g & 1][0]) : "v"(ra));
.LBB0_783:
	v_add_co_u32_e32 v72, vcc, 0x70000, v104
	v_cvt_pk_bf16_f32 v68, v68, v69
	v_cvt_pk_bf16_f32 v69, v70, v71
	v_cvt_pk_bf16_f32 v70, v64, v65
	v_cvt_pk_bf16_f32 v71, v66, v67
	s_nop 1
	v_addc_co_u32_e32 v73, vcc, 0, v105, vcc
	ds_write_b128 v153, v[68:71] offset:64
	ds_read_b128 v[68:71], v154
	ds_read_b128 v[64:67], v154 offset:1152
	s_waitcnt lgkmcnt(4)
	global_store_dwordx4 v[72:73], v[84:87], off nt
	v_add_co_u32_e32 v72, vcc, 0x8c000, v104
	s_nop 1
	v_addc_co_u32_e32 v73, vcc, 0, v105, vcc
	s_and_b64 vcc, exec, s[6:7]
	global_store_dwordx4 v[72:73], v[80:83], off nt
	s_cbranch_vccnz .LBB0_785
	v_mov_b32_e32 v72, v176
	v_mov_b32_e32 v76, v180
	v_mov_b32_e32 v73, v177
	v_mov_b32_e32 v77, v181
	v_mov_b32_e32 v74, v178
	v_mov_b32_e32 v78, v182
	v_mov_b32_e32 v75, v179
	v_mov_b32_e32 v79, v183
	v_fmac_f32_e32 v72, 0xbfb8aa3b, v60
	v_fmac_f32_e32 v76, 0xbfb8aa3b, v56
	v_fmac_f32_e32 v73, 0xbfb8aa3b, v61
	v_fmac_f32_e32 v77, 0xbfb8aa3b, v57
	v_fmac_f32_e32 v74, 0xbfb8aa3b, v62
	v_fmac_f32_e32 v78, 0xbfb8aa3b, v58
	v_fmac_f32_e32 v75, 0xbfb8aa3b, v63
	v_fmac_f32_e32 v79, 0xbfb8aa3b, v59
	v_exp_f32_e32 v56, v72
	v_exp_f32_e32 v57, v76
	v_exp_f32_e32 v58, v73
	v_exp_f32_e32 v59, v77
	v_exp_f32_e32 v60, v74
	v_exp_f32_e32 v61, v78
	v_exp_f32_e32 v62, v75
	v_exp_f32_e32 v63, v79
	v_add_f32_e32 v56, 1.0, v56
	v_add_f32_e32 v57, 1.0, v57
	v_add_f32_e32 v58, 1.0, v58
	v_add_f32_e32 v59, 1.0, v59
	v_add_f32_e32 v72, 1.0, v60
	v_add_f32_e32 v73, 1.0, v61
	v_add_f32_e32 v74, 1.0, v62
	v_add_f32_e32 v75, 1.0, v63
	v_rcp_f32_e32 v60, v56
	v_rcp_f32_e32 v56, v57
	v_rcp_f32_e32 v61, v58
	v_rcp_f32_e32 v57, v59
	v_rcp_f32_e32 v62, v72
	v_rcp_f32_e32 v58, v73
	v_rcp_f32_e32 v63, v74
	v_rcp_f32_e32 v59, v75

;     __device__ __forceinline__ void operator()(const f32x4 (&acc)[2][2][4][2], const Unit& u, int wr, int wc, int fr, int fq) const {
;     ...
;                 if (MODE == 1) {
;                     if (special) {
;                         const f32x4 b0 = *(const GAS1 f32x4*)(bias + col) * -1.4426950408889634f, b1 = *(const GAS1 f32x4*)(bias + col + 4) * -1.4426950408889634f;
; #pragma unroll
;                         for (int j = 0; j < 4; ++j) { v0[j] = __builtin_amdgcn_rcpf(1.0f + __builtin_amdgcn_exp2f(__builtin_fmaf(v0[j], -1.4426950408889634f, b0[j])));
;                                                       v1[j] = __builtin_amdgcn_rcpf(1.0f + __builtin_amdgcn_exp2f(__builtin_fmaf(v1[j], -1.4426950408889634f, b1[j]))); }
;                     }
;                 }
;                 if (MODE == 2) {
;                     if (special) {
;                         const int fi = ((col & 63) >> 3) * 4;
;                         const f32x4 c = *(const GAS1 f32x4*)(cosT + (size_t)row * 32 + fi), s_ = *(const GAS1 f32x4*)(sinT + (size_t)row * 32 + fi);
;                         const f32x4 o1 = v0 * c - v1 * s_, o2 = v1 * c + v0 * s_; v0 = o1; v1 = o2;
;                     }
;                 }
;                 if (MODE == 3 || MODE == 4) {
;                     const u32x4 gw = *(const GAS1 u32x4*)(G + (size_t)row * ldg + col);
;                     const f32x4 g0 = {bf_lo(gw.x), bf_hi(gw.x), bf_lo(gw.y), bf_hi(gw.y)}, g1 = {bf_lo(gw.z), bf_hi(gw.z), bf_lo(gw.w), bf_hi(gw.w)};
;                     v0 = v0 * g0; v1 = v1 * g1;
;                     if (MODE == 4) {
;                         const u32x4 ow = *(const GAS1 u32x4*)((const bf16_t*)O + (size_t)row * ldc + col);
;                         const f32x4 o0 = {bf_lo(ow.x), bf_hi(ow.x), bf_lo(ow.y), bf_hi(ow.y)}, o1 = {bf_lo(ow.z), bf_hi(ow.z), bf_lo(ow.w), bf_hi(ow.w)};
;                         v0 += o0; v1 += o1;
;                     }
;                 }
;                 u32x4 w; w.x = cvt_pk_bf16(v0[0], v0[1]); w.y = cvt_pk_bf16(v0[2], v0[3]); w.z = cvt_pk_bf16(v1[0], v1[1]); w.w = cvt_pk_bf16(v1[2], v1[3]);
;                 if (bj == 0) asm volatile("ds_write_b128 %0, %1" :: "v"(wa), "v"(w)); else asm volatile("ds_write_b128 %0, %1 offset:64" :: "v"(wa), "v"(w));
;             }
;             asm volatile("ds_read_b128 %0, %1" : "=&v"(rb[g & 1][0]) : "v"(ra));
.LBB0_787:
	v_add_co_u32_e32 v56, vcc, 0xa8000, v104
	v_cvt_pk_bf16_f32 v52, v52, v53
	v_cvt_pk_bf16_f32 v53, v54, v55
	v_cvt_pk_bf16_f32 v54, v48, v49
	v_cvt_pk_bf16_f32 v55, v50, v51
	s_nop 1
	v_addc_co_u32_e32 v57, vcc, 0, v105, vcc
	ds_write_b128 v153, v[52:55] offset:64
	ds_read_b128 v[52:55], v154
	ds_read_b128 v[48:51], v154 offset:1152
	s_waitcnt lgkmcnt(4)
	global_store_dwordx4 v[56:57], v[68:71], off nt
	v_add_co_u32_e32 v56, vcc, 0xc4000, v104
	s_nop 1
	v_addc_co_u32_e32 v57, vcc, 0, v105, vcc
	s_and_b64 vcc, exec, s[6:7]
	global_store_dwordx4 v[56:57], v[64:67], off nt
	s_cbranch_vccnz .LBB0_789
	v_mov_b32_e32 v56, v176
	v_mov_b32_e32 v60, v180
	v_mov_b32_e32 v57, v177
	v_mov_b32_e32 v61, v181
	v_mov_b32_e32 v58, v178
	v_mov_b32_e32 v62, v182
	v_mov_b32_e32 v59, v179
	v_mov_b32_e32 v63, v183
	v_fmac_f32_e32 v56, 0xbfb8aa3b, v44
	v_fmac_f32_e32 v60, 0xbfb8aa3b, v40
	v_fmac_f32_e32 v57, 0xbfb8aa3b, v45
	v_fmac_f32_e32 v61, 0xbfb8aa3b, v41
	v_fmac_f32_e32 v58, 0xbfb8aa3b, v46
	v_fmac_f32_e32 v62, 0xbfb8aa3b, v42
	v_fmac_f32_e32 v59, 0xbfb8aa3b, v47
	v_fmac_f32_e32 v63, 0xbfb8aa3b, v43
	v_exp_f32_e32 v40, v56
	v_exp_f32_e32 v41, v60
	v_exp_f32_e32 v42, v57
	v_exp_f32_e32 v43, v61
	v_exp_f32_e32 v44, v58
	v_exp_f32_e32 v45, v62
	v_exp_f32_e32 v46, v59
	v_exp_f32_e32 v47, v63
	v_add_f32_e32 v40, 1.0, v40
	v_add_f32_e32 v41, 1.0, v41
	v_add_f32_e32 v42, 1.0, v42
	v_add_f32_e32 v43, 1.0, v43
	v_add_f32_e32 v56, 1.0, v44
	v_add_f32_e32 v57, 1.0, v45
	v_add_f32_e32 v58, 1.0, v46
	v_add_f32_e32 v59, 1.0, v47
	v_rcp_f32_e32 v44, v40
	v_rcp_f32_e32 v40, v41
	v_rcp_f32_e32 v45, v42
	v_rcp_f32_e32 v41, v43
	v_rcp_f32_e32 v46, v56
	v_rcp_f32_e32 v42, v57
	v_rcp_f32_e32 v47, v58
	v_rcp_f32_e32 v43, v59

;     __device__ __forceinline__ void operator()(const f32x4 (&acc)[2][2][4][2], const Unit& u, int wr, int wc, int fr, int fq) const {
;     ...
;                 if (MODE == 1) {
;                     if (special) {
;                         const f32x4 b0 = *(const GAS1 f32x4*)(bias + col) * -1.4426950408889634f, b1 = *(const GAS1 f32x4*)(bias + col + 4) * -1.4426950408889634f;
; #pragma unroll
;                         for (int j = 0; j < 4; ++j) { v0[j] = __builtin_amdgcn_rcpf(1.0f + __builtin_amdgcn_exp2f(__builtin_fmaf(v0[j], -1.4426950408889634f, b0[j])));
;                                                       v1[j] = __builtin_amdgcn_rcpf(1.0f + __builtin_amdgcn_exp2f(__builtin_fmaf(v1[j], -1.4426950408889634f, b1[j]))); }
;                     }
;                 }
;                 if (MODE == 2) {
;                     if (special) {
;                         const int fi = ((col & 63) >> 3) * 4;
;                         const f32x4 c = *(const GAS1 f32x4*)(cosT + (size_t)row * 32 + fi), s_ = *(const GAS1 f32x4*)(sinT + (size_t)row * 32 + fi);
;                         const f32x4 o1 = v0 * c - v1 * s_, o2 = v1 * c + v0 * s_; v0 = o1; v1 = o2;
;                     }
;                 }
;                 if (MODE == 3 || MODE == 4) {
;                     const u32x4 gw = *(const GAS1 u32x4*)(G + (size_t)row * ldg + col);
;                     const f32x4 g0 = {bf_lo(gw.x), bf_hi(gw.x), bf_lo(gw.y), bf_hi(gw.y)}, g1 = {bf_lo(gw.z), bf_hi(gw.z), bf_lo(gw.w), bf_hi(gw.w)};
;                     v0 = v0 * g0; v1 = v1 * g1;
;                     if (MODE == 4) {
;                         const u32x4 ow = *(const GAS1 u32x4*)((const bf16_t*)O + (size_t)row * ldc + col);
;                         const f32x4 o0 = {bf_lo(ow.x), bf_hi(ow.x), bf_lo(ow.y), bf_hi(ow.y)}, o1 = {bf_lo(ow.z), bf_hi(ow.z), bf_lo(ow.w), bf_hi(ow.w)};
;                         v0 += o0; v1 += o1;
;                     }
;                 }
;                 u32x4 w; w.x = cvt_pk_bf16(v0[0], v0[1]); w.y = cvt_pk_bf16(v0[2], v0[3]); w.z = cvt_pk_bf16(v1[0], v1[1]); w.w = cvt_pk_bf16(v1[2], v1[3]);
;                 if (bj == 0) asm volatile("ds_write_b128 %0, %1" :: "v"(wa), "v"(w)); else asm volatile("ds_write_b128 %0, %1 offset:64" :: "v"(wa), "v"(w));
;             }
;             asm volatile("ds_read_b128 %0, %1" : "=&v"(rb[g & 1][0]) : "v"(ra));
.LBB0_791:
	v_add_co_u32_e32 v40, vcc, 0x1c0000, v104
	v_cvt_pk_bf16_f32 v36, v36, v37
	v_cvt_pk_bf16_f32 v37, v38, v39
	v_cvt_pk_bf16_f32 v38, v32, v33
	v_cvt_pk_bf16_f32 v39, v34, v35
	s_nop 1
	v_addc_co_u32_e32 v41, vcc, 0, v105, vcc
	ds_write_b128 v153, v[36:39] offset:64
	ds_read_b128 v[36:39], v154
	ds_read_b128 v[32:35], v154 offset:1152
	s_waitcnt lgkmcnt(4)
	global_store_dwordx4 v[40:41], v[52:55], off nt
	v_add_co_u32_e32 v40, vcc, 0x1dc000, v104
	s_nop 1
	v_addc_co_u32_e32 v41, vcc, 0, v105, vcc
	s_and_b64 vcc, exec, s[6:7]
	global_store_dwordx4 v[40:41], v[48:51], off nt
	s_cbranch_vccnz .LBB0_793
	v_mov_b32_e32 v40, v176
	v_mov_b32_e32 v44, v180
	v_mov_b32_e32 v41, v177
	v_mov_b32_e32 v45, v181
	v_mov_b32_e32 v42, v178
	v_mov_b32_e32 v46, v182
	v_mov_b32_e32 v43, v179
	v_mov_b32_e32 v47, v183
	v_fmac_f32_e32 v40, 0xbfb8aa3b, v28
	v_fmac_f32_e32 v44, 0xbfb8aa3b, v24
	v_fmac_f32_e32 v41, 0xbfb8aa3b, v29
	v_fmac_f32_e32 v45, 0xbfb8aa3b, v25
	v_fmac_f32_e32 v42, 0xbfb8aa3b, v30
	v_fmac_f32_e32 v46, 0xbfb8aa3b, v26
	v_fmac_f32_e32 v43, 0xbfb8aa3b, v31
	v_fmac_f32_e32 v47, 0xbfb8aa3b, v27
	v_exp_f32_e32 v24, v40
	v_exp_f32_e32 v25, v44
	v_exp_f32_e32 v26, v41
	v_exp_f32_e32 v27, v45
	v_exp_f32_e32 v28, v42
	v_exp_f32_e32 v29, v46
	v_exp_f32_e32 v30, v43
	v_exp_f32_e32 v31, v47
	v_add_f32_e32 v24, 1.0, v24
	v_add_f32_e32 v25, 1.0, v25
	v_add_f32_e32 v26, 1.0, v26
	v_add_f32_e32 v27, 1.0, v27
	v_add_f32_e32 v40, 1.0, v28
	v_add_f32_e32 v41, 1.0, v29
	v_add_f32_e32 v42, 1.0, v30
	v_add_f32_e32 v43, 1.0, v31
	v_rcp_f32_e32 v28, v24
	v_rcp_f32_e32 v24, v25
	v_rcp_f32_e32 v29, v26
	v_rcp_f32_e32 v25, v27
	v_rcp_f32_e32 v30, v40
	v_rcp_f32_e32 v26, v41
	v_rcp_f32_e32 v31, v42
	v_rcp_f32_e32 v27, v43

;     __device__ __forceinline__ void operator()(const f32x4 (&acc)[2][2][4][2], const Unit& u, int wr, int wc, int fr, int fq) const {
;     ...
;                 if (MODE == 1) {
;                     if (special) {
;                         const f32x4 b0 = *(const GAS1 f32x4*)(bias + col) * -1.4426950408889634f, b1 = *(const GAS1 f32x4*)(bias + col + 4) * -1.4426950408889634f;
; #pragma unroll
;                         for (int j = 0; j < 4; ++j) { v0[j] = __builtin_amdgcn_rcpf(1.0f + __builtin_amdgcn_exp2f(__builtin_fmaf(v0[j], -1.4426950408889634f, b0[j])));
;                                                       v1[j] = __builtin_amdgcn_rcpf(1.0f + __builtin_amdgcn_exp2f(__builtin_fmaf(v1[j], -1.4426950408889634f, b1[j]))); }
;                     }
;                 }
;                 if (MODE == 2) {
;                     if (special) {
;                         const int fi = ((col & 63) >> 3) * 4;
;                         const f32x4 c = *(const GAS1 f32x4*)(cosT + (size_t)row * 32 + fi), s_ = *(const GAS1 f32x4*)(sinT + (size_t)row * 32 + fi);
;                         const f32x4 o1 = v0 * c - v1 * s_, o2 = v1 * c + v0 * s_; v0 = o1; v1 = o2;
;                     }
;                 }
;                 if (MODE == 3 || MODE == 4) {
;                     const u32x4 gw = *(const GAS1 u32x4*)(G + (size_t)row * ldg + col);
;                     const f32x4 g0 = {bf_lo(gw.x), bf_hi(gw.x), bf_lo(gw.y), bf_hi(gw.y)}, g1 = {bf_lo(gw.z), bf_hi(gw.z), bf_lo(gw.w), bf_hi(gw.w)};
;                     v0 = v0 * g0; v1 = v1 * g1;
;                     if (MODE == 4) {
;                         const u32x4 ow = *(const GAS1 u32x4*)((const bf16_t*)O + (size_t)row * ldc + col);
;                         const f32x4 o0 = {bf_lo(ow.x), bf_hi(ow.x), bf_lo(ow.y), bf_hi(ow.y)}, o1 = {bf_lo(ow.z), bf_hi(ow.z), bf_lo(ow.w), bf_hi(ow.w)};
;                         v0 += o0; v1 += o1;
;                     }
;                 }
;                 u32x4 w; w.x = cvt_pk_bf16(v0[0], v0[1]); w.y = cvt_pk_bf16(v0[2], v0[3]); w.z = cvt_pk_bf16(v1[0], v1[1]); w.w = cvt_pk_bf16(v1[2], v1[3]);
;                 if (bj == 0) asm volatile("ds_write_b128 %0, %1" :: "v"(wa), "v"(w)); else asm volatile("ds_write_b128 %0, %1 offset:64" :: "v"(wa), "v"(w));
;             }
;             asm volatile("ds_read_b128 %0, %1" : "=&v"(rb[g & 1][0]) : "v"(ra));
.LBB0_795:
	v_add_co_u32_e32 v24, vcc, 0x1f8000, v104
	v_cvt_pk_bf16_f32 v20, v20, v21
	v_cvt_pk_bf16_f32 v21, v22, v23
	v_cvt_pk_bf16_f32 v22, v16, v17
	v_cvt_pk_bf16_f32 v23, v18, v19
	s_nop 1
	v_addc_co_u32_e32 v25, vcc, 0, v105, vcc
	ds_write_b128 v153, v[20:23] offset:64
	ds_read_b128 v[20:23], v154
	ds_read_b128 v[16:19], v154 offset:1152
	s_waitcnt lgkmcnt(4)
	global_store_dwordx4 v[24:25], v[36:39], off nt
	v_add_co_u32_e32 v24, vcc, 0x214000, v104
	s_nop 1
	v_addc_co_u32_e32 v25, vcc, 0, v105, vcc
	s_and_b64 vcc, exec, s[6:7]
	global_store_dwordx4 v[24:25], v[32:35], off nt
	s_cbranch_vccnz .LBB0_797
	v_mov_b32_e32 v24, v176
	v_mov_b32_e32 v28, v180
	v_mov_b32_e32 v25, v177
	v_mov_b32_e32 v29, v181
	v_mov_b32_e32 v26, v178
	v_mov_b32_e32 v30, v182
	v_mov_b32_e32 v27, v179
	v_mov_b32_e32 v31, v183
	v_fmac_f32_e32 v24, 0xbfb8aa3b, v12
	v_fmac_f32_e32 v28, 0xbfb8aa3b, v8
	v_fmac_f32_e32 v25, 0xbfb8aa3b, v13
	v_fmac_f32_e32 v29, 0xbfb8aa3b, v9
	v_fmac_f32_e32 v26, 0xbfb8aa3b, v14
	v_fmac_f32_e32 v30, 0xbfb8aa3b, v10
	v_fmac_f32_e32 v27, 0xbfb8aa3b, v15
	v_fmac_f32_e32 v31, 0xbfb8aa3b, v11
	v_exp_f32_e32 v8, v24
	v_exp_f32_e32 v9, v28
	v_exp_f32_e32 v10, v25
	v_exp_f32_e32 v11, v29
	v_exp_f32_e32 v12, v26
	v_exp_f32_e32 v13, v30
	v_exp_f32_e32 v14, v27
	v_exp_f32_e32 v15, v31
	v_add_f32_e32 v8, 1.0, v8
	v_add_f32_e32 v9, 1.0, v9
	v_add_f32_e32 v10, 1.0, v10
	v_add_f32_e32 v11, 1.0, v11
	v_add_f32_e32 v24, 1.0, v12
	v_add_f32_e32 v25, 1.0, v13
	v_add_f32_e32 v26, 1.0, v14
	v_add_f32_e32 v27, 1.0, v15
	v_rcp_f32_e32 v12, v8
	v_rcp_f32_e32 v8, v9
	v_rcp_f32_e32 v13, v10
	v_rcp_f32_e32 v9, v11
	v_rcp_f32_e32 v14, v24
	v_rcp_f32_e32 v10, v25
	v_rcp_f32_e32 v15, v26
	v_rcp_f32_e32 v11, v27

; __device__ __forceinline__ unsigned cvt_pk_bf16(float lo, float hi) { unsigned r; asm volatile("v_cvt_pk_bf16_f32 %0, %1, %2" : "=v"(r) : "v"(lo), "v"(hi)); return r; }
; #define GAS1 __attribute__((address_space(1)))
;     __device__ __forceinline__ void operator()(const f32x4 (&acc)[2][2][4][2], const Unit& u, int wr, int wc, int fr, int fq) const {
;     ...
;                 u32x4 w; w.x = cvt_pk_bf16(v0[0], v0[1]); w.y = cvt_pk_bf16(v0[2], v0[3]); w.z = cvt_pk_bf16(v1[0], v1[1]); w.w = cvt_pk_bf16(v1[2], v1[3]);
;                 if (bj == 0) asm volatile("ds_write_b128 %0, %1" :: "v"(wa), "v"(w)); else asm volatile("ds_write_b128 %0, %1 offset:64" :: "v"(wa), "v"(w));
;             }
;             asm volatile("ds_read_b128 %0, %1" : "=&v"(rb[g & 1][0]) : "v"(ra));
;             asm volatile("ds_read_b128 %0, %1 offset:1152" : "=&v"(rb[g & 1][1]) : "v"(ra));
;             if (g >= 1) {
;                 asm volatile("s_waitcnt lgkmcnt(4)" : "+v"(rb[(g - 1) & 1][0]), "+v"(rb[(g - 1) & 1][1]));
;                 bf16_t* ob = obase + (size_t)(((g - 1) >> 2) * HALF + ((g - 1) & 3) * 16) * ldc;
;                 *(GAS1 u32x4*)ob = rb[(g - 1) & 1][0]; *(GAS1 u32x4*)(ob + (size_t)8 * ldc) = rb[(g - 1) & 1][1];
;             }
;         }
;         asm volatile("s_waitcnt lgkmcnt(0)" : "+v"(rb[1][0]), "+v"(rb[1][1]));
;         { bf16_t* ob = obase + (size_t)(HALF + 3 * 16) * ldc; *(GAS1 u32x4*)ob = rb[1][0]; *(GAS1 u32x4*)(ob + (size_t)8 * ldc) = rb[1][1]; }
.LBB0_799:
	v_add_co_u32_e32 v8, vcc, s72, v104
	v_cvt_pk_bf16_f32 v4, v4, v5
	v_cvt_pk_bf16_f32 v5, v6, v7
	v_cvt_pk_bf16_f32 v6, v0, v1
	v_cvt_pk_bf16_f32 v7, v2, v3
	s_nop 1
	v_addc_co_u32_e32 v9, vcc, 0, v105, vcc
	ds_write_b128 v153, v[4:7] offset:64
	ds_read_b128 v[0:3], v154
	ds_read_b128 v[4:7], v154 offset:1152
	s_waitcnt lgkmcnt(4)
	global_store_dwordx4 v[8:9], v[20:23], off nt
	v_add_co_u32_e32 v8, vcc, s73, v104
	s_nop 1
	v_addc_co_u32_e32 v9, vcc, 0, v105, vcc
	global_store_dwordx4 v[8:9], v[16:19], off nt
	v_add_co_u32_e32 v8, vcc, 0x268000, v104
	s_waitcnt lgkmcnt(0)
	s_nop 1
	v_addc_co_u32_e32 v9, vcc, 0, v105, vcc
	global_store_dwordx4 v[8:9], v[0:3], off nt
	s_nop 1
	v_add_co_u32_e32 v0, vcc, 0x284000, v104
	s_nop 1
	v_addc_co_u32_e32 v1, vcc, 0, v105, vcc
	s_andn2_b64 vcc, exec, s[4:5]
	s_mov_b64 s[4:5], -1
	global_store_dwordx4 v[0:1], v[4:7], off nt
	s_cbranch_vccnz .LBB0_760
	s_andn2_b64 vcc, exec, s[14:15]
	s_cbranch_vccnz .LBB0_759
	s_barrier
	s_branch .LBB0_759

; __device__ __forceinline__ unsigned cvt_pk_bf16(float lo, float hi) { unsigned r; asm volatile("v_cvt_pk_bf16_f32 %0, %1, %2" : "=v"(r) : "v"(lo), "v"(hi)); return r; }
; #define GAS1 __attribute__((address_space(1)))
;     __device__ __forceinline__ void operator()(const f32x4 (&acc)[2][2][4][2], const Unit& u, int wr, int wc, int fr, int fq) const {
;     ...
;                 u32x4 w; w.x = cvt_pk_bf16(v0[0], v0[1]); w.y = cvt_pk_bf16(v0[2], v0[3]); w.z = cvt_pk_bf16(v1[0], v1[1]); w.w = cvt_pk_bf16(v1[2], v1[3]);
;                 if (bj == 0) asm volatile("ds_write_b128 %0, %1" :: "v"(wa), "v"(w)); else asm volatile("ds_write_b128 %0, %1 offset:64" :: "v"(wa), "v"(w));
;             }
;             asm volatile("ds_read_b128 %0, %1" : "=&v"(rb[g & 1][0]) : "v"(ra));
;             asm volatile("ds_read_b128 %0, %1 offset:1152" : "=&v"(rb[g & 1][1]) : "v"(ra));
;             if (g >= 1) {
;                 asm volatile("s_waitcnt lgkmcnt(4)" : "+v"(rb[(g - 1) & 1][0]), "+v"(rb[(g - 1) & 1][1]));
;                 bf16_t* ob = obase + (size_t)(((g - 1) >> 2) * HALF + ((g - 1) & 3) * 16) * ldc;
;                 *(GAS1 u32x4*)ob = rb[(g - 1) & 1][0]; *(GAS1 u32x4*)(ob + (size_t)8 * ldc) = rb[(g - 1) & 1][1];
;             }
;         }
;         asm volatile("s_waitcnt lgkmcnt(0)" : "+v"(rb[1][0]), "+v"(rb[1][1]));
;         { bf16_t* ob = obase + (size_t)(HALF + 3 * 16) * ldc; *(GAS1 u32x4*)ob = rb[1][0]; *(GAS1 u32x4*)(ob + (size_t)8 * ldc) = rb[1][1]; }
.LBB0_823:
	v_lshl_add_u32 v146, s30, 8, v151
	v_ashrrev_i32_e32 v147, 31, v146
	v_lshlrev_b64 v[146:147], 16, v[146:147]
	s_lshl_b32 s34, s83, 8
	v_lshl_add_u64 v[146:147], s[8:9], 0, v[146:147]
	s_ashr_i32 s35, s34, 31
	v_lshl_add_u64 v[146:147], s[34:35], 1, v[146:147]
	v_cvt_pk_bf16_f32 v124, v124, v125
	v_cvt_pk_bf16_f32 v125, v126, v127
	v_cvt_pk_bf16_f32 v126, v120, v121
	v_cvt_pk_bf16_f32 v127, v122, v123
	v_lshl_add_u64 v[146:147], v[146:147], 0, s[6:7]
	ds_write_b128 v152, v[124:127]
	v_cvt_pk_bf16_f32 v112, v112, v113
	v_cvt_pk_bf16_f32 v113, v114, v115
	v_cvt_pk_bf16_f32 v114, v104, v105
	v_cvt_pk_bf16_f32 v115, v106, v107
	v_lshl_add_u64 v[146:147], v[146:147], 0, v[136:137]
	ds_write_b128 v152, v[112:115] offset:64
	ds_read_b128 v[104:107], v153
	ds_read_b128 v[112:115], v153 offset:1152
	v_cvt_pk_bf16_f32 v116, v116, v117
	v_cvt_pk_bf16_f32 v117, v118, v119
	v_cvt_pk_bf16_f32 v118, v108, v109
	v_cvt_pk_bf16_f32 v119, v110, v111
	s_nop 0
	ds_write_b128 v152, v[116:119]
	v_cvt_pk_bf16_f32 v100, v100, v101
	v_cvt_pk_bf16_f32 v101, v102, v103
	v_cvt_pk_bf16_f32 v102, v92, v93
	v_cvt_pk_bf16_f32 v103, v94, v95
	s_nop 0
	ds_write_b128 v152, v[100:103] offset:64
	ds_read_b128 v[92:95], v153
	ds_read_b128 v[100:103], v153 offset:1152
	s_waitcnt lgkmcnt(4)
	global_store_dwordx4 v[146:147], v[104:107], off nt
	s_nop 1
	v_add_co_u32_e32 v104, vcc, s68, v146
	s_nop 1
	v_addc_co_u32_e32 v105, vcc, 0, v147, vcc
	global_store_dwordx4 v[104:105], v[112:115], off nt
	v_cvt_pk_bf16_f32 v96, v96, v97
	v_cvt_pk_bf16_f32 v97, v98, v99
	v_cvt_pk_bf16_f32 v98, v88, v89
	v_add_co_u32_e32 v88, vcc, s69, v146
	v_cvt_pk_bf16_f32 v99, v90, v91
	s_nop 0
	ds_write_b128 v152, v[96:99]
	v_cvt_pk_bf16_f32 v84, v84, v85
	v_cvt_pk_bf16_f32 v85, v86, v87
	v_cvt_pk_bf16_f32 v86, v76, v77
	v_cvt_pk_bf16_f32 v87, v78, v79
	s_nop 0
	v_addc_co_u32_e32 v89, vcc, 0, v147, vcc
	ds_write_b128 v152, v[84:87] offset:64
	ds_read_b128 v[76:79], v153
	ds_read_b128 v[84:87], v153 offset:1152
	s_waitcnt lgkmcnt(4)
	global_store_dwordx4 v[88:89], v[92:95], off nt
	v_add_co_u32_e32 v88, vcc, s70, v146
	s_nop 1
	v_addc_co_u32_e32 v89, vcc, 0, v147, vcc
	global_store_dwordx4 v[88:89], v[100:103], off nt
	v_cvt_pk_bf16_f32 v80, v80, v81
	v_cvt_pk_bf16_f32 v81, v82, v83
	v_cvt_pk_bf16_f32 v82, v72, v73
	v_add_co_u32_e32 v72, vcc, s71, v146
	v_cvt_pk_bf16_f32 v83, v74, v75
	s_nop 0
	ds_write_b128 v152, v[80:83]
	v_cvt_pk_bf16_f32 v68, v68, v69
	v_cvt_pk_bf16_f32 v69, v70, v71
	v_cvt_pk_bf16_f32 v70, v64, v65
	v_cvt_pk_bf16_f32 v71, v66, v67
	s_nop 0
	v_addc_co_u32_e32 v73, vcc, 0, v147, vcc
	ds_write_b128 v152, v[68:71] offset:64
	ds_read_b128 v[64:67], v153
	ds_read_b128 v[68:71], v153 offset:1152
	s_waitcnt lgkmcnt(4)
	global_store_dwordx4 v[72:73], v[76:79], off nt
	v_add_co_u32_e32 v72, vcc, s72, v146
	s_nop 1
	v_addc_co_u32_e32 v73, vcc, 0, v147, vcc
	global_store_dwordx4 v[72:73], v[84:87], off nt
	v_cvt_pk_bf16_f32 v60, v60, v61
	v_cvt_pk_bf16_f32 v61, v62, v63
	v_cvt_pk_bf16_f32 v62, v56, v57
	v_add_co_u32_e32 v56, vcc, s73, v146
	v_cvt_pk_bf16_f32 v63, v58, v59
	s_nop 0
	ds_write_b128 v152, v[60:63]
	v_cvt_pk_bf16_f32 v52, v52, v53
	v_cvt_pk_bf16_f32 v53, v54, v55
	v_cvt_pk_bf16_f32 v54, v44, v45
	v_cvt_pk_bf16_f32 v55, v46, v47
	s_nop 0
	v_addc_co_u32_e32 v57, vcc, 0, v147, vcc
	ds_write_b128 v152, v[52:55] offset:64
	ds_read_b128 v[44:47], v153
	ds_read_b128 v[52:55], v153 offset:1152
	s_waitcnt lgkmcnt(4)
	global_store_dwordx4 v[56:57], v[64:67], off nt
	v_add_co_u32_e32 v56, vcc, s74, v146
	s_nop 1
	v_addc_co_u32_e32 v57, vcc, 0, v147, vcc
	global_store_dwordx4 v[56:57], v[68:71], off nt
	v_cvt_pk_bf16_f32 v48, v48, v49
	v_cvt_pk_bf16_f32 v49, v50, v51
	v_cvt_pk_bf16_f32 v50, v40, v41
	v_add_co_u32_e32 v40, vcc, s75, v146
	v_cvt_pk_bf16_f32 v51, v42, v43
	s_nop 0
	ds_write_b128 v152, v[48:51]
	v_cvt_pk_bf16_f32 v36, v36, v37
	v_cvt_pk_bf16_f32 v37, v38, v39
	v_cvt_pk_bf16_f32 v38, v28, v29
	v_cvt_pk_bf16_f32 v39, v30, v31
	s_nop 0
	v_addc_co_u32_e32 v41, vcc, 0, v147, vcc
	ds_write_b128 v152, v[36:39] offset:64
	ds_read_b128 v[28:31], v153
	ds_read_b128 v[36:39], v153 offset:1152
	s_waitcnt lgkmcnt(4)
	global_store_dwordx4 v[40:41], v[44:47], off nt
	v_add_co_u32_e32 v40, vcc, s76, v146
	s_nop 1
	v_addc_co_u32_e32 v41, vcc, 0, v147, vcc
	global_store_dwordx4 v[40:41], v[52:55], off nt
	v_cvt_pk_bf16_f32 v32, v32, v33
	v_cvt_pk_bf16_f32 v33, v34, v35
	v_cvt_pk_bf16_f32 v34, v24, v25
	v_add_co_u32_e32 v24, vcc, s77, v146
	v_cvt_pk_bf16_f32 v35, v26, v27
	s_nop 0
	ds_write_b128 v152, v[32:35]
	v_cvt_pk_bf16_f32 v20, v20, v21
	v_cvt_pk_bf16_f32 v21, v22, v23
	v_cvt_pk_bf16_f32 v22, v12, v13
	v_cvt_pk_bf16_f32 v23, v14, v15
	s_nop 0
	v_addc_co_u32_e32 v25, vcc, 0, v147, vcc
	ds_write_b128 v152, v[20:23] offset:64
	ds_read_b128 v[12:15], v153
	ds_read_b128 v[20:23], v153 offset:1152
	s_waitcnt lgkmcnt(4)
	global_store_dwordx4 v[24:25], v[28:31], off nt
	v_add_co_u32_e32 v24, vcc, s79, v146
	s_nop 1
	v_addc_co_u32_e32 v25, vcc, 0, v147, vcc
	global_store_dwordx4 v[24:25], v[36:39], off nt
	v_cvt_pk_bf16_f32 v16, v16, v17
	v_cvt_pk_bf16_f32 v17, v18, v19
	v_cvt_pk_bf16_f32 v18, v8, v9
	v_add_co_u32_e32 v8, vcc, s80, v146
	v_cvt_pk_bf16_f32 v19, v10, v11
	s_nop 0
	ds_write_b128 v152, v[16:19]
	v_cvt_pk_bf16_f32 v4, v4, v5
	v_cvt_pk_bf16_f32 v5, v6, v7
	v_cvt_pk_bf16_f32 v6, v0, v1
	v_cvt_pk_bf16_f32 v7, v2, v3
	s_nop 0
	v_addc_co_u32_e32 v9, vcc, 0, v147, vcc
	ds_write_b128 v152, v[4:7] offset:64
	ds_read_b128 v[0:3], v153
	ds_read_b128 v[4:7], v153 offset:1152
	s_waitcnt lgkmcnt(4)
	global_store_dwordx4 v[8:9], v[12:15], off nt
	v_add_co_u32_e32 v8, vcc, s81, v146
	s_nop 1
	v_addc_co_u32_e32 v9, vcc, 0, v147, vcc
	global_store_dwordx4 v[8:9], v[20:23], off nt
	v_add_co_u32_e32 v8, vcc, 0xb00000, v146
	s_waitcnt lgkmcnt(0)
	s_nop 1
	v_addc_co_u32_e32 v9, vcc, 0, v147, vcc
	global_store_dwordx4 v[8:9], v[0:3], off nt
	s_nop 1
	v_add_co_u32_e32 v0, vcc, 0xb80000, v146
	s_nop 1
	v_addc_co_u32_e32 v1, vcc, 0, v147, vcc
	s_andn2_b64 vcc, exec, s[4:5]
	s_mov_b64 s[4:5], -1
	global_store_dwordx4 v[0:1], v[4:7], off nt
	s_cbranch_vccnz .LBB0_812
	s_andn2_b64 vcc, exec, s[10:11]
	s_cbranch_vccnz .LBB0_811
	s_barrier
	s_branch .LBB0_811

; __device__ __forceinline__ unsigned cvt_pk_bf16(float lo, float hi) { unsigned r; asm volatile("v_cvt_pk_bf16_f32 %0, %1, %2" : "=v"(r) : "v"(lo), "v"(hi)); return r; }
; #define GAS1 __attribute__((address_space(1)))
;     __device__ __forceinline__ void operator()(const f32x4 (&acc)[2][2][4][2], const Unit& u, int wr, int wc, int fr, int fq) const {
;     ...
;                 if (MODE == 2) {
;                     if (special) {
;                         const int fi = ((col & 63) >> 3) * 4;
;                         const f32x4 c = *(const GAS1 f32x4*)(cosT + (size_t)row * 32 + fi), s_ = *(const GAS1 f32x4*)(sinT + (size_t)row * 32 + fi);
;                         const f32x4 o1 = v0 * c - v1 * s_, o2 = v1 * c + v0 * s_; v0 = o1; v1 = o2;
;                     }
;                 }
;                 if (MODE == 3 || MODE == 4) {
;                     const u32x4 gw = *(const GAS1 u32x4*)(G + (size_t)row * ldg + col);
;                     const f32x4 g0 = {bf_lo(gw.x), bf_hi(gw.x), bf_lo(gw.y), bf_hi(gw.y)}, g1 = {bf_lo(gw.z), bf_hi(gw.z), bf_lo(gw.w), bf_hi(gw.w)};
;                     v0 = v0 * g0; v1 = v1 * g1;
;                     if (MODE == 4) {
;                         const u32x4 ow = *(const GAS1 u32x4*)((const bf16_t*)O + (size_t)row * ldc + col);
;                         const f32x4 o0 = {bf_lo(ow.x), bf_hi(ow.x), bf_lo(ow.y), bf_hi(ow.y)}, o1 = {bf_lo(ow.z), bf_hi(ow.z), bf_lo(ow.w), bf_hi(ow.w)};
;                         v0 += o0; v1 += o1;
;                     }
;                 }
;                 u32x4 w; w.x = cvt_pk_bf16(v0[0], v0[1]); w.y = cvt_pk_bf16(v0[2], v0[3]); w.z = cvt_pk_bf16(v1[0], v1[1]); w.w = cvt_pk_bf16(v1[2], v1[3]);
;                 if (bj == 0) asm volatile("ds_write_b128 %0, %1" :: "v"(wa), "v"(w)); else asm volatile("ds_write_b128 %0, %1 offset:64" :: "v"(wa), "v"(w));
;             }
;             asm volatile("ds_read_b128 %0, %1" : "=&v"(rb[g & 1][0]) : "v"(ra));
;             asm volatile("ds_read_b128 %0, %1 offset:1152" : "=&v"(rb[g & 1][1]) : "v"(ra));
;             if (g >= 1) {
;                 asm volatile("s_waitcnt lgkmcnt(4)" : "+v"(rb[(g - 1) & 1][0]), "+v"(rb[(g - 1) & 1][1]));
;                 bf16_t* ob = obase + (size_t)(((g - 1) >> 2) * HALF + ((g - 1) & 3) * 16) * ldc;
;                 *(GAS1 u32x4*)ob = rb[(g - 1) & 1][0]; *(GAS1 u32x4*)(ob + (size_t)8 * ldc) = rb[(g - 1) & 1][1];
.LBB0_967:
	v_or_b32_e32 v106, s23, v160
	v_mov_b64_e32 v[104:105], s[14:15]
	v_mad_i64_i32 v[104:105], s[34:35], v106, s71, v[104:105]
	s_lshl_b32 s34, s30, 8
	s_ashr_i32 s35, s34, 31
	v_lshl_add_u64 v[104:105], s[34:35], 1, v[104:105]
	v_lshl_add_u64 v[104:105], v[104:105], 0, s[10:11]
	v_lshl_add_u64 v[104:105], v[104:105], 0, v[136:137]
	v_add_co_u32_e32 v106, vcc, 0x6000, v104
	v_cvt_pk_bf16_f32 v100, v100, v101
	v_cvt_pk_bf16_f32 v101, v102, v103
	v_cvt_pk_bf16_f32 v102, v96, v97
	v_cvt_pk_bf16_f32 v103, v98, v99
	s_nop 1
	v_addc_co_u32_e32 v107, vcc, 0, v105, vcc
	ds_write_b128 v161, v[100:103] offset:64
	ds_read_b128 v[100:103], v162
	ds_read_b128 v[96:99], v162 offset:1152
	s_waitcnt lgkmcnt(4)
	global_store_dwordx4 v[106:107], v[112:115], off nt
	v_or_b32_e32 v106, 32, v154
	v_ashrrev_i32_e32 v107, 31, v106
	v_lshlrev_b64 v[106:107], 5, v[106:107]
	s_and_b64 vcc, exec, s[6:7]
	v_lshlrev_b64 v[106:107], 2, v[106:107]
	global_store_dwordx4 v[104:105], v[116:119], off nt
	s_cbranch_vccnz .LBB0_969
	v_lshl_add_u64 v[108:109], v[140:141], 0, v[106:107]
	global_load_dwordx4 v[108:111], v[108:109], off
	v_lshl_add_u64 v[112:113], v[138:139], 0, v[106:107]
	global_load_dwordx4 v[112:115], v[112:113], off
	s_waitcnt vmcnt(0)
	v_pk_mul_f32 v[116:117], v[90:91], v[110:111]
	v_pk_mul_f32 v[118:119], v[88:89], v[108:109]
	v_pk_mul_f32 v[110:111], v[94:95], v[110:111]
	v_pk_mul_f32 v[108:109], v[92:93], v[108:109]
	v_pk_fma_f32 v[94:95], v[94:95], v[114:115], v[116:117] neg_lo:[0,0,1] neg_hi:[0,0,1]
	v_pk_fma_f32 v[92:93], v[92:93], v[112:113], v[118:119] neg_lo:[0,0,1] neg_hi:[0,0,1]
	v_pk_fma_f32 v[90:91], v[90:91], v[114:115], v[110:111]
	v_pk_fma_f32 v[88:89], v[88:89], v[112:113], v[108:109]

; __device__ __forceinline__ unsigned cvt_pk_bf16(float lo, float hi) { unsigned r; asm volatile("v_cvt_pk_bf16_f32 %0, %1, %2" : "=v"(r) : "v"(lo), "v"(hi)); return r; }
; #define GAS1 __attribute__((address_space(1)))
;     __device__ __forceinline__ void operator()(const f32x4 (&acc)[2][2][4][2], const Unit& u, int wr, int wc, int fr, int fq) const {
;     ...
;                 if (MODE == 2) {
;                     if (special) {
;                         const int fi = ((col & 63) >> 3) * 4;
;                         const f32x4 c = *(const GAS1 f32x4*)(cosT + (size_t)row * 32 + fi), s_ = *(const GAS1 f32x4*)(sinT + (size_t)row * 32 + fi);
;                         const f32x4 o1 = v0 * c - v1 * s_, o2 = v1 * c + v0 * s_; v0 = o1; v1 = o2;
;                     }
;                 }
;                 if (MODE == 3 || MODE == 4) {
;                     const u32x4 gw = *(const GAS1 u32x4*)(G + (size_t)row * ldg + col);
;                     const f32x4 g0 = {bf_lo(gw.x), bf_hi(gw.x), bf_lo(gw.y), bf_hi(gw.y)}, g1 = {bf_lo(gw.z), bf_hi(gw.z), bf_lo(gw.w), bf_hi(gw.w)};
;                     v0 = v0 * g0; v1 = v1 * g1;
;                     if (MODE == 4) {
;                         const u32x4 ow = *(const GAS1 u32x4*)((const bf16_t*)O + (size_t)row * ldc + col);
;                         const f32x4 o0 = {bf_lo(ow.x), bf_hi(ow.x), bf_lo(ow.y), bf_hi(ow.y)}, o1 = {bf_lo(ow.z), bf_hi(ow.z), bf_lo(ow.w), bf_hi(ow.w)};
;                         v0 += o0; v1 += o1;
;                     }
;                 }
;                 u32x4 w; w.x = cvt_pk_bf16(v0[0], v0[1]); w.y = cvt_pk_bf16(v0[2], v0[3]); w.z = cvt_pk_bf16(v1[0], v1[1]); w.w = cvt_pk_bf16(v1[2], v1[3]);
;                 if (bj == 0) asm volatile("ds_write_b128 %0, %1" :: "v"(wa), "v"(w)); else asm volatile("ds_write_b128 %0, %1 offset:64" :: "v"(wa), "v"(w));
;             }
;             asm volatile("ds_read_b128 %0, %1" : "=&v"(rb[g & 1][0]) : "v"(ra));
;             asm volatile("ds_read_b128 %0, %1 offset:1152" : "=&v"(rb[g & 1][1]) : "v"(ra));
;             if (g >= 1) {
;                 asm volatile("s_waitcnt lgkmcnt(4)" : "+v"(rb[(g - 1) & 1][0]), "+v"(rb[(g - 1) & 1][1]));
;                 bf16_t* ob = obase + (size_t)(((g - 1) >> 2) * HALF + ((g - 1) & 3) * 16) * ldc;
;                 *(GAS1 u32x4*)ob = rb[(g - 1) & 1][0]; *(GAS1 u32x4*)(ob + (size_t)8 * ldc) = rb[(g - 1) & 1][1];
.LBB0_971:
	v_add_co_u32_e32 v88, vcc, 0xc000, v104
	v_cvt_pk_bf16_f32 v84, v84, v85
	v_cvt_pk_bf16_f32 v85, v86, v87
	v_cvt_pk_bf16_f32 v86, v80, v81
	v_cvt_pk_bf16_f32 v87, v82, v83
	s_nop 1
	v_addc_co_u32_e32 v89, vcc, 0, v105, vcc
	ds_write_b128 v161, v[84:87] offset:64
	ds_read_b128 v[84:87], v162
	ds_read_b128 v[80:83], v162 offset:1152
	s_waitcnt lgkmcnt(4)
	global_store_dwordx4 v[88:89], v[100:103], off nt
	v_add_co_u32_e32 v88, vcc, 0x12000, v104
	s_nop 1
	v_addc_co_u32_e32 v89, vcc, 0, v105, vcc
	global_store_dwordx4 v[88:89], v[96:99], off nt
	v_or_b32_e32 v88, 48, v154
	v_ashrrev_i32_e32 v89, 31, v88
	v_lshlrev_b64 v[88:89], 5, v[88:89]
	s_and_b64 vcc, exec, s[6:7]
	v_lshlrev_b64 v[88:89], 2, v[88:89]
	s_cbranch_vccnz .LBB0_973
	v_lshl_add_u64 v[90:91], v[140:141], 0, v[88:89]
	global_load_dwordx4 v[90:93], v[90:91], off
	v_lshl_add_u64 v[94:95], v[138:139], 0, v[88:89]
	global_load_dwordx4 v[94:97], v[94:95], off
	s_waitcnt vmcnt(0)
	v_pk_mul_f32 v[98:99], v[74:75], v[92:93]
	v_pk_mul_f32 v[100:101], v[72:73], v[90:91]
	v_pk_mul_f32 v[92:93], v[78:79], v[92:93]
	v_pk_mul_f32 v[90:91], v[76:77], v[90:91]
	v_pk_fma_f32 v[78:79], v[78:79], v[96:97], v[98:99] neg_lo:[0,0,1] neg_hi:[0,0,1]
	v_pk_fma_f32 v[76:77], v[76:77], v[94:95], v[100:101] neg_lo:[0,0,1] neg_hi:[0,0,1]
	v_pk_fma_f32 v[74:75], v[74:75], v[96:97], v[92:93]
	v_pk_fma_f32 v[72:73], v[72:73], v[94:95], v[90:91]

; __device__ __forceinline__ unsigned cvt_pk_bf16(float lo, float hi) { unsigned r; asm volatile("v_cvt_pk_bf16_f32 %0, %1, %2" : "=v"(r) : "v"(lo), "v"(hi)); return r; }
; #define GAS1 __attribute__((address_space(1)))
;     __device__ __forceinline__ void operator()(const f32x4 (&acc)[2][2][4][2], const Unit& u, int wr, int wc, int fr, int fq) const {
;     ...
;                 if (MODE == 2) {
;                     if (special) {
;                         const int fi = ((col & 63) >> 3) * 4;
;                         const f32x4 c = *(const GAS1 f32x4*)(cosT + (size_t)row * 32 + fi), s_ = *(const GAS1 f32x4*)(sinT + (size_t)row * 32 + fi);
;                         const f32x4 o1 = v0 * c - v1 * s_, o2 = v1 * c + v0 * s_; v0 = o1; v1 = o2;
;                     }
;                 }
;                 if (MODE == 3 || MODE == 4) {
;                     const u32x4 gw = *(const GAS1 u32x4*)(G + (size_t)row * ldg + col);
;                     const f32x4 g0 = {bf_lo(gw.x), bf_hi(gw.x), bf_lo(gw.y), bf_hi(gw.y)}, g1 = {bf_lo(gw.z), bf_hi(gw.z), bf_lo(gw.w), bf_hi(gw.w)};
;                     v0 = v0 * g0; v1 = v1 * g1;
;                     if (MODE == 4) {
;                         const u32x4 ow = *(const GAS1 u32x4*)((const bf16_t*)O + (size_t)row * ldc + col);
;                         const f32x4 o0 = {bf_lo(ow.x), bf_hi(ow.x), bf_lo(ow.y), bf_hi(ow.y)}, o1 = {bf_lo(ow.z), bf_hi(ow.z), bf_lo(ow.w), bf_hi(ow.w)};
;                         v0 += o0; v1 += o1;
;                     }
;                 }
;                 u32x4 w; w.x = cvt_pk_bf16(v0[0], v0[1]); w.y = cvt_pk_bf16(v0[2], v0[3]); w.z = cvt_pk_bf16(v1[0], v1[1]); w.w = cvt_pk_bf16(v1[2], v1[3]);
;                 if (bj == 0) asm volatile("ds_write_b128 %0, %1" :: "v"(wa), "v"(w)); else asm volatile("ds_write_b128 %0, %1 offset:64" :: "v"(wa), "v"(w));
;             }
;             asm volatile("ds_read_b128 %0, %1" : "=&v"(rb[g & 1][0]) : "v"(ra));
;             asm volatile("ds_read_b128 %0, %1 offset:1152" : "=&v"(rb[g & 1][1]) : "v"(ra));
;             if (g >= 1) {
;                 asm volatile("s_waitcnt lgkmcnt(4)" : "+v"(rb[(g - 1) & 1][0]), "+v"(rb[(g - 1) & 1][1]));
;                 bf16_t* ob = obase + (size_t)(((g - 1) >> 2) * HALF + ((g - 1) & 3) * 16) * ldc;
;                 *(GAS1 u32x4*)ob = rb[(g - 1) & 1][0]; *(GAS1 u32x4*)(ob + (size_t)8 * ldc) = rb[(g - 1) & 1][1];
.LBB0_975:
	v_add_co_u32_e32 v72, vcc, 0x18000, v104
	v_cvt_pk_bf16_f32 v68, v68, v69
	v_cvt_pk_bf16_f32 v69, v70, v71
	v_cvt_pk_bf16_f32 v70, v64, v65
	v_cvt_pk_bf16_f32 v71, v66, v67
	s_nop 1
	v_addc_co_u32_e32 v73, vcc, 0, v105, vcc
	ds_write_b128 v161, v[68:71] offset:64
	ds_read_b128 v[68:71], v162
	ds_read_b128 v[64:67], v162 offset:1152
	s_waitcnt lgkmcnt(4)
	global_store_dwordx4 v[72:73], v[84:87], off nt
	v_add_co_u32_e32 v72, vcc, 0x1e000, v104
	s_nop 1
	v_addc_co_u32_e32 v73, vcc, 0, v105, vcc
	global_store_dwordx4 v[72:73], v[80:83], off nt
	v_add_u32_e32 v72, 0x80, v154
	v_ashrrev_i32_e32 v73, 31, v72
	v_lshlrev_b64 v[74:75], 5, v[72:73]
	s_and_b64 vcc, exec, s[6:7]
	v_lshlrev_b64 v[74:75], 2, v[74:75]
	s_cbranch_vccnz .LBB0_977
	v_lshl_add_u64 v[76:77], v[140:141], 0, v[74:75]
	global_load_dwordx4 v[76:79], v[76:77], off
	v_lshl_add_u64 v[80:81], v[138:139], 0, v[74:75]
	global_load_dwordx4 v[80:83], v[80:81], off
	s_waitcnt vmcnt(0)
	v_pk_mul_f32 v[84:85], v[58:59], v[78:79]
	v_pk_mul_f32 v[86:87], v[56:57], v[76:77]
	v_pk_mul_f32 v[78:79], v[62:63], v[78:79]
	v_pk_mul_f32 v[76:77], v[60:61], v[76:77]
	v_pk_fma_f32 v[62:63], v[62:63], v[82:83], v[84:85] neg_lo:[0,0,1] neg_hi:[0,0,1]
	v_pk_fma_f32 v[60:61], v[60:61], v[80:81], v[86:87] neg_lo:[0,0,1] neg_hi:[0,0,1]
	v_pk_fma_f32 v[58:59], v[58:59], v[82:83], v[78:79]
	v_pk_fma_f32 v[56:57], v[56:57], v[80:81], v[76:77]

; __device__ __forceinline__ unsigned cvt_pk_bf16(float lo, float hi) { unsigned r; asm volatile("v_cvt_pk_bf16_f32 %0, %1, %2" : "=v"(r) : "v"(lo), "v"(hi)); return r; }
; #define GAS1 __attribute__((address_space(1)))
;     __device__ __forceinline__ void operator()(const f32x4 (&acc)[2][2][4][2], const Unit& u, int wr, int wc, int fr, int fq) const {
;     ...
;                 if (MODE == 2) {
;                     if (special) {
;                         const int fi = ((col & 63) >> 3) * 4;
;                         const f32x4 c = *(const GAS1 f32x4*)(cosT + (size_t)row * 32 + fi), s_ = *(const GAS1 f32x4*)(sinT + (size_t)row * 32 + fi);
;                         const f32x4 o1 = v0 * c - v1 * s_, o2 = v1 * c + v0 * s_; v0 = o1; v1 = o2;
;                     }
;                 }
;                 if (MODE == 3 || MODE == 4) {
;                     const u32x4 gw = *(const GAS1 u32x4*)(G + (size_t)row * ldg + col);
;                     const f32x4 g0 = {bf_lo(gw.x), bf_hi(gw.x), bf_lo(gw.y), bf_hi(gw.y)}, g1 = {bf_lo(gw.z), bf_hi(gw.z), bf_lo(gw.w), bf_hi(gw.w)};
;                     v0 = v0 * g0; v1 = v1 * g1;
;                     if (MODE == 4) {
;                         const u32x4 ow = *(const GAS1 u32x4*)((const bf16_t*)O + (size_t)row * ldc + col);
;                         const f32x4 o0 = {bf_lo(ow.x), bf_hi(ow.x), bf_lo(ow.y), bf_hi(ow.y)}, o1 = {bf_lo(ow.z), bf_hi(ow.z), bf_lo(ow.w), bf_hi(ow.w)};
;                         v0 += o0; v1 += o1;
;                     }
;                 }
;                 u32x4 w; w.x = cvt_pk_bf16(v0[0], v0[1]); w.y = cvt_pk_bf16(v0[2], v0[3]); w.z = cvt_pk_bf16(v1[0], v1[1]); w.w = cvt_pk_bf16(v1[2], v1[3]);
;                 if (bj == 0) asm volatile("ds_write_b128 %0, %1" :: "v"(wa), "v"(w)); else asm volatile("ds_write_b128 %0, %1 offset:64" :: "v"(wa), "v"(w));
;             }
;             asm volatile("ds_read_b128 %0, %1" : "=&v"(rb[g & 1][0]) : "v"(ra));
;             asm volatile("ds_read_b128 %0, %1 offset:1152" : "=&v"(rb[g & 1][1]) : "v"(ra));
;             if (g >= 1) {
;                 asm volatile("s_waitcnt lgkmcnt(4)" : "+v"(rb[(g - 1) & 1][0]), "+v"(rb[(g - 1) & 1][1]));
;                 bf16_t* ob = obase + (size_t)(((g - 1) >> 2) * HALF + ((g - 1) & 3) * 16) * ldc;
;                 *(GAS1 u32x4*)ob = rb[(g - 1) & 1][0]; *(GAS1 u32x4*)(ob + (size_t)8 * ldc) = rb[(g - 1) & 1][1];
.LBB0_979:
	v_add_co_u32_e32 v56, vcc, 0x24000, v104
	v_cvt_pk_bf16_f32 v52, v52, v53
	v_cvt_pk_bf16_f32 v53, v54, v55
	v_cvt_pk_bf16_f32 v54, v48, v49
	v_cvt_pk_bf16_f32 v55, v50, v51
	s_nop 1
	v_addc_co_u32_e32 v57, vcc, 0, v105, vcc
	ds_write_b128 v161, v[52:55] offset:64
	ds_read_b128 v[52:55], v162
	ds_read_b128 v[48:51], v162 offset:1152
	s_waitcnt lgkmcnt(4)
	global_store_dwordx4 v[56:57], v[68:71], off nt
	v_add_co_u32_e32 v56, vcc, 0x2a000, v104
	s_nop 1
	v_addc_co_u32_e32 v57, vcc, 0, v105, vcc
	global_store_dwordx4 v[56:57], v[64:67], off nt
	v_or_b32_e32 v56, 16, v72
	v_ashrrev_i32_e32 v57, 31, v56
	v_lshlrev_b64 v[56:57], 5, v[56:57]
	s_and_b64 vcc, exec, s[6:7]
	v_lshlrev_b64 v[56:57], 2, v[56:57]
	s_cbranch_vccnz .LBB0_981
	v_lshl_add_u64 v[58:59], v[140:141], 0, v[56:57]
	global_load_dwordx4 v[58:61], v[58:59], off
	v_lshl_add_u64 v[62:63], v[138:139], 0, v[56:57]
	global_load_dwordx4 v[62:65], v[62:63], off
	s_waitcnt vmcnt(0)
	v_pk_mul_f32 v[66:67], v[42:43], v[60:61]
	v_pk_mul_f32 v[68:69], v[40:41], v[58:59]
	v_pk_mul_f32 v[60:61], v[46:47], v[60:61]
	v_pk_mul_f32 v[58:59], v[44:45], v[58:59]
	v_pk_fma_f32 v[46:47], v[46:47], v[64:65], v[66:67] neg_lo:[0,0,1] neg_hi:[0,0,1]
	v_pk_fma_f32 v[44:45], v[44:45], v[62:63], v[68:69] neg_lo:[0,0,1] neg_hi:[0,0,1]
	v_pk_fma_f32 v[42:43], v[42:43], v[64:65], v[60:61]
	v_pk_fma_f32 v[40:41], v[40:41], v[62:63], v[58:59]

; __device__ __forceinline__ unsigned cvt_pk_bf16(float lo, float hi) { unsigned r; asm volatile("v_cvt_pk_bf16_f32 %0, %1, %2" : "=v"(r) : "v"(lo), "v"(hi)); return r; }
; #define GAS1 __attribute__((address_space(1)))
;     __device__ __forceinline__ void operator()(const f32x4 (&acc)[2][2][4][2], const Unit& u, int wr, int wc, int fr, int fq) const {
;     ...
;                 if (MODE == 2) {
;                     if (special) {
;                         const int fi = ((col & 63) >> 3) * 4;
;                         const f32x4 c = *(const GAS1 f32x4*)(cosT + (size_t)row * 32 + fi), s_ = *(const GAS1 f32x4*)(sinT + (size_t)row * 32 + fi);
;                         const f32x4 o1 = v0 * c - v1 * s_, o2 = v1 * c + v0 * s_; v0 = o1; v1 = o2;
;                     }
;                 }
;                 if (MODE == 3 || MODE == 4) {
;                     const u32x4 gw = *(const GAS1 u32x4*)(G + (size_t)row * ldg + col);
;                     const f32x4 g0 = {bf_lo(gw.x), bf_hi(gw.x), bf_lo(gw.y), bf_hi(gw.y)}, g1 = {bf_lo(gw.z), bf_hi(gw.z), bf_lo(gw.w), bf_hi(gw.w)};
;                     v0 = v0 * g0; v1 = v1 * g1;
;                     if (MODE == 4) {
;                         const u32x4 ow = *(const GAS1 u32x4*)((const bf16_t*)O + (size_t)row * ldc + col);
;                         const f32x4 o0 = {bf_lo(ow.x), bf_hi(ow.x), bf_lo(ow.y), bf_hi(ow.y)}, o1 = {bf_lo(ow.z), bf_hi(ow.z), bf_lo(ow.w), bf_hi(ow.w)};
;                         v0 += o0; v1 += o1;
;                     }
;                 }
;                 u32x4 w; w.x = cvt_pk_bf16(v0[0], v0[1]); w.y = cvt_pk_bf16(v0[2], v0[3]); w.z = cvt_pk_bf16(v1[0], v1[1]); w.w = cvt_pk_bf16(v1[2], v1[3]);
;                 if (bj == 0) asm volatile("ds_write_b128 %0, %1" :: "v"(wa), "v"(w)); else asm volatile("ds_write_b128 %0, %1 offset:64" :: "v"(wa), "v"(w));
;             }
;             asm volatile("ds_read_b128 %0, %1" : "=&v"(rb[g & 1][0]) : "v"(ra));
;             asm volatile("ds_read_b128 %0, %1 offset:1152" : "=&v"(rb[g & 1][1]) : "v"(ra));
;             if (g >= 1) {
;                 asm volatile("s_waitcnt lgkmcnt(4)" : "+v"(rb[(g - 1) & 1][0]), "+v"(rb[(g - 1) & 1][1]));
;                 bf16_t* ob = obase + (size_t)(((g - 1) >> 2) * HALF + ((g - 1) & 3) * 16) * ldc;
;                 *(GAS1 u32x4*)ob = rb[(g - 1) & 1][0]; *(GAS1 u32x4*)(ob + (size_t)8 * ldc) = rb[(g - 1) & 1][1];
.LBB0_983:
	v_add_co_u32_e32 v40, vcc, 0x60000, v104
	v_cvt_pk_bf16_f32 v36, v36, v37
	v_cvt_pk_bf16_f32 v37, v38, v39
	v_cvt_pk_bf16_f32 v38, v32, v33
	v_cvt_pk_bf16_f32 v39, v34, v35
	s_nop 1
	v_addc_co_u32_e32 v41, vcc, 0, v105, vcc
	ds_write_b128 v161, v[36:39] offset:64
	ds_read_b128 v[36:39], v162
	ds_read_b128 v[32:35], v162 offset:1152
	s_waitcnt lgkmcnt(4)
	global_store_dwordx4 v[40:41], v[52:55], off nt
	v_add_co_u32_e32 v40, vcc, 0x66000, v104
	s_nop 1
	v_addc_co_u32_e32 v41, vcc, 0, v105, vcc
	global_store_dwordx4 v[40:41], v[48:51], off nt
	v_or_b32_e32 v40, 32, v72
	v_ashrrev_i32_e32 v41, 31, v40
	v_lshlrev_b64 v[40:41], 5, v[40:41]
	s_and_b64 vcc, exec, s[6:7]
	v_lshlrev_b64 v[40:41], 2, v[40:41]
	s_cbranch_vccnz .LBB0_985
	v_lshl_add_u64 v[42:43], v[140:141], 0, v[40:41]
	global_load_dwordx4 v[42:45], v[42:43], off
	v_lshl_add_u64 v[46:47], v[138:139], 0, v[40:41]
	global_load_dwordx4 v[46:49], v[46:47], off
	s_waitcnt vmcnt(0)
	v_pk_mul_f32 v[50:51], v[26:27], v[44:45]
	v_pk_mul_f32 v[52:53], v[24:25], v[42:43]
	v_pk_mul_f32 v[44:45], v[30:31], v[44:45]
	v_pk_mul_f32 v[42:43], v[28:29], v[42:43]
	v_pk_fma_f32 v[30:31], v[30:31], v[48:49], v[50:51] neg_lo:[0,0,1] neg_hi:[0,0,1]
	v_pk_fma_f32 v[28:29], v[28:29], v[46:47], v[52:53] neg_lo:[0,0,1] neg_hi:[0,0,1]
	v_pk_fma_f32 v[26:27], v[26:27], v[48:49], v[44:45]
	v_pk_fma_f32 v[24:25], v[24:25], v[46:47], v[42:43]

; __device__ __forceinline__ unsigned cvt_pk_bf16(float lo, float hi) { unsigned r; asm volatile("v_cvt_pk_bf16_f32 %0, %1, %2" : "=v"(r) : "v"(lo), "v"(hi)); return r; }
; #define GAS1 __attribute__((address_space(1)))
;     __device__ __forceinline__ void operator()(const f32x4 (&acc)[2][2][4][2], const Unit& u, int wr, int wc, int fr, int fq) const {
;     ...
;                 if (MODE == 2) {
;                     if (special) {
;                         const int fi = ((col & 63) >> 3) * 4;
;                         const f32x4 c = *(const GAS1 f32x4*)(cosT + (size_t)row * 32 + fi), s_ = *(const GAS1 f32x4*)(sinT + (size_t)row * 32 + fi);
;                         const f32x4 o1 = v0 * c - v1 * s_, o2 = v1 * c + v0 * s_; v0 = o1; v1 = o2;
;                     }
;                 }
;                 if (MODE == 3 || MODE == 4) {
;                     const u32x4 gw = *(const GAS1 u32x4*)(G + (size_t)row * ldg + col);
;                     const f32x4 g0 = {bf_lo(gw.x), bf_hi(gw.x), bf_lo(gw.y), bf_hi(gw.y)}, g1 = {bf_lo(gw.z), bf_hi(gw.z), bf_lo(gw.w), bf_hi(gw.w)};
;                     v0 = v0 * g0; v1 = v1 * g1;
;                     if (MODE == 4) {
;                         const u32x4 ow = *(const GAS1 u32x4*)((const bf16_t*)O + (size_t)row * ldc + col);
;                         const f32x4 o0 = {bf_lo(ow.x), bf_hi(ow.x), bf_lo(ow.y), bf_hi(ow.y)}, o1 = {bf_lo(ow.z), bf_hi(ow.z), bf_lo(ow.w), bf_hi(ow.w)};
;                         v0 += o0; v1 += o1;
;                     }
;                 }
;                 u32x4 w; w.x = cvt_pk_bf16(v0[0], v0[1]); w.y = cvt_pk_bf16(v0[2], v0[3]); w.z = cvt_pk_bf16(v1[0], v1[1]); w.w = cvt_pk_bf16(v1[2], v1[3]);
;                 if (bj == 0) asm volatile("ds_write_b128 %0, %1" :: "v"(wa), "v"(w)); else asm volatile("ds_write_b128 %0, %1 offset:64" :: "v"(wa), "v"(w));
;             }
;             asm volatile("ds_read_b128 %0, %1" : "=&v"(rb[g & 1][0]) : "v"(ra));
;             asm volatile("ds_read_b128 %0, %1 offset:1152" : "=&v"(rb[g & 1][1]) : "v"(ra));
;             if (g >= 1) {
;                 asm volatile("s_waitcnt lgkmcnt(4)" : "+v"(rb[(g - 1) & 1][0]), "+v"(rb[(g - 1) & 1][1]));
;                 bf16_t* ob = obase + (size_t)(((g - 1) >> 2) * HALF + ((g - 1) & 3) * 16) * ldc;
;                 *(GAS1 u32x4*)ob = rb[(g - 1) & 1][0]; *(GAS1 u32x4*)(ob + (size_t)8 * ldc) = rb[(g - 1) & 1][1];
.LBB0_987:
	v_add_co_u32_e32 v24, vcc, 0x6c000, v104
	v_cvt_pk_bf16_f32 v20, v20, v21
	v_cvt_pk_bf16_f32 v21, v22, v23
	v_cvt_pk_bf16_f32 v22, v16, v17
	v_cvt_pk_bf16_f32 v23, v18, v19
	s_nop 1
	v_addc_co_u32_e32 v25, vcc, 0, v105, vcc
	ds_write_b128 v161, v[20:23] offset:64
	ds_read_b128 v[20:23], v162
	ds_read_b128 v[16:19], v162 offset:1152
	s_waitcnt lgkmcnt(4)
	global_store_dwordx4 v[24:25], v[36:39], off nt
	v_add_co_u32_e32 v24, vcc, 0x72000, v104
	s_nop 1
	v_addc_co_u32_e32 v25, vcc, 0, v105, vcc
	global_store_dwordx4 v[24:25], v[32:35], off nt
	v_or_b32_e32 v24, 48, v72
	v_ashrrev_i32_e32 v25, 31, v24
	v_lshlrev_b64 v[24:25], 5, v[24:25]
	s_and_b64 vcc, exec, s[6:7]
	v_lshlrev_b64 v[24:25], 2, v[24:25]
	s_cbranch_vccnz .LBB0_989
	v_lshl_add_u64 v[26:27], v[140:141], 0, v[24:25]
	global_load_dwordx4 v[26:29], v[26:27], off
	v_lshl_add_u64 v[30:31], v[138:139], 0, v[24:25]
	global_load_dwordx4 v[30:33], v[30:31], off
	s_waitcnt vmcnt(0)
	v_pk_mul_f32 v[34:35], v[10:11], v[28:29]
	v_pk_mul_f32 v[36:37], v[8:9], v[26:27]
	v_pk_mul_f32 v[28:29], v[14:15], v[28:29]
	v_pk_mul_f32 v[26:27], v[12:13], v[26:27]
	v_pk_fma_f32 v[14:15], v[14:15], v[32:33], v[34:35] neg_lo:[0,0,1] neg_hi:[0,0,1]
	v_pk_fma_f32 v[12:13], v[12:13], v[30:31], v[36:37] neg_lo:[0,0,1] neg_hi:[0,0,1]
	v_pk_fma_f32 v[10:11], v[10:11], v[32:33], v[28:29]
	v_pk_fma_f32 v[8:9], v[8:9], v[30:31], v[26:27]

; __device__ __forceinline__ unsigned cvt_pk_bf16(float lo, float hi) { unsigned r; asm volatile("v_cvt_pk_bf16_f32 %0, %1, %2" : "=v"(r) : "v"(lo), "v"(hi)); return r; }
; #define GAS1 __attribute__((address_space(1)))
;     __device__ __forceinline__ void operator()(const f32x4 (&acc)[2][2][4][2], const Unit& u, int wr, int wc, int fr, int fq) const {
;     ...
;                 u32x4 w; w.x = cvt_pk_bf16(v0[0], v0[1]); w.y = cvt_pk_bf16(v0[2], v0[3]); w.z = cvt_pk_bf16(v1[0], v1[1]); w.w = cvt_pk_bf16(v1[2], v1[3]);
;                 if (bj == 0) asm volatile("ds_write_b128 %0, %1" :: "v"(wa), "v"(w)); else asm volatile("ds_write_b128 %0, %1 offset:64" :: "v"(wa), "v"(w));
;             }
;             asm volatile("ds_read_b128 %0, %1" : "=&v"(rb[g & 1][0]) : "v"(ra));
;             asm volatile("ds_read_b128 %0, %1 offset:1152" : "=&v"(rb[g & 1][1]) : "v"(ra));
;             if (g >= 1) {
;                 asm volatile("s_waitcnt lgkmcnt(4)" : "+v"(rb[(g - 1) & 1][0]), "+v"(rb[(g - 1) & 1][1]));
;                 bf16_t* ob = obase + (size_t)(((g - 1) >> 2) * HALF + ((g - 1) & 3) * 16) * ldc;
;                 *(GAS1 u32x4*)ob = rb[(g - 1) & 1][0]; *(GAS1 u32x4*)(ob + (size_t)8 * ldc) = rb[(g - 1) & 1][1];
;             }
;         }
;         asm volatile("s_waitcnt lgkmcnt(0)" : "+v"(rb[1][0]), "+v"(rb[1][1]));
;         { bf16_t* ob = obase + (size_t)(HALF + 3 * 16) * ldc; *(GAS1 u32x4*)ob = rb[1][0]; *(GAS1 u32x4*)(ob + (size_t)8 * ldc) = rb[1][1]; }
.LBB0_991:
	v_add_co_u32_e32 v8, vcc, s72, v104
	v_cvt_pk_bf16_f32 v4, v4, v5
	v_cvt_pk_bf16_f32 v5, v6, v7
	v_cvt_pk_bf16_f32 v6, v0, v1
	v_cvt_pk_bf16_f32 v7, v2, v3
	s_nop 1
	v_addc_co_u32_e32 v9, vcc, 0, v105, vcc
	ds_write_b128 v161, v[4:7] offset:64
	ds_read_b128 v[0:3], v162
	ds_read_b128 v[4:7], v162 offset:1152
	s_waitcnt lgkmcnt(4)
	global_store_dwordx4 v[8:9], v[20:23], off nt
	v_add_co_u32_e32 v8, vcc, s73, v104
	s_nop 1
	v_addc_co_u32_e32 v9, vcc, 0, v105, vcc
	global_store_dwordx4 v[8:9], v[16:19], off nt
	v_add_co_u32_e32 v8, vcc, 0x84000, v104
	s_waitcnt lgkmcnt(0)
	s_nop 1
	v_addc_co_u32_e32 v9, vcc, 0, v105, vcc
	global_store_dwordx4 v[8:9], v[0:3], off nt
	s_nop 1
	v_add_co_u32_e32 v0, vcc, 0x8a000, v104
	s_nop 1
	v_addc_co_u32_e32 v1, vcc, 0, v105, vcc
	s_andn2_b64 vcc, exec, s[4:5]
	s_mov_b64 s[4:5], -1
	global_store_dwordx4 v[0:1], v[4:7], off nt
	s_cbranch_vccnz .LBB0_952
	s_andn2_b64 vcc, exec, s[12:13]
	s_cbranch_vccnz .LBB0_951
	s_barrier
	s_branch .LBB0_951

; __device__ __forceinline__ unsigned cvt_pk_bf16(float lo, float hi) { unsigned r; asm volatile("v_cvt_pk_bf16_f32 %0, %1, %2" : "=v"(r) : "v"(lo), "v"(hi)); return r; }
; #define GAS1 __attribute__((address_space(1)))
;     __device__ __forceinline__ void operator()(const f32x4 (&acc)[2][2][4][2], const Unit& u, int wr, int wc, int fr, int fq) const {
;     ...
;                 u32x4 w; w.x = cvt_pk_bf16(v0[0], v0[1]); w.y = cvt_pk_bf16(v0[2], v0[3]); w.z = cvt_pk_bf16(v1[0], v1[1]); w.w = cvt_pk_bf16(v1[2], v1[3]);
;                 if (bj == 0) asm volatile("ds_write_b128 %0, %1" :: "v"(wa), "v"(w)); else asm volatile("ds_write_b128 %0, %1 offset:64" :: "v"(wa), "v"(w));
;             }
;             asm volatile("ds_read_b128 %0, %1" : "=&v"(rb[g & 1][0]) : "v"(ra));
;             asm volatile("ds_read_b128 %0, %1 offset:1152" : "=&v"(rb[g & 1][1]) : "v"(ra));
;             if (g >= 1) {
;                 asm volatile("s_waitcnt lgkmcnt(4)" : "+v"(rb[(g - 1) & 1][0]), "+v"(rb[(g - 1) & 1][1]));
;                 bf16_t* ob = obase + (size_t)(((g - 1) >> 2) * HALF + ((g - 1) & 3) * 16) * ldc;
;                 *(GAS1 u32x4*)ob = rb[(g - 1) & 1][0]; *(GAS1 u32x4*)(ob + (size_t)8 * ldc) = rb[(g - 1) & 1][1];
;             }
;         }
;         asm volatile("s_waitcnt lgkmcnt(0)" : "+v"(rb[1][0]), "+v"(rb[1][1]));
;         { bf16_t* ob = obase + (size_t)(HALF + 3 * 16) * ldc; *(GAS1 u32x4*)ob = rb[1][0]; *(GAS1 u32x4*)(ob + (size_t)8 * ldc) = rb[1][1]; }
.LBB0_1015:
	v_lshl_add_u32 v142, s28, 8, v145
	v_ashrrev_i32_e32 v143, 31, v142
	v_lshlrev_b64 v[142:143], 11, v[142:143]
	s_lshl_b32 s30, s89, 8
	v_lshl_add_u64 v[142:143], s[14:15], 0, v[142:143]
	s_ashr_i32 s31, s30, 31
	v_lshl_add_u64 v[142:143], s[30:31], 1, v[142:143]
	v_cvt_pk_bf16_f32 v124, v124, v125
	v_cvt_pk_bf16_f32 v125, v126, v127
	v_cvt_pk_bf16_f32 v126, v120, v121
	v_cvt_pk_bf16_f32 v127, v122, v123
	v_lshl_add_u64 v[142:143], v[142:143], 0, s[10:11]
	ds_write_b128 v146, v[124:127]
	v_cvt_pk_bf16_f32 v112, v112, v113
	v_cvt_pk_bf16_f32 v113, v114, v115
	v_cvt_pk_bf16_f32 v114, v104, v105
	v_cvt_pk_bf16_f32 v115, v106, v107
	v_lshl_add_u64 v[142:143], v[142:143], 0, v[136:137]
	ds_write_b128 v146, v[112:115] offset:64
	ds_read_b128 v[104:107], v147
	ds_read_b128 v[112:115], v147 offset:1152
	v_cvt_pk_bf16_f32 v116, v116, v117
	v_cvt_pk_bf16_f32 v117, v118, v119
	v_cvt_pk_bf16_f32 v118, v108, v109
	v_cvt_pk_bf16_f32 v119, v110, v111
	s_movk_i32 s21, 0x4000
	ds_write_b128 v146, v[116:119]
	v_cvt_pk_bf16_f32 v100, v100, v101
	v_cvt_pk_bf16_f32 v101, v102, v103
	v_cvt_pk_bf16_f32 v102, v92, v93
	v_cvt_pk_bf16_f32 v103, v94, v95
	s_nop 0
	ds_write_b128 v146, v[100:103] offset:64
	ds_read_b128 v[92:95], v147
	ds_read_b128 v[100:103], v147 offset:1152
	s_waitcnt lgkmcnt(4)
	global_store_dwordx4 v[142:143], v[104:107], off nt
	s_nop 1
	v_add_co_u32_e32 v104, vcc, s21, v142
	s_mov_b32 s21, 0x8000
	s_nop 0
	v_addc_co_u32_e32 v105, vcc, 0, v143, vcc
	global_store_dwordx4 v[104:105], v[112:115], off nt
	v_cvt_pk_bf16_f32 v96, v96, v97
	v_cvt_pk_bf16_f32 v97, v98, v99
	v_cvt_pk_bf16_f32 v98, v88, v89
	v_add_co_u32_e32 v88, vcc, s21, v142
	v_cvt_pk_bf16_f32 v99, v90, v91
	s_mov_b32 s21, 0x10000
	ds_write_b128 v146, v[96:99]
	v_cvt_pk_bf16_f32 v84, v84, v85
	v_cvt_pk_bf16_f32 v85, v86, v87
	v_cvt_pk_bf16_f32 v86, v76, v77
	v_cvt_pk_bf16_f32 v87, v78, v79
	s_nop 0
	v_addc_co_u32_e32 v89, vcc, 0, v143, vcc
	ds_write_b128 v146, v[84:87] offset:64
	ds_read_b128 v[76:79], v147
	ds_read_b128 v[84:87], v147 offset:1152
	s_waitcnt lgkmcnt(4)
	global_store_dwordx4 v[88:89], v[92:95], off nt
	v_add_co_u32_e32 v88, vcc, s81, v142
	s_nop 1
	v_addc_co_u32_e32 v89, vcc, 0, v143, vcc
	global_store_dwordx4 v[88:89], v[100:103], off nt
	v_cvt_pk_bf16_f32 v80, v80, v81
	v_cvt_pk_bf16_f32 v81, v82, v83
	v_cvt_pk_bf16_f32 v82, v72, v73
	v_add_co_u32_e32 v72, vcc, s21, v142
	v_cvt_pk_bf16_f32 v83, v74, v75
	s_mov_b32 s21, 0x14000
	ds_write_b128 v146, v[80:83]
	v_cvt_pk_bf16_f32 v68, v68, v69
	v_cvt_pk_bf16_f32 v69, v70, v71
	v_cvt_pk_bf16_f32 v70, v64, v65
	v_cvt_pk_bf16_f32 v71, v66, v67
	s_nop 0
	v_addc_co_u32_e32 v73, vcc, 0, v143, vcc
	ds_write_b128 v146, v[68:71] offset:64
	ds_read_b128 v[64:67], v147
	ds_read_b128 v[68:71], v147 offset:1152
	s_waitcnt lgkmcnt(4)
	global_store_dwordx4 v[72:73], v[76:79], off nt
	v_add_co_u32_e32 v72, vcc, s21, v142
	s_mov_b32 s21, 0x18000
	s_nop 0
	v_addc_co_u32_e32 v73, vcc, 0, v143, vcc
	global_store_dwordx4 v[72:73], v[84:87], off nt
	v_cvt_pk_bf16_f32 v60, v60, v61
	v_cvt_pk_bf16_f32 v61, v62, v63
	v_cvt_pk_bf16_f32 v62, v56, v57
	v_add_co_u32_e32 v56, vcc, s21, v142
	v_cvt_pk_bf16_f32 v63, v58, v59
	s_nop 0
	ds_write_b128 v146, v[60:63]
	v_cvt_pk_bf16_f32 v52, v52, v53
	v_cvt_pk_bf16_f32 v53, v54, v55
	v_cvt_pk_bf16_f32 v54, v44, v45
	v_cvt_pk_bf16_f32 v55, v46, v47
	s_nop 0
	v_addc_co_u32_e32 v57, vcc, 0, v143, vcc
	ds_write_b128 v146, v[52:55] offset:64
	ds_read_b128 v[44:47], v147
	ds_read_b128 v[52:55], v147 offset:1152
	s_waitcnt lgkmcnt(4)
	global_store_dwordx4 v[56:57], v[64:67], off nt
	v_add_co_u32_e32 v56, vcc, s75, v142
	s_nop 1
	v_addc_co_u32_e32 v57, vcc, 0, v143, vcc
	global_store_dwordx4 v[56:57], v[68:71], off nt
	v_cvt_pk_bf16_f32 v48, v48, v49
	v_cvt_pk_bf16_f32 v49, v50, v51
	v_cvt_pk_bf16_f32 v50, v40, v41
	v_add_co_u32_e32 v40, vcc, s82, v142
	v_cvt_pk_bf16_f32 v51, v42, v43
	s_nop 0
	ds_write_b128 v146, v[48:51]
	v_cvt_pk_bf16_f32 v36, v36, v37
	v_cvt_pk_bf16_f32 v37, v38, v39
	v_cvt_pk_bf16_f32 v38, v28, v29
	v_cvt_pk_bf16_f32 v39, v30, v31
	s_nop 0
	v_addc_co_u32_e32 v41, vcc, 0, v143, vcc
	ds_write_b128 v146, v[36:39] offset:64
	ds_read_b128 v[28:31], v147
	ds_read_b128 v[36:39], v147 offset:1152
	s_waitcnt lgkmcnt(4)
	global_store_dwordx4 v[40:41], v[44:47], off nt
	v_add_co_u32_e32 v40, vcc, s83, v142
	s_nop 1
	v_addc_co_u32_e32 v41, vcc, 0, v143, vcc
	global_store_dwordx4 v[40:41], v[52:55], off nt
	v_cvt_pk_bf16_f32 v32, v32, v33
	v_cvt_pk_bf16_f32 v33, v34, v35
	v_cvt_pk_bf16_f32 v34, v24, v25
	v_add_co_u32_e32 v24, vcc, s84, v142
	v_cvt_pk_bf16_f32 v35, v26, v27
	s_nop 0
	ds_write_b128 v146, v[32:35]
	v_cvt_pk_bf16_f32 v20, v20, v21
	v_cvt_pk_bf16_f32 v21, v22, v23
	v_cvt_pk_bf16_f32 v22, v12, v13
	v_cvt_pk_bf16_f32 v23, v14, v15
	s_nop 0
	v_addc_co_u32_e32 v25, vcc, 0, v143, vcc
	ds_write_b128 v146, v[20:23] offset:64
	ds_read_b128 v[12:15], v147
	ds_read_b128 v[20:23], v147 offset:1152
	s_waitcnt lgkmcnt(4)
	global_store_dwordx4 v[24:25], v[28:31], off nt
	v_add_co_u32_e32 v24, vcc, s85, v142
	s_nop 1
	v_addc_co_u32_e32 v25, vcc, 0, v143, vcc
	global_store_dwordx4 v[24:25], v[36:39], off nt
	v_cvt_pk_bf16_f32 v16, v16, v17
	v_cvt_pk_bf16_f32 v17, v18, v19
	v_cvt_pk_bf16_f32 v18, v8, v9
	v_add_co_u32_e32 v8, vcc, s86, v142
	v_cvt_pk_bf16_f32 v19, v10, v11
	s_nop 0
	ds_write_b128 v146, v[16:19]
	v_cvt_pk_bf16_f32 v4, v4, v5
	v_cvt_pk_bf16_f32 v5, v6, v7
	v_cvt_pk_bf16_f32 v6, v0, v1
	v_cvt_pk_bf16_f32 v7, v2, v3
	s_nop 0
	v_addc_co_u32_e32 v9, vcc, 0, v143, vcc
	ds_write_b128 v146, v[4:7] offset:64
	ds_read_b128 v[0:3], v147
	ds_read_b128 v[4:7], v147 offset:1152
	s_waitcnt lgkmcnt(4)
	global_store_dwordx4 v[8:9], v[12:15], off nt
	v_add_co_u32_e32 v8, vcc, s87, v142
	s_nop 1
	v_addc_co_u32_e32 v9, vcc, 0, v143, vcc
	global_store_dwordx4 v[8:9], v[20:23], off nt
	v_add_co_u32_e32 v8, vcc, 0x58000, v142
	s_waitcnt lgkmcnt(0)
	s_nop 1
	v_addc_co_u32_e32 v9, vcc, 0, v143, vcc
	global_store_dwordx4 v[8:9], v[0:3], off nt
	s_nop 1
	v_add_co_u32_e32 v0, vcc, 0x5c000, v142
	s_nop 1
	v_addc_co_u32_e32 v1, vcc, 0, v143, vcc
	s_andn2_b64 vcc, exec, s[6:7]
	s_mov_b64 s[6:7], -1
	global_store_dwordx4 v[0:1], v[4:7], off nt
	s_cbranch_vccnz .LBB0_1004
	s_andn2_b64 vcc, exec, s[12:13]
	s_cbranch_vccnz .LBB0_1003
	s_barrier
	s_branch .LBB0_1003

; __device__ __forceinline__ unsigned cvt_pk_bf16(float lo, float hi) { unsigned r; asm volatile("v_cvt_pk_bf16_f32 %0, %1, %2" : "=v"(r) : "v"(lo), "v"(hi)); return r; }
; #define GAS1 __attribute__((address_space(1)))
;     __device__ __forceinline__ void operator()(const f32x4 (&acc)[2][2][4][2], const Unit& u, int wr, int wc, int fr, int fq) const {
;     ...
;                 u32x4 w; w.x = cvt_pk_bf16(v0[0], v0[1]); w.y = cvt_pk_bf16(v0[2], v0[3]); w.z = cvt_pk_bf16(v1[0], v1[1]); w.w = cvt_pk_bf16(v1[2], v1[3]);
;                 if (bj == 0) asm volatile("ds_write_b128 %0, %1" :: "v"(wa), "v"(w)); else asm volatile("ds_write_b128 %0, %1 offset:64" :: "v"(wa), "v"(w));
;             }
;             asm volatile("ds_read_b128 %0, %1" : "=&v"(rb[g & 1][0]) : "v"(ra));
;             asm volatile("ds_read_b128 %0, %1 offset:1152" : "=&v"(rb[g & 1][1]) : "v"(ra));
;             if (g >= 1) {
;                 asm volatile("s_waitcnt lgkmcnt(4)" : "+v"(rb[(g - 1) & 1][0]), "+v"(rb[(g - 1) & 1][1]));
;                 bf16_t* ob = obase + (size_t)(((g - 1) >> 2) * HALF + ((g - 1) & 3) * 16) * ldc;
;                 *(GAS1 u32x4*)ob = rb[(g - 1) & 1][0]; *(GAS1 u32x4*)(ob + (size_t)8 * ldc) = rb[(g - 1) & 1][1];
;             }
;         }
;         asm volatile("s_waitcnt lgkmcnt(0)" : "+v"(rb[1][0]), "+v"(rb[1][1]));
;         { bf16_t* ob = obase + (size_t)(HALF + 3 * 16) * ldc; *(GAS1 u32x4*)ob = rb[1][0]; *(GAS1 u32x4*)(ob + (size_t)8 * ldc) = rb[1][1]; }
.LBB0_1039:
	v_lshl_add_u32 v142, s24, 8, v145
	v_ashrrev_i32_e32 v143, 31, v142
	v_lshlrev_b64 v[142:143], 16, v[142:143]
	s_lshl_b32 s26, s89, 8
	v_lshl_add_u64 v[142:143], s[8:9], 0, v[142:143]
	s_ashr_i32 s27, s26, 31
	v_lshl_add_u64 v[142:143], s[26:27], 1, v[142:143]
	v_cvt_pk_bf16_f32 v124, v124, v125
	v_cvt_pk_bf16_f32 v125, v126, v127
	v_cvt_pk_bf16_f32 v126, v120, v121
	v_cvt_pk_bf16_f32 v127, v122, v123
	v_lshl_add_u64 v[142:143], v[142:143], 0, s[6:7]
	ds_write_b128 v146, v[124:127]
	v_cvt_pk_bf16_f32 v112, v112, v113
	v_cvt_pk_bf16_f32 v113, v114, v115
	v_cvt_pk_bf16_f32 v114, v104, v105
	v_cvt_pk_bf16_f32 v115, v106, v107
	v_lshl_add_u64 v[142:143], v[142:143], 0, v[136:137]
	ds_write_b128 v146, v[112:115] offset:64
	ds_read_b128 v[104:107], v147
	ds_read_b128 v[112:115], v147 offset:1152
	v_cvt_pk_bf16_f32 v116, v116, v117
	v_cvt_pk_bf16_f32 v117, v118, v119
	v_cvt_pk_bf16_f32 v118, v108, v109
	v_cvt_pk_bf16_f32 v119, v110, v111
	s_mov_b32 s17, 0x80000
	ds_write_b128 v146, v[116:119]
	v_cvt_pk_bf16_f32 v100, v100, v101
	v_cvt_pk_bf16_f32 v101, v102, v103
	v_cvt_pk_bf16_f32 v102, v92, v93
	v_cvt_pk_bf16_f32 v103, v94, v95
	s_nop 0
	ds_write_b128 v146, v[100:103] offset:64
	ds_read_b128 v[92:95], v147
	ds_read_b128 v[100:103], v147 offset:1152
	s_waitcnt lgkmcnt(4)
	global_store_dwordx4 v[142:143], v[104:107], off nt
	s_nop 1
	v_add_co_u32_e32 v104, vcc, s17, v142
	s_nop 1
	v_addc_co_u32_e32 v105, vcc, 0, v143, vcc
	global_store_dwordx4 v[104:105], v[112:115], off nt
	v_cvt_pk_bf16_f32 v96, v96, v97
	v_cvt_pk_bf16_f32 v97, v98, v99
	v_cvt_pk_bf16_f32 v98, v88, v89
	v_add_co_u32_e32 v88, vcc, s75, v142
	v_cvt_pk_bf16_f32 v99, v90, v91
	s_nop 0
	ds_write_b128 v146, v[96:99]
	v_cvt_pk_bf16_f32 v84, v84, v85
	v_cvt_pk_bf16_f32 v85, v86, v87
	v_cvt_pk_bf16_f32 v86, v76, v77
	v_cvt_pk_bf16_f32 v87, v78, v79
	s_nop 0
	v_addc_co_u32_e32 v89, vcc, 0, v143, vcc
	ds_write_b128 v146, v[84:87] offset:64
	ds_read_b128 v[76:79], v147
	ds_read_b128 v[84:87], v147 offset:1152
	s_waitcnt lgkmcnt(4)
	global_store_dwordx4 v[88:89], v[92:95], off nt
	v_add_co_u32_e32 v88, vcc, s76, v142
	s_nop 1
	v_addc_co_u32_e32 v89, vcc, 0, v143, vcc
	global_store_dwordx4 v[88:89], v[100:103], off nt
	v_cvt_pk_bf16_f32 v80, v80, v81
	v_cvt_pk_bf16_f32 v81, v82, v83
	v_cvt_pk_bf16_f32 v82, v72, v73
	v_add_co_u32_e32 v72, vcc, s77, v142
	v_cvt_pk_bf16_f32 v83, v74, v75
	s_nop 0
	ds_write_b128 v146, v[80:83]
	v_cvt_pk_bf16_f32 v68, v68, v69
	v_cvt_pk_bf16_f32 v69, v70, v71
	v_cvt_pk_bf16_f32 v70, v64, v65
	v_cvt_pk_bf16_f32 v71, v66, v67
	s_nop 0
	v_addc_co_u32_e32 v73, vcc, 0, v143, vcc
	ds_write_b128 v146, v[68:71] offset:64
	ds_read_b128 v[64:67], v147
	ds_read_b128 v[68:71], v147 offset:1152
	s_waitcnt lgkmcnt(4)
	global_store_dwordx4 v[72:73], v[76:79], off nt
	v_add_co_u32_e32 v72, vcc, s79, v142
	s_nop 1
	v_addc_co_u32_e32 v73, vcc, 0, v143, vcc
	global_store_dwordx4 v[72:73], v[84:87], off nt
	v_cvt_pk_bf16_f32 v60, v60, v61
	v_cvt_pk_bf16_f32 v61, v62, v63
	v_cvt_pk_bf16_f32 v62, v56, v57
	v_add_co_u32_e32 v56, vcc, s80, v142
	v_cvt_pk_bf16_f32 v63, v58, v59
	s_nop 0
	ds_write_b128 v146, v[60:63]
	v_cvt_pk_bf16_f32 v52, v52, v53
	v_cvt_pk_bf16_f32 v53, v54, v55
	v_cvt_pk_bf16_f32 v54, v44, v45
	v_cvt_pk_bf16_f32 v55, v46, v47
	s_nop 0
	v_addc_co_u32_e32 v57, vcc, 0, v143, vcc
	ds_write_b128 v146, v[52:55] offset:64
	ds_read_b128 v[44:47], v147
	ds_read_b128 v[52:55], v147 offset:1152
	s_waitcnt lgkmcnt(4)
	global_store_dwordx4 v[56:57], v[64:67], off nt
	v_add_co_u32_e32 v56, vcc, s81, v142
	s_nop 1
	v_addc_co_u32_e32 v57, vcc, 0, v143, vcc
	global_store_dwordx4 v[56:57], v[68:71], off nt
	v_cvt_pk_bf16_f32 v48, v48, v49
	v_cvt_pk_bf16_f32 v49, v50, v51
	v_cvt_pk_bf16_f32 v50, v40, v41
	v_add_co_u32_e32 v40, vcc, s82, v142
	v_cvt_pk_bf16_f32 v51, v42, v43
	s_nop 0
	ds_write_b128 v146, v[48:51]
	v_cvt_pk_bf16_f32 v36, v36, v37
	v_cvt_pk_bf16_f32 v37, v38, v39
	v_cvt_pk_bf16_f32 v38, v28, v29
	v_cvt_pk_bf16_f32 v39, v30, v31
	s_nop 0
	v_addc_co_u32_e32 v41, vcc, 0, v143, vcc
	ds_write_b128 v146, v[36:39] offset:64
	ds_read_b128 v[28:31], v147
	ds_read_b128 v[36:39], v147 offset:1152
	s_waitcnt lgkmcnt(4)
	global_store_dwordx4 v[40:41], v[44:47], off nt
	v_add_co_u32_e32 v40, vcc, s83, v142
	s_nop 1
	v_addc_co_u32_e32 v41, vcc, 0, v143, vcc
	global_store_dwordx4 v[40:41], v[52:55], off nt
	v_cvt_pk_bf16_f32 v32, v32, v33
	v_cvt_pk_bf16_f32 v33, v34, v35
	v_cvt_pk_bf16_f32 v34, v24, v25
	v_add_co_u32_e32 v24, vcc, s84, v142
	v_cvt_pk_bf16_f32 v35, v26, v27
	s_nop 0
	ds_write_b128 v146, v[32:35]
	v_cvt_pk_bf16_f32 v20, v20, v21
	v_cvt_pk_bf16_f32 v21, v22, v23
	v_cvt_pk_bf16_f32 v22, v12, v13
	v_cvt_pk_bf16_f32 v23, v14, v15
	s_nop 0
	v_addc_co_u32_e32 v25, vcc, 0, v143, vcc
	ds_write_b128 v146, v[20:23] offset:64
	ds_read_b128 v[12:15], v147
	ds_read_b128 v[20:23], v147 offset:1152
	s_waitcnt lgkmcnt(4)
	global_store_dwordx4 v[24:25], v[28:31], off nt
	v_add_co_u32_e32 v24, vcc, s85, v142
	s_nop 1
	v_addc_co_u32_e32 v25, vcc, 0, v143, vcc
	global_store_dwordx4 v[24:25], v[36:39], off nt
	v_cvt_pk_bf16_f32 v16, v16, v17
	v_cvt_pk_bf16_f32 v17, v18, v19
	v_cvt_pk_bf16_f32 v18, v8, v9
	v_add_co_u32_e32 v8, vcc, s86, v142
	v_cvt_pk_bf16_f32 v19, v10, v11
	s_nop 0
	ds_write_b128 v146, v[16:19]
	v_cvt_pk_bf16_f32 v4, v4, v5
	v_cvt_pk_bf16_f32 v5, v6, v7
	v_cvt_pk_bf16_f32 v6, v0, v1
	v_cvt_pk_bf16_f32 v7, v2, v3
	s_nop 0
	v_addc_co_u32_e32 v9, vcc, 0, v143, vcc
	ds_write_b128 v146, v[4:7] offset:64
	ds_read_b128 v[0:3], v147
	ds_read_b128 v[4:7], v147 offset:1152
	s_waitcnt lgkmcnt(4)
	global_store_dwordx4 v[8:9], v[12:15], off nt
	v_add_co_u32_e32 v8, vcc, s87, v142
	s_nop 1
	v_addc_co_u32_e32 v9, vcc, 0, v143, vcc
	global_store_dwordx4 v[8:9], v[20:23], off nt
	v_add_co_u32_e32 v8, vcc, 0xb00000, v142
	s_waitcnt lgkmcnt(0)
	s_nop 1
	v_addc_co_u32_e32 v9, vcc, 0, v143, vcc
	global_store_dwordx4 v[8:9], v[0:3], off nt
	s_nop 1
	v_add_co_u32_e32 v0, vcc, 0xb80000, v142
	s_nop 1
	v_addc_co_u32_e32 v1, vcc, 0, v143, vcc
	s_andn2_b64 vcc, exec, s[4:5]
	s_mov_b64 s[4:5], -1
	global_store_dwordx4 v[0:1], v[4:7], off nt
	s_cbranch_vccnz .LBB0_1028
	s_andn2_b64 vcc, exec, s[10:11]
	s_cbranch_vccnz .LBB0_1027
	s_barrier
	s_branch .LBB0_1027

; #define LAS __attribute__((address_space(3)))
; template <bool MLA, bool grpB>
; __device__ __forceinline__ void attn_unit_g(LAS unsigned char* lds, const AttnPtrs& P, int b, int h, int qblk) {
;     ...
;         const LAS unsigned char* ka = lds + koff + karow;
;         bf16x8 a[PFD];
;         auto ld = [&](int i) -> bf16x8 {
;             const int d0 = i >> 1, blk = i & 1, seg = 2 * d0;
;             int so;
;             if (MLA) so = (((seg + hi) & 24) | (((seg + hi) ^ kswz) & 7)) * 16; else so = ((seg + hi) ^ kswz) * 16;
;             return *(const LAS bf16x8*)(ka + blk * 32 * KROW + so);
;         };
; #pragma unroll
;         for (int i = 0; i < PFD; ++i) a[i] = ld(i);
; #pragma unroll
;         for (int i = 0; i < 2 * ND0; ++i) {
;             const f32x16 zc = {0.f, 0.f, 0.f, 0.f, 0.f, 0.f, 0.f, 0.f, 0.f, 0.f, 0.f, 0.f, 0.f, 0.f, 0.f, 0.f};
;             sc[i & 1] = __builtin_amdgcn_mfma_f32_32x32x16_bf16(a[i % PFD], qf[i >> 1], (MLA && i < 2) ? zc : sc[i & 1], 0, 0, 0);
;             if (i + PFD < 2 * ND0) a[i % PFD] = ld(i + PFD);
;         }
;         __builtin_amdgcn_sched_group_barrier(0x100, PFD, 0);
; #pragma unroll
;         for (int i = 0; i < 2 * ND0; ++i) { __builtin_amdgcn_sched_group_barrier(0x008, 1, 0); __builtin_amdgcn_sched_group_barrier(0x100, 1, 0); }
;     ...
;     int k0 = 0, knext = KSLOT, k2 = 2 * KSLOT, k3 = 3 * KSLOT, vcur = 0, v1 = VTILE, v2 = 2 * VTILE;
;     const int jl = ntile - 1;
;     dma_k(jl, 0); dma_v(jl, 0); dma_k(jl - 1, KSLOT);
;     dma_k(jl - 2, 2 * KSLOT); dma_v(jl - 1, VTILE);
;     if (MLA) asm volatile("s_waitcnt vmcnt(5)\n\ts_barrier" ::: "memory"); else asm volatile("s_waitcnt vmcnt(4)\n\ts_barrier" ::: "memory");
;     if (grpB) qk(0);
.LBB0_1140:
	v_and_b32_e32 v2, 3, v4
	v_lshrrev_b32_e32 v39, 1, v4
	v_lshlrev_b32_e32 v0, 2, v34
	v_and_or_b32 v2, v39, 12, v2
	s_lshl_b64 s[12:13], s[36:37], 7
	v_and_or_b32 v0, v0, 16, v2
	v_bfe_u32 v5, v2, 1, 2
	v_and_b32_e32 v48, 4, v4
	v_lshl_add_u64 v[2:3], v[154:155], 0, s[12:13]
	s_add_i32 m0, s63, 0x1c400
	v_mad_u32_u24 v161, v0, s69, 0
	global_load_lds_dwordx4 v[2:3], off
	v_lshl_add_u64 v[2:3], v[156:157], 0, s[12:13]
	s_add_i32 m0, s63, 0x1e400
	v_bitop3_b32 v0, v5, v159, v48 bitop3:0x36
	global_load_lds_dwordx4 v[2:3], off
	v_lshlrev_b32_e32 v162, 4, v0
	s_waitcnt vmcnt(5)
	s_barrier
	v_add_u32_e32 v0, v161, v162
	ds_read_b128 v[10:13], v0
	ds_read_b128 v[6:9], v0 offset:12288
	v_or_b32_e32 v2, 2, v159
	v_or_b32_e32 v3, 4, v159
	v_bitop3_b32 v2, v5, v2, v48 bitop3:0x36
	v_bitop3_b32 v3, v5, v3, v48 bitop3:0x36
	v_lshlrev_b32_e32 v163, 4, v2
	v_lshlrev_b32_e32 v164, 4, v3
	v_add_u32_e32 v2, v161, v163
	v_add_u32_e32 v3, v161, v164
	ds_read_b128 v[14:17], v2
	ds_read_b128 v[40:43], v2 offset:12288
	ds_read_b128 v[44:47], v3
	ds_read_b128 v[66:69], v3 offset:12288
	s_waitcnt vmcnt(0) lgkmcnt(0)
	v_mfma_f32_32x32x16_bf16 v[18:33], v[10:13], v[98:101], 0
	v_or_b32_e32 v10, 6, v159
	v_bitop3_b32 v5, v5, v10, v48 bitop3:0x36
	v_lshlrev_b32_e32 v165, 4, v5
	v_add_u32_e32 v5, v161, v165
	ds_read_b128 v[10:13], v5
	s_mov_b32 s12, 0
	s_mov_b32 s13, s12
	v_mfma_f32_32x32x16_bf16 v[50:65], v[6:9], v[98:101], 0
	ds_read_b128 v[6:9], v5 offset:12288
	s_ashr_i32 s40, s16, 6
	v_bfe_u32 v48, v4, 1, 3
	s_mov_b32 s14, s12
	s_mov_b32 s15, s12
	s_mov_b32 s16, s12
	s_mov_b32 s17, s12
	v_mfma_f32_32x32x16_bf16 v[18:33], v[14:17], v[102:105], v[18:33]
	ds_read_b128 v[14:17], v0 offset:128
	s_mov_b32 s18, s12
	s_mov_b32 s19, s12
	s_mov_b32 s20, s12
	s_mov_b32 s21, s12
	s_mov_b32 s22, s12
	s_mov_b32 s23, s12
	v_mfma_f32_32x32x16_bf16 v[50:65], v[40:43], v[102:105], v[50:65]
	ds_read_b128 v[40:43], v0 offset:12416
	s_mov_b32 s24, s12
	s_mov_b32 s25, s12
	s_mov_b32 s26, s12
	s_mov_b32 s27, s12
	s_setprio 1
	v_mfma_f32_32x32x16_bf16 v[18:33], v[44:47], v[106:109], v[18:33]
	ds_read_b128 v[44:47], v2 offset:128
	v_mfma_f32_32x32x16_bf16 v[50:65], v[66:69], v[106:109], v[50:65]
	ds_read_b128 v[66:69], v2 offset:12416
	s_waitcnt lgkmcnt(5)
	v_mfma_f32_32x32x16_bf16 v[18:33], v[10:13], v[110:113], v[18:33]
	ds_read_b128 v[10:13], v3 offset:128
	s_waitcnt lgkmcnt(5)
	v_mfma_f32_32x32x16_bf16 v[50:65], v[6:9], v[110:113], v[50:65]
	ds_read_b128 v[6:9], v3 offset:12416
	s_waitcnt lgkmcnt(5)
	v_mfma_f32_32x32x16_bf16 v[18:33], v[14:17], v[114:117], v[18:33]
	ds_read_b128 v[14:17], v5 offset:128
	s_waitcnt lgkmcnt(5)
	v_mfma_f32_32x32x16_bf16 v[50:65], v[40:43], v[114:117], v[50:65]
	ds_read_b128 v[40:43], v5 offset:12416
	s_waitcnt lgkmcnt(5)
	v_mfma_f32_32x32x16_bf16 v[18:33], v[44:47], v[118:121], v[18:33]
	ds_read_b128 v[44:47], v0 offset:256
	s_waitcnt lgkmcnt(5)
	v_mfma_f32_32x32x16_bf16 v[50:65], v[66:69], v[118:121], v[50:65]
	ds_read_b128 v[66:69], v0 offset:12544
	s_waitcnt lgkmcnt(5)
	v_mfma_f32_32x32x16_bf16 v[18:33], v[10:13], v[122:125], v[18:33]
	ds_read_b128 v[10:13], v2 offset:256
	s_waitcnt lgkmcnt(5)
	v_mfma_f32_32x32x16_bf16 v[50:65], v[6:9], v[122:125], v[50:65]
	ds_read_b128 v[6:9], v2 offset:12544
	s_waitcnt lgkmcnt(5)
	v_mfma_f32_32x32x16_bf16 v[18:33], v[14:17], v[126:129], v[18:33]
	ds_read_b128 v[14:17], v3 offset:256
	s_waitcnt lgkmcnt(5)
	v_mfma_f32_32x32x16_bf16 v[50:65], v[40:43], v[126:129], v[50:65]
	ds_read_b128 v[40:43], v3 offset:12544
	s_waitcnt lgkmcnt(5)
	v_mfma_f32_32x32x16_bf16 v[18:33], v[44:47], v[130:133], v[18:33]
	ds_read_b128 v[44:47], v5 offset:256
	s_waitcnt lgkmcnt(5)
	v_mfma_f32_32x32x16_bf16 v[50:65], v[66:69], v[130:133], v[50:65]
	ds_read_b128 v[66:69], v5 offset:12544
	s_waitcnt lgkmcnt(5)
	v_mfma_f32_32x32x16_bf16 v[18:33], v[10:13], v[134:137], v[18:33]
	s_waitcnt lgkmcnt(4)
	v_mfma_f32_32x32x16_bf16 v[50:65], v[6:9], v[134:137], v[50:65]
	s_waitcnt lgkmcnt(3)
	v_mfma_f32_32x32x16_bf16 v[18:33], v[14:17], v[138:141], v[18:33]
	s_setprio 0
	v_mov_b64_e32 v[2:3], s[12:13]
	v_mov_b64_e32 v[4:5], s[14:15]
	v_mov_b64_e32 v[6:7], s[16:17]
	v_mov_b64_e32 v[8:9], s[18:19]
	v_mov_b64_e32 v[10:11], s[20:21]
	v_mov_b64_e32 v[12:13], s[22:23]
	v_mov_b64_e32 v[14:15], s[24:25]
	s_waitcnt lgkmcnt(2)
	v_mfma_f32_32x32x16_bf16 v[50:65], v[40:43], v[138:141], v[50:65]
	v_mov_b64_e32 v[16:17], s[26:27]
	s_waitcnt lgkmcnt(1)
	v_mfma_f32_32x32x16_bf16 v[18:33], v[44:47], v[142:145], v[18:33]
	s_waitcnt lgkmcnt(0)
	v_mfma_f32_32x32x16_bf16 v[50:65], v[66:69], v[142:145], v[50:65]
	v_lshl_add_u32 v34, v34, 7, 0
	v_add_u32_e32 v167, 0x18400, v34
	v_lshlrev_b32_e32 v34, 1, v159
	v_cmp_eq_u32_e32 vcc, 0, v35
	v_bitop3_b32 v35, v34, v39, 7 bitop3:0x78
	v_lshlrev_b32_e32 v168, 4, v35
	v_bitop3_b32 v35, v34, v48, 1 bitop3:0x36
	v_cndmask_b32_e64 v0, 13, 17, vcc
	v_cmp_eq_u32_e32 vcc, 0, v36
	v_lshlrev_b32_e32 v169, 4, v35
	v_bitop3_b32 v35, v34, v48, 4 bitop3:0x36
	v_bitop3_b32 v34, v34, v48, 5 bitop3:0x36
	v_cndmask_b32_e64 v158, 13, 17, vcc
	s_lshl_b32 s14, s41, 10
	v_cmp_eq_u32_e32 vcc, 0, v38
	v_add_u32_e32 v166, 0, v37
	v_lshlrev_b32_e32 v175, 4, v35
	v_lshlrev_b32_e32 v177, 4, v34
	v_mov_b64_e32 v[48:49], v[16:17]
	v_mov_b64_e32 v[80:81], v[16:17]
	v_mov_b64_e32 v[96:97], v[16:17]
	s_add_i32 s13, s40, 1
	s_add_i32 s18, s14, 0
	v_cndmask_b32_e64 v160, 13, 17, vcc
	v_mov_b32_e32 v178, 0xf149f2ca
	s_movk_i32 s19, 0x6100
	s_mov_b32 s20, 0xc200
	s_mov_b32 s15, 0x12300
	s_movk_i32 s21, 0x4000
	s_mov_b32 s14, 0x8000
	v_mov_b32_e32 v176, 0
	s_mov_b32 s36, s71
	v_mov_b64_e32 v[46:47], v[14:15]
	v_mov_b64_e32 v[44:45], v[12:13]
	v_mov_b64_e32 v[42:43], v[10:11]
	v_mov_b64_e32 v[40:41], v[8:9]
	v_mov_b64_e32 v[38:39], v[6:7]
	v_mov_b64_e32 v[36:37], v[4:5]
	v_mov_b64_e32 v[34:35], v[2:3]
	v_mov_b64_e32 v[78:79], v[14:15]
	v_mov_b64_e32 v[76:77], v[12:13]
	v_mov_b64_e32 v[74:75], v[10:11]
	v_mov_b64_e32 v[72:73], v[8:9]
	v_mov_b64_e32 v[70:71], v[6:7]
	v_mov_b64_e32 v[68:69], v[4:5]
	v_mov_b64_e32 v[66:67], v[2:3]
	v_mov_b64_e32 v[94:95], v[14:15]
	v_mov_b64_e32 v[92:93], v[12:13]
	v_mov_b64_e32 v[90:91], v[10:11]
	v_mov_b64_e32 v[88:89], v[8:9]
	v_mov_b64_e32 v[86:87], v[6:7]
	v_mov_b64_e32 v[84:85], v[4:5]
	v_mov_b64_e32 v[82:83], v[2:3]

; __device__ __forceinline__ unsigned cvt_pk_bf16(float lo, float hi) { unsigned r; asm volatile("v_cvt_pk_bf16_f32 %0, %1, %2" : "=v"(r) : "v"(lo), "v"(hi)); return r; }
; #define LAS __attribute__((address_space(3)))
; template <bool MLA, bool grpB>
; __device__ __forceinline__ void attn_unit_g(LAS unsigned char* lds, const AttnPtrs& P, int b, int h, int qblk) {
;     ...
;         float ps = 0.f;
; #pragma unroll
;         for (int blk = 0; blk < 2; ++blk)
; #pragma unroll
;             for (int r = 0; r < 16; ++r) { const float pv_ = __builtin_amdgcn_exp2f(sc[blk][r] - mref); sc[blk][r] = pv_; ps += pv_; }
;         lrun += ps;
; #pragma unroll
;         for (int blk = 0; blk < 2; ++blk)
; #pragma unroll
;             for (int ks = 0; ks < 2; ++ks) { u32x4 w;
;                 w.x = pg8::cvt_pk_bf16(sc[blk][8 * ks + 0], sc[blk][8 * ks + 1]); w.y = pg8::cvt_pk_bf16(sc[blk][8 * ks + 2], sc[blk][8 * ks + 3]);
;                 w.z = pg8::cvt_pk_bf16(sc[blk][8 * ks + 4], sc[blk][8 * ks + 5]); w.w = pg8::cvt_pk_bf16(sc[blk][8 * ks + 6], sc[blk][8 * ks + 7]);
;                 pb[blk][ks] = __builtin_bit_cast(bf16x8, w); }
;         __builtin_amdgcn_sched_barrier(0);
;     };
;     auto pv = [&](int voff) {
;         const LAS unsigned char* va = lds + varow + voff;
;         bf16x8 a[PFD];
;         auto ld = [&](int i) -> bf16x8 {
;             const int dvb = i & 3, bk = i >> 2, so = ((4 * (bk >> 1) + 2 * hi + (bk & 1)) ^ vswz) * 16;
;             return *(const LAS bf16x8*)(va + 32 * dvb * VROW + so);
;         };
; #pragma unroll
;         for (int i = 0; i < PFD; ++i) a[i] = ld(i);
; #pragma unroll
;         for (int i = 0; i < 16; ++i) {
;             o[i & 3] = __builtin_amdgcn_mfma_f32_32x32x16_bf16(a[i % PFD], pb[i >> 3][(i >> 2) & 1], o[i & 3], 0, 0, 0);
;             if (i + PFD < 16) a[i % PFD] = ld(i + PFD);
;         }
;         __builtin_amdgcn_sched_group_barrier(0x100, PFD, 0);
; #pragma unroll
;         for (int i = 0; i < 16; ++i) { __builtin_amdgcn_sched_group_barrier(0x008, 1, 0); __builtin_amdgcn_sched_group_barrier(0x100, 1, 0); }
.LBB0_1151:
	v_sub_f32_e32 v18, v18, v178
	v_exp_f32_e32 v18, v18
	v_sub_f32_e32 v19, v19, v178
	v_exp_f32_e32 v19, v19
	v_sub_f32_e32 v20, v20, v178
	v_exp_f32_e32 v20, v20
	v_sub_f32_e32 v21, v21, v178
	v_exp_f32_e32 v21, v21
	v_sub_f32_e32 v22, v22, v178
	v_add_f32_e32 v179, 0, v18
	v_exp_f32_e32 v22, v22
	v_sub_f32_e32 v23, v23, v178
	v_add_f32_e32 v179, v19, v179
	v_exp_f32_e32 v23, v23
	v_sub_f32_e32 v24, v24, v178
	v_add_f32_e32 v179, v20, v179
	v_exp_f32_e32 v24, v24
	v_sub_f32_e32 v25, v25, v178
	v_add_f32_e32 v179, v21, v179
	v_exp_f32_e32 v25, v25
	v_sub_f32_e32 v26, v26, v178
	v_add_f32_e32 v179, v22, v179
	v_exp_f32_e32 v26, v26
	v_sub_f32_e32 v27, v27, v178
	v_add_f32_e32 v179, v23, v179
	v_exp_f32_e32 v27, v27
	v_sub_f32_e32 v28, v28, v178
	v_add_f32_e32 v179, v24, v179
	v_exp_f32_e32 v28, v28
	v_sub_f32_e32 v29, v29, v178
	v_add_f32_e32 v179, v25, v179
	v_exp_f32_e32 v29, v29
	v_sub_f32_e32 v30, v30, v178
	v_add_f32_e32 v179, v26, v179
	v_exp_f32_e32 v30, v30
	v_sub_f32_e32 v31, v31, v178
	v_add_f32_e32 v179, v27, v179
	v_exp_f32_e32 v31, v31
	v_sub_f32_e32 v32, v32, v178
	v_add_f32_e32 v179, v28, v179
	v_exp_f32_e32 v32, v32
	v_sub_f32_e32 v33, v33, v178
	v_add_f32_e32 v179, v29, v179
	v_exp_f32_e32 v33, v33
	v_sub_f32_e32 v50, v50, v178
	v_add_f32_e32 v179, v30, v179
	v_exp_f32_e32 v50, v50
	v_sub_f32_e32 v51, v51, v178
	v_add_f32_e32 v179, v31, v179
	v_exp_f32_e32 v51, v51
	v_sub_f32_e32 v52, v52, v178
	v_add_f32_e32 v179, v32, v179
	v_exp_f32_e32 v52, v52
	v_sub_f32_e32 v53, v53, v178
	v_add_f32_e32 v179, v33, v179
	v_exp_f32_e32 v53, v53
	v_sub_f32_e32 v54, v54, v178
	v_add_f32_e32 v179, v50, v179
	v_exp_f32_e32 v54, v54
	v_sub_f32_e32 v55, v55, v178
	v_add_f32_e32 v179, v51, v179
	v_exp_f32_e32 v55, v55
	v_sub_f32_e32 v56, v56, v178
	v_add_f32_e32 v179, v52, v179
	v_exp_f32_e32 v56, v56
	v_sub_f32_e32 v57, v57, v178
	v_add_f32_e32 v179, v53, v179
	v_exp_f32_e32 v57, v57
	v_sub_f32_e32 v58, v58, v178
	v_add_f32_e32 v179, v54, v179
	v_exp_f32_e32 v58, v58
	v_sub_f32_e32 v59, v59, v178
	v_add_f32_e32 v179, v55, v179
	v_exp_f32_e32 v59, v59
	v_sub_f32_e32 v60, v60, v178
	v_add_f32_e32 v179, v56, v179
	v_exp_f32_e32 v60, v60
	v_sub_f32_e32 v61, v61, v178
	v_add_f32_e32 v179, v57, v179
	v_exp_f32_e32 v61, v61
	v_sub_f32_e32 v62, v62, v178
	v_add_f32_e32 v179, v58, v179
	v_exp_f32_e32 v62, v62
	v_sub_f32_e32 v63, v63, v178
	v_add_f32_e32 v179, v59, v179
	v_exp_f32_e32 v63, v63
	v_sub_f32_e32 v64, v64, v178
	v_add_f32_e32 v179, v60, v179
	v_exp_f32_e32 v64, v64
	v_sub_f32_e32 v65, v65, v178
	v_add_f32_e32 v179, v61, v179
	v_exp_f32_e32 v65, v65
	v_add_f32_e32 v179, v62, v179
	v_add_f32_e32 v179, v63, v179
	v_add_f32_e32 v179, v64, v179
	v_add_f32_e32 v179, v65, v179
	v_add_f32_e32 v176, v176, v179
	v_cvt_pk_bf16_f32 v180, v18, v19
	v_cvt_pk_bf16_f32 v181, v20, v21
	v_cvt_pk_bf16_f32 v182, v22, v23
	v_cvt_pk_bf16_f32 v183, v24, v25
	v_cvt_pk_bf16_f32 v184, v26, v27
	v_cvt_pk_bf16_f32 v185, v28, v29
	v_cvt_pk_bf16_f32 v186, v30, v31
	v_cvt_pk_bf16_f32 v187, v32, v33
	v_cvt_pk_bf16_f32 v188, v50, v51
	v_cvt_pk_bf16_f32 v189, v52, v53
	v_cvt_pk_bf16_f32 v190, v54, v55
	v_cvt_pk_bf16_f32 v191, v56, v57
	v_cvt_pk_bf16_f32 v192, v58, v59
	v_cvt_pk_bf16_f32 v193, v60, v61
	v_cvt_pk_bf16_f32 v194, v62, v63
	v_cvt_pk_bf16_f32 v195, v64, v65
	v_add_u32_e32 v179, s12, v167
	v_add_u32_e32 v210, v179, v168
	ds_read_b128 v[196:199], v210
	ds_read_b128 v[202:205], v210 offset:4096
	ds_read_b128 v[206:209], v210 offset:8192
	ds_read_b128 v[210:213], v210 offset:12288
	v_add_u32_e32 v222, v179, v169
	ds_read_b128 v[214:217], v222
	ds_read_b128 v[218:221], v222 offset:4096
	s_waitcnt lgkmcnt(5)
	s_setprio 1
	v_mfma_f32_32x32x16_bf16 v[82:97], v[196:199], v[180:183], v[82:97]
	ds_read_b128 v[196:199], v222 offset:8192
	s_waitcnt lgkmcnt(5)
	v_mfma_f32_32x32x16_bf16 v[66:81], v[202:205], v[180:183], v[66:81]
	ds_read_b128 v[202:205], v222 offset:12288
	v_add_u32_e32 v222, v179, v175
	v_add_u32_e32 v179, v179, v177
	s_waitcnt lgkmcnt(5)
	v_mfma_f32_32x32x16_bf16 v[34:49], v[206:209], v[180:183], v[34:49]
	ds_read_b128 v[206:209], v222
	s_waitcnt lgkmcnt(5)
	v_mfma_f32_32x32x16_bf16 v[2:17], v[210:213], v[180:183], v[2:17]
	ds_read_b128 v[180:183], v222 offset:4096
	s_waitcnt lgkmcnt(5)
	v_mfma_f32_32x32x16_bf16 v[82:97], v[214:217], v[184:187], v[82:97]
	ds_read_b128 v[210:213], v222 offset:8192
	s_waitcnt lgkmcnt(5)
	v_mfma_f32_32x32x16_bf16 v[66:81], v[218:221], v[184:187], v[66:81]
	ds_read_b128 v[214:217], v222 offset:12288
	s_waitcnt lgkmcnt(5)
	v_mfma_f32_32x32x16_bf16 v[34:49], v[196:199], v[184:187], v[34:49]
	ds_read_b128 v[196:199], v179
	s_waitcnt lgkmcnt(5)
	v_mfma_f32_32x32x16_bf16 v[2:17], v[202:205], v[184:187], v[2:17]
	ds_read_b128 v[184:187], v179 offset:4096
	s_waitcnt lgkmcnt(5)
	v_mfma_f32_32x32x16_bf16 v[82:97], v[206:209], v[188:191], v[82:97]
	ds_read_b128 v[202:205], v179 offset:8192
	s_waitcnt lgkmcnt(5)
	v_mfma_f32_32x32x16_bf16 v[66:81], v[180:183], v[188:191], v[66:81]
	ds_read_b128 v[180:183], v179 offset:12288
	s_waitcnt lgkmcnt(5)
	v_mfma_f32_32x32x16_bf16 v[34:49], v[210:213], v[188:191], v[34:49]
	s_waitcnt lgkmcnt(4)
	v_mfma_f32_32x32x16_bf16 v[2:17], v[214:217], v[188:191], v[2:17]
	s_waitcnt lgkmcnt(3)
	v_mfma_f32_32x32x16_bf16 v[82:97], v[196:199], v[192:195], v[82:97]
	s_waitcnt lgkmcnt(2)
	v_mfma_f32_32x32x16_bf16 v[66:81], v[184:187], v[192:195], v[66:81]
	s_waitcnt lgkmcnt(1)
	v_mfma_f32_32x32x16_bf16 v[34:49], v[202:205], v[192:195], v[34:49]
	s_waitcnt lgkmcnt(0)
	v_mfma_f32_32x32x16_bf16 v[2:17], v[180:183], v[192:195], v[2:17]
	s_setprio 0
; #define LAS __attribute__((address_space(3)))
; template <bool MLA, bool grpB>
; __device__ __forceinline__ void attn_unit_g(LAS unsigned char* lds, const AttnPtrs& P, int b, int h, int qblk) {
;     ...
;         const LAS unsigned char* ka = lds + koff + karow;
;         bf16x8 a[PFD];
;         auto ld = [&](int i) -> bf16x8 {
;             const int d0 = i >> 1, blk = i & 1, seg = 2 * d0;
;             int so;
;             if (MLA) so = (((seg + hi) & 24) | (((seg + hi) ^ kswz) & 7)) * 16; else so = ((seg + hi) ^ kswz) * 16;
;             return *(const LAS bf16x8*)(ka + blk * 32 * KROW + so);
;         };
; #pragma unroll
;         for (int i = 0; i < PFD; ++i) a[i] = ld(i);
; #pragma unroll
;         for (int i = 0; i < 2 * ND0; ++i) {
;             const f32x16 zc = {0.f, 0.f, 0.f, 0.f, 0.f, 0.f, 0.f, 0.f, 0.f, 0.f, 0.f, 0.f, 0.f, 0.f, 0.f, 0.f};
;             sc[i & 1] = __builtin_amdgcn_mfma_f32_32x32x16_bf16(a[i % PFD], qf[i >> 1], (MLA && i < 2) ? zc : sc[i & 1], 0, 0, 0);
;             if (i + PFD < 2 * ND0) a[i % PFD] = ld(i + PFD);
;         }
;         __builtin_amdgcn_sched_group_barrier(0x100, PFD, 0);
; #pragma unroll
;         for (int i = 0; i < 2 * ND0; ++i) { __builtin_amdgcn_sched_group_barrier(0x008, 1, 0); __builtin_amdgcn_sched_group_barrier(0x100, 1, 0); }
.LBB0_1152:
	s_cmp_eq_u32 s36, -3
	s_cselect_b64 s[26:27], -1, 0
	s_cmp_gt_i32 s16, s13
	s_cselect_b64 s[16:17], -1, 0
	s_or_b64 s[16:17], s[26:27], s[16:17]
	s_and_b64 vcc, exec, s[16:17]
	s_cbranch_vccnz .LBB0_1156
	v_add_u32_e32 v54, s23, v161
	v_add_u32_e32 v179, v54, v162
	ds_read_b128 v[18:21], v179
	ds_read_b128 v[50:53], v179 offset:12288
	v_add_u32_e32 v206, v54, v163
	v_add_u32_e32 v207, v54, v164
	ds_read_b128 v[180:183], v206
	ds_read_b128 v[184:187], v206 offset:12288
	v_add_u32_e32 v208, v54, v165
	ds_read_b128 v[188:191], v207
	ds_read_b128 v[192:195], v207 offset:12288
	s_waitcnt lgkmcnt(5)
	s_setprio 1
	v_mfma_f32_32x32x16_bf16 v[18:33], v[18:21], v[98:101], 0
	ds_read_b128 v[196:199], v208
	s_waitcnt lgkmcnt(5)
	v_mfma_f32_32x32x16_bf16 v[50:65], v[50:53], v[98:101], 0
	ds_read_b128 v[202:205], v208 offset:12288
	s_waitcnt lgkmcnt(5)
	v_mfma_f32_32x32x16_bf16 v[18:33], v[180:183], v[102:105], v[18:33]
	ds_read_b128 v[180:183], v179 offset:128
	s_waitcnt lgkmcnt(5)
	v_mfma_f32_32x32x16_bf16 v[50:65], v[184:187], v[102:105], v[50:65]
	ds_read_b128 v[184:187], v179 offset:12416
	s_waitcnt lgkmcnt(5)
	v_mfma_f32_32x32x16_bf16 v[18:33], v[188:191], v[106:109], v[18:33]
	ds_read_b128 v[188:191], v206 offset:128
	s_waitcnt lgkmcnt(5)
	v_mfma_f32_32x32x16_bf16 v[50:65], v[192:195], v[106:109], v[50:65]
	ds_read_b128 v[192:195], v206 offset:12416
	s_waitcnt lgkmcnt(5)
	v_mfma_f32_32x32x16_bf16 v[18:33], v[196:199], v[110:113], v[18:33]
	ds_read_b128 v[196:199], v207 offset:128
	s_waitcnt lgkmcnt(5)
	v_mfma_f32_32x32x16_bf16 v[50:65], v[202:205], v[110:113], v[50:65]
	ds_read_b128 v[202:205], v207 offset:12416
	s_waitcnt lgkmcnt(5)
	v_mfma_f32_32x32x16_bf16 v[18:33], v[180:183], v[114:117], v[18:33]
	ds_read_b128 v[180:183], v208 offset:128
	s_waitcnt lgkmcnt(5)
	v_mfma_f32_32x32x16_bf16 v[50:65], v[184:187], v[114:117], v[50:65]
	ds_read_b128 v[184:187], v208 offset:12416
	s_waitcnt lgkmcnt(5)
	v_mfma_f32_32x32x16_bf16 v[18:33], v[188:191], v[118:121], v[18:33]
	ds_read_b128 v[188:191], v179 offset:256
	s_waitcnt lgkmcnt(5)
	v_mfma_f32_32x32x16_bf16 v[50:65], v[192:195], v[118:121], v[50:65]
	ds_read_b128 v[192:195], v179 offset:12544
	s_waitcnt lgkmcnt(5)
	v_mfma_f32_32x32x16_bf16 v[18:33], v[196:199], v[122:125], v[18:33]
	ds_read_b128 v[196:199], v206 offset:256
	s_waitcnt lgkmcnt(5)
	v_mfma_f32_32x32x16_bf16 v[50:65], v[202:205], v[122:125], v[50:65]
	ds_read_b128 v[202:205], v206 offset:12544
	s_waitcnt lgkmcnt(5)
	v_mfma_f32_32x32x16_bf16 v[18:33], v[180:183], v[126:129], v[18:33]
	ds_read_b128 v[180:183], v207 offset:256
	s_waitcnt lgkmcnt(5)
	v_mfma_f32_32x32x16_bf16 v[50:65], v[184:187], v[126:129], v[50:65]
	ds_read_b128 v[184:187], v207 offset:12544
	s_waitcnt lgkmcnt(5)
	v_mfma_f32_32x32x16_bf16 v[18:33], v[188:191], v[130:133], v[18:33]
	ds_read_b128 v[188:191], v208 offset:256
	s_waitcnt lgkmcnt(5)
	v_mfma_f32_32x32x16_bf16 v[50:65], v[192:195], v[130:133], v[50:65]
	ds_read_b128 v[192:195], v208 offset:12544
	s_waitcnt lgkmcnt(5)
	v_mfma_f32_32x32x16_bf16 v[18:33], v[196:199], v[134:137], v[18:33]
	s_waitcnt lgkmcnt(4)
	v_mfma_f32_32x32x16_bf16 v[50:65], v[202:205], v[134:137], v[50:65]
	s_waitcnt lgkmcnt(3)
	v_mfma_f32_32x32x16_bf16 v[18:33], v[180:183], v[138:141], v[18:33]
	s_waitcnt lgkmcnt(2)
	v_mfma_f32_32x32x16_bf16 v[50:65], v[184:187], v[138:141], v[50:65]
	s_waitcnt lgkmcnt(1)
	v_mfma_f32_32x32x16_bf16 v[18:33], v[188:191], v[142:145], v[18:33]
	s_waitcnt lgkmcnt(0)
	v_mfma_f32_32x32x16_bf16 v[50:65], v[192:195], v[142:145], v[50:65]
	s_setprio 0
	s_mov_b64 s[16:17], -1
	s_and_b64 vcc, exec, s[14:15]
	s_cbranch_vccnz .LBB0_1157

; template <bool MLA, bool grpB>
; __device__ __forceinline__ void attn_unit_g(LAS unsigned char* lds, const AttnPtrs& P, int b, int h, int qblk) {
;     ...
;         const LAS unsigned char* ka = lds + koff + karow;
;         bf16x8 a[PFD];
;         auto ld = [&](int i) -> bf16x8 {
;             const int d0 = i >> 1, blk = i & 1, seg = 2 * d0;
;             int so;
;             if (MLA) so = (((seg + hi) & 24) | (((seg + hi) ^ kswz) & 7)) * 16; else so = ((seg + hi) ^ kswz) * 16;
;             return *(const LAS bf16x8*)(ka + blk * 32 * KROW + so);
;         };
; #pragma unroll
;         for (int i = 0; i < PFD; ++i) a[i] = ld(i);
; #pragma unroll
;         for (int i = 0; i < 2 * ND0; ++i) {
;             const f32x16 zc = {0.f, 0.f, 0.f, 0.f, 0.f, 0.f, 0.f, 0.f, 0.f, 0.f, 0.f, 0.f, 0.f, 0.f, 0.f, 0.f};
;             sc[i & 1] = __builtin_amdgcn_mfma_f32_32x32x16_bf16(a[i % PFD], qf[i >> 1], (MLA && i < 2) ? zc : sc[i & 1], 0, 0, 0);
;             if (i + PFD < 2 * ND0) a[i % PFD] = ld(i + PFD);
;         }
;         __builtin_amdgcn_sched_group_barrier(0x100, PFD, 0);
; #pragma unroll
;         for (int i = 0; i < 2 * ND0; ++i) { __builtin_amdgcn_sched_group_barrier(0x008, 1, 0); __builtin_amdgcn_sched_group_barrier(0x100, 1, 0); }
;         __builtin_amdgcn_sched_barrier(0);
;     };
;     float mref = -1e30f;
;     auto sm = [&](int j) {
;         if (j >= my_last) {
;             if (MLA) { if (j > my_last) {
; #pragma unroll
;                 for (int r = 0; r < 16; ++r) { sc[0][r] = -2e30f; sc[1][r] = -2e30f; } } }
;             else { const int qpos = q0 + r32;
; #pragma unroll
;                 for (int blk = 0; blk < 2; ++blk)
; #pragma unroll
;                     for (int r = 0; r < 16; ++r) { const int key = 64 * j + 32 * blk + 16 * hi + r; if (key > qpos) sc[blk][r] = -2e30f; } }
;         }
;         float big_ = 3.0e38f; asm volatile("" : "+v"(big_));
;         float mxa = MAX2(sc[0][0], sc[0][1]), mxb = MAX2(sc[0][2], sc[0][3]), mxc = MAX2(sc[1][0], sc[1][1]), mxd = MAX2(sc[1][2], sc[1][3]);
; #pragma unroll
;         for (int r = 4; r < 16; r += 4) { mxa = MAX2(mxa, MAX2(sc[0][r], sc[0][r + 1])); mxb = MAX2(mxb, MAX2(sc[0][r + 2], sc[0][r + 3])); mxc = MAX2(mxc, MAX2(sc[1][r], sc[1][r + 1])); mxd = MAX2(mxd, MAX2(sc[1][r + 2], sc[1][r + 3])); }
;         float mx = MAX2(MAX2(mxa, mxb), MAX2(mxc, mxd));
.LBB0_1214:
	v_add_u32_e32 v0, s26, v179
	v_add_u32_e32 v14, v0, v183
	ds_read_b128 v[2:5], v14
	ds_read_b128 v[6:9], v14 offset:12288
	v_add_u32_e32 v15, v0, v184
	v_add_u32_e32 v198, v0, v185
	ds_read_b128 v[10:13], v15
	ds_read_b128 v[194:197], v15 offset:12288
	v_add_u32_e32 v0, v0, v186
	ds_read_b128 v[202:205], v198
	ds_read_b128 v[206:209], v198 offset:12288
	s_waitcnt lgkmcnt(5)
	s_setprio 1
	v_mfma_f32_32x32x16_bf16 v[96:111], v[2:5], v[112:115], 0
	ds_read_b128 v[2:5], v0
	s_waitcnt lgkmcnt(5)
	v_mfma_f32_32x32x16_bf16 v[80:95], v[6:9], v[112:115], 0
	ds_read_b128 v[6:9], v0 offset:12288
	s_waitcnt lgkmcnt(5)
	v_mfma_f32_32x32x16_bf16 v[96:111], v[10:13], v[116:119], v[96:111]
	ds_read_b128 v[10:13], v14 offset:128
	s_waitcnt lgkmcnt(5)
	v_mfma_f32_32x32x16_bf16 v[80:95], v[194:197], v[116:119], v[80:95]
	ds_read_b128 v[194:197], v14 offset:12416
	s_waitcnt lgkmcnt(5)
	v_mfma_f32_32x32x16_bf16 v[96:111], v[202:205], v[120:123], v[96:111]
	ds_read_b128 v[202:205], v15 offset:128
	s_waitcnt lgkmcnt(5)
	v_mfma_f32_32x32x16_bf16 v[80:95], v[206:209], v[120:123], v[80:95]
	ds_read_b128 v[206:209], v15 offset:12416
	s_waitcnt lgkmcnt(5)
	v_mfma_f32_32x32x16_bf16 v[96:111], v[2:5], v[124:127], v[96:111]
	ds_read_b128 v[2:5], v198 offset:128
	s_waitcnt lgkmcnt(5)
	v_mfma_f32_32x32x16_bf16 v[80:95], v[6:9], v[124:127], v[80:95]
	ds_read_b128 v[6:9], v198 offset:12416
	s_waitcnt lgkmcnt(5)
	v_mfma_f32_32x32x16_bf16 v[96:111], v[10:13], v[128:131], v[96:111]
	ds_read_b128 v[10:13], v0 offset:128
	s_waitcnt lgkmcnt(5)
	v_mfma_f32_32x32x16_bf16 v[80:95], v[194:197], v[128:131], v[80:95]
	ds_read_b128 v[194:197], v0 offset:12416
	s_waitcnt lgkmcnt(5)
	v_mfma_f32_32x32x16_bf16 v[96:111], v[202:205], v[132:135], v[96:111]
	ds_read_b128 v[202:205], v14 offset:256
	s_waitcnt lgkmcnt(5)
	v_mfma_f32_32x32x16_bf16 v[80:95], v[206:209], v[132:135], v[80:95]
	ds_read_b128 v[206:209], v14 offset:12544
	s_waitcnt lgkmcnt(5)
	v_mfma_f32_32x32x16_bf16 v[96:111], v[2:5], v[136:139], v[96:111]
	ds_read_b128 v[2:5], v15 offset:256
	s_waitcnt lgkmcnt(5)
	v_mfma_f32_32x32x16_bf16 v[80:95], v[6:9], v[136:139], v[80:95]
	ds_read_b128 v[6:9], v15 offset:12544
	s_waitcnt lgkmcnt(5)
	v_mfma_f32_32x32x16_bf16 v[96:111], v[10:13], v[140:143], v[96:111]
	ds_read_b128 v[10:13], v198 offset:256
	s_waitcnt lgkmcnt(5)
	v_mfma_f32_32x32x16_bf16 v[80:95], v[194:197], v[140:143], v[80:95]
	ds_read_b128 v[194:197], v198 offset:12544
	s_waitcnt lgkmcnt(5)
	v_mfma_f32_32x32x16_bf16 v[96:111], v[202:205], v[144:147], v[96:111]
	ds_read_b128 v[202:205], v0 offset:256
	s_waitcnt lgkmcnt(5)
	v_mfma_f32_32x32x16_bf16 v[80:95], v[206:209], v[144:147], v[80:95]
	ds_read_b128 v[206:209], v0 offset:12544
	s_waitcnt lgkmcnt(5)
	v_mfma_f32_32x32x16_bf16 v[96:111], v[2:5], v[148:151], v[96:111]
	s_waitcnt lgkmcnt(4)
	v_mfma_f32_32x32x16_bf16 v[80:95], v[6:9], v[148:151], v[80:95]
	s_waitcnt lgkmcnt(3)
	v_mfma_f32_32x32x16_bf16 v[96:111], v[10:13], v[152:155], v[96:111]
	s_waitcnt lgkmcnt(2)
	v_mfma_f32_32x32x16_bf16 v[80:95], v[194:197], v[152:155], v[80:95]
	s_waitcnt lgkmcnt(1)
	v_mfma_f32_32x32x16_bf16 v[96:111], v[202:205], v[156:159], v[96:111]
	s_waitcnt lgkmcnt(0)
	v_mfma_f32_32x32x16_bf16 v[80:95], v[206:209], v[156:159], v[80:95]
	s_setprio 0
	v_mov_b32_e32 v0, 0x7f61b1e6
	s_nop 9
	v_med3_f32 v2, v96, v97, v0
	v_med3_f32 v6, v100, v101, v0
	v_med3_f32 v3, v98, v99, v0
	v_med3_f32 v2, v2, v6, v0
	v_med3_f32 v6, v102, v103, v0
	v_med3_f32 v4, v80, v81, v0
	v_med3_f32 v3, v3, v6, v0
	v_med3_f32 v6, v84, v85, v0
	v_med3_f32 v5, v82, v83, v0
	v_med3_f32 v4, v4, v6, v0
	v_med3_f32 v6, v86, v87, v0
	v_med3_f32 v5, v5, v6, v0
	v_med3_f32 v6, v104, v105, v0
	v_med3_f32 v2, v2, v6, v0
	v_med3_f32 v6, v106, v107, v0
	v_med3_f32 v3, v3, v6, v0
	v_med3_f32 v6, v88, v89, v0
	v_med3_f32 v4, v4, v6, v0
	v_med3_f32 v6, v90, v91, v0
	v_med3_f32 v5, v5, v6, v0
	v_med3_f32 v6, v108, v109, v0
	v_med3_f32 v2, v2, v6, v0
	v_med3_f32 v6, v110, v111, v0
	v_med3_f32 v3, v3, v6, v0
	v_med3_f32 v6, v92, v93, v0
	v_med3_f32 v4, v4, v6, v0
	v_med3_f32 v6, v94, v95, v0
	v_med3_f32 v5, v5, v6, v0
	v_med3_f32 v2, v2, v3, v0
	v_med3_f32 v3, v4, v5, v0
	v_and_b32_e32 v4, 64, v171
	v_med3_f32 v2, v2, v3, v0
	v_xor_b32_e32 v3, 32, v171
	v_add_u32_e32 v4, 64, v4
	v_cmp_lt_i32_e32 vcc, v3, v4
	s_nop 1
	v_cndmask_b32_e32 v3, v171, v3, vcc
	v_lshlrev_b32_e32 v3, 2, v3
	ds_bpermute_b32 v3, v3, v2
	s_waitcnt lgkmcnt(0)
	v_med3_f32 v0, v2, v3, v0
	v_add_f32_e32 v2, 0x41000000, v193
	v_cmp_gt_f32_e32 vcc, v0, v2
	s_cbranch_vccz .LBB0_1216
	v_max_f32_e32 v0, v0, v0
	v_max_f32_e32 v2, v193, v193
	v_max_f32_e32 v2, v2, v0
	v_sub_f32_e32 v0, v193, v2
	v_exp_f32_e32 v0, v0
	v_mov_b32_e32 v193, v2
	v_mul_f32_e32 v192, v192, v0
	v_pk_mul_f32 v[78:79], v[78:79], v[0:1] op_sel_hi:[1,0]
	v_pk_mul_f32 v[76:77], v[76:77], v[0:1] op_sel_hi:[1,0]
	v_pk_mul_f32 v[74:75], v[74:75], v[0:1] op_sel_hi:[1,0]
	v_pk_mul_f32 v[72:73], v[72:73], v[0:1] op_sel_hi:[1,0]
	v_pk_mul_f32 v[70:71], v[70:71], v[0:1] op_sel_hi:[1,0]
	v_pk_mul_f32 v[68:69], v[68:69], v[0:1] op_sel_hi:[1,0]
	v_pk_mul_f32 v[66:67], v[66:67], v[0:1] op_sel_hi:[1,0]
	v_pk_mul_f32 v[64:65], v[64:65], v[0:1] op_sel_hi:[1,0]
	v_pk_mul_f32 v[62:63], v[62:63], v[0:1] op_sel_hi:[1,0]
	v_pk_mul_f32 v[60:61], v[60:61], v[0:1] op_sel_hi:[1,0]
	v_pk_mul_f32 v[58:59], v[58:59], v[0:1] op_sel_hi:[1,0]
	v_pk_mul_f32 v[56:57], v[56:57], v[0:1] op_sel_hi:[1,0]
	v_pk_mul_f32 v[54:55], v[54:55], v[0:1] op_sel_hi:[1,0]
	v_pk_mul_f32 v[52:53], v[52:53], v[0:1] op_sel_hi:[1,0]
	v_pk_mul_f32 v[50:51], v[50:51], v[0:1] op_sel_hi:[1,0]
	v_pk_mul_f32 v[48:49], v[48:49], v[0:1] op_sel_hi:[1,0]
	v_pk_mul_f32 v[46:47], v[46:47], v[0:1] op_sel_hi:[1,0]
	v_pk_mul_f32 v[44:45], v[44:45], v[0:1] op_sel_hi:[1,0]
	v_pk_mul_f32 v[42:43], v[42:43], v[0:1] op_sel_hi:[1,0]
	v_pk_mul_f32 v[40:41], v[40:41], v[0:1] op_sel_hi:[1,0]
	v_pk_mul_f32 v[38:39], v[38:39], v[0:1] op_sel_hi:[1,0]
	v_pk_mul_f32 v[36:37], v[36:37], v[0:1] op_sel_hi:[1,0]
	v_pk_mul_f32 v[34:35], v[34:35], v[0:1] op_sel_hi:[1,0]
	v_pk_mul_f32 v[32:33], v[32:33], v[0:1] op_sel_hi:[1,0]
	v_pk_mul_f32 v[30:31], v[30:31], v[0:1] op_sel_hi:[1,0]
	v_pk_mul_f32 v[28:29], v[28:29], v[0:1] op_sel_hi:[1,0]
	v_pk_mul_f32 v[26:27], v[26:27], v[0:1] op_sel_hi:[1,0]
	v_pk_mul_f32 v[24:25], v[24:25], v[0:1] op_sel_hi:[1,0]
	v_pk_mul_f32 v[22:23], v[22:23], v[0:1] op_sel_hi:[1,0]
	v_pk_mul_f32 v[20:21], v[20:21], v[0:1] op_sel_hi:[1,0]
	v_pk_mul_f32 v[18:19], v[18:19], v[0:1] op_sel_hi:[1,0]
	v_pk_mul_f32 v[16:17], v[16:17], v[0:1] op_sel_hi:[1,0]
; __device__ __forceinline__ unsigned cvt_pk_bf16(float lo, float hi) { unsigned r; asm volatile("v_cvt_pk_bf16_f32 %0, %1, %2" : "=v"(r) : "v"(lo), "v"(hi)); return r; }
; #define LAS __attribute__((address_space(3)))
; template <bool MLA, bool grpB>
; __device__ __forceinline__ void attn_unit_g(LAS unsigned char* lds, const AttnPtrs& P, int b, int h, int qblk) {
;     ...
;         float ps = 0.f;
; #pragma unroll
;         for (int blk = 0; blk < 2; ++blk)
; #pragma unroll
;             for (int r = 0; r < 16; ++r) { const float pv_ = __builtin_amdgcn_exp2f(sc[blk][r] - mref); sc[blk][r] = pv_; ps += pv_; }
;         lrun += ps;
; #pragma unroll
;         for (int blk = 0; blk < 2; ++blk)
; #pragma unroll
;             for (int ks = 0; ks < 2; ++ks) { u32x4 w;
;                 w.x = pg8::cvt_pk_bf16(sc[blk][8 * ks + 0], sc[blk][8 * ks + 1]); w.y = pg8::cvt_pk_bf16(sc[blk][8 * ks + 2], sc[blk][8 * ks + 3]);
;                 w.z = pg8::cvt_pk_bf16(sc[blk][8 * ks + 4], sc[blk][8 * ks + 5]); w.w = pg8::cvt_pk_bf16(sc[blk][8 * ks + 6], sc[blk][8 * ks + 7]);
;                 pb[blk][ks] = __builtin_bit_cast(bf16x8, w); }
;         __builtin_amdgcn_sched_barrier(0);
;     };
;     auto pv = [&](int voff) {
;         const LAS unsigned char* va = lds + varow + voff;
;         bf16x8 a[PFD];
;         auto ld = [&](int i) -> bf16x8 {
;             const int dvb = i & 3, bk = i >> 2, so = ((4 * (bk >> 1) + 2 * hi + (bk & 1)) ^ vswz) * 16;
;             return *(const LAS bf16x8*)(va + 32 * dvb * VROW + so);
;         };
; #pragma unroll
;         for (int i = 0; i < PFD; ++i) a[i] = ld(i);
; #pragma unroll
;         for (int i = 0; i < 16; ++i) {
;             o[i & 3] = __builtin_amdgcn_mfma_f32_32x32x16_bf16(a[i % PFD], pb[i >> 3][(i >> 2) & 1], o[i & 3], 0, 0, 0);
;             if (i + PFD < 16) a[i % PFD] = ld(i + PFD);
;         }
;         __builtin_amdgcn_sched_group_barrier(0x100, PFD, 0);
; #pragma unroll
;         for (int i = 0; i < 16; ++i) { __builtin_amdgcn_sched_group_barrier(0x008, 1, 0); __builtin_amdgcn_sched_group_barrier(0x100, 1, 0); }
.LBB0_1216:
	v_sub_f32_e32 v0, v96, v193
	v_exp_f32_e32 v0, v0
	v_sub_f32_e32 v2, v97, v193
	v_exp_f32_e32 v2, v2
	v_sub_f32_e32 v3, v98, v193
	v_exp_f32_e32 v3, v3
	v_sub_f32_e32 v4, v99, v193
	v_exp_f32_e32 v4, v4
	v_sub_f32_e32 v6, v100, v193
	v_add_f32_e32 v5, 0, v0
	v_exp_f32_e32 v6, v6
	v_sub_f32_e32 v7, v101, v193
	v_add_f32_e32 v5, v2, v5
	v_exp_f32_e32 v7, v7
	v_sub_f32_e32 v8, v102, v193
	v_add_f32_e32 v5, v3, v5
	v_exp_f32_e32 v8, v8
	v_sub_f32_e32 v9, v103, v193
	v_add_f32_e32 v5, v4, v5
	v_exp_f32_e32 v9, v9
	v_sub_f32_e32 v10, v104, v193
	v_add_f32_e32 v5, v6, v5
	v_exp_f32_e32 v10, v10
	v_sub_f32_e32 v11, v105, v193
	v_add_f32_e32 v5, v7, v5
	v_exp_f32_e32 v11, v11
	v_sub_f32_e32 v12, v106, v193
	v_add_f32_e32 v5, v8, v5
	v_exp_f32_e32 v12, v12
	v_sub_f32_e32 v13, v107, v193
	v_add_f32_e32 v5, v9, v5
	v_exp_f32_e32 v13, v13
	v_sub_f32_e32 v14, v108, v193
	v_add_f32_e32 v5, v10, v5
	v_exp_f32_e32 v14, v14
	v_sub_f32_e32 v15, v109, v193
	v_add_f32_e32 v5, v11, v5
	v_exp_f32_e32 v15, v15
	v_sub_f32_e32 v96, v110, v193
	v_add_f32_e32 v5, v12, v5
	v_exp_f32_e32 v96, v96
	v_sub_f32_e32 v97, v111, v193
	v_add_f32_e32 v5, v13, v5
	v_exp_f32_e32 v97, v97
	v_sub_f32_e32 v80, v80, v193
	v_add_f32_e32 v5, v14, v5
	v_exp_f32_e32 v80, v80
	v_sub_f32_e32 v81, v81, v193
	v_add_f32_e32 v5, v15, v5
	v_exp_f32_e32 v81, v81
	v_sub_f32_e32 v82, v82, v193
	v_add_f32_e32 v5, v96, v5
	v_exp_f32_e32 v82, v82
	v_sub_f32_e32 v83, v83, v193
	v_add_f32_e32 v5, v97, v5
	v_exp_f32_e32 v83, v83
	v_sub_f32_e32 v84, v84, v193
	v_add_f32_e32 v5, v80, v5
	v_exp_f32_e32 v84, v84
	v_sub_f32_e32 v85, v85, v193
	v_add_f32_e32 v5, v81, v5
	v_exp_f32_e32 v85, v85
	v_sub_f32_e32 v86, v86, v193
	v_add_f32_e32 v5, v82, v5
	v_exp_f32_e32 v86, v86
	v_sub_f32_e32 v87, v87, v193
	v_add_f32_e32 v5, v83, v5
	v_exp_f32_e32 v87, v87
	v_sub_f32_e32 v88, v88, v193
	v_add_f32_e32 v5, v84, v5
	v_exp_f32_e32 v88, v88
	v_sub_f32_e32 v89, v89, v193
	v_add_f32_e32 v5, v85, v5
	v_exp_f32_e32 v89, v89
	v_sub_f32_e32 v90, v90, v193
	v_add_f32_e32 v5, v86, v5
	v_exp_f32_e32 v90, v90
	v_sub_f32_e32 v91, v91, v193
	v_add_f32_e32 v5, v87, v5
	v_exp_f32_e32 v91, v91
	v_sub_f32_e32 v92, v92, v193
	v_add_f32_e32 v5, v88, v5
	v_exp_f32_e32 v92, v92
	v_sub_f32_e32 v93, v93, v193
	v_add_f32_e32 v5, v89, v5
	v_exp_f32_e32 v93, v93
	v_sub_f32_e32 v94, v94, v193
	v_add_f32_e32 v5, v90, v5
	v_exp_f32_e32 v94, v94
	v_sub_f32_e32 v95, v95, v193
	v_add_f32_e32 v5, v91, v5
	v_exp_f32_e32 v95, v95
	v_add_f32_e32 v5, v92, v5
	v_add_f32_e32 v5, v93, v5
	v_add_f32_e32 v5, v94, v5
	v_add_f32_e32 v5, v95, v5
	v_add_f32_e32 v192, v192, v5
	v_cvt_pk_bf16_f32 v2, v0, v2
	v_cvt_pk_bf16_f32 v3, v3, v4
	v_cvt_pk_bf16_f32 v4, v6, v7
	v_cvt_pk_bf16_f32 v5, v8, v9
	v_cvt_pk_bf16_f32 v6, v10, v11
	v_cvt_pk_bf16_f32 v7, v12, v13
	v_cvt_pk_bf16_f32 v8, v14, v15
	v_cvt_pk_bf16_f32 v9, v96, v97
	v_cvt_pk_bf16_f32 v10, v80, v81
	v_cvt_pk_bf16_f32 v11, v82, v83
	v_cvt_pk_bf16_f32 v12, v84, v85
	v_cvt_pk_bf16_f32 v13, v86, v87
	v_cvt_pk_bf16_f32 v80, v88, v89
	v_cvt_pk_bf16_f32 v81, v90, v91
	v_cvt_pk_bf16_f32 v82, v92, v93
	v_cvt_pk_bf16_f32 v83, v94, v95
	v_add_u32_e32 v0, s21, v187
	v_add_u32_e32 v14, v0, v188
	ds_read_b128 v[84:87], v14
	ds_read_b128 v[88:91], v14 offset:4096
	ds_read_b128 v[92:95], v14 offset:8192
	ds_read_b128 v[96:99], v14 offset:12288
	v_add_u32_e32 v15, v0, v189
	ds_read_b128 v[100:103], v15
	ds_read_b128 v[104:107], v15 offset:4096
	v_add_u32_e32 v14, v0, v190
	v_add_u32_e32 v0, v0, v191
	s_waitcnt lgkmcnt(5)
	s_setprio 1
	v_mfma_f32_32x32x16_bf16 v[64:79], v[84:87], v[2:5], v[64:79]
	ds_read_b128 v[84:87], v15 offset:8192
	s_waitcnt lgkmcnt(5)
	v_mfma_f32_32x32x16_bf16 v[48:63], v[88:91], v[2:5], v[48:63]
	ds_read_b128 v[88:91], v15 offset:12288
	s_waitcnt lgkmcnt(5)
	v_mfma_f32_32x32x16_bf16 v[32:47], v[92:95], v[2:5], v[32:47]
	ds_read_b128 v[92:95], v14
	s_waitcnt lgkmcnt(5)
	v_mfma_f32_32x32x16_bf16 v[16:31], v[96:99], v[2:5], v[16:31]
	ds_read_b128 v[2:5], v14 offset:4096
	s_waitcnt lgkmcnt(5)
	v_mfma_f32_32x32x16_bf16 v[64:79], v[100:103], v[6:9], v[64:79]
	ds_read_b128 v[96:99], v14 offset:8192
	s_waitcnt lgkmcnt(5)
	v_mfma_f32_32x32x16_bf16 v[48:63], v[104:107], v[6:9], v[48:63]
	ds_read_b128 v[100:103], v14 offset:12288
	s_waitcnt lgkmcnt(5)
	v_mfma_f32_32x32x16_bf16 v[32:47], v[84:87], v[6:9], v[32:47]
	ds_read_b128 v[84:87], v0
	s_waitcnt lgkmcnt(5)
	v_mfma_f32_32x32x16_bf16 v[16:31], v[88:91], v[6:9], v[16:31]
	ds_read_b128 v[6:9], v0 offset:4096
	s_waitcnt lgkmcnt(5)
	v_mfma_f32_32x32x16_bf16 v[64:79], v[92:95], v[10:13], v[64:79]
	ds_read_b128 v[88:91], v0 offset:8192
	s_waitcnt lgkmcnt(5)
	v_mfma_f32_32x32x16_bf16 v[48:63], v[2:5], v[10:13], v[48:63]
	ds_read_b128 v[2:5], v0 offset:12288
	s_waitcnt lgkmcnt(5)
	v_mfma_f32_32x32x16_bf16 v[32:47], v[96:99], v[10:13], v[32:47]
	s_waitcnt lgkmcnt(4)
	v_mfma_f32_32x32x16_bf16 v[16:31], v[100:103], v[10:13], v[16:31]
	s_waitcnt lgkmcnt(3)
	v_mfma_f32_32x32x16_bf16 v[64:79], v[84:87], v[80:83], v[64:79]
	s_waitcnt lgkmcnt(2)
	v_mfma_f32_32x32x16_bf16 v[48:63], v[6:9], v[80:83], v[48:63]
	s_waitcnt lgkmcnt(1)
	v_mfma_f32_32x32x16_bf16 v[32:47], v[88:91], v[80:83], v[32:47]
	s_waitcnt lgkmcnt(0)
	v_mfma_f32_32x32x16_bf16 v[16:31], v[2:5], v[80:83], v[16:31]
	s_setprio 0
	s_mov_b64 s[16:17], -1
	s_and_b64 vcc, exec, s[14:15]
	s_cbranch_vccnz .LBB0_1208

; #define LAS __attribute__((address_space(3)))
; template <bool MLA, bool grpB>
; __device__ __forceinline__ void attn_unit_g(LAS unsigned char* lds, const AttnPtrs& P, int b, int h, int qblk) {
;     ...
;     auto qk = [&](int koff) {
;         if (MLA) {
;         } else {
; #pragma unroll
;             for (int blk = 0; blk < 2; ++blk)
; #pragma unroll
;                 for (int g = 0; g < 4; ++g) { const f32x4 c4 = *(const LAS f32x4*)(lds + koff + KTILE + (32 * blk + 16 * hi + 4 * g) * 4);
; #pragma unroll
;                     for (int e = 0; e < 4; ++e) sc[blk][4 * g + e] = c4[e]; }
;         }
;         const LAS unsigned char* ka = lds + koff + karow;
;         bf16x8 a[PFD];
;         auto ld = [&](int i) -> bf16x8 {
;             const int d0 = i >> 1, blk = i & 1, seg = 2 * d0;
;             int so;
;             if (MLA) so = (((seg + hi) & 24) | (((seg + hi) ^ kswz) & 7)) * 16; else so = ((seg + hi) ^ kswz) * 16;
;             return *(const LAS bf16x8*)(ka + blk * 32 * KROW + so);
;         };
; #pragma unroll
;         for (int i = 0; i < PFD; ++i) a[i] = ld(i);
; #pragma unroll
;         for (int i = 0; i < 2 * ND0; ++i) {
;             const f32x16 zc = {0.f, 0.f, 0.f, 0.f, 0.f, 0.f, 0.f, 0.f, 0.f, 0.f, 0.f, 0.f, 0.f, 0.f, 0.f, 0.f};
;             sc[i & 1] = __builtin_amdgcn_mfma_f32_32x32x16_bf16(a[i % PFD], qf[i >> 1], (MLA && i < 2) ? zc : sc[i & 1], 0, 0, 0);
;             if (i + PFD < 2 * ND0) a[i % PFD] = ld(i + PFD);
;         }
;         __builtin_amdgcn_sched_group_barrier(0x100, PFD, 0);
; #pragma unroll
;         for (int i = 0; i < 2 * ND0; ++i) { __builtin_amdgcn_sched_group_barrier(0x008, 1, 0); __builtin_amdgcn_sched_group_barrier(0x100, 1, 0); }
;     ...
;     int k0 = 0, knext = KSLOT, k2 = 2 * KSLOT, k3 = 3 * KSLOT, vcur = 0, v1 = VTILE, v2 = 2 * VTILE;
;     const int jl = ntile - 1;
;     dma_k(jl, 0); dma_v(jl, 0); dma_k(jl - 1, KSLOT);
;     dma_k(jl - 2, 2 * KSLOT); dma_v(jl - 1, VTILE);
;     if (MLA) asm volatile("s_waitcnt vmcnt(5)\n\ts_barrier" ::: "memory"); else asm volatile("s_waitcnt vmcnt(4)\n\ts_barrier" ::: "memory");
;     if (grpB) qk(0);
.LBB0_1252:
	s_or_b64 exec, exec, s[10:11]
	v_lshrrev_b32_e32 v8, 1, v3
	v_and_b32_e32 v5, 3, v3
	v_and_b32_e32 v6, 12, v8
	v_lshlrev_b32_e32 v4, 2, v2
	v_or_b32_e32 v7, v6, v5
	v_and_or_b32 v4, v4, 16, v7
	v_bitop3_b32 v9, v6, 7, v5 bitop3:0xc8
	v_lshlrev_b32_e32 v5, 1, v2
	s_lshl_b64 s[10:11], s[64:65], 7
	v_and_b32_e32 v10, 8, v5
	v_lshlrev_b32_e32 v147, 8, v4
	v_lshl_add_u64 v[4:5], v[152:153], 0, s[10:11]
	s_add_i32 m0, s95, 0x14400
	v_lshlrev_b32_e32 v161, 6, v160
	global_load_lds_dwordx4 v[4:5], off
	v_lshl_add_u64 v[4:5], v[154:155], 0, s[10:11]
	s_add_i32 m0, s95, 0x16400
	v_add_u32_e32 v11, 0, v147
	global_load_lds_dwordx4 v[4:5], off
	s_waitcnt vmcnt(4)
	s_barrier
	v_add_u32_e32 v4, 0, v161
	ds_read_b128 v[16:19], v4 offset:16384
	ds_read_b128 v[20:23], v4 offset:16400
	ds_read_b128 v[24:27], v4 offset:16416
	ds_read_b128 v[28:31], v4 offset:16432
	ds_read_b128 v[32:35], v4 offset:16512
	ds_read_b128 v[36:39], v4 offset:16528
	ds_read_b128 v[40:43], v4 offset:16544
	ds_read_b128 v[44:47], v4 offset:16560
	v_bitop3_b32 v4, v9, v160, v10 bitop3:0x36
	v_lshlrev_b32_e32 v162, 4, v4
	v_add_u32_e32 v12, v11, v162
	ds_read_b128 v[4:7], v12 offset:8192
	v_or_b32_e32 v13, 2, v160
	v_bitop3_b32 v13, v9, v13, v10 bitop3:0x36
	v_lshlrev_b32_e32 v163, 4, v13
	v_add_u32_e32 v13, v11, v163
	s_waitcnt vmcnt(0) lgkmcnt(0)
	v_mfma_f32_32x32x16_bf16 v[32:47], v[4:7], v[136:139], v[32:47]
	ds_read_b128 v[4:7], v13 offset:8192
	v_or_b32_e32 v14, 4, v160
	v_bitop3_b32 v14, v9, v14, v10 bitop3:0x36
	v_lshlrev_b32_e32 v164, 4, v14
	v_add_u32_e32 v14, v11, v164
	v_or_b32_e32 v15, 6, v160
	v_bitop3_b32 v15, v9, v15, v10 bitop3:0x36
	s_waitcnt lgkmcnt(0)
	v_mfma_f32_32x32x16_bf16 v[32:47], v[4:7], v[112:115], v[32:47]
	ds_read_b128 v[4:7], v14 offset:8192
	v_lshlrev_b32_e32 v165, 4, v15
	v_add_u32_e32 v15, v11, v165
	v_or_b32_e32 v48, 8, v160
	v_bitop3_b32 v48, v9, v48, v10 bitop3:0x36
	v_lshlrev_b32_e32 v166, 4, v48
	v_add_u32_e32 v48, v11, v166
	s_waitcnt lgkmcnt(0)
	v_mfma_f32_32x32x16_bf16 v[32:47], v[4:7], v[116:119], v[32:47]
	ds_read_b128 v[4:7], v15 offset:8192
	v_or_b32_e32 v49, 10, v160
	v_bitop3_b32 v49, v9, v49, v10 bitop3:0x36
	v_lshlrev_b32_e32 v167, 4, v49
	v_add_u32_e32 v49, v11, v167
	v_or_b32_e32 v50, 12, v160
	v_bitop3_b32 v50, v9, v50, v10 bitop3:0x36
	s_waitcnt lgkmcnt(0)
	v_mfma_f32_32x32x16_bf16 v[32:47], v[4:7], v[120:123], v[32:47]
	ds_read_b128 v[4:7], v48 offset:8192
	v_lshlrev_b32_e32 v168, 4, v50
	v_add_u32_e32 v50, v11, v168
	v_or_b32_e32 v51, 14, v160
	v_bitop3_b32 v9, v9, v51, v10 bitop3:0x36
	v_lshlrev_b32_e32 v169, 4, v9
	v_add_u32_e32 v9, v11, v169
	s_waitcnt lgkmcnt(0)
	v_mfma_f32_32x32x16_bf16 v[32:47], v[4:7], v[124:127], v[32:47]
	ds_read_b128 v[4:7], v49 offset:8192
	s_ashr_i32 s78, s14, 6
	v_bfe_u32 v3, v3, 1, 3
	s_waitcnt lgkmcnt(0)
	s_setprio 1
	v_mfma_f32_32x32x16_bf16 v[32:47], v[4:7], v[128:131], v[32:47]
	ds_read_b128 v[4:7], v50 offset:8192
	s_waitcnt lgkmcnt(0)
	v_mfma_f32_32x32x16_bf16 v[32:47], v[4:7], v[132:135], v[32:47]
	ds_read_b128 v[4:7], v9 offset:8192
	s_waitcnt lgkmcnt(0)
	v_mfma_f32_32x32x16_bf16 v[32:47], v[4:7], v[140:143], v[32:47]
	ds_read_b128 v[4:7], v12
	s_waitcnt lgkmcnt(0)
	v_mfma_f32_32x32x16_bf16 v[16:31], v[4:7], v[136:139], v[16:31]
	ds_read_b128 v[4:7], v13
	s_waitcnt lgkmcnt(0)
	v_mfma_f32_32x32x16_bf16 v[16:31], v[4:7], v[112:115], v[16:31]
	ds_read_b128 v[4:7], v14
	s_waitcnt lgkmcnt(0)
	v_mfma_f32_32x32x16_bf16 v[16:31], v[4:7], v[116:119], v[16:31]
	ds_read_b128 v[4:7], v15
	s_waitcnt lgkmcnt(0)
	v_mfma_f32_32x32x16_bf16 v[16:31], v[4:7], v[120:123], v[16:31]
	ds_read_b128 v[4:7], v48
	s_waitcnt lgkmcnt(0)
	v_mfma_f32_32x32x16_bf16 v[16:31], v[4:7], v[124:127], v[16:31]
	ds_read_b128 v[4:7], v49
	s_waitcnt lgkmcnt(0)
	v_mfma_f32_32x32x16_bf16 v[16:31], v[4:7], v[128:131], v[16:31]
	ds_read_b128 v[4:7], v50
	s_waitcnt lgkmcnt(0)
	v_mfma_f32_32x32x16_bf16 v[16:31], v[4:7], v[132:135], v[16:31]
	ds_read_b128 v[4:7], v9
	s_waitcnt lgkmcnt(0)
	v_mfma_f32_32x32x16_bf16 v[16:31], v[4:7], v[140:143], v[16:31]
	s_setprio 0
	v_lshl_add_u64 v[156:157], v[0:1], 2, s[8:9]
	v_lshl_add_u32 v0, v2, 7, 0
	v_add_u32_e32 v175, 0x10400, v0
	v_lshlrev_b32_e32 v0, 1, v160
	v_or_b32_e32 v173, s14, v2
	v_bitop3_b32 v2, v0, v8, 7 bitop3:0x78
	v_lshlrev_b32_e32 v176, 4, v2
	v_bitop3_b32 v2, v0, v3, 1 bitop3:0x36
	v_lshlrev_b32_e32 v177, 4, v2
	v_bitop3_b32 v2, v0, v3, 4 bitop3:0x36
	v_bitop3_b32 v0, v0, v3, 5 bitop3:0x36
	v_mov_b32_e32 v14, v1
	v_mov_b32_e32 v15, v1
	v_lshlrev_b32_e32 v178, 4, v2
	v_lshlrev_b32_e32 v179, 4, v0
	v_mov_b32_e32 v0, v1
	v_mov_b32_e32 v2, v1
	v_mov_b32_e32 v3, v1
	v_mov_b32_e32 v4, v1
	v_mov_b32_e32 v5, v1
	v_mov_b32_e32 v6, v1
	v_mov_b32_e32 v7, v1
	v_mov_b32_e32 v8, v1
	v_mov_b32_e32 v9, v1
	v_mov_b32_e32 v10, v1
	v_mov_b32_e32 v11, v1
	v_mov_b32_e32 v12, v1
	v_mov_b32_e32 v13, v1
	v_mov_b64_e32 v[62:63], v[14:15]
	v_mov_b64_e32 v[78:79], v[14:15]
	v_mov_b64_e32 v[94:95], v[14:15]
	v_mov_b64_e32 v[110:111], v[14:15]
	s_add_i32 s97, s78, 1
	s_mov_b32 s54, 0
	v_mov_b32_e32 v181, 0xf149f2ca
	s_movk_i32 s50, 0x4100
	s_mov_b32 s55, 0x8200
	s_mov_b32 s9, 0xc300
	s_movk_i32 s57, 0x4000
	s_mov_b32 s8, 0x8000
	v_mov_b32_e32 v180, 0
	s_mov_b32 s89, s40
	s_mov_b32 s64, s90
	v_mov_b64_e32 v[60:61], v[12:13]
	v_mov_b64_e32 v[58:59], v[10:11]
	v_mov_b64_e32 v[56:57], v[8:9]
	v_mov_b64_e32 v[54:55], v[6:7]
	v_mov_b64_e32 v[52:53], v[4:5]
	v_mov_b64_e32 v[50:51], v[2:3]
	v_mov_b64_e32 v[48:49], v[0:1]
	v_mov_b64_e32 v[76:77], v[12:13]
	v_mov_b64_e32 v[74:75], v[10:11]
	v_mov_b64_e32 v[72:73], v[8:9]
	v_mov_b64_e32 v[70:71], v[6:7]
	v_mov_b64_e32 v[68:69], v[4:5]
	v_mov_b64_e32 v[66:67], v[2:3]
	v_mov_b64_e32 v[64:65], v[0:1]
	v_mov_b64_e32 v[92:93], v[12:13]
	v_mov_b64_e32 v[90:91], v[10:11]
	v_mov_b64_e32 v[88:89], v[8:9]
	v_mov_b64_e32 v[86:87], v[6:7]
	v_mov_b64_e32 v[84:85], v[4:5]
	v_mov_b64_e32 v[82:83], v[2:3]
	v_mov_b64_e32 v[80:81], v[0:1]
	v_mov_b64_e32 v[108:109], v[12:13]
	v_mov_b64_e32 v[106:107], v[10:11]
	v_mov_b64_e32 v[104:105], v[8:9]
	v_mov_b64_e32 v[102:103], v[6:7]
	v_mov_b64_e32 v[100:101], v[4:5]
	v_mov_b64_e32 v[98:99], v[2:3]
	v_mov_b64_e32 v[96:97], v[0:1]
	s_mov_b32 s41, 0

; __device__ __forceinline__ unsigned cvt_pk_bf16(float lo, float hi) { unsigned r; asm volatile("v_cvt_pk_bf16_f32 %0, %1, %2" : "=v"(r) : "v"(lo), "v"(hi)); return r; }
; #define LAS __attribute__((address_space(3)))
; template <bool MLA, bool grpB>
; __device__ __forceinline__ void attn_unit_g(LAS unsigned char* lds, const AttnPtrs& P, int b, int h, int qblk) {
;     ...
;         float ps = 0.f;
; #pragma unroll
;         for (int blk = 0; blk < 2; ++blk)
; #pragma unroll
;             for (int r = 0; r < 16; ++r) { const float pv_ = __builtin_amdgcn_exp2f(sc[blk][r] - mref); sc[blk][r] = pv_; ps += pv_; }
;         lrun += ps;
; #pragma unroll
;         for (int blk = 0; blk < 2; ++blk)
; #pragma unroll
;             for (int ks = 0; ks < 2; ++ks) { u32x4 w;
;                 w.x = pg8::cvt_pk_bf16(sc[blk][8 * ks + 0], sc[blk][8 * ks + 1]); w.y = pg8::cvt_pk_bf16(sc[blk][8 * ks + 2], sc[blk][8 * ks + 3]);
;                 w.z = pg8::cvt_pk_bf16(sc[blk][8 * ks + 4], sc[blk][8 * ks + 5]); w.w = pg8::cvt_pk_bf16(sc[blk][8 * ks + 6], sc[blk][8 * ks + 7]);
;                 pb[blk][ks] = __builtin_bit_cast(bf16x8, w); }
;         __builtin_amdgcn_sched_barrier(0);
;     };
;     auto pv = [&](int voff) {
;         const LAS unsigned char* va = lds + varow + voff;
;         bf16x8 a[PFD];
;         auto ld = [&](int i) -> bf16x8 {
;             const int dvb = i & 3, bk = i >> 2, so = ((4 * (bk >> 1) + 2 * hi + (bk & 1)) ^ vswz) * 16;
;             return *(const LAS bf16x8*)(va + 32 * dvb * VROW + so);
;         };
; #pragma unroll
;         for (int i = 0; i < PFD; ++i) a[i] = ld(i);
; #pragma unroll
;         for (int i = 0; i < 16; ++i) {
;             o[i & 3] = __builtin_amdgcn_mfma_f32_32x32x16_bf16(a[i % PFD], pb[i >> 3][(i >> 2) & 1], o[i & 3], 0, 0, 0);
;             if (i + PFD < 16) a[i % PFD] = ld(i + PFD);
;         }
;         __builtin_amdgcn_sched_group_barrier(0x100, PFD, 0);
; #pragma unroll
;         for (int i = 0; i < 16; ++i) { __builtin_amdgcn_sched_group_barrier(0x008, 1, 0); __builtin_amdgcn_sched_group_barrier(0x100, 1, 0); }
.LBB0_1268:
	v_sub_f32_e32 v0, v16, v181
	v_exp_f32_e32 v16, v0
	v_sub_f32_e32 v0, v17, v181
	v_exp_f32_e32 v17, v0
	v_sub_f32_e32 v0, v18, v181
	v_exp_f32_e32 v18, v0
	v_sub_f32_e32 v0, v19, v181
	v_exp_f32_e32 v19, v0
	v_sub_f32_e32 v2, v20, v181
	v_add_f32_e32 v0, 0, v16
	v_exp_f32_e32 v20, v2
	v_sub_f32_e32 v2, v21, v181
	v_add_f32_e32 v0, v17, v0
	v_exp_f32_e32 v21, v2
	v_sub_f32_e32 v2, v22, v181
	v_add_f32_e32 v0, v18, v0
	v_exp_f32_e32 v22, v2
	v_sub_f32_e32 v2, v23, v181
	v_add_f32_e32 v0, v19, v0
	v_exp_f32_e32 v23, v2
	v_sub_f32_e32 v2, v24, v181
	v_add_f32_e32 v0, v20, v0
	v_exp_f32_e32 v24, v2
	v_sub_f32_e32 v2, v25, v181
	v_add_f32_e32 v0, v21, v0
	v_exp_f32_e32 v25, v2
	v_sub_f32_e32 v2, v26, v181
	v_add_f32_e32 v0, v22, v0
	v_exp_f32_e32 v26, v2
	v_sub_f32_e32 v2, v27, v181
	v_add_f32_e32 v0, v23, v0
	v_exp_f32_e32 v27, v2
	v_sub_f32_e32 v2, v28, v181
	v_add_f32_e32 v0, v24, v0
	v_exp_f32_e32 v28, v2
	v_sub_f32_e32 v2, v29, v181
	v_add_f32_e32 v0, v25, v0
	v_exp_f32_e32 v29, v2
	v_sub_f32_e32 v2, v30, v181
	v_add_f32_e32 v0, v26, v0
	v_exp_f32_e32 v30, v2
	v_sub_f32_e32 v2, v31, v181
	v_add_f32_e32 v0, v27, v0
	v_exp_f32_e32 v31, v2
	v_sub_f32_e32 v2, v32, v181
	v_add_f32_e32 v0, v28, v0
	v_exp_f32_e32 v32, v2
	v_sub_f32_e32 v2, v33, v181
	v_add_f32_e32 v0, v29, v0
	v_exp_f32_e32 v33, v2
	v_sub_f32_e32 v2, v34, v181
	v_add_f32_e32 v0, v30, v0
	v_exp_f32_e32 v34, v2
	v_sub_f32_e32 v2, v35, v181
	v_add_f32_e32 v0, v31, v0
	v_exp_f32_e32 v35, v2
	v_sub_f32_e32 v2, v36, v181
	v_add_f32_e32 v0, v32, v0
	v_exp_f32_e32 v36, v2
	v_sub_f32_e32 v2, v37, v181
	v_add_f32_e32 v0, v33, v0
	v_exp_f32_e32 v37, v2
	v_sub_f32_e32 v2, v38, v181
	v_add_f32_e32 v0, v34, v0
	v_exp_f32_e32 v38, v2
	v_sub_f32_e32 v2, v39, v181
	v_add_f32_e32 v0, v35, v0
	v_exp_f32_e32 v39, v2
	v_sub_f32_e32 v2, v40, v181
	v_add_f32_e32 v0, v36, v0
	v_exp_f32_e32 v40, v2
	v_sub_f32_e32 v2, v41, v181
	v_add_f32_e32 v0, v37, v0
	v_exp_f32_e32 v41, v2
	v_sub_f32_e32 v2, v42, v181
	v_add_f32_e32 v0, v38, v0
	v_exp_f32_e32 v42, v2
	v_sub_f32_e32 v2, v43, v181
	v_add_f32_e32 v0, v39, v0
	v_exp_f32_e32 v43, v2
	v_sub_f32_e32 v2, v44, v181
	v_add_f32_e32 v0, v40, v0
	v_exp_f32_e32 v44, v2
	v_sub_f32_e32 v2, v45, v181
	v_add_f32_e32 v0, v41, v0
	v_exp_f32_e32 v45, v2
	v_sub_f32_e32 v2, v46, v181
	v_add_f32_e32 v0, v42, v0
	v_exp_f32_e32 v46, v2
	v_sub_f32_e32 v2, v47, v181
	v_add_f32_e32 v0, v43, v0
	v_exp_f32_e32 v47, v2
	v_add_f32_e32 v0, v44, v0
	v_add_f32_e32 v0, v45, v0
	v_add_f32_e32 v0, v46, v0
	v_add_f32_e32 v0, v47, v0
	v_add_f32_e32 v180, v180, v0
	v_cvt_pk_bf16_f32 v2, v16, v17
	v_cvt_pk_bf16_f32 v3, v18, v19
	v_cvt_pk_bf16_f32 v4, v20, v21
	v_cvt_pk_bf16_f32 v5, v22, v23
	v_cvt_pk_bf16_f32 v6, v24, v25
	v_cvt_pk_bf16_f32 v7, v26, v27
	v_cvt_pk_bf16_f32 v8, v28, v29
	v_cvt_pk_bf16_f32 v9, v30, v31
	v_cvt_pk_bf16_f32 v10, v32, v33
	v_cvt_pk_bf16_f32 v11, v34, v35
	v_cvt_pk_bf16_f32 v12, v36, v37
	v_cvt_pk_bf16_f32 v13, v38, v39
	v_cvt_pk_bf16_f32 v182, v40, v41
	v_cvt_pk_bf16_f32 v183, v42, v43
	v_cvt_pk_bf16_f32 v184, v44, v45
	v_cvt_pk_bf16_f32 v185, v46, v47
	v_add_u32_e32 v0, s54, v175
	v_add_u32_e32 v14, v0, v176
	ds_read_b128 v[186:189], v14
	ds_read_b128 v[190:193], v14 offset:4096
	ds_read_b128 v[194:197], v14 offset:8192
	ds_read_b128 v[202:205], v14 offset:12288
	v_add_u32_e32 v15, v0, v177
	ds_read_b128 v[206:209], v15
	ds_read_b128 v[210:213], v15 offset:4096
	v_add_u32_e32 v14, v0, v178
	v_add_u32_e32 v0, v0, v179
	s_waitcnt lgkmcnt(5)
	s_setprio 1
	v_mfma_f32_32x32x16_bf16 v[96:111], v[186:189], v[2:5], v[96:111]
	ds_read_b128 v[186:189], v15 offset:8192
	s_waitcnt lgkmcnt(5)
	v_mfma_f32_32x32x16_bf16 v[80:95], v[190:193], v[2:5], v[80:95]
	ds_read_b128 v[190:193], v15 offset:12288
	s_waitcnt lgkmcnt(5)
	v_mfma_f32_32x32x16_bf16 v[64:79], v[194:197], v[2:5], v[64:79]
	ds_read_b128 v[194:197], v14
	s_waitcnt lgkmcnt(5)
	v_mfma_f32_32x32x16_bf16 v[48:63], v[202:205], v[2:5], v[48:63]
	ds_read_b128 v[2:5], v14 offset:4096
	s_waitcnt lgkmcnt(5)
	v_mfma_f32_32x32x16_bf16 v[96:111], v[206:209], v[6:9], v[96:111]
	ds_read_b128 v[202:205], v14 offset:8192
	s_waitcnt lgkmcnt(5)
	v_mfma_f32_32x32x16_bf16 v[80:95], v[210:213], v[6:9], v[80:95]
	ds_read_b128 v[206:209], v14 offset:12288
	s_waitcnt lgkmcnt(5)
	v_mfma_f32_32x32x16_bf16 v[64:79], v[186:189], v[6:9], v[64:79]
	ds_read_b128 v[186:189], v0
	s_waitcnt lgkmcnt(5)
	v_mfma_f32_32x32x16_bf16 v[48:63], v[190:193], v[6:9], v[48:63]
	ds_read_b128 v[6:9], v0 offset:4096
	s_waitcnt lgkmcnt(5)
	v_mfma_f32_32x32x16_bf16 v[96:111], v[194:197], v[10:13], v[96:111]
	ds_read_b128 v[190:193], v0 offset:8192
	s_waitcnt lgkmcnt(5)
	v_mfma_f32_32x32x16_bf16 v[80:95], v[2:5], v[10:13], v[80:95]
	ds_read_b128 v[2:5], v0 offset:12288
	s_waitcnt lgkmcnt(5)
	v_mfma_f32_32x32x16_bf16 v[64:79], v[202:205], v[10:13], v[64:79]
	s_waitcnt lgkmcnt(4)
	v_mfma_f32_32x32x16_bf16 v[48:63], v[206:209], v[10:13], v[48:63]
	s_waitcnt lgkmcnt(3)
	v_mfma_f32_32x32x16_bf16 v[96:111], v[186:189], v[182:185], v[96:111]
	s_waitcnt lgkmcnt(2)
	v_mfma_f32_32x32x16_bf16 v[80:95], v[6:9], v[182:185], v[80:95]
	s_waitcnt lgkmcnt(1)
	v_mfma_f32_32x32x16_bf16 v[64:79], v[190:193], v[182:185], v[64:79]
	s_waitcnt lgkmcnt(0)
	v_mfma_f32_32x32x16_bf16 v[48:63], v[2:5], v[182:185], v[48:63]
	s_setprio 0
; #define LAS __attribute__((address_space(3)))
; template <bool MLA, bool grpB>
; __device__ __forceinline__ void attn_unit_g(LAS unsigned char* lds, const AttnPtrs& P, int b, int h, int qblk) {
;     ...
;     auto qk = [&](int koff) {
;         if (MLA) {
;         } else {
; #pragma unroll
;             for (int blk = 0; blk < 2; ++blk)
; #pragma unroll
;                 for (int g = 0; g < 4; ++g) { const f32x4 c4 = *(const LAS f32x4*)(lds + koff + KTILE + (32 * blk + 16 * hi + 4 * g) * 4);
; #pragma unroll
;                     for (int e = 0; e < 4; ++e) sc[blk][4 * g + e] = c4[e]; }
;         }
;         const LAS unsigned char* ka = lds + koff + karow;
;         bf16x8 a[PFD];
;         auto ld = [&](int i) -> bf16x8 {
;             const int d0 = i >> 1, blk = i & 1, seg = 2 * d0;
;             int so;
;             if (MLA) so = (((seg + hi) & 24) | (((seg + hi) ^ kswz) & 7)) * 16; else so = ((seg + hi) ^ kswz) * 16;
;             return *(const LAS bf16x8*)(ka + blk * 32 * KROW + so);
;         };
; #pragma unroll
;         for (int i = 0; i < PFD; ++i) a[i] = ld(i);
; #pragma unroll
;         for (int i = 0; i < 2 * ND0; ++i) {
;             const f32x16 zc = {0.f, 0.f, 0.f, 0.f, 0.f, 0.f, 0.f, 0.f, 0.f, 0.f, 0.f, 0.f, 0.f, 0.f, 0.f, 0.f};
;             sc[i & 1] = __builtin_amdgcn_mfma_f32_32x32x16_bf16(a[i % PFD], qf[i >> 1], (MLA && i < 2) ? zc : sc[i & 1], 0, 0, 0);
;             if (i + PFD < 2 * ND0) a[i % PFD] = ld(i + PFD);
;         }
;         __builtin_amdgcn_sched_group_barrier(0x100, PFD, 0);
; #pragma unroll
;         for (int i = 0; i < 2 * ND0; ++i) { __builtin_amdgcn_sched_group_barrier(0x008, 1, 0); __builtin_amdgcn_sched_group_barrier(0x100, 1, 0); }
.LBB0_1269:
	s_cmpk_eq_i32 s64, 0xff40
	s_cselect_b64 s[8:9], -1, 0
	s_cmp_gt_i32 s48, s97
	s_cselect_b64 s[10:11], -1, 0
	s_or_b64 s[8:9], s[8:9], s[10:11]
	s_and_b64 vcc, exec, s[8:9]
	s_cbranch_vccnz .LBB0_1273
	s_add_i32 s8, s56, 0
	v_add_u32_e32 v0, s8, v161
	ds_read_b128 v[16:19], v0 offset:16384
	ds_read_b128 v[20:23], v0 offset:16400
	ds_read_b128 v[24:27], v0 offset:16416
	ds_read_b128 v[28:31], v0 offset:16432
	ds_read_b128 v[32:35], v0 offset:16512
	ds_read_b128 v[36:39], v0 offset:16528
	ds_read_b128 v[40:43], v0 offset:16544
	ds_read_b128 v[44:47], v0 offset:16560
	v_add_u32_e32 v0, s8, v147
	v_add_u32_e32 v6, v0, v162
	v_add_u32_e32 v7, v0, v163
	v_add_u32_e32 v8, v0, v164
	v_add_u32_e32 v9, v0, v165
	v_add_u32_e32 v10, v0, v166
	v_add_u32_e32 v11, v0, v167
	v_add_u32_e32 v12, v0, v168
	v_add_u32_e32 v0, v0, v169
	ds_read_b128 v[182:185], v6 offset:8192
	ds_read_b128 v[186:189], v7 offset:8192
	ds_read_b128 v[190:193], v8 offset:8192
	ds_read_b128 v[194:197], v9 offset:8192
	ds_read_b128 v[202:205], v10 offset:8192
	ds_read_b128 v[210:213], v11 offset:8192
	s_waitcnt lgkmcnt(5)
	s_setprio 1
	v_mfma_f32_32x32x16_bf16 v[32:47], v[182:185], v[136:139], v[32:47]
	ds_read_b128 v[182:185], v12 offset:8192
	s_waitcnt lgkmcnt(5)
	v_mfma_f32_32x32x16_bf16 v[32:47], v[186:189], v[112:115], v[32:47]
	ds_read_b128 v[186:189], v0 offset:8192
	s_waitcnt lgkmcnt(5)
	v_mfma_f32_32x32x16_bf16 v[32:47], v[190:193], v[116:119], v[32:47]
	ds_read_b128 v[190:193], v6
	s_waitcnt lgkmcnt(5)
	v_mfma_f32_32x32x16_bf16 v[32:47], v[194:197], v[120:123], v[32:47]
	ds_read_b128 v[194:197], v7
	s_waitcnt lgkmcnt(5)
	v_mfma_f32_32x32x16_bf16 v[32:47], v[202:205], v[124:127], v[32:47]
	ds_read_b128 v[202:205], v8
	s_waitcnt lgkmcnt(5)
	v_mfma_f32_32x32x16_bf16 v[32:47], v[210:213], v[128:131], v[32:47]
	ds_read_b128 v[210:213], v9
	s_waitcnt lgkmcnt(5)
	v_mfma_f32_32x32x16_bf16 v[32:47], v[182:185], v[132:135], v[32:47]
	ds_read_b128 v[182:185], v10
	s_waitcnt lgkmcnt(5)
	v_mfma_f32_32x32x16_bf16 v[32:47], v[186:189], v[140:143], v[32:47]
	ds_read_b128 v[186:189], v11
	s_waitcnt lgkmcnt(5)
	v_mfma_f32_32x32x16_bf16 v[16:31], v[190:193], v[136:139], v[16:31]
	ds_read_b128 v[190:193], v12
	s_waitcnt lgkmcnt(5)
	v_mfma_f32_32x32x16_bf16 v[16:31], v[194:197], v[112:115], v[16:31]
	ds_read_b128 v[194:197], v0
	s_waitcnt lgkmcnt(5)
	v_mfma_f32_32x32x16_bf16 v[16:31], v[202:205], v[116:119], v[16:31]
	s_waitcnt lgkmcnt(4)
	v_mfma_f32_32x32x16_bf16 v[16:31], v[210:213], v[120:123], v[16:31]
	s_waitcnt lgkmcnt(3)
	v_mfma_f32_32x32x16_bf16 v[16:31], v[182:185], v[124:127], v[16:31]
	s_waitcnt lgkmcnt(2)
	v_mfma_f32_32x32x16_bf16 v[16:31], v[186:189], v[128:131], v[16:31]
	s_waitcnt lgkmcnt(1)
	v_mfma_f32_32x32x16_bf16 v[16:31], v[190:193], v[132:135], v[16:31]
	s_waitcnt lgkmcnt(0)
	v_mfma_f32_32x32x16_bf16 v[16:31], v[194:197], v[140:143], v[16:31]
	s_setprio 0
	s_mov_b64 s[8:9], -1
	s_and_b64 vcc, exec, s[74:75]
	s_cbranch_vccnz .LBB0_1274

; #define LAS __attribute__((address_space(3)))
; template <bool MLA, bool grpB>
; __device__ __forceinline__ void attn_unit_g(LAS unsigned char* lds, const AttnPtrs& P, int b, int h, int qblk) {
;     ...
;     auto qk = [&](int koff) {
;         if (MLA) {
;         } else {
; #pragma unroll
;             for (int blk = 0; blk < 2; ++blk)
; #pragma unroll
;                 for (int g = 0; g < 4; ++g) { const f32x4 c4 = *(const LAS f32x4*)(lds + koff + KTILE + (32 * blk + 16 * hi + 4 * g) * 4);
; #pragma unroll
;                     for (int e = 0; e < 4; ++e) sc[blk][4 * g + e] = c4[e]; }
;         }
;         const LAS unsigned char* ka = lds + koff + karow;
;         bf16x8 a[PFD];
;         auto ld = [&](int i) -> bf16x8 {
;             const int d0 = i >> 1, blk = i & 1, seg = 2 * d0;
;             int so;
;             if (MLA) so = (((seg + hi) & 24) | (((seg + hi) ^ kswz) & 7)) * 16; else so = ((seg + hi) ^ kswz) * 16;
;             return *(const LAS bf16x8*)(ka + blk * 32 * KROW + so);
;         };
; #pragma unroll
;         for (int i = 0; i < PFD; ++i) a[i] = ld(i);
; #pragma unroll
;         for (int i = 0; i < 2 * ND0; ++i) {
;             const f32x16 zc = {0.f, 0.f, 0.f, 0.f, 0.f, 0.f, 0.f, 0.f, 0.f, 0.f, 0.f, 0.f, 0.f, 0.f, 0.f, 0.f};
;             sc[i & 1] = __builtin_amdgcn_mfma_f32_32x32x16_bf16(a[i % PFD], qf[i >> 1], (MLA && i < 2) ? zc : sc[i & 1], 0, 0, 0);
;             if (i + PFD < 2 * ND0) a[i % PFD] = ld(i + PFD);
;         }
;         __builtin_amdgcn_sched_group_barrier(0x100, PFD, 0);
; #pragma unroll
;         for (int i = 0; i < 2 * ND0; ++i) { __builtin_amdgcn_sched_group_barrier(0x008, 1, 0); __builtin_amdgcn_sched_group_barrier(0x100, 1, 0); }
;         __builtin_amdgcn_sched_barrier(0);
;     };
;     float mref = -1e30f;
;     auto sm = [&](int j) {
;         if (j >= my_last) {
;             if (MLA) { if (j > my_last) {
; #pragma unroll
;                 for (int r = 0; r < 16; ++r) { sc[0][r] = -2e30f; sc[1][r] = -2e30f; } } }
;             else { const int qpos = q0 + r32;
; #pragma unroll
;                 for (int blk = 0; blk < 2; ++blk)
; #pragma unroll
;                     for (int r = 0; r < 16; ++r) { const int key = 64 * j + 32 * blk + 16 * hi + r; if (key > qpos) sc[blk][r] = -2e30f; } }
.LBB0_1313:
	s_add_i32 s8, s51, 0
	v_add_u32_e32 v0, s8, v161
	ds_read_b128 v[96:99], v0 offset:16384
	ds_read_b128 v[100:103], v0 offset:16400
	ds_read_b128 v[104:107], v0 offset:16416
	ds_read_b128 v[108:111], v0 offset:16432
	ds_read_b128 v[80:83], v0 offset:16512
	ds_read_b128 v[84:87], v0 offset:16528
	ds_read_b128 v[88:91], v0 offset:16544
	ds_read_b128 v[92:95], v0 offset:16560
	v_add_u32_e32 v0, s8, v147
	v_add_u32_e32 v6, v0, v162
	v_add_u32_e32 v7, v0, v163
	v_add_u32_e32 v8, v0, v164
	v_add_u32_e32 v9, v0, v165
	v_add_u32_e32 v10, v0, v166
	v_add_u32_e32 v11, v0, v167
	v_add_u32_e32 v12, v0, v168
	v_add_u32_e32 v0, v0, v169
	ds_read_b128 v[182:185], v6 offset:8192
	ds_read_b128 v[186:189], v7 offset:8192
	ds_read_b128 v[190:193], v8 offset:8192
	ds_read_b128 v[194:197], v9 offset:8192
	ds_read_b128 v[202:205], v10 offset:8192
	ds_read_b128 v[210:213], v11 offset:8192
	s_waitcnt lgkmcnt(5)
	s_setprio 1
	v_mfma_f32_32x32x16_bf16 v[80:95], v[182:185], v[136:139], v[80:95]
	ds_read_b128 v[182:185], v12 offset:8192
	s_waitcnt lgkmcnt(5)
	v_mfma_f32_32x32x16_bf16 v[80:95], v[186:189], v[112:115], v[80:95]
	ds_read_b128 v[186:189], v0 offset:8192
	s_waitcnt lgkmcnt(5)
	v_mfma_f32_32x32x16_bf16 v[80:95], v[190:193], v[116:119], v[80:95]
	ds_read_b128 v[190:193], v6
	s_waitcnt lgkmcnt(5)
	v_mfma_f32_32x32x16_bf16 v[80:95], v[194:197], v[120:123], v[80:95]
	ds_read_b128 v[194:197], v7
	s_waitcnt lgkmcnt(5)
	v_mfma_f32_32x32x16_bf16 v[80:95], v[202:205], v[124:127], v[80:95]
	ds_read_b128 v[202:205], v8
	s_waitcnt lgkmcnt(5)
	v_mfma_f32_32x32x16_bf16 v[80:95], v[210:213], v[128:131], v[80:95]
	ds_read_b128 v[210:213], v9
	s_waitcnt lgkmcnt(5)
	v_mfma_f32_32x32x16_bf16 v[80:95], v[182:185], v[132:135], v[80:95]
	ds_read_b128 v[182:185], v10
	s_waitcnt lgkmcnt(5)
	v_mfma_f32_32x32x16_bf16 v[80:95], v[186:189], v[140:143], v[80:95]
	ds_read_b128 v[186:189], v11
	s_waitcnt lgkmcnt(5)
	v_mfma_f32_32x32x16_bf16 v[96:111], v[190:193], v[136:139], v[96:111]
	ds_read_b128 v[190:193], v12
	s_waitcnt lgkmcnt(5)
	v_mfma_f32_32x32x16_bf16 v[96:111], v[194:197], v[112:115], v[96:111]
	ds_read_b128 v[194:197], v0
	s_waitcnt lgkmcnt(5)
	v_mfma_f32_32x32x16_bf16 v[96:111], v[202:205], v[116:119], v[96:111]
	s_waitcnt lgkmcnt(4)
	v_mfma_f32_32x32x16_bf16 v[96:111], v[210:213], v[120:123], v[96:111]
	s_waitcnt lgkmcnt(3)
	v_mfma_f32_32x32x16_bf16 v[96:111], v[182:185], v[124:127], v[96:111]
	s_waitcnt lgkmcnt(2)
	v_mfma_f32_32x32x16_bf16 v[96:111], v[186:189], v[128:131], v[96:111]
	s_waitcnt lgkmcnt(1)
	v_mfma_f32_32x32x16_bf16 v[96:111], v[190:193], v[132:135], v[96:111]
	s_waitcnt lgkmcnt(0)
	v_mfma_f32_32x32x16_bf16 v[96:111], v[194:197], v[140:143], v[96:111]
	s_setprio 0
	s_cmp_lt_u32 s10, s54
	s_cbranch_scc1 .LBB0_1317
	v_add_u32_e32 v0, s64, v146
	v_add_u32_e32 v2, 0xc0, v0
	v_cmp_le_i32_e32 vcc, v2, v173
	v_cmp_lt_i32_e64 s[8:9], v2, v173
	v_add_u32_e32 v2, 0xc2, v0
	v_cmp_le_i32_e64 s[10:11], v2, v173
	v_add_u32_e32 v2, 0xc3, v0
	v_cmp_le_i32_e64 s[12:13], v2, v173
	v_add_u32_e32 v2, 0xc4, v0
	v_cmp_le_i32_e64 s[14:15], v2, v173
	v_add_u32_e32 v2, 0xc5, v0
	v_cmp_le_i32_e64 s[16:17], v2, v173
	v_add_u32_e32 v2, 0xc6, v0
	v_cmp_le_i32_e64 s[18:19], v2, v173
	v_add_u32_e32 v2, 0xc7, v0
	v_cmp_le_i32_e64 s[20:21], v2, v173
	v_add_u32_e32 v2, 0xc8, v0
	v_cmp_le_i32_e64 s[22:23], v2, v173
	v_add_u32_e32 v2, 0xc9, v0
	v_cmp_le_i32_e64 s[24:25], v2, v173
	v_add_u32_e32 v2, 0xca, v0
	v_cmp_le_i32_e64 s[26:27], v2, v173
	v_add_u32_e32 v2, 0xcb, v0
	v_cmp_le_i32_e64 s[28:29], v2, v173
	v_add_u32_e32 v2, 0xcc, v0
	v_cmp_le_i32_e64 s[30:31], v2, v173
	v_add_u32_e32 v2, 0xcd, v0
	v_cmp_le_i32_e64 s[34:35], v2, v173
	v_add_u32_e32 v2, 0xce, v0
	v_cmp_le_i32_e64 s[36:37], v2, v173
	v_add_u32_e32 v2, 0xcf, v0
	v_cmp_le_i32_e64 s[38:39], v2, v173
	v_add_u32_e32 v2, 0xe0, v0
	v_cmp_le_i32_e64 s[42:43], v2, v173
	v_add_u32_e32 v2, 0xe1, v0
	s_nop 0
	v_cndmask_b32_e64 v80, v159, v80, s[42:43]
	v_cmp_le_i32_e64 s[42:43], v2, v173
	v_add_u32_e32 v2, 0xe2, v0
	s_nop 0
	v_cndmask_b32_e64 v81, v159, v81, s[42:43]
	v_cmp_le_i32_e64 s[42:43], v2, v173
	v_add_u32_e32 v2, 0xe3, v0
	s_nop 0
	v_cndmask_b32_e64 v82, v159, v82, s[42:43]
	v_cmp_le_i32_e64 s[42:43], v2, v173
	v_add_u32_e32 v2, 0xe4, v0
	s_nop 0
	v_cndmask_b32_e64 v83, v159, v83, s[42:43]
	v_cmp_le_i32_e64 s[42:43], v2, v173
	v_add_u32_e32 v2, 0xe5, v0
	s_nop 0
	v_cndmask_b32_e64 v84, v159, v84, s[42:43]
	v_cmp_le_i32_e64 s[42:43], v2, v173
	v_add_u32_e32 v2, 0xe6, v0
	s_nop 0
	v_cndmask_b32_e64 v85, v159, v85, s[42:43]
	v_cmp_le_i32_e64 s[42:43], v2, v173
	v_add_u32_e32 v2, 0xe7, v0
	s_nop 0
	v_cndmask_b32_e64 v86, v159, v86, s[42:43]
	v_cmp_le_i32_e64 s[42:43], v2, v173
	v_add_u32_e32 v2, 0xe8, v0
	s_nop 0
	v_cndmask_b32_e64 v87, v159, v87, s[42:43]
	v_cmp_le_i32_e64 s[42:43], v2, v173
	v_add_u32_e32 v2, 0xe9, v0
	s_nop 0
	v_cndmask_b32_e64 v88, v159, v88, s[42:43]
	v_cmp_le_i32_e64 s[42:43], v2, v173
	v_add_u32_e32 v2, 0xea, v0
	s_nop 0
	v_cndmask_b32_e64 v89, v159, v89, s[42:43]
	v_cmp_le_i32_e64 s[42:43], v2, v173
	v_add_u32_e32 v2, 0xeb, v0
	s_nop 0
	v_cndmask_b32_e64 v90, v159, v90, s[42:43]
	v_cmp_le_i32_e64 s[42:43], v2, v173
	v_add_u32_e32 v2, 0xec, v0
	s_nop 0
	v_cndmask_b32_e64 v91, v159, v91, s[42:43]
	v_cmp_le_i32_e64 s[42:43], v2, v173
	v_add_u32_e32 v2, 0xed, v0
	s_nop 0
	v_cndmask_b32_e64 v92, v159, v92, s[42:43]
	v_cmp_le_i32_e64 s[42:43], v2, v173
	v_add_u32_e32 v2, 0xee, v0
	v_add_u32_e32 v0, 0xef, v0
	v_cndmask_b32_e64 v93, v159, v93, s[42:43]
	v_cmp_le_i32_e64 s[42:43], v2, v173
	s_nop 1
	v_cndmask_b32_e64 v94, v159, v94, s[42:43]
	v_cmp_gt_i32_e64 s[42:43], v0, v173
	s_and_saveexec_b64 s[76:77], s[42:43]
	v_mov_b32_e32 v95, s87
	s_or_b64 exec, exec, s[76:77]
	v_cndmask_b32_e64 v97, v159, v97, s[8:9]
	v_cndmask_b32_e32 v96, v159, v96, vcc
	v_cndmask_b32_e64 v98, v159, v98, s[10:11]
	v_cndmask_b32_e64 v99, v159, v99, s[12:13]
	v_cndmask_b32_e64 v100, v159, v100, s[14:15]
	v_cndmask_b32_e64 v101, v159, v101, s[16:17]
	v_cndmask_b32_e64 v102, v159, v102, s[18:19]
	v_cndmask_b32_e64 v103, v159, v103, s[20:21]
	v_cndmask_b32_e64 v104, v159, v104, s[22:23]
	v_cndmask_b32_e64 v105, v159, v105, s[24:25]
	v_cndmask_b32_e64 v106, v159, v106, s[26:27]
	v_cndmask_b32_e64 v107, v159, v107, s[28:29]
	v_cndmask_b32_e64 v108, v159, v108, s[30:31]
	v_cndmask_b32_e64 v109, v159, v109, s[34:35]
	v_cndmask_b32_e64 v110, v159, v110, s[36:37]
	v_cndmask_b32_e64 v111, v159, v111, s[38:39]

; __device__ __forceinline__ unsigned cvt_pk_bf16(float lo, float hi) { unsigned r; asm volatile("v_cvt_pk_bf16_f32 %0, %1, %2" : "=v"(r) : "v"(lo), "v"(hi)); return r; }
; #define LAS __attribute__((address_space(3)))
; template <bool MLA, bool grpB>
; __device__ __forceinline__ void attn_unit_g(LAS unsigned char* lds, const AttnPtrs& P, int b, int h, int qblk) {
;     ...
;         float ps = 0.f;
; #pragma unroll
;         for (int blk = 0; blk < 2; ++blk)
; #pragma unroll
;             for (int r = 0; r < 16; ++r) { const float pv_ = __builtin_amdgcn_exp2f(sc[blk][r] - mref); sc[blk][r] = pv_; ps += pv_; }
;         lrun += ps;
; #pragma unroll
;         for (int blk = 0; blk < 2; ++blk)
; #pragma unroll
;             for (int ks = 0; ks < 2; ++ks) { u32x4 w;
;                 w.x = pg8::cvt_pk_bf16(sc[blk][8 * ks + 0], sc[blk][8 * ks + 1]); w.y = pg8::cvt_pk_bf16(sc[blk][8 * ks + 2], sc[blk][8 * ks + 3]);
;                 w.z = pg8::cvt_pk_bf16(sc[blk][8 * ks + 4], sc[blk][8 * ks + 5]); w.w = pg8::cvt_pk_bf16(sc[blk][8 * ks + 6], sc[blk][8 * ks + 7]);
;                 pb[blk][ks] = __builtin_bit_cast(bf16x8, w); }
;         __builtin_amdgcn_sched_barrier(0);
;     };
;     auto pv = [&](int voff) {
;         const LAS unsigned char* va = lds + varow + voff;
;         bf16x8 a[PFD];
;         auto ld = [&](int i) -> bf16x8 {
;             const int dvb = i & 3, bk = i >> 2, so = ((4 * (bk >> 1) + 2 * hi + (bk & 1)) ^ vswz) * 16;
;             return *(const LAS bf16x8*)(va + 32 * dvb * VROW + so);
;         };
; #pragma unroll
;         for (int i = 0; i < PFD; ++i) a[i] = ld(i);
; #pragma unroll
;         for (int i = 0; i < 16; ++i) {
;             o[i & 3] = __builtin_amdgcn_mfma_f32_32x32x16_bf16(a[i % PFD], pb[i >> 3][(i >> 2) & 1], o[i & 3], 0, 0, 0);
;             if (i + PFD < 16) a[i % PFD] = ld(i + PFD);
;         }
;         __builtin_amdgcn_sched_group_barrier(0x100, PFD, 0);
; #pragma unroll
;         for (int i = 0; i < 16; ++i) { __builtin_amdgcn_sched_group_barrier(0x008, 1, 0); __builtin_amdgcn_sched_group_barrier(0x100, 1, 0); }
.LBB0_1319:
	v_sub_f32_e32 v0, v96, v181
	v_exp_f32_e32 v0, v0
	v_sub_f32_e32 v2, v97, v181
	v_exp_f32_e32 v2, v2
	v_sub_f32_e32 v3, v98, v181
	v_exp_f32_e32 v3, v3
	v_sub_f32_e32 v4, v99, v181
	v_exp_f32_e32 v4, v4
	v_sub_f32_e32 v6, v100, v181
	v_add_f32_e32 v5, 0, v0
	v_exp_f32_e32 v6, v6
	v_sub_f32_e32 v7, v101, v181
	v_add_f32_e32 v5, v2, v5
	v_exp_f32_e32 v7, v7
	v_sub_f32_e32 v8, v102, v181
	v_add_f32_e32 v5, v3, v5
	v_exp_f32_e32 v8, v8
	v_sub_f32_e32 v9, v103, v181
	v_add_f32_e32 v5, v4, v5
	v_exp_f32_e32 v9, v9
	v_sub_f32_e32 v10, v104, v181
	v_add_f32_e32 v5, v6, v5
	v_exp_f32_e32 v10, v10
	v_sub_f32_e32 v11, v105, v181
	v_add_f32_e32 v5, v7, v5
	v_exp_f32_e32 v11, v11
	v_sub_f32_e32 v12, v106, v181
	v_add_f32_e32 v5, v8, v5
	v_exp_f32_e32 v12, v12
	v_sub_f32_e32 v13, v107, v181
	v_add_f32_e32 v5, v9, v5
	v_exp_f32_e32 v13, v13
	v_sub_f32_e32 v14, v108, v181
	v_add_f32_e32 v5, v10, v5
	v_exp_f32_e32 v14, v14
	v_sub_f32_e32 v15, v109, v181
	v_add_f32_e32 v5, v11, v5
	v_exp_f32_e32 v15, v15
	v_sub_f32_e32 v96, v110, v181
	v_add_f32_e32 v5, v12, v5
	v_exp_f32_e32 v96, v96
	v_sub_f32_e32 v97, v111, v181
	v_add_f32_e32 v5, v13, v5
	v_exp_f32_e32 v97, v97
	v_sub_f32_e32 v80, v80, v181
	v_add_f32_e32 v5, v14, v5
	v_exp_f32_e32 v80, v80
	v_sub_f32_e32 v81, v81, v181
	v_add_f32_e32 v5, v15, v5
	v_exp_f32_e32 v81, v81
	v_sub_f32_e32 v82, v82, v181
	v_add_f32_e32 v5, v96, v5
	v_exp_f32_e32 v82, v82
	v_sub_f32_e32 v83, v83, v181
	v_add_f32_e32 v5, v97, v5
	v_exp_f32_e32 v83, v83
	v_sub_f32_e32 v84, v84, v181
	v_add_f32_e32 v5, v80, v5
	v_exp_f32_e32 v84, v84
	v_sub_f32_e32 v85, v85, v181
	v_add_f32_e32 v5, v81, v5
	v_exp_f32_e32 v85, v85
	v_sub_f32_e32 v86, v86, v181
	v_add_f32_e32 v5, v82, v5
	v_exp_f32_e32 v86, v86
	v_sub_f32_e32 v87, v87, v181
	v_add_f32_e32 v5, v83, v5
	v_exp_f32_e32 v87, v87
	v_sub_f32_e32 v88, v88, v181
	v_add_f32_e32 v5, v84, v5
	v_exp_f32_e32 v88, v88
	v_sub_f32_e32 v89, v89, v181
	v_add_f32_e32 v5, v85, v5
	v_exp_f32_e32 v89, v89
	v_sub_f32_e32 v90, v90, v181
	v_add_f32_e32 v5, v86, v5
	v_exp_f32_e32 v90, v90
	v_sub_f32_e32 v91, v91, v181
	v_add_f32_e32 v5, v87, v5
	v_exp_f32_e32 v91, v91
	v_sub_f32_e32 v92, v92, v181
	v_add_f32_e32 v5, v88, v5
	v_exp_f32_e32 v92, v92
	v_sub_f32_e32 v93, v93, v181
	v_add_f32_e32 v5, v89, v5
	v_exp_f32_e32 v93, v93
	v_sub_f32_e32 v94, v94, v181
	v_add_f32_e32 v5, v90, v5
	v_exp_f32_e32 v94, v94
	v_sub_f32_e32 v95, v95, v181
	v_add_f32_e32 v5, v91, v5
	v_exp_f32_e32 v95, v95
	v_add_f32_e32 v5, v92, v5
	v_add_f32_e32 v5, v93, v5
	v_add_f32_e32 v5, v94, v5
	v_add_f32_e32 v5, v95, v5
	v_add_f32_e32 v180, v180, v5
	v_cvt_pk_bf16_f32 v2, v0, v2
	v_cvt_pk_bf16_f32 v3, v3, v4
	v_cvt_pk_bf16_f32 v4, v6, v7
	v_cvt_pk_bf16_f32 v5, v8, v9
	v_cvt_pk_bf16_f32 v6, v10, v11
	v_cvt_pk_bf16_f32 v7, v12, v13
	v_cvt_pk_bf16_f32 v8, v14, v15
	v_cvt_pk_bf16_f32 v9, v96, v97
	v_cvt_pk_bf16_f32 v10, v80, v81
	v_cvt_pk_bf16_f32 v11, v82, v83
	v_cvt_pk_bf16_f32 v12, v84, v85
	v_cvt_pk_bf16_f32 v13, v86, v87
	v_cvt_pk_bf16_f32 v80, v88, v89
	v_cvt_pk_bf16_f32 v81, v90, v91
	v_cvt_pk_bf16_f32 v82, v92, v93
	v_cvt_pk_bf16_f32 v83, v94, v95
	v_add_u32_e32 v0, s41, v175
	v_add_u32_e32 v14, v0, v176
	ds_read_b128 v[84:87], v14
	ds_read_b128 v[88:91], v14 offset:4096
	ds_read_b128 v[92:95], v14 offset:8192
	ds_read_b128 v[96:99], v14 offset:12288
	v_add_u32_e32 v15, v0, v177
	ds_read_b128 v[100:103], v15
	ds_read_b128 v[104:107], v15 offset:4096
	v_add_u32_e32 v14, v0, v178
	v_add_u32_e32 v0, v0, v179
	s_waitcnt lgkmcnt(5)
	s_setprio 1
	v_mfma_f32_32x32x16_bf16 v[64:79], v[84:87], v[2:5], v[64:79]
	ds_read_b128 v[84:87], v15 offset:8192
	s_waitcnt lgkmcnt(5)
	v_mfma_f32_32x32x16_bf16 v[48:63], v[88:91], v[2:5], v[48:63]
	ds_read_b128 v[88:91], v15 offset:12288
	s_waitcnt lgkmcnt(5)
	v_mfma_f32_32x32x16_bf16 v[32:47], v[92:95], v[2:5], v[32:47]
	ds_read_b128 v[92:95], v14
	s_waitcnt lgkmcnt(5)
	v_mfma_f32_32x32x16_bf16 v[16:31], v[96:99], v[2:5], v[16:31]
	ds_read_b128 v[2:5], v14 offset:4096
	s_waitcnt lgkmcnt(5)
	v_mfma_f32_32x32x16_bf16 v[64:79], v[100:103], v[6:9], v[64:79]
	ds_read_b128 v[96:99], v14 offset:8192
	s_waitcnt lgkmcnt(5)
	v_mfma_f32_32x32x16_bf16 v[48:63], v[104:107], v[6:9], v[48:63]
	ds_read_b128 v[100:103], v14 offset:12288
	s_waitcnt lgkmcnt(5)
	v_mfma_f32_32x32x16_bf16 v[32:47], v[84:87], v[6:9], v[32:47]
	ds_read_b128 v[84:87], v0
	s_waitcnt lgkmcnt(5)
	v_mfma_f32_32x32x16_bf16 v[16:31], v[88:91], v[6:9], v[16:31]
	ds_read_b128 v[6:9], v0 offset:4096
	s_waitcnt lgkmcnt(5)
	v_mfma_f32_32x32x16_bf16 v[64:79], v[92:95], v[10:13], v[64:79]
	ds_read_b128 v[88:91], v0 offset:8192
	s_waitcnt lgkmcnt(5)
	v_mfma_f32_32x32x16_bf16 v[48:63], v[2:5], v[10:13], v[48:63]
	ds_read_b128 v[2:5], v0 offset:12288
	s_waitcnt lgkmcnt(5)
	v_mfma_f32_32x32x16_bf16 v[32:47], v[96:99], v[10:13], v[32:47]
	s_waitcnt lgkmcnt(4)
	v_mfma_f32_32x32x16_bf16 v[16:31], v[100:103], v[10:13], v[16:31]
	s_waitcnt lgkmcnt(3)
	v_mfma_f32_32x32x16_bf16 v[64:79], v[84:87], v[80:83], v[64:79]
	s_waitcnt lgkmcnt(2)
	v_mfma_f32_32x32x16_bf16 v[48:63], v[6:9], v[80:83], v[48:63]
	s_waitcnt lgkmcnt(1)
	v_mfma_f32_32x32x16_bf16 v[32:47], v[88:91], v[80:83], v[32:47]
	s_waitcnt lgkmcnt(0)
	v_mfma_f32_32x32x16_bf16 v[16:31], v[2:5], v[80:83], v[16:31]
	s_setprio 0
	s_mov_b64 s[8:9], -1
	s_and_b64 vcc, exec, s[74:75]
	s_cbranch_vccnz .LBB0_1325

; __device__ __forceinline__ unsigned cvt_pk_bf16(float lo, float hi) { unsigned r; asm volatile("v_cvt_pk_bf16_f32 %0, %1, %2" : "=v"(r) : "v"(lo), "v"(hi)); return r; }
; __device__ __forceinline__ float bf_lo(unsigned w) { return __uint_as_float(w << 16); }
; __device__ __forceinline__ float bf_hi(unsigned w) { return __uint_as_float(w & 0xffff0000u); }
; #define GAS1 __attribute__((address_space(1)))
;     __device__ __forceinline__ void operator()(const f32x4 (&acc)[2][2][4][2], const Unit& u, int wr, int wc, int fr, int fq) const {
;     ...
;                 if (MODE == 3 || MODE == 4) {
;                     const u32x4 gw = *(const GAS1 u32x4*)(G + (size_t)row * ldg + col);
;                     const f32x4 g0 = {bf_lo(gw.x), bf_hi(gw.x), bf_lo(gw.y), bf_hi(gw.y)}, g1 = {bf_lo(gw.z), bf_hi(gw.z), bf_lo(gw.w), bf_hi(gw.w)};
;                     v0 = v0 * g0; v1 = v1 * g1;
;                     if (MODE == 4) {
;                         const u32x4 ow = *(const GAS1 u32x4*)((const bf16_t*)O + (size_t)row * ldc + col);
;                         const f32x4 o0 = {bf_lo(ow.x), bf_hi(ow.x), bf_lo(ow.y), bf_hi(ow.y)}, o1 = {bf_lo(ow.z), bf_hi(ow.z), bf_lo(ow.w), bf_hi(ow.w)};
;                         v0 += o0; v1 += o1;
;                     }
;                 }
;                 u32x4 w; w.x = cvt_pk_bf16(v0[0], v0[1]); w.y = cvt_pk_bf16(v0[2], v0[3]); w.z = cvt_pk_bf16(v1[0], v1[1]); w.w = cvt_pk_bf16(v1[2], v1[3]);
;                 if (bj == 0) asm volatile("ds_write_b128 %0, %1" :: "v"(wa), "v"(w)); else asm volatile("ds_write_b128 %0, %1 offset:64" :: "v"(wa), "v"(w));
;             }
;             asm volatile("ds_read_b128 %0, %1" : "=&v"(rb[g & 1][0]) : "v"(ra));
;             asm volatile("ds_read_b128 %0, %1 offset:1152" : "=&v"(rb[g & 1][1]) : "v"(ra));
;             if (g >= 1) {
;                 asm volatile("s_waitcnt lgkmcnt(4)" : "+v"(rb[(g - 1) & 1][0]), "+v"(rb[(g - 1) & 1][1]));
;                 bf16_t* ob = obase + (size_t)(((g - 1) >> 2) * HALF + ((g - 1) & 3) * 16) * ldc;
;                 *(GAS1 u32x4*)ob = rb[(g - 1) & 1][0]; *(GAS1 u32x4*)(ob + (size_t)8 * ldc) = rb[(g - 1) & 1][1];
.LBB0_1410:
	s_lshl_b32 s25, s34, 8
	s_lshl_b32 s34, s35, 8
	s_add_i32 s25, s25, s65
	v_or_b32_e32 v148, s34, v153
	v_or_b32_e32 v159, s25, v150
	v_mov_b64_e32 v[146:147], s[18:19]
	v_ashrrev_i32_e32 v149, 31, v148
	v_mad_i64_i32 v[160:161], s[36:37], v159, s74, v[146:147]
	v_lshlrev_b64 v[148:149], 1, v[148:149]
	v_lshl_add_u64 v[164:165], v[160:161], 0, v[148:149]
	v_add_u32_e32 v234, 0, v159
	v_mad_i64_i32 v[206:207], s[98:99], v234, s74, v[146:147]
	v_lshl_add_u64 v[206:207], v[206:207], 0, v[148:149]
	global_load_dwordx4 v[176:179], v[206:207], off
	global_load_dwordx4 v[180:183], v[206:207], off offset:64
	v_add_u32_e32 v234, 16, v159
	v_mad_i64_i32 v[206:207], s[98:99], v234, s74, v[146:147]
	v_lshl_add_u64 v[206:207], v[206:207], 0, v[148:149]
	global_load_dwordx4 v[184:187], v[206:207], off
	global_load_dwordx4 v[188:191], v[206:207], off offset:64
	v_add_u32_e32 v234, 32, v159
	v_mad_i64_i32 v[206:207], s[98:99], v234, s74, v[146:147]
	v_lshl_add_u64 v[206:207], v[206:207], 0, v[148:149]
	global_load_dwordx4 v[192:195], v[206:207], off
	global_load_dwordx4 v[196:199], v[206:207], off offset:64
	v_add_u32_e32 v234, 48, v159
	v_mad_i64_i32 v[206:207], s[98:99], v234, s74, v[146:147]
	v_lshl_add_u64 v[206:207], v[206:207], 0, v[148:149]
	global_load_dwordx4 v[202:205], v[206:207], off
	global_load_dwordx4 v[210:213], v[206:207], off offset:64
	v_add_u32_e32 v234, 128, v159
	v_mad_i64_i32 v[206:207], s[98:99], v234, s74, v[146:147]
	v_lshl_add_u64 v[206:207], v[206:207], 0, v[148:149]
	global_load_dwordx4 v[214:217], v[206:207], off
	global_load_dwordx4 v[218:221], v[206:207], off offset:64
	v_add_u32_e32 v234, 144, v159
	v_mad_i64_i32 v[206:207], s[98:99], v234, s74, v[146:147]
	v_lshl_add_u64 v[206:207], v[206:207], 0, v[148:149]
	global_load_dwordx4 v[222:225], v[206:207], off
	global_load_dwordx4 v[226:229], v[206:207], off offset:64
	v_add_u32_e32 v234, 160, v159
	v_mad_i64_i32 v[206:207], s[98:99], v234, s74, v[146:147]
	v_lshl_add_u64 v[206:207], v[206:207], 0, v[148:149]
	global_load_dwordx4 v[236:239], v[206:207], off
	global_load_dwordx4 v[240:243], v[206:207], off offset:64
	v_add_u32_e32 v234, 176, v159
	v_mad_i64_i32 v[206:207], s[98:99], v234, s74, v[146:147]
	v_lshl_add_u64 v[206:207], v[206:207], 0, v[148:149]
	global_load_dwordx4 v[246:249], v[206:207], off
	global_load_dwordx4 v[250:253], v[206:207], off offset:64
	s_ashr_i32 s35, s34, 31
	s_waitcnt vmcnt(15)
	v_mov_b32_e32 v160, v176
	v_mov_b32_e32 v161, v177
	v_mov_b32_e32 v162, v178
	v_mov_b32_e32 v163, v179
	v_lshlrev_b32_e32 v166, 16, v160
	v_and_b32_e32 v167, 0xffff0000, v160
	v_lshlrev_b32_e32 v160, 16, v161
	v_and_b32_e32 v161, 0xffff0000, v161
	v_lshlrev_b32_e32 v168, 16, v162
	v_and_b32_e32 v169, 0xffff0000, v162
	v_lshlrev_b32_e32 v162, 16, v163
	v_and_b32_e32 v163, 0xffff0000, v163
	v_pk_mul_f32 v[126:127], v[126:127], v[160:161]
	v_pk_mul_f32 v[160:161], v[122:123], v[162:163]
	v_pk_mul_f32 v[122:123], v[120:121], v[168:169]
	v_pk_mul_f32 v[124:125], v[124:125], v[166:167]
	s_nop 0
	v_cvt_pk_bf16_f32 v120, v124, v125
	v_cvt_pk_bf16_f32 v121, v126, v127
	v_cvt_pk_bf16_f32 v122, v122, v123
	v_cvt_pk_bf16_f32 v123, v160, v161
	v_or_b32_e32 v124, 16, v159
	ds_write_b128 v154, v[120:123]
	v_mad_i64_i32 v[124:125], s[36:37], v124, s74, v[146:147]
	v_lshl_add_u64 v[124:125], v[124:125], 0, v[148:149]
	s_waitcnt vmcnt(14)
	v_mov_b32_e32 v120, v180
	v_mov_b32_e32 v121, v181
	v_mov_b32_e32 v122, v182
	v_mov_b32_e32 v123, v183
	v_lshlrev_b32_e32 v126, 16, v120
	v_and_b32_e32 v127, 0xffff0000, v120
	v_lshlrev_b32_e32 v120, 16, v121
	v_and_b32_e32 v121, 0xffff0000, v121
	v_lshlrev_b32_e32 v160, 16, v122
	v_and_b32_e32 v161, 0xffff0000, v122
	v_lshlrev_b32_e32 v122, 16, v123
	v_and_b32_e32 v123, 0xffff0000, v123
	v_pk_mul_f32 v[118:119], v[118:119], v[120:121]
	v_pk_mul_f32 v[120:121], v[110:111], v[122:123]
	v_pk_mul_f32 v[110:111], v[108:109], v[160:161]
	v_pk_mul_f32 v[116:117], v[116:117], v[126:127]
	s_nop 0
	v_cvt_pk_bf16_f32 v108, v116, v117
	v_cvt_pk_bf16_f32 v109, v118, v119
	v_cvt_pk_bf16_f32 v110, v110, v111
	v_cvt_pk_bf16_f32 v111, v120, v121
	s_nop 0
	ds_write_b128 v154, v[108:111] offset:64
	ds_read_b128 v[108:111], v155
	ds_read_b128 v[116:119], v155 offset:1152
	s_waitcnt vmcnt(13)
	v_mov_b32_e32 v120, v184
	v_mov_b32_e32 v121, v185
	v_mov_b32_e32 v122, v186
	v_mov_b32_e32 v123, v187
	v_lshlrev_b32_e32 v126, 16, v120
	v_and_b32_e32 v127, 0xffff0000, v120
	v_lshlrev_b32_e32 v120, 16, v121
	v_and_b32_e32 v121, 0xffff0000, v121
	v_lshlrev_b32_e32 v160, 16, v122
	v_and_b32_e32 v161, 0xffff0000, v122
	v_lshlrev_b32_e32 v122, 16, v123
	v_and_b32_e32 v123, 0xffff0000, v123
	v_pk_mul_f32 v[114:115], v[114:115], v[120:121]
	v_pk_mul_f32 v[112:113], v[112:113], v[126:127]
	v_pk_mul_f32 v[120:121], v[106:107], v[122:123]
	v_pk_mul_f32 v[106:107], v[104:105], v[160:161]
	v_cvt_pk_bf16_f32 v104, v112, v113
	v_cvt_pk_bf16_f32 v105, v114, v115
	s_nop 0
	v_cvt_pk_bf16_f32 v106, v106, v107
	v_cvt_pk_bf16_f32 v107, v120, v121
	s_nop 0
	ds_write_b128 v154, v[104:107]
	v_or_b32_e32 v104, s25, v152
	v_ashrrev_i32_e32 v105, 31, v104
	v_lshlrev_b64 v[104:105], 12, v[104:105]
	v_lshl_add_u64 v[104:105], s[8:9], 0, v[104:105]
	v_lshl_add_u64 v[104:105], s[34:35], 1, v[104:105]
	v_or_b32_e32 v106, 32, v159
	v_lshl_add_u64 v[104:105], v[104:105], 0, s[12:13]
	v_mad_i64_i32 v[106:107], s[36:37], v106, s74, v[146:147]
	v_lshl_add_u64 v[104:105], v[104:105], 0, v[136:137]
	v_lshl_add_u64 v[120:121], v[106:107], 0, v[148:149]
	v_add_co_u32_e32 v106, vcc, s69, v104
	s_waitcnt vmcnt(12)
; __device__ __forceinline__ unsigned cvt_pk_bf16(float lo, float hi) { unsigned r; asm volatile("v_cvt_pk_bf16_f32 %0, %1, %2" : "=v"(r) : "v"(lo), "v"(hi)); return r; }
; __device__ __forceinline__ float bf_lo(unsigned w) { return __uint_as_float(w << 16); }
; __device__ __forceinline__ float bf_hi(unsigned w) { return __uint_as_float(w & 0xffff0000u); }
; #define GAS1 __attribute__((address_space(1)))
;     __device__ __forceinline__ void operator()(const f32x4 (&acc)[2][2][4][2], const Unit& u, int wr, int wc, int fr, int fq) const {
;     ...
;                 if (MODE == 3 || MODE == 4) {
;                     const u32x4 gw = *(const GAS1 u32x4*)(G + (size_t)row * ldg + col);
;                     const f32x4 g0 = {bf_lo(gw.x), bf_hi(gw.x), bf_lo(gw.y), bf_hi(gw.y)}, g1 = {bf_lo(gw.z), bf_hi(gw.z), bf_lo(gw.w), bf_hi(gw.w)};
;                     v0 = v0 * g0; v1 = v1 * g1;
;                     if (MODE == 4) {
;                         const u32x4 ow = *(const GAS1 u32x4*)((const bf16_t*)O + (size_t)row * ldc + col);
;                         const f32x4 o0 = {bf_lo(ow.x), bf_hi(ow.x), bf_lo(ow.y), bf_hi(ow.y)}, o1 = {bf_lo(ow.z), bf_hi(ow.z), bf_lo(ow.w), bf_hi(ow.w)};
;                         v0 += o0; v1 += o1;
;                     }
;                 }
;                 u32x4 w; w.x = cvt_pk_bf16(v0[0], v0[1]); w.y = cvt_pk_bf16(v0[2], v0[3]); w.z = cvt_pk_bf16(v1[0], v1[1]); w.w = cvt_pk_bf16(v1[2], v1[3]);
;                 if (bj == 0) asm volatile("ds_write_b128 %0, %1" :: "v"(wa), "v"(w)); else asm volatile("ds_write_b128 %0, %1 offset:64" :: "v"(wa), "v"(w));
;             }
;             asm volatile("ds_read_b128 %0, %1" : "=&v"(rb[g & 1][0]) : "v"(ra));
;             asm volatile("ds_read_b128 %0, %1 offset:1152" : "=&v"(rb[g & 1][1]) : "v"(ra));
;             if (g >= 1) {
;                 asm volatile("s_waitcnt lgkmcnt(4)" : "+v"(rb[(g - 1) & 1][0]), "+v"(rb[(g - 1) & 1][1]));
;                 bf16_t* ob = obase + (size_t)(((g - 1) >> 2) * HALF + ((g - 1) & 3) * 16) * ldc;
;                 *(GAS1 u32x4*)ob = rb[(g - 1) & 1][0]; *(GAS1 u32x4*)(ob + (size_t)8 * ldc) = rb[(g - 1) & 1][1];
	v_mov_b32_e32 v112, v188
	v_mov_b32_e32 v113, v189
	v_mov_b32_e32 v114, v190
	v_mov_b32_e32 v115, v191
	v_lshlrev_b32_e32 v122, 16, v112
	v_and_b32_e32 v123, 0xffff0000, v112
	v_lshlrev_b32_e32 v112, 16, v113
	v_and_b32_e32 v113, 0xffff0000, v113
	v_lshlrev_b32_e32 v124, 16, v114
	v_and_b32_e32 v125, 0xffff0000, v114
	v_lshlrev_b32_e32 v114, 16, v115
	v_and_b32_e32 v115, 0xffff0000, v115
	v_pk_mul_f32 v[102:103], v[102:103], v[112:113]
	v_pk_mul_f32 v[112:113], v[94:95], v[114:115]
	v_pk_mul_f32 v[94:95], v[92:93], v[124:125]
	v_pk_mul_f32 v[100:101], v[100:101], v[122:123]
	v_addc_co_u32_e32 v107, vcc, 0, v105, vcc
	v_cvt_pk_bf16_f32 v92, v100, v101
	v_cvt_pk_bf16_f32 v93, v102, v103
	v_cvt_pk_bf16_f32 v94, v94, v95
	v_cvt_pk_bf16_f32 v95, v112, v113
	s_nop 0
	ds_write_b128 v154, v[92:95] offset:64
	ds_read_b128 v[92:95], v155
	ds_read_b128 v[100:103], v155 offset:1152
	s_waitcnt lgkmcnt(4)
	global_store_dwordx4 v[104:105], v[108:111], off nt
	global_store_dwordx4 v[106:107], v[116:119], off nt
	s_waitcnt vmcnt(13)
	v_mov_b32_e32 v106, v192
	v_mov_b32_e32 v107, v193
	v_mov_b32_e32 v108, v194
	v_mov_b32_e32 v109, v195
	v_lshlrev_b32_e32 v110, 16, v106
	v_and_b32_e32 v111, 0xffff0000, v106
	v_lshlrev_b32_e32 v106, 16, v107
	v_and_b32_e32 v107, 0xffff0000, v107
	v_lshlrev_b32_e32 v112, 16, v108
	v_and_b32_e32 v113, 0xffff0000, v108
	v_lshlrev_b32_e32 v108, 16, v109
	v_and_b32_e32 v109, 0xffff0000, v109
	v_pk_mul_f32 v[98:99], v[98:99], v[106:107]
	v_pk_mul_f32 v[106:107], v[90:91], v[108:109]
	v_pk_mul_f32 v[90:91], v[88:89], v[112:113]
	v_pk_mul_f32 v[96:97], v[96:97], v[110:111]
	s_nop 0
	v_cvt_pk_bf16_f32 v88, v96, v97
	v_cvt_pk_bf16_f32 v89, v98, v99
	v_cvt_pk_bf16_f32 v90, v90, v91
	v_cvt_pk_bf16_f32 v91, v106, v107
	v_add_co_u32_e32 v98, vcc, s64, v104
	ds_write_b128 v154, v[88:91]
	v_or_b32_e32 v96, 48, v159
	v_addc_co_u32_e32 v99, vcc, 0, v105, vcc
	v_mad_i64_i32 v[96:97], s[34:35], v96, s74, v[146:147]
	v_add_co_u32_e32 v106, vcc, s68, v104
	v_lshl_add_u64 v[96:97], v[96:97], 0, v[148:149]
	s_nop 0
	v_addc_co_u32_e32 v107, vcc, 0, v105, vcc
	s_waitcnt vmcnt(12)
	v_mov_b32_e32 v88, v196
	v_mov_b32_e32 v89, v197
	v_mov_b32_e32 v90, v198
	v_mov_b32_e32 v91, v199
	v_lshlrev_b32_e32 v108, 16, v88
	v_and_b32_e32 v109, 0xffff0000, v88
	v_lshlrev_b32_e32 v88, 16, v89
	v_and_b32_e32 v89, 0xffff0000, v89
	v_lshlrev_b32_e32 v110, 16, v90
	v_and_b32_e32 v111, 0xffff0000, v90
	v_lshlrev_b32_e32 v90, 16, v91
	v_and_b32_e32 v91, 0xffff0000, v91
	v_pk_mul_f32 v[86:87], v[86:87], v[88:89]
	v_pk_mul_f32 v[88:89], v[78:79], v[90:91]
	v_pk_mul_f32 v[78:79], v[76:77], v[110:111]
	v_pk_mul_f32 v[84:85], v[84:85], v[108:109]
	s_nop 0
	v_cvt_pk_bf16_f32 v76, v84, v85
	v_cvt_pk_bf16_f32 v77, v86, v87
	v_cvt_pk_bf16_f32 v78, v78, v79
	v_cvt_pk_bf16_f32 v79, v88, v89
	s_nop 0
	ds_write_b128 v154, v[76:79] offset:64
	ds_read_b128 v[76:79], v155
	ds_read_b128 v[84:87], v155 offset:1152
	s_waitcnt lgkmcnt(4)
	global_store_dwordx4 v[98:99], v[92:95], off nt
	global_store_dwordx4 v[106:107], v[100:103], off nt
	s_waitcnt vmcnt(13)
	v_mov_b32_e32 v88, v202
	v_mov_b32_e32 v89, v203
	v_mov_b32_e32 v90, v204
	v_mov_b32_e32 v91, v205
	v_lshlrev_b32_e32 v92, 16, v88
	v_and_b32_e32 v93, 0xffff0000, v88
	v_lshlrev_b32_e32 v88, 16, v89
	v_and_b32_e32 v89, 0xffff0000, v89
	v_lshlrev_b32_e32 v94, 16, v90
	v_and_b32_e32 v95, 0xffff0000, v90
	v_lshlrev_b32_e32 v90, 16, v91
	v_and_b32_e32 v91, 0xffff0000, v91
	v_pk_mul_f32 v[82:83], v[82:83], v[88:89]
	v_pk_mul_f32 v[88:89], v[74:75], v[90:91]
	v_pk_mul_f32 v[74:75], v[72:73], v[94:95]
	v_pk_mul_f32 v[80:81], v[80:81], v[92:93]
	s_nop 0
	v_cvt_pk_bf16_f32 v72, v80, v81
	v_cvt_pk_bf16_f32 v73, v82, v83
	v_cvt_pk_bf16_f32 v74, v74, v75
	v_cvt_pk_bf16_f32 v75, v88, v89
	v_add_co_u32_e32 v82, vcc, s75, v104
	ds_write_b128 v154, v[72:75]
	v_add_u32_e32 v80, 0x80, v159
	v_addc_co_u32_e32 v83, vcc, 0, v105, vcc
	v_mad_i64_i32 v[80:81], s[34:35], v80, s74, v[146:147]
	v_add_co_u32_e32 v88, vcc, s76, v104
	v_lshl_add_u64 v[80:81], v[80:81], 0, v[148:149]
	s_nop 0
	v_addc_co_u32_e32 v89, vcc, 0, v105, vcc
	s_waitcnt vmcnt(12)
	v_mov_b32_e32 v72, v210
	v_mov_b32_e32 v73, v211
	v_mov_b32_e32 v74, v212
	v_mov_b32_e32 v75, v213
	v_lshlrev_b32_e32 v90, 16, v72
	v_and_b32_e32 v91, 0xffff0000, v72
	v_lshlrev_b32_e32 v72, 16, v73
	v_and_b32_e32 v73, 0xffff0000, v73
	v_lshlrev_b32_e32 v92, 16, v74
	v_and_b32_e32 v93, 0xffff0000, v74
	v_lshlrev_b32_e32 v74, 16, v75
	v_and_b32_e32 v75, 0xffff0000, v75
	v_pk_mul_f32 v[70:71], v[70:71], v[72:73]
	v_pk_mul_f32 v[72:73], v[66:67], v[74:75]
	v_pk_mul_f32 v[66:67], v[64:65], v[92:93]
	v_pk_mul_f32 v[68:69], v[68:69], v[90:91]
	s_nop 0
	v_cvt_pk_bf16_f32 v64, v68, v69
	v_cvt_pk_bf16_f32 v65, v70, v71
	v_cvt_pk_bf16_f32 v66, v66, v67
	v_cvt_pk_bf16_f32 v67, v72, v73
	s_nop 0
	ds_write_b128 v154, v[64:67] offset:64
	ds_read_b128 v[64:67], v155
	ds_read_b128 v[68:71], v155 offset:1152
	s_waitcnt lgkmcnt(4)
	global_store_dwordx4 v[82:83], v[76:79], off nt
	global_store_dwordx4 v[88:89], v[84:87], off nt
	s_waitcnt vmcnt(13)
	v_mov_b32_e32 v72, v214
	v_mov_b32_e32 v73, v215
	v_mov_b32_e32 v74, v216
	v_mov_b32_e32 v75, v217
	v_lshlrev_b32_e32 v76, 16, v72
	v_and_b32_e32 v77, 0xffff0000, v72
	v_lshlrev_b32_e32 v72, 16, v73
	v_and_b32_e32 v73, 0xffff0000, v73
	v_lshlrev_b32_e32 v78, 16, v74
	v_and_b32_e32 v79, 0xffff0000, v74
	v_lshlrev_b32_e32 v74, 16, v75
	v_and_b32_e32 v75, 0xffff0000, v75
	v_pk_mul_f32 v[62:63], v[62:63], v[72:73]
	v_pk_mul_f32 v[72:73], v[58:59], v[74:75]
	v_pk_mul_f32 v[58:59], v[56:57], v[78:79]
	v_pk_mul_f32 v[60:61], v[60:61], v[76:77]
	s_nop 0
	v_cvt_pk_bf16_f32 v56, v60, v61
	v_cvt_pk_bf16_f32 v57, v62, v63
	v_cvt_pk_bf16_f32 v58, v58, v59
	v_cvt_pk_bf16_f32 v59, v72, v73
	v_add_co_u32_e32 v62, vcc, s77, v104
	ds_write_b128 v154, v[56:59]
	v_add_u32_e32 v60, 0x90, v159
	v_addc_co_u32_e32 v63, vcc, 0, v105, vcc
	v_mad_i64_i32 v[60:61], s[34:35], v60, s74, v[146:147]
	v_add_co_u32_e32 v72, vcc, s79, v104
	v_lshl_add_u64 v[60:61], v[60:61], 0, v[148:149]
	s_nop 0
	v_addc_co_u32_e32 v73, vcc, 0, v105, vcc
	s_waitcnt vmcnt(12)
; __device__ __forceinline__ unsigned cvt_pk_bf16(float lo, float hi) { unsigned r; asm volatile("v_cvt_pk_bf16_f32 %0, %1, %2" : "=v"(r) : "v"(lo), "v"(hi)); return r; }
; __device__ __forceinline__ float bf_lo(unsigned w) { return __uint_as_float(w << 16); }
; __device__ __forceinline__ float bf_hi(unsigned w) { return __uint_as_float(w & 0xffff0000u); }
; #define GAS1 __attribute__((address_space(1)))
;     __device__ __forceinline__ void operator()(const f32x4 (&acc)[2][2][4][2], const Unit& u, int wr, int wc, int fr, int fq) const {
;     ...
;                 if (MODE == 3 || MODE == 4) {
;                     const u32x4 gw = *(const GAS1 u32x4*)(G + (size_t)row * ldg + col);
;                     const f32x4 g0 = {bf_lo(gw.x), bf_hi(gw.x), bf_lo(gw.y), bf_hi(gw.y)}, g1 = {bf_lo(gw.z), bf_hi(gw.z), bf_lo(gw.w), bf_hi(gw.w)};
;                     v0 = v0 * g0; v1 = v1 * g1;
;                     if (MODE == 4) {
;                         const u32x4 ow = *(const GAS1 u32x4*)((const bf16_t*)O + (size_t)row * ldc + col);
;                         const f32x4 o0 = {bf_lo(ow.x), bf_hi(ow.x), bf_lo(ow.y), bf_hi(ow.y)}, o1 = {bf_lo(ow.z), bf_hi(ow.z), bf_lo(ow.w), bf_hi(ow.w)};
;                         v0 += o0; v1 += o1;
;                     }
;                 }
;                 u32x4 w; w.x = cvt_pk_bf16(v0[0], v0[1]); w.y = cvt_pk_bf16(v0[2], v0[3]); w.z = cvt_pk_bf16(v1[0], v1[1]); w.w = cvt_pk_bf16(v1[2], v1[3]);
;                 if (bj == 0) asm volatile("ds_write_b128 %0, %1" :: "v"(wa), "v"(w)); else asm volatile("ds_write_b128 %0, %1 offset:64" :: "v"(wa), "v"(w));
;             }
;             asm volatile("ds_read_b128 %0, %1" : "=&v"(rb[g & 1][0]) : "v"(ra));
;             asm volatile("ds_read_b128 %0, %1 offset:1152" : "=&v"(rb[g & 1][1]) : "v"(ra));
;             if (g >= 1) {
;                 asm volatile("s_waitcnt lgkmcnt(4)" : "+v"(rb[(g - 1) & 1][0]), "+v"(rb[(g - 1) & 1][1]));
;                 bf16_t* ob = obase + (size_t)(((g - 1) >> 2) * HALF + ((g - 1) & 3) * 16) * ldc;
;                 *(GAS1 u32x4*)ob = rb[(g - 1) & 1][0]; *(GAS1 u32x4*)(ob + (size_t)8 * ldc) = rb[(g - 1) & 1][1];
	v_mov_b32_e32 v56, v218
	v_mov_b32_e32 v57, v219
	v_mov_b32_e32 v58, v220
	v_mov_b32_e32 v59, v221
	v_lshlrev_b32_e32 v74, 16, v56
	v_and_b32_e32 v75, 0xffff0000, v56
	v_lshlrev_b32_e32 v56, 16, v57
	v_and_b32_e32 v57, 0xffff0000, v57
	v_lshlrev_b32_e32 v76, 16, v58
	v_and_b32_e32 v77, 0xffff0000, v58
	v_lshlrev_b32_e32 v58, 16, v59
	v_and_b32_e32 v59, 0xffff0000, v59
	v_pk_mul_f32 v[54:55], v[54:55], v[56:57]
	v_pk_mul_f32 v[56:57], v[46:47], v[58:59]
	v_pk_mul_f32 v[46:47], v[44:45], v[76:77]
	v_pk_mul_f32 v[52:53], v[52:53], v[74:75]
	s_nop 0
	v_cvt_pk_bf16_f32 v44, v52, v53
	v_cvt_pk_bf16_f32 v45, v54, v55
	v_cvt_pk_bf16_f32 v46, v46, v47
	v_cvt_pk_bf16_f32 v47, v56, v57
	s_nop 0
	ds_write_b128 v154, v[44:47] offset:64
	ds_read_b128 v[44:47], v155
	ds_read_b128 v[52:55], v155 offset:1152
	s_waitcnt lgkmcnt(4)
	global_store_dwordx4 v[62:63], v[64:67], off nt
	global_store_dwordx4 v[72:73], v[68:71], off nt
	s_waitcnt vmcnt(13)
	v_mov_b32_e32 v56, v222
	v_mov_b32_e32 v57, v223
	v_mov_b32_e32 v58, v224
	v_mov_b32_e32 v59, v225
	v_lshlrev_b32_e32 v62, 16, v56
	v_and_b32_e32 v63, 0xffff0000, v56
	v_lshlrev_b32_e32 v56, 16, v57
	v_and_b32_e32 v57, 0xffff0000, v57
	v_lshlrev_b32_e32 v64, 16, v58
	v_and_b32_e32 v65, 0xffff0000, v58
	v_lshlrev_b32_e32 v58, 16, v59
	v_and_b32_e32 v59, 0xffff0000, v59
	v_pk_mul_f32 v[50:51], v[50:51], v[56:57]
	v_pk_mul_f32 v[56:57], v[42:43], v[58:59]
	v_pk_mul_f32 v[42:43], v[40:41], v[64:65]
	v_pk_mul_f32 v[48:49], v[48:49], v[62:63]
	s_nop 0
	v_cvt_pk_bf16_f32 v40, v48, v49
	v_cvt_pk_bf16_f32 v41, v50, v51
	v_cvt_pk_bf16_f32 v42, v42, v43
	v_cvt_pk_bf16_f32 v43, v56, v57
	v_add_co_u32_e32 v50, vcc, s80, v104
	ds_write_b128 v154, v[40:43]
	v_add_u32_e32 v48, 0xa0, v159
	v_addc_co_u32_e32 v51, vcc, 0, v105, vcc
	v_mad_i64_i32 v[48:49], s[34:35], v48, s74, v[146:147]
	v_add_co_u32_e32 v56, vcc, s81, v104
	v_lshl_add_u64 v[48:49], v[48:49], 0, v[148:149]
	s_nop 0
	v_addc_co_u32_e32 v57, vcc, 0, v105, vcc
	s_waitcnt vmcnt(12)
	v_mov_b32_e32 v40, v226
	v_mov_b32_e32 v41, v227
	v_mov_b32_e32 v42, v228
	v_mov_b32_e32 v43, v229
	v_lshlrev_b32_e32 v58, 16, v40
	v_and_b32_e32 v59, 0xffff0000, v40
	v_lshlrev_b32_e32 v40, 16, v41
	v_and_b32_e32 v41, 0xffff0000, v41
	v_lshlrev_b32_e32 v60, 16, v42
	v_and_b32_e32 v61, 0xffff0000, v42
	v_lshlrev_b32_e32 v42, 16, v43
	v_and_b32_e32 v43, 0xffff0000, v43
	v_pk_mul_f32 v[38:39], v[38:39], v[40:41]
	v_pk_mul_f32 v[40:41], v[30:31], v[42:43]
	v_pk_mul_f32 v[30:31], v[28:29], v[60:61]
	v_pk_mul_f32 v[36:37], v[36:37], v[58:59]
	s_nop 0
	v_cvt_pk_bf16_f32 v28, v36, v37
	v_cvt_pk_bf16_f32 v29, v38, v39
	v_cvt_pk_bf16_f32 v30, v30, v31
	v_cvt_pk_bf16_f32 v31, v40, v41
	s_nop 0
	ds_write_b128 v154, v[28:31] offset:64
	ds_read_b128 v[28:31], v155
	ds_read_b128 v[36:39], v155 offset:1152
	s_waitcnt lgkmcnt(4)
	global_store_dwordx4 v[50:51], v[44:47], off nt
	global_store_dwordx4 v[56:57], v[52:55], off nt
	s_waitcnt vmcnt(13)
	v_mov_b32_e32 v40, v236
	v_mov_b32_e32 v41, v237
	v_mov_b32_e32 v42, v238
	v_mov_b32_e32 v43, v239
	v_lshlrev_b32_e32 v44, 16, v40
	v_and_b32_e32 v45, 0xffff0000, v40
	v_lshlrev_b32_e32 v40, 16, v41
	v_and_b32_e32 v41, 0xffff0000, v41
	v_lshlrev_b32_e32 v46, 16, v42
	v_and_b32_e32 v47, 0xffff0000, v42
	v_lshlrev_b32_e32 v42, 16, v43
	v_and_b32_e32 v43, 0xffff0000, v43
	v_pk_mul_f32 v[34:35], v[34:35], v[40:41]
	v_pk_mul_f32 v[40:41], v[26:27], v[42:43]
	v_pk_mul_f32 v[26:27], v[24:25], v[46:47]
	v_pk_mul_f32 v[32:33], v[32:33], v[44:45]
	s_nop 0
	v_cvt_pk_bf16_f32 v24, v32, v33
	v_cvt_pk_bf16_f32 v25, v34, v35
	v_cvt_pk_bf16_f32 v26, v26, v27
	v_cvt_pk_bf16_f32 v27, v40, v41
	v_add_co_u32_e32 v34, vcc, s82, v104
	ds_write_b128 v154, v[24:27]
	v_add_u32_e32 v32, 0xb0, v159
	v_addc_co_u32_e32 v35, vcc, 0, v105, vcc
	v_mad_i64_i32 v[32:33], s[34:35], v32, s74, v[146:147]
	v_add_co_u32_e32 v40, vcc, s83, v104
	v_lshl_add_u64 v[32:33], v[32:33], 0, v[148:149]
	s_nop 0
	v_addc_co_u32_e32 v41, vcc, 0, v105, vcc
	s_waitcnt vmcnt(12)
; __device__ __forceinline__ unsigned cvt_pk_bf16(float lo, float hi) { unsigned r; asm volatile("v_cvt_pk_bf16_f32 %0, %1, %2" : "=v"(r) : "v"(lo), "v"(hi)); return r; }
; __device__ __forceinline__ float bf_lo(unsigned w) { return __uint_as_float(w << 16); }
; __device__ __forceinline__ float bf_hi(unsigned w) { return __uint_as_float(w & 0xffff0000u); }
; #define GAS1 __attribute__((address_space(1)))
;     __device__ __forceinline__ void operator()(const f32x4 (&acc)[2][2][4][2], const Unit& u, int wr, int wc, int fr, int fq) const {
;     ...
;                 if (MODE == 3 || MODE == 4) {
;                     const u32x4 gw = *(const GAS1 u32x4*)(G + (size_t)row * ldg + col);
;                     const f32x4 g0 = {bf_lo(gw.x), bf_hi(gw.x), bf_lo(gw.y), bf_hi(gw.y)}, g1 = {bf_lo(gw.z), bf_hi(gw.z), bf_lo(gw.w), bf_hi(gw.w)};
;                     v0 = v0 * g0; v1 = v1 * g1;
;                     if (MODE == 4) {
;                         const u32x4 ow = *(const GAS1 u32x4*)((const bf16_t*)O + (size_t)row * ldc + col);
;                         const f32x4 o0 = {bf_lo(ow.x), bf_hi(ow.x), bf_lo(ow.y), bf_hi(ow.y)}, o1 = {bf_lo(ow.z), bf_hi(ow.z), bf_lo(ow.w), bf_hi(ow.w)};
;                         v0 += o0; v1 += o1;
;                     }
;                 }
;                 u32x4 w; w.x = cvt_pk_bf16(v0[0], v0[1]); w.y = cvt_pk_bf16(v0[2], v0[3]); w.z = cvt_pk_bf16(v1[0], v1[1]); w.w = cvt_pk_bf16(v1[2], v1[3]);
;                 if (bj == 0) asm volatile("ds_write_b128 %0, %1" :: "v"(wa), "v"(w)); else asm volatile("ds_write_b128 %0, %1 offset:64" :: "v"(wa), "v"(w));
;             }
;             asm volatile("ds_read_b128 %0, %1" : "=&v"(rb[g & 1][0]) : "v"(ra));
;             asm volatile("ds_read_b128 %0, %1 offset:1152" : "=&v"(rb[g & 1][1]) : "v"(ra));
;             if (g >= 1) {
;                 asm volatile("s_waitcnt lgkmcnt(4)" : "+v"(rb[(g - 1) & 1][0]), "+v"(rb[(g - 1) & 1][1]));
;                 bf16_t* ob = obase + (size_t)(((g - 1) >> 2) * HALF + ((g - 1) & 3) * 16) * ldc;
;                 *(GAS1 u32x4*)ob = rb[(g - 1) & 1][0]; *(GAS1 u32x4*)(ob + (size_t)8 * ldc) = rb[(g - 1) & 1][1];
;             }
;         }
;         asm volatile("s_waitcnt lgkmcnt(0)" : "+v"(rb[1][0]), "+v"(rb[1][1]));
;         { bf16_t* ob = obase + (size_t)(HALF + 3 * 16) * ldc; *(GAS1 u32x4*)ob = rb[1][0]; *(GAS1 u32x4*)(ob + (size_t)8 * ldc) = rb[1][1]; }
	v_mov_b32_e32 v24, v240
	v_mov_b32_e32 v25, v241
	v_mov_b32_e32 v26, v242
	v_mov_b32_e32 v27, v243
	v_lshlrev_b32_e32 v42, 16, v24
	v_and_b32_e32 v43, 0xffff0000, v24
	v_lshlrev_b32_e32 v24, 16, v25
	v_and_b32_e32 v25, 0xffff0000, v25
	v_lshlrev_b32_e32 v44, 16, v26
	v_and_b32_e32 v45, 0xffff0000, v26
	v_lshlrev_b32_e32 v26, 16, v27
	v_and_b32_e32 v27, 0xffff0000, v27
	v_pk_mul_f32 v[22:23], v[22:23], v[24:25]
	v_pk_mul_f32 v[24:25], v[14:15], v[26:27]
	v_pk_mul_f32 v[14:15], v[12:13], v[44:45]
	v_pk_mul_f32 v[20:21], v[20:21], v[42:43]
	s_nop 0
	v_cvt_pk_bf16_f32 v12, v20, v21
	v_cvt_pk_bf16_f32 v13, v22, v23
	v_cvt_pk_bf16_f32 v14, v14, v15
	v_cvt_pk_bf16_f32 v15, v24, v25
	s_nop 0
	ds_write_b128 v154, v[12:15] offset:64
	ds_read_b128 v[12:15], v155
	ds_read_b128 v[20:23], v155 offset:1152
	s_waitcnt lgkmcnt(4)
	global_store_dwordx4 v[34:35], v[28:31], off nt
	global_store_dwordx4 v[40:41], v[36:39], off nt
	s_waitcnt vmcnt(13)
	v_mov_b32_e32 v24, v246
	v_mov_b32_e32 v25, v247
	v_mov_b32_e32 v26, v248
	v_mov_b32_e32 v27, v249
	v_lshlrev_b32_e32 v28, 16, v24
	v_and_b32_e32 v29, 0xffff0000, v24
	v_lshlrev_b32_e32 v24, 16, v25
	v_and_b32_e32 v25, 0xffff0000, v25
	v_lshlrev_b32_e32 v30, 16, v26
	v_and_b32_e32 v31, 0xffff0000, v26
	v_lshlrev_b32_e32 v26, 16, v27
	v_and_b32_e32 v27, 0xffff0000, v27
	v_pk_mul_f32 v[18:19], v[18:19], v[24:25]
	v_pk_mul_f32 v[24:25], v[10:11], v[26:27]
	v_pk_mul_f32 v[10:11], v[8:9], v[30:31]
	v_pk_mul_f32 v[16:17], v[16:17], v[28:29]
	s_nop 0
	v_cvt_pk_bf16_f32 v8, v16, v17
	v_cvt_pk_bf16_f32 v9, v18, v19
	v_cvt_pk_bf16_f32 v10, v10, v11
	v_cvt_pk_bf16_f32 v11, v24, v25
	v_add_co_u32_e32 v16, vcc, s84, v104
	ds_write_b128 v154, v[8:11]
	s_nop 0
	v_addc_co_u32_e32 v17, vcc, 0, v105, vcc
	v_add_co_u32_e32 v18, vcc, s85, v104
	s_waitcnt vmcnt(12)
	v_mov_b32_e32 v8, v250
	v_mov_b32_e32 v9, v251
	v_mov_b32_e32 v10, v252
	v_mov_b32_e32 v11, v253
	v_lshlrev_b32_e32 v28, 16, v8
	v_addc_co_u32_e32 v19, vcc, 0, v105, vcc
	v_add_co_u32_e32 v24, vcc, 0xb0000, v104
	v_and_b32_e32 v29, 0xffff0000, v8
	v_lshlrev_b32_e32 v8, 16, v9
	v_and_b32_e32 v9, 0xffff0000, v9
	v_lshlrev_b32_e32 v30, 16, v10
	v_and_b32_e32 v31, 0xffff0000, v10
	v_lshlrev_b32_e32 v10, 16, v11
	v_and_b32_e32 v11, 0xffff0000, v11
	v_addc_co_u32_e32 v25, vcc, 0, v105, vcc
	v_pk_mul_f32 v[6:7], v[6:7], v[8:9]
	v_pk_mul_f32 v[8:9], v[2:3], v[10:11]
	v_pk_mul_f32 v[2:3], v[0:1], v[30:31]
	v_add_co_u32_e32 v26, vcc, 0xb8000, v104
	v_pk_mul_f32 v[4:5], v[4:5], v[28:29]
	s_nop 0
	v_addc_co_u32_e32 v27, vcc, 0, v105, vcc
	v_cvt_pk_bf16_f32 v0, v4, v5
	v_cvt_pk_bf16_f32 v1, v6, v7
	v_cvt_pk_bf16_f32 v2, v2, v3
	v_cvt_pk_bf16_f32 v3, v8, v9
	s_andn2_b64 vcc, exec, s[6:7]
	ds_write_b128 v154, v[0:3] offset:64
	ds_read_b128 v[0:3], v155
	ds_read_b128 v[4:7], v155 offset:1152
	s_waitcnt lgkmcnt(4)
	global_store_dwordx4 v[16:17], v[12:15], off nt
	global_store_dwordx4 v[18:19], v[20:23], off nt
	s_waitcnt lgkmcnt(0)
	s_mov_b64 s[6:7], -1
	global_store_dwordx4 v[24:25], v[0:3], off nt
	global_store_dwordx4 v[26:27], v[4:7], off nt
	s_cbranch_vccnz .LBB0_1399
	s_andn2_b64 vcc, exec, s[16:17]
	s_cbranch_vccnz .LBB0_1398
	s_barrier
	s_branch .LBB0_1398

; #define PG8_LAS __attribute__((address_space(3)))
; #define GAS1 __attribute__((address_space(1)))
;     __device__ __forceinline__ void operator()(const f32x4 (&acc)[2][2][4][2], const Unit& u, int wr, int wc, int fr, int fq) const {
;         const int row0 = u.pm * BM + wr * 64 + fr, col0 = u.pn * BM + wc * 64 + 8 * fq;
;         PG8_LAS unsigned char* sl = stg + (wr * 4 + wc) * 2304; const int L = fq * 16 + fr;
;         const unsigned wa = (unsigned)(size_t)(sl + fr * 144 + fq * 16), ra = (unsigned)(size_t)(sl + (L >> 3) * 144 + (L & 7) * 16);
;         const bool special = (MODE == 1) ? (u.pn < ntile_special) : (MODE == 2 ? (u.pn >= ntile_special) : false);
;         u32x4 rb[2][2];
;         bf16_t* obase = (bf16_t*)O + (size_t)(u.pm * BM + wr * 64 + (L >> 3)) * ldc + u.pn * BM + wc * 64 + 8 * (L & 7);
; #pragma unroll
;         for (int g = 0; g < 8; ++g) {
;             const int ai = g >> 2, m = g & 3;
;             const int row = row0 + ai * HALF + m * 16;
; #pragma unroll
;             for (int bj = 0; bj < 2; ++bj) {
;                 const int col = col0 + bj * 32;
;                 f32x4 v0 = acc[ai][bj][m][0], v1 = acc[ai][bj][m][1];
;                 if (MODE == 1) {
;                     if (special) {
;                         const f32x4 b0 = *(const GAS1 f32x4*)(bias + col) * -1.4426950408889634f, b1 = *(const GAS1 f32x4*)(bias + col + 4) * -1.4426950408889634f;
; #pragma unroll
;                         for (int j = 0; j < 4; ++j) { v0[j] = __builtin_amdgcn_rcpf(1.0f + __builtin_amdgcn_exp2f(__builtin_fmaf(v0[j], -1.4426950408889634f, b0[j])));
;                                                       v1[j] = __builtin_amdgcn_rcpf(1.0f + __builtin_amdgcn_exp2f(__builtin_fmaf(v1[j], -1.4426950408889634f, b1[j]))); }
;                     }
;                 }
;                 if (MODE == 2) {
;                     if (special) {
;                         const int fi = ((col & 63) >> 3) * 4;
;                         const f32x4 c = *(const GAS1 f32x4*)(cosT + (size_t)row * 32 + fi), s_ = *(const GAS1 f32x4*)(sinT + (size_t)row * 32 + fi);
;                         const f32x4 o1 = v0 * c - v1 * s_, o2 = v1 * c + v0 * s_; v0 = o1; v1 = o2;
;                     }
;                 }
;                 if (MODE == 3 || MODE == 4) {
;                     const u32x4 gw = *(const GAS1 u32x4*)(G + (size_t)row * ldg + col);
.LBB0_1434:
	s_lshl_b32 s21, s28, 8
	s_add_i32 s21, s21, s63
	v_or_b32_e32 v148, s21, v152
	s_lshl_b32 s28, s29, 8
	v_or_b32_e32 v146, s28, v155
	v_ashrrev_i32_e32 v149, 31, v148
	v_mov_b64_e32 v[150:151], s[14:15]
	v_ashrrev_i32_e32 v147, 31, v146
	v_lshlrev_b64 v[166:167], 12, v[148:149]
	v_mad_i64_i32 v[162:163], s[30:31], v148, s72, v[150:151]
	v_lshlrev_b64 v[146:147], 1, v[146:147]
	v_lshl_add_u64 v[166:167], s[8:9], 0, v[166:167]
	v_lshl_add_u64 v[176:177], v[162:163], 0, v[146:147]
	v_lshl_add_u64 v[178:179], v[166:167], 0, v[146:147]
	v_add_u32_e32 v254, 0, v148
	v_ashrrev_i32_e32 v255, 31, v254
	v_mad_i64_i32 v[206:207], s[98:99], v254, s72, v[150:151]
	v_lshlrev_b64 v[232:233], 12, v[254:255]
	v_lshl_add_u64 v[206:207], v[206:207], 0, v[146:147]
	v_lshl_add_u64 v[232:233], s[8:9], 0, v[232:233]
	v_lshl_add_u64 v[232:233], v[232:233], 0, v[146:147]
	global_load_dwordx4 v[188:191], v[206:207], off
	global_load_dwordx4 v[192:195], v[232:233], off
	global_load_dwordx4 v[196:199], v[206:207], off offset:64
	global_load_dwordx4 v[202:205], v[232:233], off offset:64
	v_add_u32_e32 v254, 16, v148
	v_ashrrev_i32_e32 v255, 31, v254
	v_mad_i64_i32 v[206:207], s[98:99], v254, s72, v[150:151]
	v_lshlrev_b64 v[232:233], 12, v[254:255]
	v_lshl_add_u64 v[206:207], v[206:207], 0, v[146:147]
	v_lshl_add_u64 v[232:233], s[8:9], 0, v[232:233]
	v_lshl_add_u64 v[232:233], v[232:233], 0, v[146:147]
	global_load_dwordx4 v[210:213], v[206:207], off
	global_load_dwordx4 v[214:217], v[232:233], off
	global_load_dwordx4 v[218:221], v[206:207], off offset:64
	global_load_dwordx4 v[222:225], v[232:233], off offset:64
	v_add_u32_e32 v254, 32, v148
	v_ashrrev_i32_e32 v255, 31, v254
	v_mad_i64_i32 v[206:207], s[98:99], v254, s72, v[150:151]
	v_lshlrev_b64 v[232:233], 12, v[254:255]
	v_lshl_add_u64 v[206:207], v[206:207], 0, v[146:147]
	v_lshl_add_u64 v[232:233], s[8:9], 0, v[232:233]
	v_lshl_add_u64 v[232:233], v[232:233], 0, v[146:147]
	global_load_dwordx4 v[226:229], v[206:207], off
	global_load_dwordx4 v[236:239], v[232:233], off
	global_load_dwordx4 v[240:243], v[206:207], off offset:64
	global_load_dwordx4 v[246:249], v[232:233], off offset:64
	s_ashr_i32 s29, s28, 31
	s_waitcnt vmcnt(10)
	v_mov_b32_e32 v162, v188
	v_mov_b32_e32 v163, v189
	v_mov_b32_e32 v164, v190
	v_mov_b32_e32 v165, v191
	v_mov_b32_e32 v166, v192
	v_mov_b32_e32 v167, v193
	v_mov_b32_e32 v168, v194
	v_mov_b32_e32 v169, v195
	v_lshlrev_b32_e32 v180, 16, v162
	v_and_b32_e32 v181, 0xffff0000, v162
	v_lshlrev_b32_e32 v162, 16, v163
	v_and_b32_e32 v163, 0xffff0000, v163
	v_lshlrev_b32_e32 v182, 16, v164
	v_and_b32_e32 v183, 0xffff0000, v164
	v_lshlrev_b32_e32 v164, 16, v165
	v_and_b32_e32 v165, 0xffff0000, v165
	v_lshlrev_b32_e32 v184, 16, v166
	v_and_b32_e32 v185, 0xffff0000, v166
	v_lshlrev_b32_e32 v166, 16, v167
	v_and_b32_e32 v167, 0xffff0000, v167
	v_lshlrev_b32_e32 v186, 16, v168
	v_and_b32_e32 v187, 0xffff0000, v168
	v_lshlrev_b32_e32 v168, 16, v169
	v_and_b32_e32 v169, 0xffff0000, v169
	v_pk_fma_f32 v[126:127], v[126:127], v[162:163], v[166:167]
	v_pk_fma_f32 v[162:163], v[122:123], v[164:165], v[168:169]
	v_pk_fma_f32 v[122:123], v[120:121], v[182:183], v[186:187]
	v_pk_fma_f32 v[124:125], v[124:125], v[180:181], v[184:185]
	s_nop 0
	v_cvt_pk_bf16_f32 v120, v124, v125
	v_cvt_pk_bf16_f32 v121, v126, v127
	v_cvt_pk_bf16_f32 v122, v122, v123
	v_cvt_pk_bf16_f32 v123, v162, v163
	v_or_b32_e32 v162, 16, v148
	ds_write_b128 v156, v[120:123]
	v_ashrrev_i32_e32 v163, 31, v162
	v_mad_i64_i32 v[164:165], s[30:31], v162, s72, v[150:151]
	v_lshl_add_u64 v[164:165], v[164:165], 0, v[146:147]
	s_waitcnt vmcnt(9)
	v_mov_b32_e32 v120, v196
	v_mov_b32_e32 v121, v197
	v_mov_b32_e32 v122, v198
	v_mov_b32_e32 v123, v199
	v_lshlrev_b32_e32 v166, 16, v120
	v_and_b32_e32 v167, 0xffff0000, v120
	v_lshlrev_b32_e32 v120, 16, v121
	v_and_b32_e32 v121, 0xffff0000, v121
	s_waitcnt vmcnt(8)
	v_mov_b32_e32 v124, v202
	v_mov_b32_e32 v125, v203
	v_mov_b32_e32 v126, v204
	v_mov_b32_e32 v127, v205
	v_lshlrev_b32_e32 v176, 16, v124
	v_and_b32_e32 v177, 0xffff0000, v124
	v_lshlrev_b32_e32 v124, 16, v125
	v_and_b32_e32 v125, 0xffff0000, v125
	v_lshlrev_b32_e32 v168, 16, v122
	v_and_b32_e32 v169, 0xffff0000, v122
	v_lshlrev_b32_e32 v122, 16, v123
	v_and_b32_e32 v123, 0xffff0000, v123
	v_lshlrev_b32_e32 v178, 16, v126
	v_and_b32_e32 v179, 0xffff0000, v126
	v_lshlrev_b32_e32 v126, 16, v127
	v_and_b32_e32 v127, 0xffff0000, v127
	v_pk_fma_f32 v[118:119], v[118:119], v[120:121], v[124:125]
	v_lshlrev_b64 v[124:125], 12, v[162:163]
	v_pk_fma_f32 v[120:121], v[114:115], v[122:123], v[126:127]
	v_pk_fma_f32 v[114:115], v[112:113], v[168:169], v[178:179]
	v_lshl_add_u64 v[124:125], s[8:9], 0, v[124:125]
	v_pk_fma_f32 v[116:117], v[116:117], v[166:167], v[176:177]
	v_lshl_add_u64 v[162:163], v[124:125], 0, v[146:147]
	v_cvt_pk_bf16_f32 v112, v116, v117
	v_cvt_pk_bf16_f32 v113, v118, v119
	v_cvt_pk_bf16_f32 v114, v114, v115
	v_cvt_pk_bf16_f32 v115, v120, v121
	s_nop 0
	ds_write_b128 v156, v[112:115] offset:64
	ds_read_b128 v[112:115], v157
	ds_read_b128 v[116:119], v157 offset:1152
	s_waitcnt vmcnt(7)
	v_mov_b32_e32 v120, v210
	v_mov_b32_e32 v121, v211
	v_mov_b32_e32 v122, v212
	v_mov_b32_e32 v123, v213
	v_lshlrev_b32_e32 v166, 16, v120
	v_and_b32_e32 v167, 0xffff0000, v120
	v_lshlrev_b32_e32 v120, 16, v121
	v_and_b32_e32 v121, 0xffff0000, v121
	v_lshlrev_b32_e32 v168, 16, v122
	v_and_b32_e32 v169, 0xffff0000, v122
	v_lshlrev_b32_e32 v122, 16, v123
	v_and_b32_e32 v123, 0xffff0000, v123
	s_waitcnt vmcnt(6)
; __device__ __forceinline__ unsigned cvt_pk_bf16(float lo, float hi) { unsigned r; asm volatile("v_cvt_pk_bf16_f32 %0, %1, %2" : "=v"(r) : "v"(lo), "v"(hi)); return r; }
; __device__ __forceinline__ float bf_lo(unsigned w) { return __uint_as_float(w << 16); }
; __device__ __forceinline__ float bf_hi(unsigned w) { return __uint_as_float(w & 0xffff0000u); }
; #define GAS1 __attribute__((address_space(1)))
;     __device__ __forceinline__ void operator()(const f32x4 (&acc)[2][2][4][2], const Unit& u, int wr, int wc, int fr, int fq) const {
;     ...
;                 if (MODE == 3 || MODE == 4) {
;                     const u32x4 gw = *(const GAS1 u32x4*)(G + (size_t)row * ldg + col);
;                     const f32x4 g0 = {bf_lo(gw.x), bf_hi(gw.x), bf_lo(gw.y), bf_hi(gw.y)}, g1 = {bf_lo(gw.z), bf_hi(gw.z), bf_lo(gw.w), bf_hi(gw.w)};
;                     v0 = v0 * g0; v1 = v1 * g1;
;                     if (MODE == 4) {
;                         const u32x4 ow = *(const GAS1 u32x4*)((const bf16_t*)O + (size_t)row * ldc + col);
;                         const f32x4 o0 = {bf_lo(ow.x), bf_hi(ow.x), bf_lo(ow.y), bf_hi(ow.y)}, o1 = {bf_lo(ow.z), bf_hi(ow.z), bf_lo(ow.w), bf_hi(ow.w)};
;                         v0 += o0; v1 += o1;
;                     }
;                 }
;                 u32x4 w; w.x = cvt_pk_bf16(v0[0], v0[1]); w.y = cvt_pk_bf16(v0[2], v0[3]); w.z = cvt_pk_bf16(v1[0], v1[1]); w.w = cvt_pk_bf16(v1[2], v1[3]);
;                 if (bj == 0) asm volatile("ds_write_b128 %0, %1" :: "v"(wa), "v"(w)); else asm volatile("ds_write_b128 %0, %1 offset:64" :: "v"(wa), "v"(w));
;             }
;             asm volatile("ds_read_b128 %0, %1" : "=&v"(rb[g & 1][0]) : "v"(ra));
;             asm volatile("ds_read_b128 %0, %1 offset:1152" : "=&v"(rb[g & 1][1]) : "v"(ra));
;             if (g >= 1) {
;                 asm volatile("s_waitcnt lgkmcnt(4)" : "+v"(rb[(g - 1) & 1][0]), "+v"(rb[(g - 1) & 1][1]));
;                 bf16_t* ob = obase + (size_t)(((g - 1) >> 2) * HALF + ((g - 1) & 3) * 16) * ldc;
;                 *(GAS1 u32x4*)ob = rb[(g - 1) & 1][0]; *(GAS1 u32x4*)(ob + (size_t)8 * ldc) = rb[(g - 1) & 1][1];
	v_mov_b32_e32 v124, v214
	v_mov_b32_e32 v125, v215
	v_mov_b32_e32 v126, v216
	v_mov_b32_e32 v127, v217
	v_lshlrev_b32_e32 v176, 16, v124
	v_and_b32_e32 v177, 0xffff0000, v124
	v_lshlrev_b32_e32 v124, 16, v125
	v_and_b32_e32 v125, 0xffff0000, v125
	v_lshlrev_b32_e32 v178, 16, v126
	v_and_b32_e32 v179, 0xffff0000, v126
	v_lshlrev_b32_e32 v126, 16, v127
	v_and_b32_e32 v127, 0xffff0000, v127
	v_pk_fma_f32 v[110:111], v[110:111], v[120:121], v[124:125]
	v_pk_fma_f32 v[120:121], v[106:107], v[122:123], v[126:127]
	v_pk_fma_f32 v[106:107], v[104:105], v[168:169], v[178:179]
	v_pk_fma_f32 v[108:109], v[108:109], v[166:167], v[176:177]
	s_nop 0
	v_cvt_pk_bf16_f32 v104, v108, v109
	v_cvt_pk_bf16_f32 v105, v110, v111
	v_cvt_pk_bf16_f32 v106, v106, v107
	v_cvt_pk_bf16_f32 v107, v120, v121
	v_or_b32_e32 v110, 32, v148
	ds_write_b128 v156, v[104:107]
	v_or_b32_e32 v104, s21, v154
	v_ashrrev_i32_e32 v105, 31, v104
	v_lshlrev_b64 v[104:105], 12, v[104:105]
	v_lshl_add_u64 v[104:105], s[8:9], 0, v[104:105]
	v_lshl_add_u64 v[104:105], s[28:29], 1, v[104:105]
	v_lshl_add_u64 v[104:105], v[104:105], 0, s[10:11]
	v_ashrrev_i32_e32 v111, 31, v110
	v_mad_i64_i32 v[124:125], s[30:31], v110, s72, v[150:151]
	v_lshl_add_u64 v[104:105], v[104:105], 0, v[136:137]
	v_lshlrev_b64 v[110:111], 12, v[110:111]
	v_add_co_u32_e32 v126, vcc, s67, v104
	v_lshl_add_u64 v[110:111], s[8:9], 0, v[110:111]
	v_lshl_add_u64 v[124:125], v[124:125], 0, v[146:147]
	v_addc_co_u32_e32 v127, vcc, 0, v105, vcc
	s_waitcnt vmcnt(5)
	v_mov_b32_e32 v106, v218
	v_mov_b32_e32 v107, v219
	v_mov_b32_e32 v108, v220
	v_mov_b32_e32 v109, v221
	v_lshlrev_b32_e32 v162, 16, v106
	v_and_b32_e32 v163, 0xffff0000, v106
	v_lshlrev_b32_e32 v106, 16, v107
	v_and_b32_e32 v107, 0xffff0000, v107
	v_lshlrev_b32_e32 v164, 16, v108
	v_and_b32_e32 v165, 0xffff0000, v108
	v_lshlrev_b32_e32 v108, 16, v109
	v_and_b32_e32 v109, 0xffff0000, v109
	s_waitcnt vmcnt(4)
	v_mov_b32_e32 v120, v222
	v_mov_b32_e32 v121, v223
	v_mov_b32_e32 v122, v224
	v_mov_b32_e32 v123, v225
	v_lshlrev_b32_e32 v166, 16, v120
	v_and_b32_e32 v167, 0xffff0000, v120
	v_lshlrev_b32_e32 v120, 16, v121
	v_and_b32_e32 v121, 0xffff0000, v121
	v_lshlrev_b32_e32 v168, 16, v122
	v_and_b32_e32 v169, 0xffff0000, v122
	v_lshlrev_b32_e32 v122, 16, v123
	v_and_b32_e32 v123, 0xffff0000, v123
	v_pk_fma_f32 v[102:103], v[102:103], v[106:107], v[120:121]
	v_pk_fma_f32 v[106:107], v[98:99], v[108:109], v[122:123]
	v_pk_fma_f32 v[98:99], v[96:97], v[164:165], v[168:169]
	v_pk_fma_f32 v[100:101], v[100:101], v[162:163], v[166:167]
	s_nop 0
	v_cvt_pk_bf16_f32 v96, v100, v101
	v_cvt_pk_bf16_f32 v97, v102, v103
	v_cvt_pk_bf16_f32 v98, v98, v99
	v_cvt_pk_bf16_f32 v99, v106, v107
	s_nop 0
	ds_write_b128 v156, v[96:99] offset:64
	ds_read_b128 v[96:99], v157
	ds_read_b128 v[100:103], v157 offset:1152
	s_waitcnt lgkmcnt(4)
	global_store_dwordx4 v[104:105], v[112:115], off nt
	global_store_dwordx4 v[126:127], v[116:119], off nt
	v_lshl_add_u64 v[114:115], v[110:111], 0, v[146:147]
	s_waitcnt vmcnt(5)
	v_mov_b32_e32 v106, v226
	v_mov_b32_e32 v107, v227
	v_mov_b32_e32 v108, v228
	v_mov_b32_e32 v109, v229
	v_lshlrev_b32_e32 v116, 16, v106
	v_and_b32_e32 v117, 0xffff0000, v106
	v_lshlrev_b32_e32 v106, 16, v107
	v_and_b32_e32 v107, 0xffff0000, v107
	v_lshlrev_b32_e32 v118, 16, v108
	v_and_b32_e32 v119, 0xffff0000, v108
	v_lshlrev_b32_e32 v108, 16, v109
	v_and_b32_e32 v109, 0xffff0000, v109
	s_waitcnt vmcnt(4)
	v_mov_b32_e32 v110, v236
	v_mov_b32_e32 v111, v237
	v_mov_b32_e32 v112, v238
	v_mov_b32_e32 v113, v239
	v_lshlrev_b32_e32 v120, 16, v110
	v_and_b32_e32 v121, 0xffff0000, v110
	v_lshlrev_b32_e32 v110, 16, v111
	v_and_b32_e32 v111, 0xffff0000, v111
	v_lshlrev_b32_e32 v122, 16, v112
	v_and_b32_e32 v123, 0xffff0000, v112
	v_lshlrev_b32_e32 v112, 16, v113
	v_and_b32_e32 v113, 0xffff0000, v113
	v_pk_fma_f32 v[94:95], v[94:95], v[106:107], v[110:111]
	v_pk_fma_f32 v[106:107], v[90:91], v[108:109], v[112:113]
	v_pk_fma_f32 v[90:91], v[88:89], v[118:119], v[122:123]
	v_pk_fma_f32 v[92:93], v[92:93], v[116:117], v[120:121]
	v_add_co_u32_e32 v110, vcc, s62, v104
	v_cvt_pk_bf16_f32 v88, v92, v93
	v_cvt_pk_bf16_f32 v89, v94, v95
	v_cvt_pk_bf16_f32 v90, v90, v91
	v_cvt_pk_bf16_f32 v91, v106, v107
	v_or_b32_e32 v106, 48, v148
	ds_write_b128 v156, v[88:91]
	v_ashrrev_i32_e32 v107, 31, v106
	v_addc_co_u32_e32 v111, vcc, 0, v105, vcc
	v_mad_i64_i32 v[108:109], s[28:29], v106, s72, v[150:151]
	v_add_co_u32_e32 v112, vcc, s66, v104
	v_lshl_add_u64 v[108:109], v[108:109], 0, v[146:147]
	s_nop 0
	v_addc_co_u32_e32 v113, vcc, 0, v105, vcc
	s_waitcnt vmcnt(3)
	v_mov_b32_e32 v88, v240
	v_mov_b32_e32 v89, v241
	v_mov_b32_e32 v90, v242
	v_mov_b32_e32 v91, v243
	v_lshlrev_b32_e32 v114, 16, v88
	v_and_b32_e32 v115, 0xffff0000, v88
	v_lshlrev_b32_e32 v88, 16, v89
	v_and_b32_e32 v89, 0xffff0000, v89
	v_lshlrev_b32_e32 v116, 16, v90
	v_and_b32_e32 v117, 0xffff0000, v90
	v_lshlrev_b32_e32 v90, 16, v91
	v_and_b32_e32 v91, 0xffff0000, v91
	s_waitcnt vmcnt(2)
; __device__ __forceinline__ unsigned cvt_pk_bf16(float lo, float hi) { unsigned r; asm volatile("v_cvt_pk_bf16_f32 %0, %1, %2" : "=v"(r) : "v"(lo), "v"(hi)); return r; }
; __device__ __forceinline__ float bf_lo(unsigned w) { return __uint_as_float(w << 16); }
; __device__ __forceinline__ float bf_hi(unsigned w) { return __uint_as_float(w & 0xffff0000u); }
; #define GAS1 __attribute__((address_space(1)))
;     __device__ __forceinline__ void operator()(const f32x4 (&acc)[2][2][4][2], const Unit& u, int wr, int wc, int fr, int fq) const {
;     ...
;                 if (MODE == 3 || MODE == 4) {
;                     const u32x4 gw = *(const GAS1 u32x4*)(G + (size_t)row * ldg + col);
;                     const f32x4 g0 = {bf_lo(gw.x), bf_hi(gw.x), bf_lo(gw.y), bf_hi(gw.y)}, g1 = {bf_lo(gw.z), bf_hi(gw.z), bf_lo(gw.w), bf_hi(gw.w)};
;                     v0 = v0 * g0; v1 = v1 * g1;
;                     if (MODE == 4) {
;                         const u32x4 ow = *(const GAS1 u32x4*)((const bf16_t*)O + (size_t)row * ldc + col);
;                         const f32x4 o0 = {bf_lo(ow.x), bf_hi(ow.x), bf_lo(ow.y), bf_hi(ow.y)}, o1 = {bf_lo(ow.z), bf_hi(ow.z), bf_lo(ow.w), bf_hi(ow.w)};
;                         v0 += o0; v1 += o1;
;                     }
;                 }
;                 u32x4 w; w.x = cvt_pk_bf16(v0[0], v0[1]); w.y = cvt_pk_bf16(v0[2], v0[3]); w.z = cvt_pk_bf16(v1[0], v1[1]); w.w = cvt_pk_bf16(v1[2], v1[3]);
;                 if (bj == 0) asm volatile("ds_write_b128 %0, %1" :: "v"(wa), "v"(w)); else asm volatile("ds_write_b128 %0, %1 offset:64" :: "v"(wa), "v"(w));
;             }
;             asm volatile("ds_read_b128 %0, %1" : "=&v"(rb[g & 1][0]) : "v"(ra));
;             asm volatile("ds_read_b128 %0, %1 offset:1152" : "=&v"(rb[g & 1][1]) : "v"(ra));
;             if (g >= 1) {
;                 asm volatile("s_waitcnt lgkmcnt(4)" : "+v"(rb[(g - 1) & 1][0]), "+v"(rb[(g - 1) & 1][1]));
;                 bf16_t* ob = obase + (size_t)(((g - 1) >> 2) * HALF + ((g - 1) & 3) * 16) * ldc;
;                 *(GAS1 u32x4*)ob = rb[(g - 1) & 1][0]; *(GAS1 u32x4*)(ob + (size_t)8 * ldc) = rb[(g - 1) & 1][1];
	v_mov_b32_e32 v92, v246
	v_mov_b32_e32 v93, v247
	v_mov_b32_e32 v94, v248
	v_mov_b32_e32 v95, v249
	v_add_u32_e32 v254, 48, v148
	v_ashrrev_i32_e32 v255, 31, v254
	v_mad_i64_i32 v[206:207], s[98:99], v254, s72, v[150:151]
	v_lshlrev_b64 v[232:233], 12, v[254:255]
	v_lshl_add_u64 v[206:207], v[206:207], 0, v[146:147]
	v_lshl_add_u64 v[232:233], s[8:9], 0, v[232:233]
	v_lshl_add_u64 v[232:233], v[232:233], 0, v[146:147]
	global_load_dwordx4 v[188:191], v[206:207], off
	global_load_dwordx4 v[192:195], v[232:233], off
	global_load_dwordx4 v[196:199], v[206:207], off offset:64
	global_load_dwordx4 v[202:205], v[232:233], off offset:64
	v_add_u32_e32 v254, 128, v148
	v_ashrrev_i32_e32 v255, 31, v254
	v_mad_i64_i32 v[206:207], s[98:99], v254, s72, v[150:151]
	v_lshlrev_b64 v[232:233], 12, v[254:255]
	v_lshl_add_u64 v[206:207], v[206:207], 0, v[146:147]
	v_lshl_add_u64 v[232:233], s[8:9], 0, v[232:233]
	v_lshl_add_u64 v[232:233], v[232:233], 0, v[146:147]
	global_load_dwordx4 v[210:213], v[206:207], off
	global_load_dwordx4 v[214:217], v[232:233], off
	global_load_dwordx4 v[218:221], v[206:207], off offset:64
	global_load_dwordx4 v[222:225], v[232:233], off offset:64
	v_add_u32_e32 v254, 144, v148
	v_ashrrev_i32_e32 v255, 31, v254
	v_mad_i64_i32 v[206:207], s[98:99], v254, s72, v[150:151]
	v_lshlrev_b64 v[232:233], 12, v[254:255]
	v_lshl_add_u64 v[206:207], v[206:207], 0, v[146:147]
	v_lshl_add_u64 v[232:233], s[8:9], 0, v[232:233]
	v_lshl_add_u64 v[232:233], v[232:233], 0, v[146:147]
	global_load_dwordx4 v[226:229], v[206:207], off
	global_load_dwordx4 v[236:239], v[232:233], off
	global_load_dwordx4 v[240:243], v[206:207], off offset:64
	global_load_dwordx4 v[246:249], v[232:233], off offset:64
	v_lshlrev_b32_e32 v118, 16, v92
	v_and_b32_e32 v119, 0xffff0000, v92
	v_lshlrev_b32_e32 v92, 16, v93
	v_and_b32_e32 v93, 0xffff0000, v93
	v_lshlrev_b32_e32 v120, 16, v94
	v_and_b32_e32 v121, 0xffff0000, v94
	v_lshlrev_b32_e32 v94, 16, v95
	v_and_b32_e32 v95, 0xffff0000, v95
	v_pk_fma_f32 v[86:87], v[86:87], v[88:89], v[92:93]
	v_pk_fma_f32 v[88:89], v[82:83], v[90:91], v[94:95]
	v_pk_fma_f32 v[82:83], v[80:81], v[116:117], v[120:121]
	v_pk_fma_f32 v[84:85], v[84:85], v[114:115], v[118:119]
	v_lshlrev_b64 v[92:93], 12, v[106:107]
	v_cvt_pk_bf16_f32 v80, v84, v85
	v_cvt_pk_bf16_f32 v81, v86, v87
	v_cvt_pk_bf16_f32 v82, v82, v83
	v_cvt_pk_bf16_f32 v83, v88, v89
	v_lshl_add_u64 v[92:93], s[8:9], 0, v[92:93]
	ds_write_b128 v156, v[80:83] offset:64
	ds_read_b128 v[80:83], v157
	ds_read_b128 v[84:87], v157 offset:1152
	s_waitcnt lgkmcnt(4)
	global_store_dwordx4 v[110:111], v[96:99], off nt
	global_store_dwordx4 v[112:113], v[100:103], off nt
	v_lshl_add_u64 v[96:97], v[92:93], 0, v[146:147]
	s_waitcnt vmcnt(13)
	v_mov_b32_e32 v88, v188
	v_mov_b32_e32 v89, v189
	v_mov_b32_e32 v90, v190
	v_mov_b32_e32 v91, v191
	v_lshlrev_b32_e32 v98, 16, v88
	v_and_b32_e32 v99, 0xffff0000, v88
	v_lshlrev_b32_e32 v88, 16, v89
	v_and_b32_e32 v89, 0xffff0000, v89
	v_lshlrev_b32_e32 v100, 16, v90
	v_and_b32_e32 v101, 0xffff0000, v90
	v_lshlrev_b32_e32 v90, 16, v91
	v_and_b32_e32 v91, 0xffff0000, v91
	s_waitcnt vmcnt(12)
	v_mov_b32_e32 v92, v192
	v_mov_b32_e32 v93, v193
	v_mov_b32_e32 v94, v194
	v_mov_b32_e32 v95, v195
	v_lshlrev_b32_e32 v102, 16, v92
	v_and_b32_e32 v103, 0xffff0000, v92
	v_lshlrev_b32_e32 v92, 16, v93
	v_and_b32_e32 v93, 0xffff0000, v93
	v_lshlrev_b32_e32 v106, 16, v94
	v_and_b32_e32 v107, 0xffff0000, v94
	v_lshlrev_b32_e32 v94, 16, v95
	v_and_b32_e32 v95, 0xffff0000, v95
	v_pk_fma_f32 v[78:79], v[78:79], v[88:89], v[92:93]
	v_pk_fma_f32 v[88:89], v[74:75], v[90:91], v[94:95]
	v_pk_fma_f32 v[74:75], v[72:73], v[100:101], v[106:107]
	v_pk_fma_f32 v[76:77], v[76:77], v[98:99], v[102:103]
	v_add_co_u32_e32 v92, vcc, s73, v104
	v_cvt_pk_bf16_f32 v72, v76, v77
	v_cvt_pk_bf16_f32 v73, v78, v79
	v_cvt_pk_bf16_f32 v74, v74, v75
	v_cvt_pk_bf16_f32 v75, v88, v89
	v_add_u32_e32 v88, 0x80, v148
	ds_write_b128 v156, v[72:75]
	v_ashrrev_i32_e32 v89, 31, v88
	v_addc_co_u32_e32 v93, vcc, 0, v105, vcc
	v_mad_i64_i32 v[90:91], s[28:29], v88, s72, v[150:151]
	v_add_co_u32_e32 v94, vcc, s74, v104
	v_lshl_add_u64 v[90:91], v[90:91], 0, v[146:147]
	s_nop 0
	v_addc_co_u32_e32 v95, vcc, 0, v105, vcc
	s_waitcnt vmcnt(11)
	v_mov_b32_e32 v72, v196
	v_mov_b32_e32 v73, v197
	v_mov_b32_e32 v74, v198
	v_mov_b32_e32 v75, v199
	v_lshlrev_b32_e32 v96, 16, v72
	v_and_b32_e32 v97, 0xffff0000, v72
	v_lshlrev_b32_e32 v72, 16, v73
	v_and_b32_e32 v73, 0xffff0000, v73
	v_lshlrev_b32_e32 v98, 16, v74
	v_and_b32_e32 v99, 0xffff0000, v74
	v_lshlrev_b32_e32 v74, 16, v75
	v_and_b32_e32 v75, 0xffff0000, v75
	s_waitcnt vmcnt(10)
	v_mov_b32_e32 v76, v202
	v_mov_b32_e32 v77, v203
	v_mov_b32_e32 v78, v204
	v_mov_b32_e32 v79, v205
	v_lshlrev_b32_e32 v100, 16, v76
	v_and_b32_e32 v101, 0xffff0000, v76
	v_lshlrev_b32_e32 v76, 16, v77
	v_and_b32_e32 v77, 0xffff0000, v77
	v_lshlrev_b32_e32 v102, 16, v78
	v_and_b32_e32 v103, 0xffff0000, v78
	v_lshlrev_b32_e32 v78, 16, v79
	v_and_b32_e32 v79, 0xffff0000, v79
	v_pk_fma_f32 v[70:71], v[70:71], v[72:73], v[76:77]
	v_pk_fma_f32 v[72:73], v[66:67], v[74:75], v[78:79]
	v_pk_fma_f32 v[66:67], v[64:65], v[98:99], v[102:103]
	v_pk_fma_f32 v[68:69], v[68:69], v[96:97], v[100:101]
	v_lshlrev_b64 v[76:77], 12, v[88:89]
	v_cvt_pk_bf16_f32 v64, v68, v69
	v_cvt_pk_bf16_f32 v65, v70, v71
	v_cvt_pk_bf16_f32 v66, v66, v67
	v_cvt_pk_bf16_f32 v67, v72, v73
	v_lshl_add_u64 v[76:77], s[8:9], 0, v[76:77]
	ds_write_b128 v156, v[64:67] offset:64
	ds_read_b128 v[64:67], v157
	ds_read_b128 v[68:71], v157 offset:1152
	s_waitcnt lgkmcnt(4)
; __device__ __forceinline__ unsigned cvt_pk_bf16(float lo, float hi) { unsigned r; asm volatile("v_cvt_pk_bf16_f32 %0, %1, %2" : "=v"(r) : "v"(lo), "v"(hi)); return r; }
; __device__ __forceinline__ float bf_lo(unsigned w) { return __uint_as_float(w << 16); }
; __device__ __forceinline__ float bf_hi(unsigned w) { return __uint_as_float(w & 0xffff0000u); }
; #define GAS1 __attribute__((address_space(1)))
;     __device__ __forceinline__ void operator()(const f32x4 (&acc)[2][2][4][2], const Unit& u, int wr, int wc, int fr, int fq) const {
;     ...
;                 if (MODE == 3 || MODE == 4) {
;                     const u32x4 gw = *(const GAS1 u32x4*)(G + (size_t)row * ldg + col);
;                     const f32x4 g0 = {bf_lo(gw.x), bf_hi(gw.x), bf_lo(gw.y), bf_hi(gw.y)}, g1 = {bf_lo(gw.z), bf_hi(gw.z), bf_lo(gw.w), bf_hi(gw.w)};
;                     v0 = v0 * g0; v1 = v1 * g1;
;                     if (MODE == 4) {
;                         const u32x4 ow = *(const GAS1 u32x4*)((const bf16_t*)O + (size_t)row * ldc + col);
;                         const f32x4 o0 = {bf_lo(ow.x), bf_hi(ow.x), bf_lo(ow.y), bf_hi(ow.y)}, o1 = {bf_lo(ow.z), bf_hi(ow.z), bf_lo(ow.w), bf_hi(ow.w)};
;                         v0 += o0; v1 += o1;
;                     }
;                 }
;                 u32x4 w; w.x = cvt_pk_bf16(v0[0], v0[1]); w.y = cvt_pk_bf16(v0[2], v0[3]); w.z = cvt_pk_bf16(v1[0], v1[1]); w.w = cvt_pk_bf16(v1[2], v1[3]);
;                 if (bj == 0) asm volatile("ds_write_b128 %0, %1" :: "v"(wa), "v"(w)); else asm volatile("ds_write_b128 %0, %1 offset:64" :: "v"(wa), "v"(w));
;             }
;             asm volatile("ds_read_b128 %0, %1" : "=&v"(rb[g & 1][0]) : "v"(ra));
;             asm volatile("ds_read_b128 %0, %1 offset:1152" : "=&v"(rb[g & 1][1]) : "v"(ra));
;             if (g >= 1) {
;                 asm volatile("s_waitcnt lgkmcnt(4)" : "+v"(rb[(g - 1) & 1][0]), "+v"(rb[(g - 1) & 1][1]));
;                 bf16_t* ob = obase + (size_t)(((g - 1) >> 2) * HALF + ((g - 1) & 3) * 16) * ldc;
;                 *(GAS1 u32x4*)ob = rb[(g - 1) & 1][0]; *(GAS1 u32x4*)(ob + (size_t)8 * ldc) = rb[(g - 1) & 1][1];
	global_store_dwordx4 v[92:93], v[80:83], off nt
	global_store_dwordx4 v[94:95], v[84:87], off nt
	v_lshl_add_u64 v[80:81], v[76:77], 0, v[146:147]
	s_waitcnt vmcnt(11)
	v_mov_b32_e32 v72, v210
	v_mov_b32_e32 v73, v211
	v_mov_b32_e32 v74, v212
	v_mov_b32_e32 v75, v213
	v_lshlrev_b32_e32 v82, 16, v72
	v_and_b32_e32 v83, 0xffff0000, v72
	v_lshlrev_b32_e32 v72, 16, v73
	v_and_b32_e32 v73, 0xffff0000, v73
	v_lshlrev_b32_e32 v84, 16, v74
	v_and_b32_e32 v85, 0xffff0000, v74
	v_lshlrev_b32_e32 v74, 16, v75
	v_and_b32_e32 v75, 0xffff0000, v75
	s_waitcnt vmcnt(10)
	v_mov_b32_e32 v76, v214
	v_mov_b32_e32 v77, v215
	v_mov_b32_e32 v78, v216
	v_mov_b32_e32 v79, v217
	v_lshlrev_b32_e32 v86, 16, v76
	v_and_b32_e32 v87, 0xffff0000, v76
	v_lshlrev_b32_e32 v76, 16, v77
	v_and_b32_e32 v77, 0xffff0000, v77
	v_lshlrev_b32_e32 v88, 16, v78
	v_and_b32_e32 v89, 0xffff0000, v78
	v_lshlrev_b32_e32 v78, 16, v79
	v_and_b32_e32 v79, 0xffff0000, v79
	v_pk_fma_f32 v[62:63], v[62:63], v[72:73], v[76:77]
	v_pk_fma_f32 v[72:73], v[58:59], v[74:75], v[78:79]
	v_pk_fma_f32 v[58:59], v[56:57], v[84:85], v[88:89]
	v_pk_fma_f32 v[60:61], v[60:61], v[82:83], v[86:87]
	v_add_co_u32_e32 v76, vcc, s75, v104
	v_cvt_pk_bf16_f32 v56, v60, v61
	v_cvt_pk_bf16_f32 v57, v62, v63
	v_cvt_pk_bf16_f32 v58, v58, v59
	v_cvt_pk_bf16_f32 v59, v72, v73
	v_add_u32_e32 v72, 0x90, v148
	ds_write_b128 v156, v[56:59]
	v_ashrrev_i32_e32 v73, 31, v72
	v_addc_co_u32_e32 v77, vcc, 0, v105, vcc
	v_mad_i64_i32 v[74:75], s[28:29], v72, s72, v[150:151]
	v_add_co_u32_e32 v78, vcc, s76, v104
	v_lshl_add_u64 v[74:75], v[74:75], 0, v[146:147]
	s_nop 0
	v_addc_co_u32_e32 v79, vcc, 0, v105, vcc
	s_waitcnt vmcnt(9)
	v_mov_b32_e32 v56, v218
	v_mov_b32_e32 v57, v219
	v_mov_b32_e32 v58, v220
	v_mov_b32_e32 v59, v221
	v_lshlrev_b32_e32 v80, 16, v56
	v_and_b32_e32 v81, 0xffff0000, v56
	v_lshlrev_b32_e32 v56, 16, v57
	v_and_b32_e32 v57, 0xffff0000, v57
	v_lshlrev_b32_e32 v82, 16, v58
	v_and_b32_e32 v83, 0xffff0000, v58
	v_lshlrev_b32_e32 v58, 16, v59
	v_and_b32_e32 v59, 0xffff0000, v59
	s_waitcnt vmcnt(8)
	v_mov_b32_e32 v60, v222
	v_mov_b32_e32 v61, v223
	v_mov_b32_e32 v62, v224
	v_mov_b32_e32 v63, v225
	v_lshlrev_b32_e32 v84, 16, v60
	v_and_b32_e32 v85, 0xffff0000, v60
	v_lshlrev_b32_e32 v60, 16, v61
	v_and_b32_e32 v61, 0xffff0000, v61
	v_lshlrev_b32_e32 v86, 16, v62
	v_and_b32_e32 v87, 0xffff0000, v62
	v_lshlrev_b32_e32 v62, 16, v63
	v_and_b32_e32 v63, 0xffff0000, v63
	v_pk_fma_f32 v[54:55], v[54:55], v[56:57], v[60:61]
	v_pk_fma_f32 v[56:57], v[50:51], v[58:59], v[62:63]
	v_pk_fma_f32 v[50:51], v[48:49], v[82:83], v[86:87]
	v_pk_fma_f32 v[52:53], v[52:53], v[80:81], v[84:85]
	v_lshlrev_b64 v[60:61], 12, v[72:73]
	v_cvt_pk_bf16_f32 v48, v52, v53
	v_cvt_pk_bf16_f32 v49, v54, v55
	v_cvt_pk_bf16_f32 v50, v50, v51
	v_cvt_pk_bf16_f32 v51, v56, v57
	v_lshl_add_u64 v[60:61], s[8:9], 0, v[60:61]
	ds_write_b128 v156, v[48:51] offset:64
	ds_read_b128 v[48:51], v157
	ds_read_b128 v[52:55], v157 offset:1152
	s_waitcnt lgkmcnt(4)
	global_store_dwordx4 v[76:77], v[64:67], off nt
	global_store_dwordx4 v[78:79], v[68:71], off nt
	v_lshl_add_u64 v[64:65], v[60:61], 0, v[146:147]
	s_waitcnt vmcnt(9)
	v_mov_b32_e32 v56, v226
	v_mov_b32_e32 v57, v227
	v_mov_b32_e32 v58, v228
	v_mov_b32_e32 v59, v229
	v_lshlrev_b32_e32 v66, 16, v56
	v_and_b32_e32 v67, 0xffff0000, v56
	v_lshlrev_b32_e32 v56, 16, v57
	v_and_b32_e32 v57, 0xffff0000, v57
	v_lshlrev_b32_e32 v68, 16, v58
	v_and_b32_e32 v69, 0xffff0000, v58
	v_lshlrev_b32_e32 v58, 16, v59
	v_and_b32_e32 v59, 0xffff0000, v59
	s_waitcnt vmcnt(8)
	v_mov_b32_e32 v60, v236
	v_mov_b32_e32 v61, v237
	v_mov_b32_e32 v62, v238
	v_mov_b32_e32 v63, v239
	v_lshlrev_b32_e32 v70, 16, v60
	v_and_b32_e32 v71, 0xffff0000, v60
	v_lshlrev_b32_e32 v60, 16, v61
	v_and_b32_e32 v61, 0xffff0000, v61
	v_lshlrev_b32_e32 v72, 16, v62
	v_and_b32_e32 v73, 0xffff0000, v62
	v_lshlrev_b32_e32 v62, 16, v63
	v_and_b32_e32 v63, 0xffff0000, v63
	v_pk_fma_f32 v[46:47], v[46:47], v[56:57], v[60:61]
	v_pk_fma_f32 v[56:57], v[42:43], v[58:59], v[62:63]
	v_pk_fma_f32 v[42:43], v[40:41], v[68:69], v[72:73]
	v_pk_fma_f32 v[44:45], v[44:45], v[66:67], v[70:71]
	v_add_co_u32_e32 v60, vcc, s77, v104
	v_cvt_pk_bf16_f32 v40, v44, v45
	v_cvt_pk_bf16_f32 v41, v46, v47
	v_cvt_pk_bf16_f32 v42, v42, v43
	v_cvt_pk_bf16_f32 v43, v56, v57
	v_add_u32_e32 v56, 0xa0, v148
	ds_write_b128 v156, v[40:43]
	v_ashrrev_i32_e32 v57, 31, v56
	v_addc_co_u32_e32 v61, vcc, 0, v105, vcc
	v_mad_i64_i32 v[58:59], s[28:29], v56, s72, v[150:151]
	v_add_co_u32_e32 v62, vcc, s79, v104
	v_lshl_add_u64 v[58:59], v[58:59], 0, v[146:147]
	s_nop 0
	v_addc_co_u32_e32 v63, vcc, 0, v105, vcc
	s_waitcnt vmcnt(7)
	v_mov_b32_e32 v40, v240
	v_mov_b32_e32 v41, v241
	v_mov_b32_e32 v42, v242
	v_mov_b32_e32 v43, v243
	v_lshlrev_b32_e32 v64, 16, v40
	v_and_b32_e32 v65, 0xffff0000, v40
	v_lshlrev_b32_e32 v40, 16, v41
	v_and_b32_e32 v41, 0xffff0000, v41
	v_lshlrev_b32_e32 v66, 16, v42
	v_and_b32_e32 v67, 0xffff0000, v42
	v_lshlrev_b32_e32 v42, 16, v43
	v_and_b32_e32 v43, 0xffff0000, v43
	s_waitcnt vmcnt(6)
; __device__ __forceinline__ unsigned cvt_pk_bf16(float lo, float hi) { unsigned r; asm volatile("v_cvt_pk_bf16_f32 %0, %1, %2" : "=v"(r) : "v"(lo), "v"(hi)); return r; }
; __device__ __forceinline__ float bf_lo(unsigned w) { return __uint_as_float(w << 16); }
; __device__ __forceinline__ float bf_hi(unsigned w) { return __uint_as_float(w & 0xffff0000u); }
; #define GAS1 __attribute__((address_space(1)))
;     __device__ __forceinline__ void operator()(const f32x4 (&acc)[2][2][4][2], const Unit& u, int wr, int wc, int fr, int fq) const {
;     ...
;                 if (MODE == 3 || MODE == 4) {
;                     const u32x4 gw = *(const GAS1 u32x4*)(G + (size_t)row * ldg + col);
;                     const f32x4 g0 = {bf_lo(gw.x), bf_hi(gw.x), bf_lo(gw.y), bf_hi(gw.y)}, g1 = {bf_lo(gw.z), bf_hi(gw.z), bf_lo(gw.w), bf_hi(gw.w)};
;                     v0 = v0 * g0; v1 = v1 * g1;
;                     if (MODE == 4) {
;                         const u32x4 ow = *(const GAS1 u32x4*)((const bf16_t*)O + (size_t)row * ldc + col);
;                         const f32x4 o0 = {bf_lo(ow.x), bf_hi(ow.x), bf_lo(ow.y), bf_hi(ow.y)}, o1 = {bf_lo(ow.z), bf_hi(ow.z), bf_lo(ow.w), bf_hi(ow.w)};
;                         v0 += o0; v1 += o1;
;                     }
;                 }
;                 u32x4 w; w.x = cvt_pk_bf16(v0[0], v0[1]); w.y = cvt_pk_bf16(v0[2], v0[3]); w.z = cvt_pk_bf16(v1[0], v1[1]); w.w = cvt_pk_bf16(v1[2], v1[3]);
;                 if (bj == 0) asm volatile("ds_write_b128 %0, %1" :: "v"(wa), "v"(w)); else asm volatile("ds_write_b128 %0, %1 offset:64" :: "v"(wa), "v"(w));
;             }
;             asm volatile("ds_read_b128 %0, %1" : "=&v"(rb[g & 1][0]) : "v"(ra));
;             asm volatile("ds_read_b128 %0, %1 offset:1152" : "=&v"(rb[g & 1][1]) : "v"(ra));
;             if (g >= 1) {
;                 asm volatile("s_waitcnt lgkmcnt(4)" : "+v"(rb[(g - 1) & 1][0]), "+v"(rb[(g - 1) & 1][1]));
;                 bf16_t* ob = obase + (size_t)(((g - 1) >> 2) * HALF + ((g - 1) & 3) * 16) * ldc;
;                 *(GAS1 u32x4*)ob = rb[(g - 1) & 1][0]; *(GAS1 u32x4*)(ob + (size_t)8 * ldc) = rb[(g - 1) & 1][1];
	v_mov_b32_e32 v44, v246
	v_mov_b32_e32 v45, v247
	v_mov_b32_e32 v46, v248
	v_mov_b32_e32 v47, v249
	v_add_u32_e32 v254, 160, v148
	v_ashrrev_i32_e32 v255, 31, v254
	v_mad_i64_i32 v[206:207], s[98:99], v254, s72, v[150:151]
	v_lshlrev_b64 v[232:233], 12, v[254:255]
	v_lshl_add_u64 v[206:207], v[206:207], 0, v[146:147]
	v_lshl_add_u64 v[232:233], s[8:9], 0, v[232:233]
	v_lshl_add_u64 v[232:233], v[232:233], 0, v[146:147]
	global_load_dwordx4 v[188:191], v[206:207], off
	global_load_dwordx4 v[192:195], v[232:233], off
	global_load_dwordx4 v[196:199], v[206:207], off offset:64
	global_load_dwordx4 v[202:205], v[232:233], off offset:64
	v_add_u32_e32 v254, 176, v148
	v_ashrrev_i32_e32 v255, 31, v254
	v_mad_i64_i32 v[206:207], s[98:99], v254, s72, v[150:151]
	v_lshlrev_b64 v[232:233], 12, v[254:255]
	v_lshl_add_u64 v[206:207], v[206:207], 0, v[146:147]
	v_lshl_add_u64 v[232:233], s[8:9], 0, v[232:233]
	v_lshl_add_u64 v[232:233], v[232:233], 0, v[146:147]
	global_load_dwordx4 v[210:213], v[206:207], off
	global_load_dwordx4 v[214:217], v[232:233], off
	global_load_dwordx4 v[218:221], v[206:207], off offset:64
	global_load_dwordx4 v[222:225], v[232:233], off offset:64
	v_lshlrev_b32_e32 v68, 16, v44
	v_and_b32_e32 v69, 0xffff0000, v44
	v_lshlrev_b32_e32 v44, 16, v45
	v_and_b32_e32 v45, 0xffff0000, v45
	v_lshlrev_b32_e32 v70, 16, v46
	v_and_b32_e32 v71, 0xffff0000, v46
	v_lshlrev_b32_e32 v46, 16, v47
	v_and_b32_e32 v47, 0xffff0000, v47
	v_pk_fma_f32 v[38:39], v[38:39], v[40:41], v[44:45]
	v_pk_fma_f32 v[40:41], v[34:35], v[42:43], v[46:47]
	v_pk_fma_f32 v[34:35], v[32:33], v[66:67], v[70:71]
	v_pk_fma_f32 v[36:37], v[36:37], v[64:65], v[68:69]
	v_lshlrev_b64 v[44:45], 12, v[56:57]
	v_cvt_pk_bf16_f32 v32, v36, v37
	v_cvt_pk_bf16_f32 v33, v38, v39
	v_cvt_pk_bf16_f32 v34, v34, v35
	v_cvt_pk_bf16_f32 v35, v40, v41
	v_lshl_add_u64 v[44:45], s[8:9], 0, v[44:45]
	ds_write_b128 v156, v[32:35] offset:64
	ds_read_b128 v[32:35], v157
	ds_read_b128 v[36:39], v157 offset:1152
	s_waitcnt lgkmcnt(4)
	global_store_dwordx4 v[60:61], v[48:51], off nt
	global_store_dwordx4 v[62:63], v[52:55], off nt
	v_lshl_add_u64 v[48:49], v[44:45], 0, v[146:147]
	s_waitcnt vmcnt(9)
	v_mov_b32_e32 v40, v188
	v_mov_b32_e32 v41, v189
	v_mov_b32_e32 v42, v190
	v_mov_b32_e32 v43, v191
	v_lshlrev_b32_e32 v50, 16, v40
	v_and_b32_e32 v51, 0xffff0000, v40
	v_lshlrev_b32_e32 v40, 16, v41
	v_and_b32_e32 v41, 0xffff0000, v41
	v_lshlrev_b32_e32 v52, 16, v42
	v_and_b32_e32 v53, 0xffff0000, v42
	v_lshlrev_b32_e32 v42, 16, v43
	v_and_b32_e32 v43, 0xffff0000, v43
	s_waitcnt vmcnt(8)
	v_mov_b32_e32 v44, v192
	v_mov_b32_e32 v45, v193
	v_mov_b32_e32 v46, v194
	v_mov_b32_e32 v47, v195
	v_lshlrev_b32_e32 v54, 16, v44
	v_and_b32_e32 v55, 0xffff0000, v44
	v_lshlrev_b32_e32 v44, 16, v45
	v_and_b32_e32 v45, 0xffff0000, v45
	v_lshlrev_b32_e32 v56, 16, v46
	v_and_b32_e32 v57, 0xffff0000, v46
	v_lshlrev_b32_e32 v46, 16, v47
	v_and_b32_e32 v47, 0xffff0000, v47
	v_pk_fma_f32 v[30:31], v[30:31], v[40:41], v[44:45]
	v_pk_fma_f32 v[40:41], v[26:27], v[42:43], v[46:47]
	v_pk_fma_f32 v[26:27], v[24:25], v[52:53], v[56:57]
	v_pk_fma_f32 v[28:29], v[28:29], v[50:51], v[54:55]
	v_add_co_u32_e32 v44, vcc, s80, v104
	v_cvt_pk_bf16_f32 v24, v28, v29
	v_cvt_pk_bf16_f32 v25, v30, v31
	v_cvt_pk_bf16_f32 v26, v26, v27
	v_cvt_pk_bf16_f32 v27, v40, v41
	v_add_u32_e32 v40, 0xb0, v148
	ds_write_b128 v156, v[24:27]
	v_ashrrev_i32_e32 v41, 31, v40
	v_addc_co_u32_e32 v45, vcc, 0, v105, vcc
	v_mad_i64_i32 v[42:43], s[28:29], v40, s72, v[150:151]
	v_add_co_u32_e32 v46, vcc, s81, v104
	v_lshl_add_u64 v[42:43], v[42:43], 0, v[146:147]
	s_nop 0
	v_addc_co_u32_e32 v47, vcc, 0, v105, vcc
	s_waitcnt vmcnt(7)
	v_mov_b32_e32 v24, v196
	v_mov_b32_e32 v25, v197
	v_mov_b32_e32 v26, v198
	v_mov_b32_e32 v27, v199
	v_lshlrev_b32_e32 v48, 16, v24
	v_and_b32_e32 v49, 0xffff0000, v24
	v_lshlrev_b32_e32 v24, 16, v25
	v_and_b32_e32 v25, 0xffff0000, v25
	v_lshlrev_b32_e32 v50, 16, v26
	v_and_b32_e32 v51, 0xffff0000, v26
	v_lshlrev_b32_e32 v26, 16, v27
	v_and_b32_e32 v27, 0xffff0000, v27
	s_waitcnt vmcnt(6)
; __device__ __forceinline__ unsigned cvt_pk_bf16(float lo, float hi) { unsigned r; asm volatile("v_cvt_pk_bf16_f32 %0, %1, %2" : "=v"(r) : "v"(lo), "v"(hi)); return r; }
; __device__ __forceinline__ float bf_lo(unsigned w) { return __uint_as_float(w << 16); }
; __device__ __forceinline__ float bf_hi(unsigned w) { return __uint_as_float(w & 0xffff0000u); }
; #define GAS1 __attribute__((address_space(1)))
;     __device__ __forceinline__ void operator()(const f32x4 (&acc)[2][2][4][2], const Unit& u, int wr, int wc, int fr, int fq) const {
;     ...
;                 if (MODE == 3 || MODE == 4) {
;                     const u32x4 gw = *(const GAS1 u32x4*)(G + (size_t)row * ldg + col);
;                     const f32x4 g0 = {bf_lo(gw.x), bf_hi(gw.x), bf_lo(gw.y), bf_hi(gw.y)}, g1 = {bf_lo(gw.z), bf_hi(gw.z), bf_lo(gw.w), bf_hi(gw.w)};
;                     v0 = v0 * g0; v1 = v1 * g1;
;                     if (MODE == 4) {
;                         const u32x4 ow = *(const GAS1 u32x4*)((const bf16_t*)O + (size_t)row * ldc + col);
;                         const f32x4 o0 = {bf_lo(ow.x), bf_hi(ow.x), bf_lo(ow.y), bf_hi(ow.y)}, o1 = {bf_lo(ow.z), bf_hi(ow.z), bf_lo(ow.w), bf_hi(ow.w)};
;                         v0 += o0; v1 += o1;
;                     }
;                 }
;                 u32x4 w; w.x = cvt_pk_bf16(v0[0], v0[1]); w.y = cvt_pk_bf16(v0[2], v0[3]); w.z = cvt_pk_bf16(v1[0], v1[1]); w.w = cvt_pk_bf16(v1[2], v1[3]);
;                 if (bj == 0) asm volatile("ds_write_b128 %0, %1" :: "v"(wa), "v"(w)); else asm volatile("ds_write_b128 %0, %1 offset:64" :: "v"(wa), "v"(w));
;             }
;             asm volatile("ds_read_b128 %0, %1" : "=&v"(rb[g & 1][0]) : "v"(ra));
;             asm volatile("ds_read_b128 %0, %1 offset:1152" : "=&v"(rb[g & 1][1]) : "v"(ra));
;             if (g >= 1) {
;                 asm volatile("s_waitcnt lgkmcnt(4)" : "+v"(rb[(g - 1) & 1][0]), "+v"(rb[(g - 1) & 1][1]));
;                 bf16_t* ob = obase + (size_t)(((g - 1) >> 2) * HALF + ((g - 1) & 3) * 16) * ldc;
;                 *(GAS1 u32x4*)ob = rb[(g - 1) & 1][0]; *(GAS1 u32x4*)(ob + (size_t)8 * ldc) = rb[(g - 1) & 1][1];
;             }
;         }
;         asm volatile("s_waitcnt lgkmcnt(0)" : "+v"(rb[1][0]), "+v"(rb[1][1]));
;         { bf16_t* ob = obase + (size_t)(HALF + 3 * 16) * ldc; *(GAS1 u32x4*)ob = rb[1][0]; *(GAS1 u32x4*)(ob + (size_t)8 * ldc) = rb[1][1]; }
	v_mov_b32_e32 v28, v202
	v_mov_b32_e32 v29, v203
	v_mov_b32_e32 v30, v204
	v_mov_b32_e32 v31, v205
	v_lshlrev_b32_e32 v52, 16, v28
	v_and_b32_e32 v53, 0xffff0000, v28
	v_lshlrev_b32_e32 v28, 16, v29
	v_and_b32_e32 v29, 0xffff0000, v29
	v_lshlrev_b32_e32 v54, 16, v30
	v_and_b32_e32 v55, 0xffff0000, v30
	v_lshlrev_b32_e32 v30, 16, v31
	v_and_b32_e32 v31, 0xffff0000, v31
	v_pk_fma_f32 v[22:23], v[22:23], v[24:25], v[28:29]
	v_pk_fma_f32 v[24:25], v[18:19], v[26:27], v[30:31]
	v_pk_fma_f32 v[18:19], v[16:17], v[50:51], v[54:55]
	v_pk_fma_f32 v[20:21], v[20:21], v[48:49], v[52:53]
	v_lshlrev_b64 v[28:29], 12, v[40:41]
	v_cvt_pk_bf16_f32 v16, v20, v21
	v_cvt_pk_bf16_f32 v17, v22, v23
	v_cvt_pk_bf16_f32 v18, v18, v19
	v_cvt_pk_bf16_f32 v19, v24, v25
	v_lshl_add_u64 v[28:29], s[8:9], 0, v[28:29]
	ds_write_b128 v156, v[16:19] offset:64
	ds_read_b128 v[16:19], v157
	ds_read_b128 v[20:23], v157 offset:1152
	s_waitcnt lgkmcnt(4)
	global_store_dwordx4 v[44:45], v[32:35], off nt
	global_store_dwordx4 v[46:47], v[36:39], off nt
	v_lshl_add_u64 v[32:33], v[28:29], 0, v[146:147]
	s_waitcnt vmcnt(7)
	v_mov_b32_e32 v24, v210
	v_mov_b32_e32 v25, v211
	v_mov_b32_e32 v26, v212
	v_mov_b32_e32 v27, v213
	v_lshlrev_b32_e32 v34, 16, v24
	v_and_b32_e32 v35, 0xffff0000, v24
	v_lshlrev_b32_e32 v24, 16, v25
	v_and_b32_e32 v25, 0xffff0000, v25
	v_lshlrev_b32_e32 v36, 16, v26
	v_and_b32_e32 v37, 0xffff0000, v26
	v_lshlrev_b32_e32 v26, 16, v27
	v_and_b32_e32 v27, 0xffff0000, v27
	s_waitcnt vmcnt(6)
	v_mov_b32_e32 v28, v214
	v_mov_b32_e32 v29, v215
	v_mov_b32_e32 v30, v216
	v_mov_b32_e32 v31, v217
	v_lshlrev_b32_e32 v38, 16, v28
	v_and_b32_e32 v39, 0xffff0000, v28
	v_lshlrev_b32_e32 v28, 16, v29
	v_and_b32_e32 v29, 0xffff0000, v29
	v_lshlrev_b32_e32 v40, 16, v30
	v_and_b32_e32 v41, 0xffff0000, v30
	v_lshlrev_b32_e32 v30, 16, v31
	v_and_b32_e32 v31, 0xffff0000, v31
	v_pk_fma_f32 v[14:15], v[14:15], v[24:25], v[28:29]
	v_pk_fma_f32 v[24:25], v[10:11], v[26:27], v[30:31]
	v_pk_fma_f32 v[10:11], v[8:9], v[36:37], v[40:41]
	v_pk_fma_f32 v[12:13], v[12:13], v[34:35], v[38:39]
	s_nop 0
	v_cvt_pk_bf16_f32 v8, v12, v13
	v_cvt_pk_bf16_f32 v9, v14, v15
	v_cvt_pk_bf16_f32 v10, v10, v11
	v_cvt_pk_bf16_f32 v11, v24, v25
	v_add_co_u32_e32 v24, vcc, s82, v104
	ds_write_b128 v156, v[8:11]
	v_addc_co_u32_e32 v25, vcc, 0, v105, vcc
	v_add_co_u32_e32 v26, vcc, s83, v104
	s_waitcnt vmcnt(5)
	v_mov_b32_e32 v8, v218
	v_mov_b32_e32 v9, v219
	v_mov_b32_e32 v10, v220
	v_mov_b32_e32 v11, v221
	v_lshlrev_b32_e32 v32, 16, v8
	v_addc_co_u32_e32 v27, vcc, 0, v105, vcc
	v_add_co_u32_e32 v28, vcc, 0xb0000, v104
	v_and_b32_e32 v33, 0xffff0000, v8
	v_lshlrev_b32_e32 v8, 16, v9
	v_and_b32_e32 v9, 0xffff0000, v9
	v_lshlrev_b32_e32 v34, 16, v10
	v_and_b32_e32 v35, 0xffff0000, v10
	v_lshlrev_b32_e32 v10, 16, v11
	v_and_b32_e32 v11, 0xffff0000, v11
	s_waitcnt vmcnt(4)
	v_mov_b32_e32 v12, v222
	v_mov_b32_e32 v13, v223
	v_mov_b32_e32 v14, v224
	v_mov_b32_e32 v15, v225
	v_lshlrev_b32_e32 v36, 16, v12
	v_and_b32_e32 v37, 0xffff0000, v12
	v_lshlrev_b32_e32 v12, 16, v13
	v_and_b32_e32 v13, 0xffff0000, v13
	v_lshlrev_b32_e32 v38, 16, v14
	v_and_b32_e32 v39, 0xffff0000, v14
	v_lshlrev_b32_e32 v14, 16, v15
	v_and_b32_e32 v15, 0xffff0000, v15
	v_addc_co_u32_e32 v29, vcc, 0, v105, vcc
	v_pk_fma_f32 v[6:7], v[6:7], v[8:9], v[12:13]
	v_pk_fma_f32 v[8:9], v[2:3], v[10:11], v[14:15]
	v_pk_fma_f32 v[2:3], v[0:1], v[34:35], v[38:39]
	v_add_co_u32_e32 v30, vcc, 0xb8000, v104
	v_pk_fma_f32 v[4:5], v[4:5], v[32:33], v[36:37]
	s_nop 0
	v_addc_co_u32_e32 v31, vcc, 0, v105, vcc
	v_cvt_pk_bf16_f32 v0, v4, v5
	v_cvt_pk_bf16_f32 v1, v6, v7
	v_cvt_pk_bf16_f32 v2, v2, v3
	v_cvt_pk_bf16_f32 v3, v8, v9
	s_andn2_b64 vcc, exec, s[6:7]
	ds_write_b128 v156, v[0:3] offset:64
	ds_read_b128 v[0:3], v157
	ds_read_b128 v[4:7], v157 offset:1152
	s_waitcnt lgkmcnt(4)
	global_store_dwordx4 v[24:25], v[16:19], off nt
	global_store_dwordx4 v[26:27], v[20:23], off nt
	s_waitcnt lgkmcnt(0)
	s_mov_b64 s[6:7], -1
	global_store_dwordx4 v[28:29], v[0:3], off nt
	global_store_dwordx4 v[30:31], v[4:7], off nt
	s_cbranch_vccnz .LBB0_1423
	s_andn2_b64 vcc, exec, s[12:13]
	s_cbranch_vccnz .LBB0_1422
	s_barrier
	s_branch .LBB0_1422

; __device__ __forceinline__ unsigned cvt_pk_bf16(float lo, float hi) { unsigned r; asm volatile("v_cvt_pk_bf16_f32 %0, %1, %2" : "=v"(r) : "v"(lo), "v"(hi)); return r; }
; #define GAS1 __attribute__((address_space(1)))
;     __device__ __forceinline__ void operator()(const f32x4 (&acc)[2][2][4][2], const Unit& u, int wr, int wc, int fr, int fq) const {
;     ...
;                 u32x4 w; w.x = cvt_pk_bf16(v0[0], v0[1]); w.y = cvt_pk_bf16(v0[2], v0[3]); w.z = cvt_pk_bf16(v1[0], v1[1]); w.w = cvt_pk_bf16(v1[2], v1[3]);
;                 if (bj == 0) asm volatile("ds_write_b128 %0, %1" :: "v"(wa), "v"(w)); else asm volatile("ds_write_b128 %0, %1 offset:64" :: "v"(wa), "v"(w));
;             }
;             asm volatile("ds_read_b128 %0, %1" : "=&v"(rb[g & 1][0]) : "v"(ra));
;             asm volatile("ds_read_b128 %0, %1 offset:1152" : "=&v"(rb[g & 1][1]) : "v"(ra));
;             if (g >= 1) {
;                 asm volatile("s_waitcnt lgkmcnt(4)" : "+v"(rb[(g - 1) & 1][0]), "+v"(rb[(g - 1) & 1][1]));
;                 bf16_t* ob = obase + (size_t)(((g - 1) >> 2) * HALF + ((g - 1) & 3) * 16) * ldc;
;                 *(GAS1 u32x4*)ob = rb[(g - 1) & 1][0]; *(GAS1 u32x4*)(ob + (size_t)8 * ldc) = rb[(g - 1) & 1][1];
;             }
;         }
;         asm volatile("s_waitcnt lgkmcnt(0)" : "+v"(rb[1][0]), "+v"(rb[1][1]));
;         { bf16_t* ob = obase + (size_t)(HALF + 3 * 16) * ldc; *(GAS1 u32x4*)ob = rb[1][0]; *(GAS1 u32x4*)(ob + (size_t)8 * ldc) = rb[1][1]; }
.LBB0_1510:
	v_lshl_add_u32 v146, s26, 8, v149
	v_ashrrev_i32_e32 v147, 31, v146
	v_lshlrev_b64 v[146:147], 12, v[146:147]
	s_lshl_b32 s28, s80, 8
	v_lshl_add_u64 v[146:147], s[12:13], 0, v[146:147]
	s_ashr_i32 s29, s28, 31
	v_lshl_add_u64 v[146:147], s[28:29], 1, v[146:147]
	v_cvt_pk_bf16_f32 v124, v124, v125
	v_cvt_pk_bf16_f32 v125, v126, v127
	v_cvt_pk_bf16_f32 v126, v120, v121
	v_cvt_pk_bf16_f32 v127, v122, v123
	v_lshl_add_u64 v[146:147], v[146:147], 0, s[8:9]
	ds_write_b128 v150, v[124:127]
	v_cvt_pk_bf16_f32 v112, v112, v113
	v_cvt_pk_bf16_f32 v113, v114, v115
	v_cvt_pk_bf16_f32 v114, v104, v105
	v_cvt_pk_bf16_f32 v115, v106, v107
	v_lshl_add_u64 v[146:147], v[146:147], 0, v[136:137]
	ds_write_b128 v150, v[112:115] offset:64
	ds_read_b128 v[104:107], v151
	ds_read_b128 v[112:115], v151 offset:1152
	v_cvt_pk_bf16_f32 v116, v116, v117
	v_cvt_pk_bf16_f32 v117, v118, v119
	v_cvt_pk_bf16_f32 v118, v108, v109
	v_cvt_pk_bf16_f32 v119, v110, v111
	s_nop 0
	ds_write_b128 v150, v[116:119]
	v_cvt_pk_bf16_f32 v100, v100, v101
	v_cvt_pk_bf16_f32 v101, v102, v103
	v_cvt_pk_bf16_f32 v102, v92, v93
	v_cvt_pk_bf16_f32 v103, v94, v95
	s_nop 0
	ds_write_b128 v150, v[100:103] offset:64
	ds_read_b128 v[92:95], v151
	ds_read_b128 v[100:103], v151 offset:1152
	s_waitcnt lgkmcnt(4)
	global_store_dwordx4 v[146:147], v[104:107], off nt
	s_nop 1
	v_add_co_u32_e32 v104, vcc, s63, v146
	s_nop 1
	v_addc_co_u32_e32 v105, vcc, 0, v147, vcc
	global_store_dwordx4 v[104:105], v[112:115], off nt
	v_cvt_pk_bf16_f32 v96, v96, v97
	v_cvt_pk_bf16_f32 v97, v98, v99
	v_cvt_pk_bf16_f32 v98, v88, v89
	v_add_co_u32_e32 v88, vcc, s59, v146
	v_cvt_pk_bf16_f32 v99, v90, v91
	s_nop 0
	ds_write_b128 v150, v[96:99]
	v_cvt_pk_bf16_f32 v84, v84, v85
	v_cvt_pk_bf16_f32 v85, v86, v87
	v_cvt_pk_bf16_f32 v86, v76, v77
	v_cvt_pk_bf16_f32 v87, v78, v79
	s_nop 0
	v_addc_co_u32_e32 v89, vcc, 0, v147, vcc
	ds_write_b128 v150, v[84:87] offset:64
	ds_read_b128 v[76:79], v151
	ds_read_b128 v[84:87], v151 offset:1152
	s_waitcnt lgkmcnt(4)
	global_store_dwordx4 v[88:89], v[92:95], off nt
	v_add_co_u32_e32 v88, vcc, s62, v146
	s_nop 1
	v_addc_co_u32_e32 v89, vcc, 0, v147, vcc
	global_store_dwordx4 v[88:89], v[100:103], off nt
	v_cvt_pk_bf16_f32 v80, v80, v81
	v_cvt_pk_bf16_f32 v81, v82, v83
	v_cvt_pk_bf16_f32 v82, v72, v73
	v_add_co_u32_e32 v72, vcc, s68, v146
	v_cvt_pk_bf16_f32 v83, v74, v75
	s_nop 0
	ds_write_b128 v150, v[80:83]
	v_cvt_pk_bf16_f32 v68, v68, v69
	v_cvt_pk_bf16_f32 v69, v70, v71
	v_cvt_pk_bf16_f32 v70, v64, v65
	v_cvt_pk_bf16_f32 v71, v66, v67
	s_nop 0
	v_addc_co_u32_e32 v73, vcc, 0, v147, vcc
	ds_write_b128 v150, v[68:71] offset:64
	ds_read_b128 v[64:67], v151
	ds_read_b128 v[68:71], v151 offset:1152
	s_waitcnt lgkmcnt(4)
	global_store_dwordx4 v[72:73], v[76:79], off nt
	v_add_co_u32_e32 v72, vcc, s69, v146
	s_nop 1
	v_addc_co_u32_e32 v73, vcc, 0, v147, vcc
	global_store_dwordx4 v[72:73], v[84:87], off nt
	v_cvt_pk_bf16_f32 v60, v60, v61
	v_cvt_pk_bf16_f32 v61, v62, v63
	v_cvt_pk_bf16_f32 v62, v56, v57
	v_add_co_u32_e32 v56, vcc, s70, v146
	v_cvt_pk_bf16_f32 v63, v58, v59
	s_nop 0
	ds_write_b128 v150, v[60:63]
	v_cvt_pk_bf16_f32 v52, v52, v53
	v_cvt_pk_bf16_f32 v53, v54, v55
	v_cvt_pk_bf16_f32 v54, v44, v45
	v_cvt_pk_bf16_f32 v55, v46, v47
	s_nop 0
	v_addc_co_u32_e32 v57, vcc, 0, v147, vcc
	ds_write_b128 v150, v[52:55] offset:64
	ds_read_b128 v[44:47], v151
	ds_read_b128 v[52:55], v151 offset:1152
	s_waitcnt lgkmcnt(4)
	global_store_dwordx4 v[56:57], v[64:67], off nt
	v_add_co_u32_e32 v56, vcc, s71, v146
	s_nop 1
	v_addc_co_u32_e32 v57, vcc, 0, v147, vcc
	global_store_dwordx4 v[56:57], v[68:71], off nt
	v_cvt_pk_bf16_f32 v48, v48, v49
	v_cvt_pk_bf16_f32 v49, v50, v51
	v_cvt_pk_bf16_f32 v50, v40, v41
	v_add_co_u32_e32 v40, vcc, s72, v146
	v_cvt_pk_bf16_f32 v51, v42, v43
	s_nop 0
	ds_write_b128 v150, v[48:51]
	v_cvt_pk_bf16_f32 v36, v36, v37
	v_cvt_pk_bf16_f32 v37, v38, v39
	v_cvt_pk_bf16_f32 v38, v28, v29
	v_cvt_pk_bf16_f32 v39, v30, v31
	s_nop 0
	v_addc_co_u32_e32 v41, vcc, 0, v147, vcc
	ds_write_b128 v150, v[36:39] offset:64
	ds_read_b128 v[28:31], v151
	ds_read_b128 v[36:39], v151 offset:1152
	s_waitcnt lgkmcnt(4)
	global_store_dwordx4 v[40:41], v[44:47], off nt
	v_add_co_u32_e32 v40, vcc, s73, v146
	s_nop 1
	v_addc_co_u32_e32 v41, vcc, 0, v147, vcc
	global_store_dwordx4 v[40:41], v[52:55], off nt
	v_cvt_pk_bf16_f32 v32, v32, v33
	v_cvt_pk_bf16_f32 v33, v34, v35
	v_cvt_pk_bf16_f32 v34, v24, v25
	v_add_co_u32_e32 v24, vcc, s74, v146
	v_cvt_pk_bf16_f32 v35, v26, v27
	s_nop 0
	ds_write_b128 v150, v[32:35]
	v_cvt_pk_bf16_f32 v20, v20, v21
	v_cvt_pk_bf16_f32 v21, v22, v23
	v_cvt_pk_bf16_f32 v22, v12, v13
	v_cvt_pk_bf16_f32 v23, v14, v15
	s_nop 0
	v_addc_co_u32_e32 v25, vcc, 0, v147, vcc
	ds_write_b128 v150, v[20:23] offset:64
	ds_read_b128 v[12:15], v151
	ds_read_b128 v[20:23], v151 offset:1152
	s_waitcnt lgkmcnt(4)
	global_store_dwordx4 v[24:25], v[28:31], off nt
	v_add_co_u32_e32 v24, vcc, s75, v146
	s_nop 1
	v_addc_co_u32_e32 v25, vcc, 0, v147, vcc
	global_store_dwordx4 v[24:25], v[36:39], off nt
	v_cvt_pk_bf16_f32 v16, v16, v17
	v_cvt_pk_bf16_f32 v17, v18, v19
	v_cvt_pk_bf16_f32 v18, v8, v9
	v_add_co_u32_e32 v8, vcc, s76, v146
	v_cvt_pk_bf16_f32 v19, v10, v11
	s_nop 0
	ds_write_b128 v150, v[16:19]
	v_cvt_pk_bf16_f32 v4, v4, v5
	v_cvt_pk_bf16_f32 v5, v6, v7
	v_cvt_pk_bf16_f32 v6, v0, v1
	v_cvt_pk_bf16_f32 v7, v2, v3
	s_nop 0
	v_addc_co_u32_e32 v9, vcc, 0, v147, vcc
	ds_write_b128 v150, v[4:7] offset:64
	ds_read_b128 v[0:3], v151
	ds_read_b128 v[4:7], v151 offset:1152
	s_waitcnt lgkmcnt(4)
	global_store_dwordx4 v[8:9], v[12:15], off nt
	v_add_co_u32_e32 v8, vcc, s77, v146
	s_nop 1
	v_addc_co_u32_e32 v9, vcc, 0, v147, vcc
	global_store_dwordx4 v[8:9], v[20:23], off nt
	v_add_co_u32_e32 v8, vcc, 0xb0000, v146
	s_waitcnt lgkmcnt(0)
	s_nop 1
	v_addc_co_u32_e32 v9, vcc, 0, v147, vcc
	global_store_dwordx4 v[8:9], v[0:3], off nt
	s_nop 1
	v_add_co_u32_e32 v0, vcc, 0xb8000, v146
	s_nop 1
	v_addc_co_u32_e32 v1, vcc, 0, v147, vcc
	s_andn2_b64 vcc, exec, s[6:7]
	s_mov_b64 s[6:7], -1
	global_store_dwordx4 v[0:1], v[4:7], off nt
	s_cbranch_vccnz .LBB0_1499
	s_andn2_b64 vcc, exec, s[10:11]
	s_cbranch_vccnz .LBB0_1498
	s_barrier
	s_branch .LBB0_1498

; #define PG8_LAS __attribute__((address_space(3)))
;     __device__ __forceinline__ int hidx(int ai, int wr, int wc, int slot, int bj, int fq, int n) const { return ((((((ai * 2 + wr) * 4 + wc) * 2 + slot) * 2 + bj) * 4 + fq) * 2 + n) * 16; }
;     __device__ __forceinline__ void operator()(const f32x4 (&acc)[2][2][4][2], const Unit& u, int wr, int wc, int fr, int fq) const {
;         if (fr >= 14) {
; #pragma unroll
;             for (int ai = 0; ai < 2; ++ai)
; #pragma unroll
;                 for (int bj = 0; bj < 2; ++bj)
; #pragma unroll
;                     for (int n = 0; n < 2; ++n) *(PG8_LAS f32x4*)(hl + hidx(ai, wr, wc, fr - 14, bj, fq, n)) = acc[ai][bj][3][n];
;             if (wr == 1) {
; #pragma unroll
;                 for (int bj = 0; bj < 2; ++bj)
; #pragma unroll
;                     for (int n = 0; n < 2; ++n) *(f32x4*)(HU + ((size_t)(u.pm * 4 + 2 + (fr - 14)) * nN + u.pn) * 256 + 128 * bj + 32 * wc + 8 * fq + 4 * n) = acc[1][bj][3][n];
;             }
;         }
;         if (fr < 2 && wr == 0) {
; #pragma unroll
;             for (int bj = 0; bj < 2; ++bj)
; #pragma unroll
;                 for (int n = 0; n < 2; ++n) *(f32x4*)(HU + ((size_t)(u.pm * 4 + fr) * nN + u.pn) * 256 + 128 * bj + 32 * wc + 8 * fq + 4 * n) = acc[0][bj][0][n];
;         }
.LBB0_1635:
	v_cndmask_b32_e64 v128, 0, 1, s[14:15]
	v_cmp_ne_u32_e64 s[12:13], 1, v128
	s_and_saveexec_b64 s[68:69], s[8:9]
	s_cbranch_execz .LBB0_1638
	v_add_u32_e32 v128, s85, v202
	s_and_b64 vcc, exec, s[12:13]
	ds_write_b128 v208, v[100:103]
	ds_write_b128 v208, v[36:39] offset:16
	ds_write_b128 v208, v[96:99] offset:128
	ds_write_b128 v208, v[32:35] offset:144
	ds_write_b128 v128, v[68:71]
	ds_write_b128 v128, v[4:7] offset:16
	ds_write_b128 v209, v[64:67]
	ds_write_b128 v210, v[0:3]
	s_cbranch_vccnz .LBB0_1638
	s_ashr_i32 s40, s66, 31
	v_lshl_add_u32 v130, s64, 2, v203
	v_mov_b32_e32 v128, s66
	v_mov_b32_e32 v129, s40
	v_mad_i64_i32 v[128:129], s[40:41], v130, 44, v[128:129]
	v_lshlrev_b64 v[128:129], 10, v[128:129]
	v_lshl_add_u64 v[128:129], v[184:185], 0, v[128:129]
	flat_store_dwordx4 v[128:129], v[68:71] nt
	flat_store_dwordx4 v[128:129], v[4:7] offset:16 nt
	flat_store_dwordx4 v[128:129], v[64:67] offset:512 nt
	flat_store_dwordx4 v[128:129], v[0:3] offset:528 nt
.LBB0_1638:
	s_or_b64 exec, exec, s[68:69]
	s_and_saveexec_b64 s[68:69], s[42:43]
	s_cbranch_execz .LBB0_1640
	s_ashr_i32 s40, s66, 31
	v_lshl_or_b32 v130, s64, 2, v171
	v_mov_b32_e32 v128, s66
	v_mov_b32_e32 v129, s40
	v_mad_i64_i32 v[128:129], s[40:41], v130, 44, v[128:129]
	v_lshlrev_b64 v[128:129], 10, v[128:129]
	v_lshl_add_u64 v[128:129], v[184:185], 0, v[128:129]
	flat_store_dwordx4 v[128:129], v[124:127] nt
	flat_store_dwordx4 v[128:129], v[60:63] offset:16 nt
	flat_store_dwordx4 v[128:129], v[120:123] offset:512 nt
	flat_store_dwordx4 v[128:129], v[56:59] offset:528 nt

; #define PG8_LAS __attribute__((address_space(3)))
; __device__ __forceinline__ h2_t pkh(float a, float b) { return __builtin_bit_cast(h2_t, __builtin_amdgcn_cvt_pkrtz(a, b)); }
;     __device__ __forceinline__ void operator()(const f32x4 (&acc)[2][2][4][2], const Unit& u, int wr, int wc, int fr, int fq) const {
;     ...
;             for (int ai = 0; ai < 2; ++ai) {
;                 f32x4 pg = {0.f, 0.f, 0.f, 0.f}, pv = pg;
;                 const bool has = !(ai == 0 && wr == 0);
;                 if (has && fr >= 14) { const int pai = (wr == 1) ? ai : ai - 1, pwr = (wr == 1) ? 0 : 1;
;                     pg = *(const PG8_LAS f32x4*)(hl + hidx(pai, pwr, wc, fr - 14, 0, fq, n)); pv = *(const PG8_LAS f32x4*)(hl + hidx(pai, pwr, wc, fr - 14, 1, fq, n)); }
;                 h2_t qgh[2] = {pkh(pg[0], pg[1]), pkh(pg[2], pg[3])}, qvh[2] = {pkh(pv[0], pv[1]), pkh(pv[2], pv[3])};
; #pragma unroll
;                 for (int m = 0; m < 4; ++m) {
;                     const f32x4 cg = acc[ai][0][m][n], cv = acc[ai][1][m][n];
;                     const h2_t cgh[2] = {pkh(cg[0], cg[1]), pkh(cg[2], cg[3])}, cvh[2] = {pkh(cv[0], cv[1]), pkh(cv[2], cv[3])};
;                     float o[4];
; #pragma unroll
;                     for (int p = 0; p < 2; ++p) {
;                         const h2_t g1 = dpph1(qgh[p], cgh[p]), g2 = dpph2(qgh[p], cgh[p]);
;                         const h2_t v1 = dpph1(qvh[p], cvh[p]), v2 = dpph2(qvh[p], cvh[p]);
;                         const h2_t gg = wg2h[p] * cgh[p] + wg1h[p] * g1 + wg0h[p] * g2 + bgh[p];
;                         const h2_t vv = wv2h[p] * cvh[p] + wv1h[p] * v1 + wv0h[p] * v2 + bvh[p];
;                         const h2_t q = gg * gg * (h2_t){(_Float16)-0.10294325f, (_Float16)-0.10294325f} + (h2_t){(_Float16)-2.3022082f, (_Float16)-2.3022082f};
;                         const h2_t arg = gg * q;
;                         h2_t ex; ex.x = __builtin_exp2f16(arg.x); ex.y = __builtin_exp2f16(arg.y);
;                         const h2_t den = ex + (h2_t){(_Float16)1.0f, (_Float16)1.0f};
;                         h2_t rc; rc.x = __builtin_amdgcn_rcph(den.x); rc.y = __builtin_amdgcn_rcph(den.y);
;                         const h2_t og = gg * rc * vv;
;                         o[2 * p] = (float)og.x; o[2 * p + 1] = (float)og.y;
.LBB0_1646:
	s_or_b64 exec, exec, s[66:67]
	s_waitcnt lgkmcnt(1)
	v_cvt_pkrtz_f16_f32 v69, v120, v121
	v_cvt_pkrtz_f16_f32 v121, v56, v57
	v_mov_b32_e32 v56, v69
	s_waitcnt lgkmcnt(0)
	v_cvt_pkrtz_f16_f32 v116, v116, v117
	v_cvt_pkrtz_f16_f32 v117, v118, v119
	v_cvt_pkrtz_f16_f32 v118, v60, v61
	v_mov_b32_dpp v56, v56 row_ror:1 row_mask:0xf bank_mask:0xf
	s_waitcnt vmcnt(6)
	v_cvt_pk_f16_f32 v78, v92, v93
	v_cvt_pkrtz_f16_f32 v119, v62, v63
	v_mov_b32_dpp v56, v118 row_shr:1 row_mask:0xf bank_mask:0xf
	v_mov_b32_dpp v69, v69 row_ror:2 row_mask:0xf bank_mask:0xf
	s_waitcnt vmcnt(5)
	v_cvt_pk_f16_f32 v63, v104, v105
	v_pk_mul_f16 v56, v78, v56
	v_mov_b32_dpp v69, v118 row_shr:2 row_mask:0xf bank_mask:0xf
	v_pk_fma_f16 v56, v118, v63, v56
	v_cvt_pk_f16_f32 v79, v84, v85
	v_pk_fma_f16 v56, v79, v69, v56
	s_waitcnt vmcnt(1)
	v_cvt_pk_f16_f32 v92, v108, v109
	v_pk_add_f16 v56, v92, v56
	v_cvt_pkrtz_f16_f32 v120, v122, v123
	v_cvt_pkrtz_f16_f32 v122, v58, v59
	v_pk_mul_f16 v58, v56, v56
	v_cvt_pkrtz_f16_f32 v52, v52, v53
	v_pk_fma_f16 v58, v58, s89, v212 op_sel_hi:[1,0,0] neg_lo:[1,0,0] neg_hi:[1,0,0]
	v_cvt_pkrtz_f16_f32 v53, v54, v55
	v_pk_mul_f16 v58, v56, v58
	v_cvt_pkrtz_f16_f32 v54, v48, v49
	v_exp_f16_e32 v59, v58
	v_exp_f16_sdwa v58, v58 dst_sel:DWORD dst_unused:UNUSED_PAD src0_sel:WORD_1
	v_mov_b32_e32 v48, v118
	v_mov_b32_dpp v118, v118 row_ror:2 row_mask:0xf bank_mask:0xf
	v_cvt_pkrtz_f16_f32 v50, v50, v51
	v_mov_b32_dpp v48, v48 row_ror:1 row_mask:0xf bank_mask:0xf
	v_pack_b32_f16 v58, v59, v58
	v_pk_add_f16 v58, v58, 1.0 op_sel_hi:[1,0]
	v_mov_b32_dpp v48, v52 row_shr:1 row_mask:0xf bank_mask:0xf
	v_pk_mul_f16 v48, v78, v48
	v_rcp_f16_e32 v59, v58
	v_rcp_f16_sdwa v58, v58 dst_sel:DWORD dst_unused:UNUSED_PAD src0_sel:WORD_1
	v_mov_b32_dpp v118, v52 row_shr:2 row_mask:0xf bank_mask:0xf
	v_pk_fma_f16 v48, v52, v63, v48
	v_cvt_pk_f16_f32 v93, v94, v95
	v_pk_fma_f16 v48, v79, v118, v48
	v_pack_b32_f16 v58, v59, v58
	v_pk_add_f16 v48, v92, v48
	v_pk_mul_f16 v56, v56, v58
	v_pk_mul_f16 v51, v48, v48
	v_mov_b32_e32 v58, v120
	v_pk_fma_f16 v51, v51, s89, v212 op_sel_hi:[1,0,0] neg_lo:[1,0,0] neg_hi:[1,0,0]
	v_cvt_pk_f16_f32 v61, v88, v89
	v_pk_mul_f16 v51, v48, v51
	v_mov_b32_dpp v58, v58 row_ror:1 row_mask:0xf bank_mask:0xf
	v_exp_f16_e32 v55, v51
	v_exp_f16_sdwa v51, v51 dst_sel:DWORD dst_unused:UNUSED_PAD src0_sel:WORD_1
	v_mov_b32_dpp v58, v119 row_shr:1 row_mask:0xf bank_mask:0xf
	v_mov_b32_dpp v120, v120 row_ror:2 row_mask:0xf bank_mask:0xf
	v_cvt_pk_f16_f32 v89, v106, v107
	v_pk_mul_f16 v58, v93, v58
	v_mov_b32_dpp v120, v119 row_shr:2 row_mask:0xf bank_mask:0xf
	v_pk_fma_f16 v58, v119, v89, v58
	v_cvt_pk_f16_f32 v86, v86, v87
	v_mov_b32_e32 v57, v116
	v_pk_fma_f16 v58, v86, v120, v58
	v_cvt_pk_f16_f32 v87, v110, v111
	v_pack_b32_f16 v51, v55, v51
	v_mov_b32_dpp v57, v57 row_ror:1 row_mask:0xf bank_mask:0xf
	v_pk_add_f16 v58, v87, v58
	v_mov_b32_e32 v49, v121
	v_pk_add_f16 v51, v51, 1.0 op_sel_hi:[1,0]
	v_mov_b32_dpp v57, v121 row_shr:1 row_mask:0xf bank_mask:0xf
	v_pk_mul_f16 v69, v58, v58
	v_mov_b32_dpp v49, v49 row_ror:1 row_mask:0xf bank_mask:0xf
	v_rcp_f16_e32 v55, v51
	v_rcp_f16_sdwa v51, v51 dst_sel:DWORD dst_unused:UNUSED_PAD src0_sel:WORD_1
	v_mov_b32_dpp v116, v116 row_ror:2 row_mask:0xf bank_mask:0xf
	v_cvt_pk_f16_f32 v60, v100, v101
	v_pk_mul_f16 v57, v61, v57
	v_pk_fma_f16 v69, v69, s89, v212 op_sel_hi:[1,0,0] neg_lo:[1,0,0] neg_hi:[1,0,0]
	v_mov_b32_dpp v49, v54 row_shr:1 row_mask:0xf bank_mask:0xf
	v_cvt_pkrtz_f16_f32 v44, v44, v45
	v_cvt_pkrtz_f16_f32 v45, v46, v47
	v_cvt_pkrtz_f16_f32 v46, v40, v41
	v_mov_b32_e32 v40, v52
	v_mov_b32_dpp v116, v121 row_shr:2 row_mask:0xf bank_mask:0xf
	v_pk_fma_f16 v57, v121, v60, v57
	v_pk_mul_f16 v69, v58, v69
	v_mov_b32_dpp v121, v121 row_ror:2 row_mask:0xf bank_mask:0xf
	v_pk_mul_f16 v49, v61, v49
	v_mov_b32_dpp v40, v40 row_ror:1 row_mask:0xf bank_mask:0xf
	v_cvt_pk_f16_f32 v88, v70, v71
	v_exp_f16_e32 v70, v69
	v_exp_f16_sdwa v69, v69 dst_sel:DWORD dst_unused:UNUSED_PAD src0_sel:WORD_1
	v_mov_b32_dpp v121, v54 row_shr:2 row_mask:0xf bank_mask:0xf
	v_pk_fma_f16 v49, v54, v60, v49
	v_mov_b32_dpp v40, v44 row_shr:1 row_mask:0xf bank_mask:0xf
	s_waitcnt vmcnt(0)
	v_cvt_pk_f16_f32 v75, v74, v75
	v_pk_fma_f16 v49, v88, v121, v49
	v_pack_b32_f16 v51, v55, v51
	v_mov_b32_dpp v52, v52 row_ror:2 row_mask:0xf bank_mask:0xf
	v_pk_mul_f16 v40, v78, v40
	v_cvt_pkrtz_f16_f32 v32, v32, v33
	v_cvt_pkrtz_f16_f32 v33, v34, v35
	v_mov_b32_e32 v34, v44
	v_pk_add_f16 v49, v75, v49
	v_pk_mul_f16 v48, v48, v51
	v_mov_b32_dpp v52, v44 row_shr:2 row_mask:0xf bank_mask:0xf
	v_pk_fma_f16 v40, v44, v63, v40
	v_cvt_pkrtz_f16_f32 v36, v36, v37
	v_mov_b32_dpp v34, v34 row_ror:1 row_mask:0xf bank_mask:0xf
	v_pk_mul_f16 v48, v49, v48
	v_pk_fma_f16 v40, v79, v52, v40
	v_mov_b32_dpp v34, v36 row_shr:1 row_mask:0xf bank_mask:0xf
	v_pack_b32_f16 v69, v70, v69
	v_cvt_f32_f16_e32 v51, v48
	v_cvt_f32_f16_sdwa v55, v48 dst_sel:DWORD dst_unused:UNUSED_PAD src0_sel:WORD_1
	v_mov_b32_e32 v48, v119
	v_pk_add_f16 v40, v92, v40
	v_mov_b32_dpp v44, v44 row_ror:2 row_mask:0xf bank_mask:0xf
	v_pk_mul_f16 v34, v78, v34
	v_pk_add_f16 v69, v69, 1.0 op_sel_hi:[1,0]
	v_mov_b32_dpp v48, v48 row_ror:1 row_mask:0xf bank_mask:0xf
	v_cvt_pkrtz_f16_f32 v42, v42, v43
	v_pk_mul_f16 v43, v40, v40
	v_mov_b32_dpp v44, v36 row_shr:2 row_mask:0xf bank_mask:0xf
	v_pk_fma_f16 v34, v36, v63, v34
	v_rcp_f16_e32 v70, v69
	v_rcp_f16_sdwa v69, v69 dst_sel:DWORD dst_unused:UNUSED_PAD src0_sel:WORD_1
	v_mov_b32_dpp v48, v53 row_shr:1 row_mask:0xf bank_mask:0xf
	v_pk_fma_f16 v43, v43, s89, v212 op_sel_hi:[1,0,0] neg_lo:[1,0,0] neg_hi:[1,0,0]
; #define PG8_LAS __attribute__((address_space(3)))
;     __device__ __forceinline__ void operator()(const f32x4 (&acc)[2][2][4][2], const Unit& u, int wr, int wc, int fr, int fq) const {
;     ...
;             for (int ai = 0; ai < 2; ++ai) {
;                 f32x4 pg = {0.f, 0.f, 0.f, 0.f}, pv = pg;
;                 const bool has = !(ai == 0 && wr == 0);
;                 if (has && fr >= 14) { const int pai = (wr == 1) ? ai : ai - 1, pwr = (wr == 1) ? 0 : 1;
;                     pg = *(const PG8_LAS f32x4*)(hl + hidx(pai, pwr, wc, fr - 14, 0, fq, n)); pv = *(const PG8_LAS f32x4*)(hl + hidx(pai, pwr, wc, fr - 14, 1, fq, n)); }
;                 h2_t qgh[2] = {pkh(pg[0], pg[1]), pkh(pg[2], pg[3])}, qvh[2] = {pkh(pv[0], pv[1]), pkh(pv[2], pv[3])};
; #pragma unroll
;                 for (int m = 0; m < 4; ++m) {
;                     const f32x4 cg = acc[ai][0][m][n], cv = acc[ai][1][m][n];
;                     const h2_t cgh[2] = {pkh(cg[0], cg[1]), pkh(cg[2], cg[3])}, cvh[2] = {pkh(cv[0], cv[1]), pkh(cv[2], cv[3])};
;                     float o[4];
; #pragma unroll
;                     for (int p = 0; p < 2; ++p) {
;                         const h2_t g1 = dpph1(qgh[p], cgh[p]), g2 = dpph2(qgh[p], cgh[p]);
;                         const h2_t v1 = dpph1(qvh[p], cvh[p]), v2 = dpph2(qvh[p], cvh[p]);
;                         const h2_t gg = wg2h[p] * cgh[p] + wg1h[p] * g1 + wg0h[p] * g2 + bgh[p];
;                         const h2_t vv = wv2h[p] * cvh[p] + wv1h[p] * v1 + wv0h[p] * v2 + bvh[p];
;                         const h2_t q = gg * gg * (h2_t){(_Float16)-0.10294325f, (_Float16)-0.10294325f} + (h2_t){(_Float16)-2.3022082f, (_Float16)-2.3022082f};
;                         const h2_t arg = gg * q;
;                         h2_t ex; ex.x = __builtin_exp2f16(arg.x); ex.y = __builtin_exp2f16(arg.y);
;                         const h2_t den = ex + (h2_t){(_Float16)1.0f, (_Float16)1.0f};
;                         h2_t rc; rc.x = __builtin_amdgcn_rcph(den.x); rc.y = __builtin_amdgcn_rcph(den.y);
;                         const h2_t og = gg * rc * vv;
;                         o[2 * p] = (float)og.x; o[2 * p + 1] = (float)og.y;
;                         qgh[p] = cgh[p]; qvh[p] = cvh[p];
;                     }
;                     u32x2e w; w.x = cvt_pk_bf16(o[0], o[1]); w.y = cvt_pk_bf16(o[2], o[3]);
;                     if (n == 0) res[ai][m] = w;
	v_pk_fma_f16 v34, v79, v44, v34
	v_mov_b32_dpp v119, v119 row_ror:2 row_mask:0xf bank_mask:0xf
	v_pk_mul_f16 v48, v93, v48
	v_pk_mul_f16 v43, v40, v43
	v_pk_add_f16 v34, v92, v34
	v_mov_b32_dpp v119, v53 row_shr:2 row_mask:0xf bank_mask:0xf
	v_pk_fma_f16 v48, v53, v89, v48
	v_exp_f16_e32 v47, v43
	v_exp_f16_sdwa v43, v43 dst_sel:DWORD dst_unused:UNUSED_PAD src0_sel:WORD_1
	v_pk_mul_f16 v36, v34, v34
	v_pk_fma_f16 v48, v86, v119, v48
	v_pk_fma_f16 v36, v36, s89, v212 op_sel_hi:[1,0,0] neg_lo:[1,0,0] neg_hi:[1,0,0]
	v_pack_b32_f16 v69, v70, v69
	v_pk_add_f16 v48, v87, v48
	v_pk_mul_f16 v36, v34, v36
	v_pk_mul_f16 v58, v58, v69
	v_pk_mul_f16 v69, v48, v48
	v_cvt_pkrtz_f16_f32 v37, v38, v39
	v_exp_f16_e32 v38, v36
	v_exp_f16_sdwa v36, v36 dst_sel:DWORD dst_unused:UNUSED_PAD src0_sel:WORD_1
	v_pk_fma_f16 v69, v69, s89, v212 op_sel_hi:[1,0,0] neg_lo:[1,0,0] neg_hi:[1,0,0]
	v_pack_b32_f16 v43, v47, v43
	v_pk_mul_f16 v69, v48, v69
	v_mov_b32_e32 v41, v54
	v_pk_add_f16 v43, v43, 1.0 op_sel_hi:[1,0]
	v_cvt_pk_f16_f32 v76, v76, v77
	v_exp_f16_e32 v77, v69
	v_exp_f16_sdwa v69, v69 dst_sel:DWORD dst_unused:UNUSED_PAD src0_sel:WORD_1
	v_mov_b32_dpp v41, v41 row_ror:1 row_mask:0xf bank_mask:0xf
	v_rcp_f16_e32 v47, v43
	v_rcp_f16_sdwa v43, v43 dst_sel:DWORD dst_unused:UNUSED_PAD src0_sel:WORD_1
	v_mov_b32_dpp v41, v46 row_shr:1 row_mask:0xf bank_mask:0xf
	v_pack_b32_f16 v36, v38, v36
	v_mov_b32_e32 v59, v117
	v_mov_b32_dpp v54, v54 row_ror:2 row_mask:0xf bank_mask:0xf
	v_pk_mul_f16 v41, v61, v41
	v_mov_b32_e32 v35, v46
	v_pk_add_f16 v36, v36, 1.0 op_sel_hi:[1,0]
	v_mov_b32_dpp v59, v59 row_ror:1 row_mask:0xf bank_mask:0xf
	v_mov_b32_dpp v54, v46 row_shr:2 row_mask:0xf bank_mask:0xf
	v_pk_fma_f16 v41, v46, v60, v41
	v_mov_b32_dpp v35, v35 row_ror:1 row_mask:0xf bank_mask:0xf
	v_rcp_f16_e32 v38, v36
	v_rcp_f16_sdwa v36, v36 dst_sel:DWORD dst_unused:UNUSED_PAD src0_sel:WORD_1
	v_mov_b32_dpp v59, v122 row_shr:1 row_mask:0xf bank_mask:0xf
	v_cvt_pk_f16_f32 v74, v90, v91
	v_pack_b32_f16 v69, v77, v69
	v_pk_fma_f16 v41, v88, v54, v41
	v_pack_b32_f16 v43, v47, v43
	v_mov_b32_dpp v35, v32 row_shr:1 row_mask:0xf bank_mask:0xf
	v_mov_b32_dpp v117, v117 row_ror:2 row_mask:0xf bank_mask:0xf
	v_cvt_pk_f16_f32 v62, v102, v103
	v_pk_mul_f16 v59, v74, v59
	v_mov_b32_e32 v49, v122
	v_pk_add_f16 v69, v69, 1.0 op_sel_hi:[1,0]
	v_pk_add_f16 v41, v75, v41
	v_pk_mul_f16 v40, v40, v43
	v_mov_b32_dpp v46, v46 row_ror:2 row_mask:0xf bank_mask:0xf
	v_pk_mul_f16 v35, v61, v35
	v_mov_b32_dpp v117, v122 row_shr:2 row_mask:0xf bank_mask:0xf
	v_pk_fma_f16 v59, v122, v62, v59
	v_cvt_pk_f16_f32 v73, v72, v73
	v_mov_b32_dpp v49, v49 row_ror:1 row_mask:0xf bank_mask:0xf
	v_rcp_f16_e32 v77, v69
	v_rcp_f16_sdwa v69, v69 dst_sel:DWORD dst_unused:UNUSED_PAD src0_sel:WORD_1
	v_pk_mul_f16 v40, v41, v40
	v_mov_b32_dpp v46, v32 row_shr:2 row_mask:0xf bank_mask:0xf
	v_pk_fma_f16 v32, v32, v60, v35
	v_pk_fma_f16 v59, v73, v117, v59
	v_mov_b32_dpp v49, v50 row_shr:1 row_mask:0xf bank_mask:0xf
	v_cvt_f32_f16_e32 v43, v40
	v_cvt_f32_f16_sdwa v47, v40 dst_sel:DWORD dst_unused:UNUSED_PAD src0_sel:WORD_1
	v_mov_b32_e32 v40, v53
	v_pk_fma_f16 v32, v88, v46, v32
	v_pack_b32_f16 v35, v38, v36
	v_pk_fma_f16 v57, v88, v116, v57
	v_pk_add_f16 v59, v76, v59
	v_mov_b32_dpp v122, v122 row_ror:2 row_mask:0xf bank_mask:0xf
	v_pk_mul_f16 v49, v74, v49
	v_mov_b32_dpp v40, v40 row_ror:1 row_mask:0xf bank_mask:0xf
	v_pk_add_f16 v32, v75, v32
	v_pk_mul_f16 v34, v34, v35
	v_pk_add_f16 v57, v75, v57
	v_pk_mul_f16 v58, v59, v58
	v_mov_b32_dpp v122, v50 row_shr:2 row_mask:0xf bank_mask:0xf
	v_pk_fma_f16 v49, v50, v62, v49
	v_mov_b32_dpp v40, v45 row_shr:1 row_mask:0xf bank_mask:0xf
	v_pk_mul_f16 v32, v32, v34
	v_pk_mul_f16 v56, v57, v56
	v_cvt_f32_f16_e32 v59, v58
	v_cvt_f32_f16_sdwa v58, v58 dst_sel:DWORD dst_unused:UNUSED_PAD src0_sel:WORD_1
	v_pk_fma_f16 v49, v73, v122, v49
	v_pack_b32_f16 v69, v77, v69
	v_mov_b32_dpp v53, v53 row_ror:2 row_mask:0xf bank_mask:0xf
	v_pk_mul_f16 v40, v93, v40
	v_cvt_f32_f16_e32 v34, v32
	v_cvt_f32_f16_sdwa v35, v32 dst_sel:DWORD dst_unused:UNUSED_PAD src0_sel:WORD_1
	v_mov_b32_e32 v32, v45
	v_cvt_f32_f16_e32 v57, v56
	v_cvt_f32_f16_sdwa v56, v56 dst_sel:DWORD dst_unused:UNUSED_PAD src0_sel:WORD_1
	v_lshl_add_u32 v72, s64, 8, v173
	v_cvt_pk_bf16_f32 v116, v57, v56
	v_cvt_pk_bf16_f32 v117, v59, v58
	v_mov_b64_e32 v[58:59], s[34:35]
	v_pk_add_f16 v49, v76, v49
	v_pk_mul_f16 v48, v48, v69
	v_mov_b32_dpp v53, v45 row_shr:2 row_mask:0xf bank_mask:0xf
	v_pk_fma_f16 v40, v45, v89, v40
	v_mov_b32_dpp v32, v32 row_ror:1 row_mask:0xf bank_mask:0xf
	v_mad_i64_i32 v[70:71], s[40:41], v72, s90, v[58:59]
	v_lshlrev_b64 v[56:57], 1, v[194:195]
	v_pk_mul_f16 v48, v49, v48
	v_pk_fma_f16 v40, v86, v53, v40
	v_mov_b32_dpp v32, v37 row_shr:1 row_mask:0xf bank_mask:0xf
	v_cvt_f32_f16_e32 v69, v48
	v_cvt_f32_f16_sdwa v77, v48 dst_sel:DWORD dst_unused:UNUSED_PAD src0_sel:WORD_1
	v_lshl_add_u64 v[48:49], v[70:71], 0, v[56:57]
	v_pk_add_f16 v40, v87, v40
	v_mov_b32_dpp v45, v45 row_ror:2 row_mask:0xf bank_mask:0xf
	v_pk_mul_f16 v32, v93, v32
	flat_store_dwordx4 v[48:49], v[114:117] nt
	v_mov_b32_dpp v45, v37 row_shr:2 row_mask:0xf bank_mask:0xf
	v_pk_fma_f16 v32, v37, v89, v32
	v_cvt_pk_bf16_f32 v114, v51, v55
	v_pk_mul_f16 v51, v40, v40
	v_pk_fma_f16 v32, v86, v45, v32
	v_pk_fma_f16 v51, v51, s89, v212 op_sel_hi:[1,0,0] neg_lo:[1,0,0] neg_hi:[1,0,0]
	v_pk_add_f16 v32, v87, v32
	v_pk_mul_f16 v51, v40, v51
	v_pk_mul_f16 v37, v32, v32
	v_exp_f16_e32 v52, v51
	v_exp_f16_sdwa v51, v51 dst_sel:DWORD dst_unused:UNUSED_PAD src0_sel:WORD_1
	v_pk_fma_f16 v37, v37, s89, v212 op_sel_hi:[1,0,0] neg_lo:[1,0,0] neg_hi:[1,0,0]
; #define PG8_LAS __attribute__((address_space(3)))
;     __device__ __forceinline__ void operator()(const f32x4 (&acc)[2][2][4][2], const Unit& u, int wr, int wc, int fr, int fq) const {
;     ...
;             for (int ai = 0; ai < 2; ++ai) {
;                 f32x4 pg = {0.f, 0.f, 0.f, 0.f}, pv = pg;
;                 const bool has = !(ai == 0 && wr == 0);
;                 if (has && fr >= 14) { const int pai = (wr == 1) ? ai : ai - 1, pwr = (wr == 1) ? 0 : 1;
;                     pg = *(const PG8_LAS f32x4*)(hl + hidx(pai, pwr, wc, fr - 14, 0, fq, n)); pv = *(const PG8_LAS f32x4*)(hl + hidx(pai, pwr, wc, fr - 14, 1, fq, n)); }
;                 h2_t qgh[2] = {pkh(pg[0], pg[1]), pkh(pg[2], pg[3])}, qvh[2] = {pkh(pv[0], pv[1]), pkh(pv[2], pv[3])};
; #pragma unroll
;                 for (int m = 0; m < 4; ++m) {
;                     const f32x4 cg = acc[ai][0][m][n], cv = acc[ai][1][m][n];
;                     const h2_t cgh[2] = {pkh(cg[0], cg[1]), pkh(cg[2], cg[3])}, cvh[2] = {pkh(cv[0], cv[1]), pkh(cv[2], cv[3])};
;                     float o[4];
; #pragma unroll
;                     for (int p = 0; p < 2; ++p) {
;                         const h2_t g1 = dpph1(qgh[p], cgh[p]), g2 = dpph2(qgh[p], cgh[p]);
;                         const h2_t v1 = dpph1(qvh[p], cvh[p]), v2 = dpph2(qvh[p], cvh[p]);
;                         const h2_t gg = wg2h[p] * cgh[p] + wg1h[p] * g1 + wg0h[p] * g2 + bgh[p];
;                         const h2_t vv = wv2h[p] * cvh[p] + wv1h[p] * v1 + wv0h[p] * v2 + bvh[p];
;                         const h2_t q = gg * gg * (h2_t){(_Float16)-0.10294325f, (_Float16)-0.10294325f} + (h2_t){(_Float16)-2.3022082f, (_Float16)-2.3022082f};
;                         const h2_t arg = gg * q;
;                         h2_t ex; ex.x = __builtin_exp2f16(arg.x); ex.y = __builtin_exp2f16(arg.y);
;                         const h2_t den = ex + (h2_t){(_Float16)1.0f, (_Float16)1.0f};
;                         h2_t rc; rc.x = __builtin_amdgcn_rcph(den.x); rc.y = __builtin_amdgcn_rcph(den.y);
;                         const h2_t og = gg * rc * vv;
;                         o[2 * p] = (float)og.x; o[2 * p + 1] = (float)og.y;
;                         qgh[p] = cgh[p]; qvh[p] = cvh[p];
;                     }
;                     u32x2e w; w.x = cvt_pk_bf16(o[0], o[1]); w.y = cvt_pk_bf16(o[2], o[3]);
;                     if (n == 0) res[ai][m] = w;
	v_mov_b32_e32 v41, v50
	v_pk_mul_f16 v37, v32, v37
	v_pack_b32_f16 v51, v52, v51
	v_exp_f16_e32 v38, v37
	v_exp_f16_sdwa v37, v37 dst_sel:DWORD dst_unused:UNUSED_PAD src0_sel:WORD_1
	v_pk_add_f16 v51, v51, 1.0 op_sel_hi:[1,0]
	v_mov_b32_dpp v41, v41 row_ror:1 row_mask:0xf bank_mask:0xf
	v_rcp_f16_e32 v52, v51
	v_rcp_f16_sdwa v51, v51 dst_sel:DWORD dst_unused:UNUSED_PAD src0_sel:WORD_1
	v_mov_b32_dpp v41, v42 row_shr:1 row_mask:0xf bank_mask:0xf
	v_pack_b32_f16 v37, v38, v37
	v_mov_b32_dpp v50, v50 row_ror:2 row_mask:0xf bank_mask:0xf
	v_pk_mul_f16 v41, v74, v41
	v_mov_b32_e32 v36, v42
	v_pk_add_f16 v37, v37, 1.0 op_sel_hi:[1,0]
	v_mov_b32_dpp v50, v42 row_shr:2 row_mask:0xf bank_mask:0xf
	v_pk_fma_f16 v41, v42, v62, v41
	v_mov_b32_dpp v36, v36 row_ror:1 row_mask:0xf bank_mask:0xf
	v_rcp_f16_e32 v38, v37
	v_rcp_f16_sdwa v37, v37 dst_sel:DWORD dst_unused:UNUSED_PAD src0_sel:WORD_1
	v_pk_fma_f16 v41, v73, v50, v41
	v_pack_b32_f16 v50, v52, v51
	v_mov_b32_dpp v36, v33 row_shr:1 row_mask:0xf bank_mask:0xf
	v_or_b32_e32 v48, 16, v72
	v_pk_add_f16 v41, v76, v41
	v_pk_mul_f16 v40, v40, v50
	v_mov_b32_dpp v42, v42 row_ror:2 row_mask:0xf bank_mask:0xf
	v_pk_mul_f16 v36, v74, v36
	v_mad_i64_i32 v[48:49], s[40:41], v48, s90, v[58:59]
	v_pk_mul_f16 v40, v41, v40
	v_mov_b32_dpp v42, v33 row_shr:2 row_mask:0xf bank_mask:0xf
	v_pk_fma_f16 v33, v33, v62, v36
	v_cvt_f32_f16_e32 v50, v40
	v_cvt_f32_f16_sdwa v51, v40 dst_sel:DWORD dst_unused:UNUSED_PAD src0_sel:WORD_1
	v_lshl_add_u64 v[40:41], v[48:49], 0, v[56:57]
	v_pk_fma_f16 v33, v73, v42, v33
	v_pack_b32_f16 v36, v38, v37
	v_cvt_pk_bf16_f32 v115, v69, v77
	flat_store_dwordx4 v[40:41], v[112:115] nt
	v_or_b32_e32 v40, 32, v72
	v_pk_add_f16 v33, v76, v33
	v_pk_mul_f16 v32, v32, v36
	v_mad_i64_i32 v[40:41], s[40:41], v40, s90, v[58:59]
	v_pk_mul_f16 v32, v33, v32
	v_cvt_pk_bf16_f32 v100, v43, v47
	v_cvt_pk_bf16_f32 v101, v50, v51
	v_mov_b32_e32 v69, 0
	v_cvt_f32_f16_e32 v36, v32
	v_cvt_f32_f16_sdwa v37, v32 dst_sel:DWORD dst_unused:UNUSED_PAD src0_sel:WORD_1
	v_lshl_add_u64 v[32:33], v[40:41], 0, v[56:57]
	flat_store_dwordx4 v[32:33], v[98:101] nt
	v_or_b32_e32 v32, 48, v72
	v_mad_i64_i32 v[32:33], s[40:41], v32, s90, v[58:59]
	v_lshl_add_u64 v[32:33], v[32:33], 0, v[56:57]
	v_cvt_pk_bf16_f32 v98, v34, v35
	v_cvt_pk_bf16_f32 v99, v36, v37
	flat_store_dwordx4 v[32:33], v[96:99] nt
	v_mov_b32_e32 v70, 0
	v_mov_b32_e32 v71, 0
	v_mov_b32_e32 v32, 0
	v_mov_b32_e32 v33, 0
	v_mov_b32_e32 v34, 0
	v_mov_b32_e32 v35, 0
	s_and_saveexec_b64 s[64:65], s[8:9]
	s_cbranch_execz .LBB0_1648
	ds_read_b128 v[32:35], v213 offset:16
	ds_read_b128 v[68:71], v213 offset:144
.LBB0_1648:
	s_or_b64 exec, exec, s[64:65]
	s_waitcnt lgkmcnt(0)
	v_cvt_pkrtz_f16_f32 v32, v32, v33
	v_cvt_pkrtz_f16_f32 v28, v28, v29
	v_cvt_pkrtz_f16_f32 v29, v30, v31
	v_cvt_pkrtz_f16_f32 v30, v24, v25
	v_mov_b32_e32 v24, v32
	v_cvt_pkrtz_f16_f32 v20, v20, v21
	v_cvt_pkrtz_f16_f32 v21, v22, v23
	v_mov_b32_dpp v24, v24 row_ror:1 row_mask:0xf bank_mask:0xf
	v_cvt_pkrtz_f16_f32 v22, v16, v17
	v_mov_b32_e32 v16, v28
	v_mov_b32_dpp v24, v28 row_shr:1 row_mask:0xf bank_mask:0xf
	v_mov_b32_dpp v32, v32 row_ror:2 row_mask:0xf bank_mask:0xf
	v_mov_b32_dpp v16, v16 row_ror:1 row_mask:0xf bank_mask:0xf
	v_pk_mul_f16 v24, v78, v24
	v_mov_b32_dpp v32, v28 row_shr:2 row_mask:0xf bank_mask:0xf
	v_mov_b32_dpp v16, v20 row_shr:1 row_mask:0xf bank_mask:0xf
	v_pk_fma_f16 v24, v28, v63, v24
	v_mov_b32_dpp v28, v28 row_ror:2 row_mask:0xf bank_mask:0xf
	v_pk_mul_f16 v16, v78, v16
	v_pk_fma_f16 v24, v79, v32, v24
	v_mov_b32_dpp v28, v20 row_shr:2 row_mask:0xf bank_mask:0xf
	v_pk_fma_f16 v16, v20, v63, v16
	v_pk_add_f16 v24, v92, v24
	v_pk_fma_f16 v16, v79, v28, v16
	v_cvt_pkrtz_f16_f32 v31, v26, v27
	v_pk_add_f16 v16, v92, v16
	v_pk_mul_f16 v26, v24, v24
	v_cvt_pkrtz_f16_f32 v18, v18, v19
	v_pk_mul_f16 v19, v16, v16
	v_pk_fma_f16 v26, v26, s89, v212 op_sel_hi:[1,0,0] neg_lo:[1,0,0] neg_hi:[1,0,0]
	v_pk_fma_f16 v19, v19, s89, v212 op_sel_hi:[1,0,0] neg_lo:[1,0,0] neg_hi:[1,0,0]
	v_pk_mul_f16 v26, v24, v26
	v_pk_mul_f16 v19, v16, v19
	v_exp_f16_e32 v27, v26
	v_exp_f16_sdwa v26, v26 dst_sel:DWORD dst_unused:UNUSED_PAD src0_sel:WORD_1
	v_exp_f16_e32 v23, v19
	v_exp_f16_sdwa v19, v19 dst_sel:DWORD dst_unused:UNUSED_PAD src0_sel:WORD_1
	v_cvt_pkrtz_f16_f32 v33, v34, v35
	v_cvt_pkrtz_f16_f32 v34, v68, v69
	v_mov_b32_e32 v25, v34
	v_pack_b32_f16 v26, v27, v26
	v_pack_b32_f16 v19, v23, v19
	v_mov_b32_dpp v25, v25 row_ror:1 row_mask:0xf bank_mask:0xf
	v_pk_add_f16 v26, v26, 1.0 op_sel_hi:[1,0]
	v_mov_b32_e32 v17, v30
	v_pk_add_f16 v19, v19, 1.0 op_sel_hi:[1,0]
	v_mov_b32_dpp v25, v30 row_shr:1 row_mask:0xf bank_mask:0xf
	v_rcp_f16_e32 v27, v26
	v_rcp_f16_sdwa v26, v26 dst_sel:DWORD dst_unused:UNUSED_PAD src0_sel:WORD_1
	v_mov_b32_dpp v17, v17 row_ror:1 row_mask:0xf bank_mask:0xf
	v_rcp_f16_e32 v23, v19
	v_rcp_f16_sdwa v19, v19 dst_sel:DWORD dst_unused:UNUSED_PAD src0_sel:WORD_1
	v_mov_b32_dpp v34, v34 row_ror:2 row_mask:0xf bank_mask:0xf
	v_pk_mul_f16 v25, v61, v25
	v_mov_b32_dpp v17, v22 row_shr:1 row_mask:0xf bank_mask:0xf
	v_cvt_pkrtz_f16_f32 v12, v12, v13
	v_cvt_pkrtz_f16_f32 v13, v14, v15
	v_cvt_pkrtz_f16_f32 v14, v8, v9
	v_mov_b32_e32 v8, v20
	v_mov_b32_dpp v34, v30 row_shr:2 row_mask:0xf bank_mask:0xf
	v_pk_fma_f16 v25, v30, v60, v25
	v_mov_b32_dpp v30, v30 row_ror:2 row_mask:0xf bank_mask:0xf
	v_pk_mul_f16 v17, v61, v17
	v_mov_b32_dpp v8, v8 row_ror:1 row_mask:0xf bank_mask:0xf
	v_mov_b32_dpp v30, v22 row_shr:2 row_mask:0xf bank_mask:0xf
	v_pk_fma_f16 v17, v22, v60, v17
	v_mov_b32_dpp v8, v12 row_shr:1 row_mask:0xf bank_mask:0xf
	v_pack_b32_f16 v26, v27, v26
	v_pk_fma_f16 v17, v88, v30, v17
; __device__ __forceinline__ h2_t pkh(float a, float b) { return __builtin_bit_cast(h2_t, __builtin_amdgcn_cvt_pkrtz(a, b)); }
;     __device__ __forceinline__ void operator()(const f32x4 (&acc)[2][2][4][2], const Unit& u, int wr, int wc, int fr, int fq) const {
;     ...
;                 for (int m = 0; m < 4; ++m) {
;                     const f32x4 cg = acc[ai][0][m][n], cv = acc[ai][1][m][n];
;                     const h2_t cgh[2] = {pkh(cg[0], cg[1]), pkh(cg[2], cg[3])}, cvh[2] = {pkh(cv[0], cv[1]), pkh(cv[2], cv[3])};
;                     float o[4];
; #pragma unroll
;                     for (int p = 0; p < 2; ++p) {
;                         const h2_t g1 = dpph1(qgh[p], cgh[p]), g2 = dpph2(qgh[p], cgh[p]);
;                         const h2_t v1 = dpph1(qvh[p], cvh[p]), v2 = dpph2(qvh[p], cvh[p]);
;                         const h2_t gg = wg2h[p] * cgh[p] + wg1h[p] * g1 + wg0h[p] * g2 + bgh[p];
;                         const h2_t vv = wv2h[p] * cvh[p] + wv1h[p] * v1 + wv0h[p] * v2 + bvh[p];
;                         const h2_t q = gg * gg * (h2_t){(_Float16)-0.10294325f, (_Float16)-0.10294325f} + (h2_t){(_Float16)-2.3022082f, (_Float16)-2.3022082f};
;                         const h2_t arg = gg * q;
;                         h2_t ex; ex.x = __builtin_exp2f16(arg.x); ex.y = __builtin_exp2f16(arg.y);
;                         const h2_t den = ex + (h2_t){(_Float16)1.0f, (_Float16)1.0f};
;                         h2_t rc; rc.x = __builtin_amdgcn_rcph(den.x); rc.y = __builtin_amdgcn_rcph(den.y);
;                         const h2_t og = gg * rc * vv;
;                         o[2 * p] = (float)og.x; o[2 * p + 1] = (float)og.y;
;                         qgh[p] = cgh[p]; qvh[p] = cvh[p];
;                     }
	v_pack_b32_f16 v19, v23, v19
	v_mov_b32_dpp v20, v20 row_ror:2 row_mask:0xf bank_mask:0xf
	v_pk_mul_f16 v8, v78, v8
	v_cvt_pkrtz_f16_f32 v0, v0, v1
	v_cvt_pkrtz_f16_f32 v1, v2, v3
	v_mov_b32_e32 v2, v12
	v_pk_mul_f16 v24, v24, v26
	v_mov_b32_e32 v26, v33
	v_pk_add_f16 v17, v75, v17
	v_pk_mul_f16 v16, v16, v19
	v_mov_b32_dpp v20, v12 row_shr:2 row_mask:0xf bank_mask:0xf
	v_pk_fma_f16 v8, v12, v63, v8
	v_cvt_pkrtz_f16_f32 v4, v4, v5
	v_mov_b32_dpp v2, v2 row_ror:1 row_mask:0xf bank_mask:0xf
	v_mov_b32_dpp v26, v26 row_ror:1 row_mask:0xf bank_mask:0xf
	v_pk_mul_f16 v16, v17, v16
	v_pk_fma_f16 v8, v79, v20, v8
	v_mov_b32_dpp v2, v4 row_shr:1 row_mask:0xf bank_mask:0xf
	v_mov_b32_dpp v26, v29 row_shr:1 row_mask:0xf bank_mask:0xf
	v_cvt_f32_f16_e32 v19, v16
	v_cvt_f32_f16_sdwa v23, v16 dst_sel:DWORD dst_unused:UNUSED_PAD src0_sel:WORD_1
	v_mov_b32_e32 v16, v29
	v_pk_add_f16 v8, v92, v8
	v_mov_b32_dpp v12, v12 row_ror:2 row_mask:0xf bank_mask:0xf
	v_pk_mul_f16 v2, v78, v2
	v_mov_b32_dpp v33, v33 row_ror:2 row_mask:0xf bank_mask:0xf
	v_pk_mul_f16 v26, v93, v26
	v_mov_b32_dpp v16, v16 row_ror:1 row_mask:0xf bank_mask:0xf
	v_cvt_pkrtz_f16_f32 v10, v10, v11
	v_pk_mul_f16 v11, v8, v8
	v_mov_b32_dpp v12, v4 row_shr:2 row_mask:0xf bank_mask:0xf
	v_pk_fma_f16 v2, v4, v63, v2
	v_mov_b32_dpp v33, v29 row_shr:2 row_mask:0xf bank_mask:0xf
	v_pk_fma_f16 v26, v29, v89, v26
	v_mov_b32_dpp v16, v21 row_shr:1 row_mask:0xf bank_mask:0xf
	v_pk_fma_f16 v11, v11, s89, v212 op_sel_hi:[1,0,0] neg_lo:[1,0,0] neg_hi:[1,0,0]
	v_pk_fma_f16 v2, v79, v12, v2
	v_pk_fma_f16 v26, v86, v33, v26
	v_mov_b32_dpp v29, v29 row_ror:2 row_mask:0xf bank_mask:0xf
	v_pk_mul_f16 v16, v93, v16
	v_pk_mul_f16 v11, v8, v11
	v_pk_add_f16 v2, v92, v2
	v_pk_add_f16 v26, v87, v26
	v_mov_b32_dpp v29, v21 row_shr:2 row_mask:0xf bank_mask:0xf
	v_pk_fma_f16 v16, v21, v89, v16
	v_exp_f16_e32 v15, v11
	v_exp_f16_sdwa v11, v11 dst_sel:DWORD dst_unused:UNUSED_PAD src0_sel:WORD_1
	v_pk_mul_f16 v4, v2, v2
	v_pk_mul_f16 v32, v26, v26
	v_pk_fma_f16 v16, v86, v29, v16
	v_pk_fma_f16 v4, v4, s89, v212 op_sel_hi:[1,0,0] neg_lo:[1,0,0] neg_hi:[1,0,0]
	v_pk_fma_f16 v32, v32, s89, v212 op_sel_hi:[1,0,0] neg_lo:[1,0,0] neg_hi:[1,0,0]
	v_pk_add_f16 v16, v87, v16
	v_pk_mul_f16 v4, v2, v4
	v_pk_mul_f16 v32, v26, v32
	v_pk_mul_f16 v28, v16, v16
	v_cvt_pkrtz_f16_f32 v5, v6, v7
	v_exp_f16_e32 v6, v4
	v_exp_f16_sdwa v4, v4 dst_sel:DWORD dst_unused:UNUSED_PAD src0_sel:WORD_1
	v_exp_f16_e32 v33, v32
	v_exp_f16_sdwa v32, v32 dst_sel:DWORD dst_unused:UNUSED_PAD src0_sel:WORD_1
	v_pk_fma_f16 v28, v28, s89, v212 op_sel_hi:[1,0,0] neg_lo:[1,0,0] neg_hi:[1,0,0]
	v_pack_b32_f16 v11, v15, v11
	v_pk_mul_f16 v28, v16, v28
	v_mov_b32_e32 v9, v22
	v_pk_add_f16 v11, v11, 1.0 op_sel_hi:[1,0]
	v_exp_f16_e32 v29, v28
	v_exp_f16_sdwa v28, v28 dst_sel:DWORD dst_unused:UNUSED_PAD src0_sel:WORD_1
	v_mov_b32_dpp v9, v9 row_ror:1 row_mask:0xf bank_mask:0xf
	v_rcp_f16_e32 v15, v11
	v_rcp_f16_sdwa v11, v11 dst_sel:DWORD dst_unused:UNUSED_PAD src0_sel:WORD_1
	v_mov_b32_dpp v9, v14 row_shr:1 row_mask:0xf bank_mask:0xf
	v_pack_b32_f16 v4, v6, v4
	v_cvt_pkrtz_f16_f32 v35, v70, v71
	v_pack_b32_f16 v32, v33, v32
	v_mov_b32_dpp v22, v22 row_ror:2 row_mask:0xf bank_mask:0xf
	v_pk_mul_f16 v9, v61, v9
	v_mov_b32_e32 v3, v14
	v_pk_add_f16 v4, v4, 1.0 op_sel_hi:[1,0]
	v_mov_b32_e32 v27, v35
	v_pk_add_f16 v32, v32, 1.0 op_sel_hi:[1,0]
	v_mov_b32_dpp v22, v14 row_shr:2 row_mask:0xf bank_mask:0xf
	v_pk_fma_f16 v9, v14, v60, v9
	v_mov_b32_dpp v3, v3 row_ror:1 row_mask:0xf bank_mask:0xf
	v_rcp_f16_e32 v6, v4
	v_rcp_f16_sdwa v4, v4 dst_sel:DWORD dst_unused:UNUSED_PAD src0_sel:WORD_1
	v_mov_b32_dpp v27, v27 row_ror:1 row_mask:0xf bank_mask:0xf
	v_rcp_f16_e32 v33, v32
	v_rcp_f16_sdwa v32, v32 dst_sel:DWORD dst_unused:UNUSED_PAD src0_sel:WORD_1
	v_pack_b32_f16 v28, v29, v28
	v_pk_fma_f16 v9, v88, v22, v9
	v_pack_b32_f16 v11, v15, v11
	v_mov_b32_dpp v3, v0 row_shr:1 row_mask:0xf bank_mask:0xf
	v_mov_b32_dpp v27, v31 row_shr:1 row_mask:0xf bank_mask:0xf
	v_mov_b32_e32 v17, v31
	v_pk_add_f16 v28, v28, 1.0 op_sel_hi:[1,0]
	v_pk_add_f16 v9, v75, v9
	v_pk_mul_f16 v8, v8, v11
	v_mov_b32_dpp v14, v14 row_ror:2 row_mask:0xf bank_mask:0xf
	v_pk_mul_f16 v3, v61, v3
	v_mov_b32_dpp v35, v35 row_ror:2 row_mask:0xf bank_mask:0xf
	v_pk_mul_f16 v27, v74, v27
	v_mov_b32_dpp v17, v17 row_ror:1 row_mask:0xf bank_mask:0xf
	v_rcp_f16_e32 v29, v28
	v_rcp_f16_sdwa v28, v28 dst_sel:DWORD dst_unused:UNUSED_PAD src0_sel:WORD_1
	v_pk_mul_f16 v8, v9, v8
	v_mov_b32_dpp v14, v0 row_shr:2 row_mask:0xf bank_mask:0xf
	v_pk_fma_f16 v0, v0, v60, v3
	v_pk_fma_f16 v25, v88, v34, v25
	v_mov_b32_dpp v35, v31 row_shr:2 row_mask:0xf bank_mask:0xf
	v_pk_fma_f16 v27, v31, v62, v27
	v_mov_b32_dpp v17, v18 row_shr:1 row_mask:0xf bank_mask:0xf
	v_cvt_f32_f16_e32 v11, v8
	v_cvt_f32_f16_sdwa v15, v8 dst_sel:DWORD dst_unused:UNUSED_PAD src0_sel:WORD_1
	v_mov_b32_e32 v8, v21
; #define PG8_LAS __attribute__((address_space(3)))
;     __device__ __forceinline__ void operator()(const f32x4 (&acc)[2][2][4][2], const Unit& u, int wr, int wc, int fr, int fq) const {
;     ...
;             for (int ai = 0; ai < 2; ++ai) {
;                 f32x4 pg = {0.f, 0.f, 0.f, 0.f}, pv = pg;
;                 const bool has = !(ai == 0 && wr == 0);
;                 if (has && fr >= 14) { const int pai = (wr == 1) ? ai : ai - 1, pwr = (wr == 1) ? 0 : 1;
;                     pg = *(const PG8_LAS f32x4*)(hl + hidx(pai, pwr, wc, fr - 14, 0, fq, n)); pv = *(const PG8_LAS f32x4*)(hl + hidx(pai, pwr, wc, fr - 14, 1, fq, n)); }
;                 h2_t qgh[2] = {pkh(pg[0], pg[1]), pkh(pg[2], pg[3])}, qvh[2] = {pkh(pv[0], pv[1]), pkh(pv[2], pv[3])};
; #pragma unroll
;                 for (int m = 0; m < 4; ++m) {
;                     const f32x4 cg = acc[ai][0][m][n], cv = acc[ai][1][m][n];
;                     const h2_t cgh[2] = {pkh(cg[0], cg[1]), pkh(cg[2], cg[3])}, cvh[2] = {pkh(cv[0], cv[1]), pkh(cv[2], cv[3])};
;                     float o[4];
; #pragma unroll
;                     for (int p = 0; p < 2; ++p) {
;                         const h2_t g1 = dpph1(qgh[p], cgh[p]), g2 = dpph2(qgh[p], cgh[p]);
;                         const h2_t v1 = dpph1(qvh[p], cvh[p]), v2 = dpph2(qvh[p], cvh[p]);
;                         const h2_t gg = wg2h[p] * cgh[p] + wg1h[p] * g1 + wg0h[p] * g2 + bgh[p];
;                         const h2_t vv = wv2h[p] * cvh[p] + wv1h[p] * v1 + wv0h[p] * v2 + bvh[p];
;                         const h2_t q = gg * gg * (h2_t){(_Float16)-0.10294325f, (_Float16)-0.10294325f} + (h2_t){(_Float16)-2.3022082f, (_Float16)-2.3022082f};
;                         const h2_t arg = gg * q;
;                         h2_t ex; ex.x = __builtin_exp2f16(arg.x); ex.y = __builtin_exp2f16(arg.y);
;                         const h2_t den = ex + (h2_t){(_Float16)1.0f, (_Float16)1.0f};
;                         h2_t rc; rc.x = __builtin_amdgcn_rcph(den.x); rc.y = __builtin_amdgcn_rcph(den.y);
;                         const h2_t og = gg * rc * vv;
;                         o[2 * p] = (float)og.x; o[2 * p + 1] = (float)og.y;
;                         qgh[p] = cgh[p]; qvh[p] = cvh[p];
;                     }
;                     u32x2e w; w.x = cvt_pk_bf16(o[0], o[1]); w.y = cvt_pk_bf16(o[2], o[3]);
;                     if (n == 0) res[ai][m] = w;
	v_pk_fma_f16 v0, v88, v14, v0
	v_pack_b32_f16 v3, v6, v4
	v_pk_add_f16 v25, v75, v25
	v_pk_fma_f16 v27, v73, v35, v27
	v_pack_b32_f16 v32, v33, v32
	v_mov_b32_dpp v31, v31 row_ror:2 row_mask:0xf bank_mask:0xf
	v_pk_mul_f16 v17, v74, v17
	v_mov_b32_dpp v8, v8 row_ror:1 row_mask:0xf bank_mask:0xf
	v_pk_add_f16 v0, v75, v0
	v_pk_mul_f16 v2, v2, v3
	v_pk_mul_f16 v24, v25, v24
	v_pk_add_f16 v27, v76, v27
	v_pk_mul_f16 v26, v26, v32
	v_mov_b32_dpp v31, v18 row_shr:2 row_mask:0xf bank_mask:0xf
	v_pk_fma_f16 v17, v18, v62, v17
	v_mov_b32_dpp v8, v13 row_shr:1 row_mask:0xf bank_mask:0xf
	v_pk_mul_f16 v0, v0, v2
	v_cvt_f32_f16_e32 v25, v24
	v_cvt_f32_f16_sdwa v24, v24 dst_sel:DWORD dst_unused:UNUSED_PAD src0_sel:WORD_1
	v_pk_mul_f16 v26, v27, v26
	v_pk_fma_f16 v17, v73, v31, v17
	v_pack_b32_f16 v28, v29, v28
	v_mov_b32_dpp v21, v21 row_ror:2 row_mask:0xf bank_mask:0xf
	v_pk_mul_f16 v8, v93, v8
	v_cvt_f32_f16_e32 v2, v0
	v_cvt_f32_f16_sdwa v3, v0 dst_sel:DWORD dst_unused:UNUSED_PAD src0_sel:WORD_1
	v_mov_b32_e32 v0, v13
	v_cvt_f32_f16_e32 v27, v26
	v_cvt_f32_f16_sdwa v26, v26 dst_sel:DWORD dst_unused:UNUSED_PAD src0_sel:WORD_1
	v_add_u32_e32 v32, 0x80, v72
	v_cvt_pk_bf16_f32 v84, v25, v24
	v_mov_b64_e32 v[24:25], s[34:35]
	v_pk_add_f16 v17, v76, v17
	v_pk_mul_f16 v16, v16, v28
	v_mov_b32_dpp v21, v13 row_shr:2 row_mask:0xf bank_mask:0xf
	v_pk_fma_f16 v8, v13, v89, v8
	v_mov_b32_dpp v0, v0 row_ror:1 row_mask:0xf bank_mask:0xf
	v_cvt_pk_bf16_f32 v85, v27, v26
	v_mad_i64_i32 v[26:27], s[40:41], v32, s90, v[24:25]
	v_pk_mul_f16 v16, v17, v16
	v_pk_fma_f16 v8, v86, v21, v8
	v_mov_b32_dpp v0, v5 row_shr:1 row_mask:0xf bank_mask:0xf
	v_cvt_f32_f16_e32 v28, v16
	v_cvt_f32_f16_sdwa v29, v16 dst_sel:DWORD dst_unused:UNUSED_PAD src0_sel:WORD_1
	v_lshl_add_u64 v[16:17], v[26:27], 0, v[56:57]
	v_pk_add_f16 v8, v87, v8
	v_mov_b32_dpp v13, v13 row_ror:2 row_mask:0xf bank_mask:0xf
	v_pk_mul_f16 v0, v93, v0
	flat_store_dwordx4 v[16:17], v[82:85] nt
	v_mov_b32_dpp v13, v5 row_shr:2 row_mask:0xf bank_mask:0xf
	v_pk_fma_f16 v0, v5, v89, v0
	v_cvt_pk_bf16_f32 v82, v19, v23
	v_pk_mul_f16 v19, v8, v8
	v_pk_fma_f16 v0, v86, v13, v0
	v_pk_fma_f16 v19, v19, s89, v212 op_sel_hi:[1,0,0] neg_lo:[1,0,0] neg_hi:[1,0,0]
	v_pk_add_f16 v0, v87, v0
	v_pk_mul_f16 v19, v8, v19
	v_pk_mul_f16 v5, v0, v0
	v_exp_f16_e32 v20, v19
	v_exp_f16_sdwa v19, v19 dst_sel:DWORD dst_unused:UNUSED_PAD src0_sel:WORD_1
	v_pk_fma_f16 v5, v5, s89, v212 op_sel_hi:[1,0,0] neg_lo:[1,0,0] neg_hi:[1,0,0]
	v_mov_b32_e32 v9, v18
	v_pk_mul_f16 v5, v0, v5
	v_pack_b32_f16 v19, v20, v19
	v_exp_f16_e32 v6, v5
	v_exp_f16_sdwa v5, v5 dst_sel:DWORD dst_unused:UNUSED_PAD src0_sel:WORD_1
	v_pk_add_f16 v19, v19, 1.0 op_sel_hi:[1,0]
	v_mov_b32_dpp v9, v9 row_ror:1 row_mask:0xf bank_mask:0xf
	v_rcp_f16_e32 v20, v19
	v_rcp_f16_sdwa v19, v19 dst_sel:DWORD dst_unused:UNUSED_PAD src0_sel:WORD_1
	v_mov_b32_dpp v9, v10 row_shr:1 row_mask:0xf bank_mask:0xf
	v_pack_b32_f16 v5, v6, v5
	v_mov_b32_dpp v18, v18 row_ror:2 row_mask:0xf bank_mask:0xf
	v_pk_mul_f16 v9, v74, v9
	v_mov_b32_e32 v4, v10
	v_pk_add_f16 v5, v5, 1.0 op_sel_hi:[1,0]
	v_mov_b32_dpp v18, v10 row_shr:2 row_mask:0xf bank_mask:0xf
	v_pk_fma_f16 v9, v10, v62, v9
	v_mov_b32_dpp v4, v4 row_ror:1 row_mask:0xf bank_mask:0xf
	v_rcp_f16_e32 v6, v5
	v_rcp_f16_sdwa v5, v5 dst_sel:DWORD dst_unused:UNUSED_PAD src0_sel:WORD_1
	v_pk_fma_f16 v9, v73, v18, v9
	v_pack_b32_f16 v18, v20, v19
	v_mov_b32_dpp v4, v1 row_shr:1 row_mask:0xf bank_mask:0xf
	v_add_u32_e32 v16, 0x90, v72
	v_pk_add_f16 v9, v76, v9
	v_pk_mul_f16 v8, v8, v18
	v_mov_b32_dpp v10, v10 row_ror:2 row_mask:0xf bank_mask:0xf
	v_pk_mul_f16 v4, v74, v4
	v_mad_i64_i32 v[16:17], s[40:41], v16, s90, v[24:25]
	v_pk_mul_f16 v8, v9, v8
	v_mov_b32_dpp v10, v1 row_shr:2 row_mask:0xf bank_mask:0xf
	v_pk_fma_f16 v1, v1, v62, v4
	v_cvt_f32_f16_e32 v18, v8
	v_cvt_f32_f16_sdwa v19, v8 dst_sel:DWORD dst_unused:UNUSED_PAD src0_sel:WORD_1
	v_lshl_add_u64 v[8:9], v[16:17], 0, v[56:57]
	v_pk_fma_f16 v1, v73, v10, v1
	v_pack_b32_f16 v4, v6, v5
	v_cvt_pk_bf16_f32 v83, v28, v29
	flat_store_dwordx4 v[8:9], v[80:83] nt
	v_add_u32_e32 v8, 0xa0, v72
	v_pk_add_f16 v1, v76, v1
	v_pk_mul_f16 v0, v0, v4
	v_mad_i64_i32 v[8:9], s[40:41], v8, s90, v[24:25]
	v_pk_mul_f16 v0, v1, v0
	v_cvt_pk_bf16_f32 v68, v11, v15
	v_cvt_pk_bf16_f32 v69, v18, v19
	s_andn2_b64 vcc, exec, s[10:11]
	v_cvt_f32_f16_e32 v4, v0
	v_cvt_f32_f16_sdwa v5, v0 dst_sel:DWORD dst_unused:UNUSED_PAD src0_sel:WORD_1
	v_lshl_add_u64 v[0:1], v[8:9], 0, v[56:57]
	flat_store_dwordx4 v[0:1], v[66:69] nt
	v_add_u32_e32 v0, 0xb0, v72
	v_mad_i64_i32 v[0:1], s[40:41], v0, s90, v[24:25]
	v_lshl_add_u64 v[0:1], v[0:1], 0, v[56:57]
	s_mov_b64 s[10:11], -1
	v_cvt_pk_bf16_f32 v66, v2, v3
	v_cvt_pk_bf16_f32 v67, v4, v5
	flat_store_dwordx4 v[0:1], v[64:67] nt
	s_cbranch_vccnz .LBB0_1628
	s_and_b64 vcc, exec, s[12:13]
	s_cbranch_vccnz .LBB0_1627
	s_barrier
	s_branch .LBB0_1627

; __device__ __forceinline__ unsigned cvt_pk_bf16(float lo, float hi) { unsigned r; asm volatile("v_cvt_pk_bf16_f32 %0, %1, %2" : "=v"(r) : "v"(lo), "v"(hi)); return r; }
; #define GAS1 __attribute__((address_space(1)))
;     __device__ __forceinline__ void operator()(const f32x4 (&acc)[2][2][4][2], const Unit& u, int wr, int wc, int fr, int fq) const {
;     ...
;                 u32x4 w; w.x = cvt_pk_bf16(v0[0], v0[1]); w.y = cvt_pk_bf16(v0[2], v0[3]); w.z = cvt_pk_bf16(v1[0], v1[1]); w.w = cvt_pk_bf16(v1[2], v1[3]);
;                 if (bj == 0) asm volatile("ds_write_b128 %0, %1" :: "v"(wa), "v"(w)); else asm volatile("ds_write_b128 %0, %1 offset:64" :: "v"(wa), "v"(w));
;             }
;             asm volatile("ds_read_b128 %0, %1" : "=&v"(rb[g & 1][0]) : "v"(ra));
;             asm volatile("ds_read_b128 %0, %1 offset:1152" : "=&v"(rb[g & 1][1]) : "v"(ra));
;             if (g >= 1) {
;                 asm volatile("s_waitcnt lgkmcnt(4)" : "+v"(rb[(g - 1) & 1][0]), "+v"(rb[(g - 1) & 1][1]));
;                 bf16_t* ob = obase + (size_t)(((g - 1) >> 2) * HALF + ((g - 1) & 3) * 16) * ldc;
;                 *(GAS1 u32x4*)ob = rb[(g - 1) & 1][0]; *(GAS1 u32x4*)(ob + (size_t)8 * ldc) = rb[(g - 1) & 1][1];
;             }
;         }
;         asm volatile("s_waitcnt lgkmcnt(0)" : "+v"(rb[1][0]), "+v"(rb[1][1]));
;         { bf16_t* ob = obase + (size_t)(HALF + 3 * 16) * ldc; *(GAS1 u32x4*)ob = rb[1][0]; *(GAS1 u32x4*)(ob + (size_t)8 * ldc) = rb[1][1]; }
.LBB0_1788:
	v_lshl_add_u32 v146, s72, 8, v149
	v_ashrrev_i32_e32 v147, 31, v146
	v_lshlrev_b64 v[146:147], 12, v[146:147]
	s_lshl_b32 s22, s73, 8
	v_lshl_add_u64 v[146:147], s[14:15], 0, v[146:147]
	s_ashr_i32 s23, s22, 31
	v_lshl_add_u64 v[146:147], s[22:23], 1, v[146:147]
	v_cvt_pk_bf16_f32 v124, v124, v125
	v_cvt_pk_bf16_f32 v125, v126, v127
	v_cvt_pk_bf16_f32 v126, v120, v121
	v_cvt_pk_bf16_f32 v127, v122, v123
	v_lshl_add_u64 v[146:147], v[146:147], 0, s[10:11]
	ds_write_b128 v150, v[124:127]
	v_cvt_pk_bf16_f32 v112, v112, v113
	v_cvt_pk_bf16_f32 v113, v114, v115
	v_cvt_pk_bf16_f32 v114, v104, v105
	v_cvt_pk_bf16_f32 v115, v106, v107
	v_lshl_add_u64 v[146:147], v[146:147], 0, v[136:137]
	ds_write_b128 v150, v[112:115] offset:64
	ds_read_b128 v[104:107], v151
	ds_read_b128 v[112:115], v151 offset:1152
	v_cvt_pk_bf16_f32 v116, v116, v117
	v_cvt_pk_bf16_f32 v117, v118, v119
	v_cvt_pk_bf16_f32 v118, v108, v109
	v_cvt_pk_bf16_f32 v119, v110, v111
	s_nop 0
	ds_write_b128 v150, v[116:119]
	v_cvt_pk_bf16_f32 v100, v100, v101
	v_cvt_pk_bf16_f32 v101, v102, v103
	v_cvt_pk_bf16_f32 v102, v92, v93
	v_cvt_pk_bf16_f32 v103, v94, v95
	s_nop 0
	ds_write_b128 v150, v[100:103] offset:64
	ds_read_b128 v[92:95], v151
	ds_read_b128 v[100:103], v151 offset:1152
	s_waitcnt lgkmcnt(4)
	global_store_dwordx4 v[146:147], v[104:107], off nt
	s_nop 1
	v_add_co_u32_e32 v104, vcc, s57, v146
	s_nop 1
	v_addc_co_u32_e32 v105, vcc, 0, v147, vcc
	global_store_dwordx4 v[104:105], v[112:115], off nt
	v_cvt_pk_bf16_f32 v96, v96, v97
	v_cvt_pk_bf16_f32 v97, v98, v99
	v_cvt_pk_bf16_f32 v98, v88, v89
	v_add_co_u32_e32 v88, vcc, s43, v146
	v_cvt_pk_bf16_f32 v99, v90, v91
	s_nop 0
	ds_write_b128 v150, v[96:99]
	v_cvt_pk_bf16_f32 v84, v84, v85
	v_cvt_pk_bf16_f32 v85, v86, v87
	v_cvt_pk_bf16_f32 v86, v76, v77
	v_cvt_pk_bf16_f32 v87, v78, v79
	s_nop 0
	v_addc_co_u32_e32 v89, vcc, 0, v147, vcc
	ds_write_b128 v150, v[84:87] offset:64
	ds_read_b128 v[76:79], v151
	ds_read_b128 v[84:87], v151 offset:1152
	s_waitcnt lgkmcnt(4)
	global_store_dwordx4 v[88:89], v[92:95], off nt
	v_add_co_u32_e32 v88, vcc, s56, v146
	s_nop 1
	v_addc_co_u32_e32 v89, vcc, 0, v147, vcc
	global_store_dwordx4 v[88:89], v[100:103], off nt
	v_cvt_pk_bf16_f32 v80, v80, v81
	v_cvt_pk_bf16_f32 v81, v82, v83
	v_cvt_pk_bf16_f32 v82, v72, v73
	v_add_co_u32_e32 v72, vcc, s60, v146
	v_cvt_pk_bf16_f32 v83, v74, v75
	s_nop 0
	ds_write_b128 v150, v[80:83]
	v_cvt_pk_bf16_f32 v68, v68, v69
	v_cvt_pk_bf16_f32 v69, v70, v71
	v_cvt_pk_bf16_f32 v70, v64, v65
	v_cvt_pk_bf16_f32 v71, v66, v67
	s_nop 0
	v_addc_co_u32_e32 v73, vcc, 0, v147, vcc
	ds_write_b128 v150, v[68:71] offset:64
	ds_read_b128 v[64:67], v151
	ds_read_b128 v[68:71], v151 offset:1152
	s_waitcnt lgkmcnt(4)
	global_store_dwordx4 v[72:73], v[76:79], off nt
	v_add_co_u32_e32 v72, vcc, s61, v146
	s_nop 1
	v_addc_co_u32_e32 v73, vcc, 0, v147, vcc
	global_store_dwordx4 v[72:73], v[84:87], off nt
	v_cvt_pk_bf16_f32 v60, v60, v61
	v_cvt_pk_bf16_f32 v61, v62, v63
	v_cvt_pk_bf16_f32 v62, v56, v57
	v_add_co_u32_e32 v56, vcc, s62, v146
	v_cvt_pk_bf16_f32 v63, v58, v59
	s_nop 0
	ds_write_b128 v150, v[60:63]
	v_cvt_pk_bf16_f32 v52, v52, v53
	v_cvt_pk_bf16_f32 v53, v54, v55
	v_cvt_pk_bf16_f32 v54, v44, v45
	v_cvt_pk_bf16_f32 v55, v46, v47
	s_nop 0
	v_addc_co_u32_e32 v57, vcc, 0, v147, vcc
	ds_write_b128 v150, v[52:55] offset:64
	ds_read_b128 v[44:47], v151
	ds_read_b128 v[52:55], v151 offset:1152
	s_waitcnt lgkmcnt(4)
	global_store_dwordx4 v[56:57], v[64:67], off nt
	v_add_co_u32_e32 v56, vcc, s63, v146
	s_nop 1
	v_addc_co_u32_e32 v57, vcc, 0, v147, vcc
	global_store_dwordx4 v[56:57], v[68:71], off nt
	v_cvt_pk_bf16_f32 v48, v48, v49
	v_cvt_pk_bf16_f32 v49, v50, v51
	v_cvt_pk_bf16_f32 v50, v40, v41
	v_add_co_u32_e32 v40, vcc, s64, v146
	v_cvt_pk_bf16_f32 v51, v42, v43
	s_nop 0
	ds_write_b128 v150, v[48:51]
	v_cvt_pk_bf16_f32 v36, v36, v37
	v_cvt_pk_bf16_f32 v37, v38, v39
	v_cvt_pk_bf16_f32 v38, v28, v29
	v_cvt_pk_bf16_f32 v39, v30, v31
	s_nop 0
	v_addc_co_u32_e32 v41, vcc, 0, v147, vcc
	ds_write_b128 v150, v[36:39] offset:64
	ds_read_b128 v[28:31], v151
	ds_read_b128 v[36:39], v151 offset:1152
	s_waitcnt lgkmcnt(4)
	global_store_dwordx4 v[40:41], v[44:47], off nt
	v_add_co_u32_e32 v40, vcc, s65, v146
	s_nop 1
	v_addc_co_u32_e32 v41, vcc, 0, v147, vcc
	global_store_dwordx4 v[40:41], v[52:55], off nt
	v_cvt_pk_bf16_f32 v32, v32, v33
	v_cvt_pk_bf16_f32 v33, v34, v35
	v_cvt_pk_bf16_f32 v34, v24, v25
	v_add_co_u32_e32 v24, vcc, s66, v146
	v_cvt_pk_bf16_f32 v35, v26, v27
	s_nop 0
	ds_write_b128 v150, v[32:35]
	v_cvt_pk_bf16_f32 v20, v20, v21
	v_cvt_pk_bf16_f32 v21, v22, v23
	v_cvt_pk_bf16_f32 v22, v12, v13
	v_cvt_pk_bf16_f32 v23, v14, v15
	s_nop 0
	v_addc_co_u32_e32 v25, vcc, 0, v147, vcc
	ds_write_b128 v150, v[20:23] offset:64
	ds_read_b128 v[12:15], v151
	ds_read_b128 v[20:23], v151 offset:1152
	s_waitcnt lgkmcnt(4)
	global_store_dwordx4 v[24:25], v[28:31], off nt
	v_add_co_u32_e32 v24, vcc, s67, v146
	s_nop 1
	v_addc_co_u32_e32 v25, vcc, 0, v147, vcc
	global_store_dwordx4 v[24:25], v[36:39], off nt
	v_cvt_pk_bf16_f32 v16, v16, v17
	v_cvt_pk_bf16_f32 v17, v18, v19
	v_cvt_pk_bf16_f32 v18, v8, v9
	v_add_co_u32_e32 v8, vcc, s68, v146
	v_cvt_pk_bf16_f32 v19, v10, v11
	s_nop 0
	ds_write_b128 v150, v[16:19]
	v_cvt_pk_bf16_f32 v4, v4, v5
	v_cvt_pk_bf16_f32 v5, v6, v7
	v_cvt_pk_bf16_f32 v6, v0, v1
	v_cvt_pk_bf16_f32 v7, v2, v3
	s_nop 0
	v_addc_co_u32_e32 v9, vcc, 0, v147, vcc
	ds_write_b128 v150, v[4:7] offset:64
	ds_read_b128 v[0:3], v151
	ds_read_b128 v[4:7], v151 offset:1152
	s_waitcnt lgkmcnt(4)
	global_store_dwordx4 v[8:9], v[12:15], off nt
	v_add_co_u32_e32 v8, vcc, 0xa8000, v146
	s_nop 1
	v_addc_co_u32_e32 v9, vcc, 0, v147, vcc
	global_store_dwordx4 v[8:9], v[20:23], off nt
	v_add_co_u32_e32 v8, vcc, 0xb0000, v146
	s_waitcnt lgkmcnt(0)
	s_nop 1
	v_addc_co_u32_e32 v9, vcc, 0, v147, vcc
	global_store_dwordx4 v[8:9], v[0:3], off nt
	s_nop 1
	v_add_co_u32_e32 v0, vcc, 0xb8000, v146
	s_nop 1
	v_addc_co_u32_e32 v1, vcc, 0, v147, vcc
	s_and_b64 vcc, exec, s[4:5]
	s_mov_b64 s[4:5], -1
	global_store_dwordx4 v[0:1], v[4:7], off nt
	s_cbranch_vccnz .LBB0_1773
	s_andn2_b64 vcc, exec, s[12:13]
	s_cbranch_vccnz .LBB0_1772
	s_barrier
	s_branch .LBB0_1772
